# K-loops split in two bodies: waves 0-3 MFMA-first, waves 4-7 LDS-reads-first after the barrier
# baseline (speedup 1.0000x reference)
.LBB0_146:
	s_and_b32 s7, s4, 7
	v_lshl_add_u32 v0, s7, 8, v201
	v_ashrrev_i32_e32 v1, 31, v0
	v_lshlrev_b64 v[0:1], 11, v[0:1]
	s_and_b32 s7, s6, 0xffffff00
	v_lshl_add_u64 v[170:171], v[160:161], 0, v[0:1]
	v_add_u32_e32 v0, s7, v175
	s_and_b32 s7, s10, 7
	v_ashrrev_i32_e32 v1, 31, v0
	s_or_b32 s7, s7, s5
	v_lshlrev_b64 v[0:1], 11, v[0:1]
	s_lshl_b32 s7, s7, 8
	v_lshl_add_u64 v[172:173], v[168:169], 0, v[0:1]
	v_add_u32_e32 v0, s7, v175
	s_lshl_b32 s11, s10, 5
	v_ashrrev_i32_e32 v1, 31, v0
	s_and_b32 s11, s11, 0xffffff00
	v_add_u32_e32 v2, s11, v175
	v_lshlrev_b64 v[0:1], 11, v[0:1]
	s_waitcnt vmcnt(0) lgkmcnt(0)
	s_barrier
	v_ashrrev_i32_e32 v3, 31, v2
	v_lshl_add_u64 v[0:1], v[154:155], 0, v[0:1]
	v_readfirstlane_b32 s12, v180
	s_mov_b32 m0, s12
	s_nop 0
	global_load_lds_dwordx4 v[0:1], off
	v_lshlrev_b64 v[2:3], 11, v[2:3]
	v_lshl_add_u64 v[4:5], v[0:1], 0, s[34:35]
	s_add_i32 s13, s12, 0x2000
	s_mov_b32 m0, s13
	s_nop 0
	global_load_lds_dwordx4 v[4:5], off
	v_lshl_add_u64 v[2:3], v[156:157], 0, v[2:3]
	s_add_i32 s13, s12, 0x4000
	s_mov_b32 m0, s13
	s_nop 0
	global_load_lds_dwordx4 v[2:3], off
	v_lshl_add_u64 v[4:5], v[2:3], 0, s[34:35]
	s_add_i32 s13, s12, 0x6000
	s_mov_b32 m0, s13
	s_nop 0
	global_load_lds_dwordx4 v[4:5], off
	s_add_i32 s13, s12, 0x8000
	v_lshl_add_u64 v[4:5], v[0:1], 0, 64
	s_mov_b32 m0, s13
	s_nop 0
	global_load_lds_dwordx4 v[4:5], off
	s_mov_b64 s[14:15], 0x40040
	v_lshl_add_u64 v[4:5], v[0:1], 0, s[14:15]
	s_add_i32 s13, s12, 0xa000
	s_mov_b32 m0, s13
	s_nop 0
	global_load_lds_dwordx4 v[4:5], off
	v_lshl_add_u64 v[4:5], v[2:3], 0, 64
	s_add_i32 s13, s12, 0xc000
	s_mov_b32 m0, s13
	s_nop 0
	global_load_lds_dwordx4 v[4:5], off
	v_lshl_add_u64 v[4:5], v[2:3], 0, s[14:15]
	s_add_i32 s13, s12, 0xe000
	s_mov_b32 m0, s13
	s_nop 0
	global_load_lds_dwordx4 v[4:5], off
	s_mov_b64 s[14:15], 0x80
	s_add_i32 s13, s12, 0x10000
	v_lshl_add_u64 v[4:5], v[0:1], 0, s[14:15]
	s_mov_b32 m0, s13
	s_nop 0
	global_load_lds_dwordx4 v[4:5], off
	s_mov_b64 s[16:17], 0x40080
	v_lshl_add_u64 v[0:1], v[0:1], 0, s[16:17]
	s_add_i32 s13, s12, 0x12000
	s_mov_b32 m0, s13
	s_nop 0
	global_load_lds_dwordx4 v[0:1], off
	v_lshl_add_u64 v[0:1], v[2:3], 0, s[14:15]
	s_add_i32 s13, s12, 0x14000
	s_mov_b32 m0, s13
	s_nop 0
	global_load_lds_dwordx4 v[0:1], off
	v_lshl_add_u64 v[0:1], v[2:3], 0, s[16:17]
	s_add_i32 s12, s12, 0x16000
	s_mov_b32 m0, s12
	s_nop 0
	global_load_lds_dwordx4 v[0:1], off
	v_mov_b32_e32 v130, 0
	v_mov_b32_e32 v134, 0
	v_mov_b32_e32 v0, 0
	s_mov_b32 s12, 0x18000
	v_mov_b32_e32 v1, v0
	v_mov_b32_e32 v2, v0
	v_mov_b32_e32 v3, v0
	v_mov_b32_e32 v4, v0
	v_mov_b32_e32 v5, v0
	v_mov_b32_e32 v6, v0
	v_mov_b32_e32 v7, v0
	v_mov_b32_e32 v8, v0
	v_mov_b32_e32 v9, v0
	v_mov_b32_e32 v10, v0
	v_mov_b32_e32 v11, v0
	v_mov_b32_e32 v12, v0
	v_mov_b32_e32 v13, v0
	v_mov_b32_e32 v14, v0
	v_mov_b32_e32 v15, v0
	v_mov_b32_e32 v16, v0
	v_mov_b32_e32 v17, v0
	v_mov_b32_e32 v18, v0
	v_mov_b32_e32 v19, v0
	v_mov_b32_e32 v20, v0
	v_mov_b32_e32 v21, v0
	v_mov_b32_e32 v22, v0
	v_mov_b32_e32 v23, v0
	v_mov_b32_e32 v24, v0
	v_mov_b32_e32 v25, v0
	v_mov_b32_e32 v26, v0
	v_mov_b32_e32 v27, v0
	v_mov_b32_e32 v28, v0
	v_mov_b32_e32 v29, v0
	v_mov_b32_e32 v30, v0
	v_mov_b32_e32 v31, v0
	v_mov_b32_e32 v32, v0
	v_mov_b32_e32 v33, v0
	v_mov_b32_e32 v34, v0
	v_mov_b32_e32 v35, v0
	v_mov_b32_e32 v36, v0
	v_mov_b32_e32 v37, v0
	v_mov_b32_e32 v38, v0
	v_mov_b32_e32 v39, v0
	v_mov_b32_e32 v40, v0
	v_mov_b32_e32 v41, v0
	v_mov_b32_e32 v42, v0
	v_mov_b32_e32 v43, v0
	v_mov_b32_e32 v44, v0
	v_mov_b32_e32 v45, v0
	v_mov_b32_e32 v46, v0
	v_mov_b32_e32 v47, v0
	v_mov_b32_e32 v48, v0
	v_mov_b32_e32 v49, v0
	v_mov_b32_e32 v50, v0
	v_mov_b32_e32 v51, v0
	v_mov_b32_e32 v52, v0
	v_mov_b32_e32 v53, v0
	v_mov_b32_e32 v54, v0
	v_mov_b32_e32 v55, v0
	v_mov_b32_e32 v56, v0
	v_mov_b32_e32 v57, v0
	v_mov_b32_e32 v58, v0
	v_mov_b32_e32 v59, v0
	v_mov_b32_e32 v60, v0
	v_mov_b32_e32 v61, v0
	v_mov_b32_e32 v62, v0
	v_mov_b32_e32 v63, v0
	v_mov_b32_e32 v64, v0
	v_mov_b32_e32 v65, v0
	v_mov_b32_e32 v66, v0
	v_mov_b32_e32 v67, v0
	v_mov_b32_e32 v68, v0
	v_mov_b32_e32 v69, v0
	v_mov_b32_e32 v70, v0
	v_mov_b32_e32 v71, v0
	v_mov_b32_e32 v72, v0
	v_mov_b32_e32 v73, v0
	v_mov_b32_e32 v74, v0
	v_mov_b32_e32 v75, v0
	v_mov_b32_e32 v76, v0
	v_mov_b32_e32 v77, v0
	v_mov_b32_e32 v78, v0
	v_mov_b32_e32 v79, v0
	v_mov_b32_e32 v80, v0
	v_mov_b32_e32 v81, v0
	v_mov_b32_e32 v82, v0
	v_mov_b32_e32 v83, v0
	v_mov_b32_e32 v84, v0
	v_mov_b32_e32 v85, v0
	v_mov_b32_e32 v86, v0
	v_mov_b32_e32 v87, v0
	v_mov_b32_e32 v88, v0
	v_mov_b32_e32 v89, v0
	v_mov_b32_e32 v90, v0
	v_mov_b32_e32 v91, v0
	v_mov_b32_e32 v92, v0
	v_mov_b32_e32 v93, v0
	v_mov_b32_e32 v94, v0
	v_mov_b32_e32 v95, v0
	v_mov_b32_e32 v96, v0
	v_mov_b32_e32 v97, v0
	v_mov_b32_e32 v98, v0
	v_mov_b32_e32 v99, v0
	v_mov_b32_e32 v100, v0
	v_mov_b32_e32 v101, v0
	v_mov_b32_e32 v102, v0
	v_mov_b32_e32 v103, v0
	v_mov_b32_e32 v104, v0
	v_mov_b32_e32 v105, v0
	v_mov_b32_e32 v106, v0
	v_mov_b32_e32 v107, v0
	v_mov_b32_e32 v108, v0
	v_mov_b32_e32 v109, v0
	v_mov_b32_e32 v110, v0
	v_mov_b32_e32 v111, v0
	v_mov_b32_e32 v112, v0
	v_mov_b32_e32 v113, v0
	v_mov_b32_e32 v114, v0
	v_mov_b32_e32 v115, v0
	v_mov_b32_e32 v116, v0
	v_mov_b32_e32 v117, v0
	v_mov_b32_e32 v118, v0
	v_mov_b32_e32 v119, v0
	v_mov_b32_e32 v120, v0
	v_mov_b32_e32 v121, v0
	v_mov_b32_e32 v122, v0
	v_mov_b32_e32 v123, v0
	v_mov_b32_e32 v124, v0
	v_mov_b32_e32 v125, v0
	v_mov_b32_e32 v126, v0
	v_mov_b32_e32 v127, v0
	v_mov_b32_e32 v135, v134
	v_mov_b32_e32 v136, v134
	v_mov_b32_e32 v137, v134
	v_mov_b32_e32 v138, v134
	v_mov_b32_e32 v139, v134
	v_mov_b32_e32 v140, v134
	v_mov_b32_e32 v141, v134
	v_mov_b32_e32 v146, v134
	v_mov_b32_e32 v147, v134
	v_mov_b32_e32 v148, v134
	v_mov_b32_e32 v149, v134
	v_mov_b32_e32 v150, v134
	v_mov_b32_e32 v151, v134
	v_mov_b32_e32 v152, v134
	v_mov_b32_e32 v153, v134
	v_mov_b32_e32 v131, v130
	v_mov_b32_e32 v132, v130
	v_mov_b32_e32 v133, v130
	v_mov_b32_e32 v142, v130
	v_mov_b32_e32 v143, v130
	v_mov_b32_e32 v144, v130
	v_mov_b32_e32 v145, v130
	v_readfirstlane_b32 s100, v163
	s_cmp_ge_u32 s100, 0x100
	s_cbranch_scc1 .Lky_0
.LBB0_147:
	s_and_b32 s13, s12, 0x18000
	v_add_u32_e32 v222, s13, v180
	s_add_i32 s13, s12, 0xfffe8000
	s_and_b32 s13, s13, 0x18000
	v_or_b32_e32 v223, s13, v179
	v_add_u32_e32 v233, s13, v176
	s_waitcnt vmcnt(8) lgkmcnt(0)
	s_barrier
	v_mfma_f32_32x32x16_bf16 v[112:127], v[150:153], v[142:145], v[112:127]
	v_mfma_f32_32x32x16_bf16 v[96:111], v[150:153], v[130:133], v[96:111]
	v_add_u32_e32 v206, v223, v177
	v_add_u32_e32 v234, v233, v177
	ds_read_b128 v[202:205], v206 offset:16384
	ds_read_b128 v[206:209], v206 offset:18432
	ds_read_b128 v[210:213], v234
	ds_read_b128 v[214:217], v234 offset:2048
	ds_read_b128 v[224:227], v234 offset:4096
	ds_read_b128 v[234:237], v234 offset:6144
	v_mfma_f32_32x32x16_bf16 v[80:95], v[146:149], v[142:145], v[80:95]
	v_mfma_f32_32x32x16_bf16 v[64:79], v[146:149], v[130:133], v[64:79]
	v_readfirstlane_b32 s13, v222
	s_mov_b32 m0, s13
	s_nop 0
	global_load_lds_dwordx4 v[170:171], off
	v_mfma_f32_32x32x16_bf16 v[48:63], v[138:141], v[142:145], v[48:63]
	v_mfma_f32_32x32x16_bf16 v[32:47], v[138:141], v[130:133], v[32:47]
	s_add_i32 s14, s13, 0x2000
	v_lshl_add_u64 v[150:151], v[170:171], 0, s[34:35]
	s_mov_b32 m0, s14
	s_nop 0
	global_load_lds_dwordx4 v[150:151], off
	v_mfma_f32_32x32x16_bf16 v[16:31], v[134:137], v[142:145], v[16:31]
	v_mfma_f32_32x32x16_bf16 v[0:15], v[134:137], v[130:133], v[0:15]
	v_add_u32_e32 v130, v223, v178
	v_add_u32_e32 v134, v233, v178
	ds_read_b128 v[142:145], v130 offset:16384
	ds_read_b128 v[130:133], v130 offset:18432
	ds_read_b128 v[150:153], v134
	ds_read_b128 v[146:149], v134 offset:2048
	ds_read_b128 v[138:141], v134 offset:4096
	ds_read_b128 v[134:137], v134 offset:6144
	s_waitcnt lgkmcnt(9)
	v_mfma_f32_32x32x16_bf16 v[112:127], v[210:213], v[202:205], v[112:127]
	s_add_i32 s14, s13, 0x6000
	s_addk_i32 s13, 0x4000
	v_mfma_f32_32x32x16_bf16 v[96:111], v[210:213], v[206:209], v[96:111]
	s_mov_b32 m0, s13
	s_nop 0
	global_load_lds_dwordx4 v[172:173], off
	v_lshl_add_u64 v[222:223], v[172:173], 0, s[34:35]
	s_waitcnt lgkmcnt(8)
	v_mfma_f32_32x32x16_bf16 v[80:95], v[214:217], v[202:205], v[80:95]
	v_mfma_f32_32x32x16_bf16 v[64:79], v[214:217], v[206:209], v[64:79]
	s_waitcnt lgkmcnt(7)
	v_mfma_f32_32x32x16_bf16 v[48:63], v[224:227], v[202:205], v[48:63]
	v_mfma_f32_32x32x16_bf16 v[32:47], v[224:227], v[206:209], v[32:47]
	s_mov_b32 m0, s14
	s_nop 0
	global_load_lds_dwordx4 v[222:223], off
	s_waitcnt lgkmcnt(6)
	v_mfma_f32_32x32x16_bf16 v[16:31], v[234:237], v[202:205], v[16:31]
	s_add_i32 s12, s12, 0x8000
	v_lshl_add_u64 v[170:171], v[170:171], 0, 64
	v_lshl_add_u64 v[172:173], v[172:173], 0, 64
	s_cmp_eq_u32 s12, 0x100000
	v_mfma_f32_32x32x16_bf16 v[0:15], v[234:237], v[206:209], v[0:15]
	s_cbranch_scc0 .LBB0_147
	s_branch .Lktail_0
.Lky_0:
	s_and_b32 s13, s12, 0x18000
	v_add_u32_e32 v222, s13, v180
	s_add_i32 s13, s12, 0xfffe8000
	s_and_b32 s13, s13, 0x18000
	v_or_b32_e32 v223, s13, v179
	v_add_u32_e32 v233, s13, v176
	s_waitcnt vmcnt(8) lgkmcnt(0)
	s_barrier
	v_add_u32_e32 v206, v223, v177
	v_add_u32_e32 v234, v233, v177
	ds_read_b128 v[202:205], v206 offset:16384
	ds_read_b128 v[206:209], v206 offset:18432
	ds_read_b128 v[210:213], v234
	ds_read_b128 v[214:217], v234 offset:2048
	ds_read_b128 v[224:227], v234 offset:4096
	ds_read_b128 v[234:237], v234 offset:6144
	v_mfma_f32_32x32x16_bf16 v[112:127], v[150:153], v[142:145], v[112:127]
	v_mfma_f32_32x32x16_bf16 v[96:111], v[150:153], v[130:133], v[96:111]
	v_readfirstlane_b32 s13, v222
	s_mov_b32 m0, s13
	s_nop 0
	global_load_lds_dwordx4 v[170:171], off
	v_mfma_f32_32x32x16_bf16 v[80:95], v[146:149], v[142:145], v[80:95]
	v_mfma_f32_32x32x16_bf16 v[64:79], v[146:149], v[130:133], v[64:79]
	v_mfma_f32_32x32x16_bf16 v[48:63], v[138:141], v[142:145], v[48:63]
	v_mfma_f32_32x32x16_bf16 v[32:47], v[138:141], v[130:133], v[32:47]
	s_add_i32 s14, s13, 0x2000
	v_lshl_add_u64 v[150:151], v[170:171], 0, s[34:35]
	s_mov_b32 m0, s14
	s_nop 0
	global_load_lds_dwordx4 v[150:151], off
	v_mfma_f32_32x32x16_bf16 v[16:31], v[134:137], v[142:145], v[16:31]
	v_mfma_f32_32x32x16_bf16 v[0:15], v[134:137], v[130:133], v[0:15]
	v_add_u32_e32 v130, v223, v178
	v_add_u32_e32 v134, v233, v178
	ds_read_b128 v[142:145], v130 offset:16384
	ds_read_b128 v[130:133], v130 offset:18432
	ds_read_b128 v[150:153], v134
	ds_read_b128 v[146:149], v134 offset:2048
	ds_read_b128 v[138:141], v134 offset:4096
	ds_read_b128 v[134:137], v134 offset:6144
	s_waitcnt lgkmcnt(9)
	v_mfma_f32_32x32x16_bf16 v[112:127], v[210:213], v[202:205], v[112:127]
	s_add_i32 s14, s13, 0x6000
	s_addk_i32 s13, 0x4000
	v_mfma_f32_32x32x16_bf16 v[96:111], v[210:213], v[206:209], v[96:111]
	s_mov_b32 m0, s13
	s_nop 0
	global_load_lds_dwordx4 v[172:173], off
	v_lshl_add_u64 v[222:223], v[172:173], 0, s[34:35]
	s_waitcnt lgkmcnt(8)
	v_mfma_f32_32x32x16_bf16 v[80:95], v[214:217], v[202:205], v[80:95]
	v_mfma_f32_32x32x16_bf16 v[64:79], v[214:217], v[206:209], v[64:79]
	s_waitcnt lgkmcnt(7)
	v_mfma_f32_32x32x16_bf16 v[48:63], v[224:227], v[202:205], v[48:63]
	v_mfma_f32_32x32x16_bf16 v[32:47], v[224:227], v[206:209], v[32:47]
	s_mov_b32 m0, s14
	s_nop 0
	global_load_lds_dwordx4 v[222:223], off
	s_waitcnt lgkmcnt(6)
	v_mfma_f32_32x32x16_bf16 v[16:31], v[234:237], v[202:205], v[16:31]
	s_add_i32 s12, s12, 0x8000
	v_lshl_add_u64 v[170:171], v[170:171], 0, 64
	v_lshl_add_u64 v[172:173], v[172:173], 0, 64
	s_cmp_eq_u32 s12, 0x100000
	v_mfma_f32_32x32x16_bf16 v[0:15], v[234:237], v[206:209], v[0:15]
	s_cbranch_scc0 .Lky_0
.Lktail_0:
	s_waitcnt vmcnt(8) lgkmcnt(0)
	s_barrier
	v_add_u32_e32 v202, v179, v177
	v_add_u32_e32 v222, v176, v177
	ds_read_b128 v[170:173], v202 offset:49152
	ds_read_b128 v[202:205], v202 offset:51200
	ds_read_b128 v[206:209], v222 offset:32768
	ds_read_b128 v[210:213], v222 offset:34816
	ds_read_b128 v[214:217], v222 offset:36864
	ds_read_b128 v[224:227], v222 offset:38912
	s_waitcnt lgkmcnt(9)
	v_mfma_f32_32x32x16_bf16 v[112:127], v[150:153], v[142:145], v[112:127]
	v_mfma_f32_32x32x16_bf16 v[96:111], v[150:153], v[130:133], v[96:111]
	s_waitcnt lgkmcnt(8)
	v_mfma_f32_32x32x16_bf16 v[80:95], v[146:149], v[142:145], v[80:95]
	v_mfma_f32_32x32x16_bf16 v[64:79], v[146:149], v[130:133], v[64:79]
	s_waitcnt lgkmcnt(7)
	v_mfma_f32_32x32x16_bf16 v[48:63], v[138:141], v[142:145], v[48:63]
	v_mfma_f32_32x32x16_bf16 v[32:47], v[138:141], v[130:133], v[32:47]
	s_waitcnt lgkmcnt(6)
	v_mfma_f32_32x32x16_bf16 v[16:31], v[134:137], v[142:145], v[16:31]
	v_mfma_f32_32x32x16_bf16 v[0:15], v[134:137], v[130:133], v[0:15]
	v_add_u32_e32 v134, v179, v178
	v_add_u32_e32 v150, v176, v178
	ds_read_b128 v[130:133], v134 offset:49152
	ds_read_b128 v[134:137], v134 offset:51200
	ds_read_b128 v[138:141], v150 offset:32768
	ds_read_b128 v[142:145], v150 offset:34816
	ds_read_b128 v[146:149], v150 offset:36864
	ds_read_b128 v[150:153], v150 offset:38912
	s_waitcnt lgkmcnt(9)
	v_mfma_f32_32x32x16_bf16 v[112:127], v[206:209], v[170:173], v[112:127]
	v_mfma_f32_32x32x16_bf16 v[96:111], v[206:209], v[202:205], v[96:111]
	s_waitcnt lgkmcnt(8)
	v_mfma_f32_32x32x16_bf16 v[80:95], v[210:213], v[170:173], v[80:95]
	v_mfma_f32_32x32x16_bf16 v[64:79], v[210:213], v[202:205], v[64:79]
	s_waitcnt lgkmcnt(7)
	v_mfma_f32_32x32x16_bf16 v[48:63], v[214:217], v[170:173], v[48:63]
	v_mfma_f32_32x32x16_bf16 v[32:47], v[214:217], v[202:205], v[32:47]
	s_waitcnt lgkmcnt(6)
	v_mfma_f32_32x32x16_bf16 v[0:15], v[224:227], v[202:205], v[0:15]
	s_waitcnt vmcnt(4) lgkmcnt(0)
	s_barrier
	v_add_u32_e32 v202, v199, v177
	v_add_u32_e32 v222, v200, v177
	v_mfma_f32_32x32x16_bf16 v[16:31], v[224:227], v[170:173], v[16:31]
	ds_read_b128 v[170:173], v202 offset:16384
	ds_read_b128 v[202:205], v202 offset:18432
	ds_read_b128 v[206:209], v222
	ds_read_b128 v[210:213], v222 offset:2048
	ds_read_b128 v[214:217], v222 offset:4096
	ds_read_b128 v[224:227], v222 offset:6144
	s_waitcnt lgkmcnt(9)
	v_mfma_f32_32x32x16_bf16 v[112:127], v[138:141], v[130:133], v[112:127]
	v_mfma_f32_32x32x16_bf16 v[96:111], v[138:141], v[134:137], v[96:111]
	s_waitcnt lgkmcnt(8)
	v_mfma_f32_32x32x16_bf16 v[80:95], v[142:145], v[130:133], v[80:95]
	v_mfma_f32_32x32x16_bf16 v[64:79], v[142:145], v[134:137], v[64:79]
	s_waitcnt lgkmcnt(7)
	v_mfma_f32_32x32x16_bf16 v[48:63], v[146:149], v[130:133], v[48:63]
	v_mfma_f32_32x32x16_bf16 v[32:47], v[146:149], v[134:137], v[32:47]
	s_waitcnt lgkmcnt(6)
	v_mfma_f32_32x32x16_bf16 v[16:31], v[150:153], v[130:133], v[16:31]
	v_mfma_f32_32x32x16_bf16 v[0:15], v[150:153], v[134:137], v[0:15]
	v_add_u32_e32 v134, v199, v178
	v_add_u32_e32 v150, v200, v178
	ds_read_b128 v[130:133], v134 offset:16384
	ds_read_b128 v[134:137], v134 offset:18432
	ds_read_b128 v[138:141], v150
	ds_read_b128 v[142:145], v150 offset:2048
	ds_read_b128 v[146:149], v150 offset:4096
	ds_read_b128 v[150:153], v150 offset:6144
	s_waitcnt lgkmcnt(9)
	v_mfma_f32_32x32x16_bf16 v[112:127], v[206:209], v[170:173], v[112:127]
	v_mfma_f32_32x32x16_bf16 v[96:111], v[206:209], v[202:205], v[96:111]
	s_waitcnt lgkmcnt(8)
	v_mfma_f32_32x32x16_bf16 v[80:95], v[210:213], v[170:173], v[80:95]
	v_mfma_f32_32x32x16_bf16 v[64:79], v[210:213], v[202:205], v[64:79]
	s_waitcnt lgkmcnt(7)
	v_mfma_f32_32x32x16_bf16 v[48:63], v[214:217], v[170:173], v[48:63]
	v_mfma_f32_32x32x16_bf16 v[32:47], v[214:217], v[202:205], v[32:47]
	s_waitcnt lgkmcnt(6)
	v_mfma_f32_32x32x16_bf16 v[0:15], v[224:227], v[202:205], v[0:15]
	s_waitcnt vmcnt(0) lgkmcnt(0)
	s_barrier
	v_add_u32_e32 v202, v197, v177
	v_add_u32_e32 v222, v198, v177
	v_mfma_f32_32x32x16_bf16 v[16:31], v[224:227], v[170:173], v[16:31]
	ds_read_b128 v[170:173], v202 offset:16384
	ds_read_b128 v[202:205], v202 offset:18432
	ds_read_b128 v[206:209], v222
	ds_read_b128 v[210:213], v222 offset:2048
	ds_read_b128 v[214:217], v222 offset:4096
	ds_read_b128 v[224:227], v222 offset:6144
	s_waitcnt lgkmcnt(9)
	v_mfma_f32_32x32x16_bf16 v[112:127], v[138:141], v[130:133], v[112:127]
	v_mfma_f32_32x32x16_bf16 v[96:111], v[138:141], v[134:137], v[96:111]
	s_waitcnt lgkmcnt(8)
	v_mfma_f32_32x32x16_bf16 v[80:95], v[142:145], v[130:133], v[80:95]
	v_mfma_f32_32x32x16_bf16 v[64:79], v[142:145], v[134:137], v[64:79]
	s_waitcnt lgkmcnt(7)
	v_mfma_f32_32x32x16_bf16 v[48:63], v[146:149], v[130:133], v[48:63]
	v_mfma_f32_32x32x16_bf16 v[32:47], v[146:149], v[134:137], v[32:47]
	s_waitcnt lgkmcnt(6)
	v_mfma_f32_32x32x16_bf16 v[16:31], v[150:153], v[130:133], v[16:31]
	v_mfma_f32_32x32x16_bf16 v[0:15], v[150:153], v[134:137], v[0:15]
	v_add_u32_e32 v134, v197, v178
	v_add_u32_e32 v150, v198, v178
	ds_read_b128 v[130:133], v134 offset:16384
	ds_read_b128 v[134:137], v134 offset:18432
	ds_read_b128 v[138:141], v150
	ds_read_b128 v[142:145], v150 offset:2048
	ds_read_b128 v[146:149], v150 offset:4096
	ds_read_b128 v[150:153], v150 offset:6144
	s_waitcnt lgkmcnt(9)
	v_mfma_f32_32x32x16_bf16 v[112:127], v[206:209], v[170:173], v[112:127]
	v_mfma_f32_32x32x16_bf16 v[96:111], v[206:209], v[202:205], v[96:111]
	s_waitcnt lgkmcnt(8)
	v_mfma_f32_32x32x16_bf16 v[80:95], v[210:213], v[170:173], v[80:95]
	v_mfma_f32_32x32x16_bf16 v[64:79], v[210:213], v[202:205], v[64:79]
	s_waitcnt lgkmcnt(7)
	v_mfma_f32_32x32x16_bf16 v[48:63], v[214:217], v[170:173], v[48:63]
	v_mfma_f32_32x32x16_bf16 v[32:47], v[214:217], v[202:205], v[32:47]
	s_waitcnt lgkmcnt(6)
	v_mfma_f32_32x32x16_bf16 v[16:31], v[224:227], v[170:173], v[16:31]
	v_mfma_f32_32x32x16_bf16 v[0:15], v[224:227], v[202:205], v[0:15]
	s_waitcnt lgkmcnt(3)
	v_mfma_f32_32x32x16_bf16 v[96:111], v[138:141], v[134:137], v[96:111]
	v_mfma_f32_32x32x16_bf16 v[112:127], v[138:141], v[130:133], v[112:127]
	s_nop 10
	v_cvt_pk_bf16_f32 v96, v96, s0
	v_cvt_pk_bf16_f32 v98, v98, s0
	s_waitcnt lgkmcnt(2)
	v_mfma_f32_32x32x16_bf16 v[80:95], v[142:145], v[130:133], v[80:95]
	v_cvt_pk_bf16_f32 v112, v112, s0
	s_waitcnt lgkmcnt(1)
	v_mfma_f32_32x32x16_bf16 v[48:63], v[146:149], v[130:133], v[48:63]
	s_nop 8
	v_cvt_pk_bf16_f32 v80, v80, s0
	s_waitcnt lgkmcnt(0)
	v_mfma_f32_32x32x16_bf16 v[16:31], v[150:153], v[130:133], v[16:31]
	v_or_b32_e32 v130, s11, v174
	v_ashrrev_i32_e32 v131, 31, v130
	v_lshl_add_u64 v[130:131], v[130:131], 1, v[158:159]
	v_cvt_pk_bf16_f32 v48, v48, s0
	v_mfma_f32_32x32x16_bf16 v[64:79], v[142:145], v[134:137], v[64:79]
	s_nop 6
	v_cvt_pk_bf16_f32 v16, v16, s0
	v_mfma_f32_32x32x16_bf16 v[32:47], v[146:149], v[134:137], v[32:47]
	s_nop 2
	v_cvt_pk_bf16_f32 v64, v64, s0
	v_cvt_pk_bf16_f32 v66, v66, s0
	v_mfma_f32_32x32x16_bf16 v[0:15], v[150:153], v[134:137], v[0:15]
	v_add_u32_e32 v134, s7, v128
	v_or_b32_e32 v132, v134, v181
	s_movk_i32 s7, 0x1800
	v_mad_i64_i32 v[132:133], s[12:13], v132, s7, v[130:131]
	global_store_short v[132:133], v96, off offset:64
	v_or_b32_e32 v96, v134, v182
	global_store_short v[132:133], v112, off
	v_mad_i64_i32 v[132:133], s[12:13], v96, s7, v[130:131]
	v_cvt_pk_bf16_f32 v96, v113, s0
	global_store_short v[132:133], v96, off
	v_cvt_pk_bf16_f32 v96, v97, s0
	global_store_short v[132:133], v96, off offset:64
	v_or_b32_e32 v96, v134, v183
	v_mad_i64_i32 v[96:97], s[12:13], v96, s7, v[130:131]
	v_cvt_pk_bf16_f32 v112, v114, s0
	global_store_short v[96:97], v112, off
	global_store_short v[96:97], v98, off offset:64
	v_or_b32_e32 v96, v134, v184
	v_mad_i64_i32 v[96:97], s[12:13], v96, s7, v[130:131]
	v_cvt_pk_bf16_f32 v98, v115, s0
	global_store_short v[96:97], v98, off
	v_cvt_pk_bf16_f32 v98, v99, s0
	global_store_short v[96:97], v98, off offset:64
	v_or_b32_e32 v96, v134, v185
	v_mad_i64_i32 v[96:97], s[12:13], v96, s7, v[130:131]
	v_cvt_pk_bf16_f32 v98, v116, s0
	global_store_short v[96:97], v98, off
	v_cvt_pk_bf16_f32 v98, v100, s0
	global_store_short v[96:97], v98, off offset:64
	v_or_b32_e32 v96, v134, v186
	v_mad_i64_i32 v[96:97], s[12:13], v96, s7, v[130:131]
	v_cvt_pk_bf16_f32 v98, v117, s0
	global_store_short v[96:97], v98, off
	v_cvt_pk_bf16_f32 v98, v101, s0
	global_store_short v[96:97], v98, off offset:64
	v_or_b32_e32 v96, v134, v187
	v_mad_i64_i32 v[96:97], s[12:13], v96, s7, v[130:131]
	v_cvt_pk_bf16_f32 v98, v118, s0
	global_store_short v[96:97], v98, off
	v_cvt_pk_bf16_f32 v98, v102, s0
	global_store_short v[96:97], v98, off offset:64
	v_or_b32_e32 v96, v134, v188
	v_mad_i64_i32 v[96:97], s[12:13], v96, s7, v[130:131]
	v_cvt_pk_bf16_f32 v98, v119, s0
	global_store_short v[96:97], v98, off
	v_cvt_pk_bf16_f32 v98, v103, s0
	global_store_short v[96:97], v98, off offset:64
	v_or_b32_e32 v96, v134, v189
	v_mad_i64_i32 v[96:97], s[12:13], v96, s7, v[130:131]
	v_cvt_pk_bf16_f32 v98, v120, s0
	global_store_short v[96:97], v98, off
	v_cvt_pk_bf16_f32 v98, v104, s0
	global_store_short v[96:97], v98, off offset:64
	v_or_b32_e32 v96, v134, v190
	v_mad_i64_i32 v[96:97], s[12:13], v96, s7, v[130:131]
	v_cvt_pk_bf16_f32 v98, v121, s0
	global_store_short v[96:97], v98, off
	v_cvt_pk_bf16_f32 v98, v105, s0
	global_store_short v[96:97], v98, off offset:64
	v_or_b32_e32 v96, v134, v191
	v_mad_i64_i32 v[96:97], s[12:13], v96, s7, v[130:131]
	v_cvt_pk_bf16_f32 v98, v122, s0
	global_store_short v[96:97], v98, off
	v_cvt_pk_bf16_f32 v98, v106, s0
	global_store_short v[96:97], v98, off offset:64
	v_or_b32_e32 v96, v134, v192
	v_mad_i64_i32 v[96:97], s[12:13], v96, s7, v[130:131]
	v_cvt_pk_bf16_f32 v98, v123, s0
	global_store_short v[96:97], v98, off
	v_cvt_pk_bf16_f32 v98, v107, s0
	global_store_short v[96:97], v98, off offset:64
	v_or_b32_e32 v96, v134, v193
	v_mad_i64_i32 v[96:97], s[12:13], v96, s7, v[130:131]
	v_cvt_pk_bf16_f32 v98, v124, s0
	global_store_short v[96:97], v98, off
	v_cvt_pk_bf16_f32 v98, v108, s0
	global_store_short v[96:97], v98, off offset:64
	v_or_b32_e32 v96, v134, v194
	v_mad_i64_i32 v[96:97], s[12:13], v96, s7, v[130:131]
	v_cvt_pk_bf16_f32 v98, v125, s0
	global_store_short v[96:97], v98, off
	v_cvt_pk_bf16_f32 v98, v109, s0
	global_store_short v[96:97], v98, off offset:64
	v_or_b32_e32 v96, v134, v195
	v_mad_i64_i32 v[96:97], s[12:13], v96, s7, v[130:131]
	v_cvt_pk_bf16_f32 v98, v126, s0
	global_store_short v[96:97], v98, off
	v_cvt_pk_bf16_f32 v98, v110, s0
	global_store_short v[96:97], v98, off offset:64
	v_or_b32_e32 v96, v134, v196
	v_mad_i64_i32 v[96:97], s[12:13], v96, s7, v[130:131]
	v_cvt_pk_bf16_f32 v98, v127, s0
	global_store_short v[96:97], v98, off
	v_cvt_pk_bf16_f32 v98, v111, s0
	global_store_short v[96:97], v98, off offset:64
	v_or_b32_e32 v98, 32, v134
	v_or_b32_e32 v96, v98, v181
	v_mad_i64_i32 v[96:97], s[12:13], v96, s7, v[130:131]
	global_store_short v[96:97], v64, off offset:64
	v_or_b32_e32 v64, v98, v182
	global_store_short v[96:97], v80, off
	v_mad_i64_i32 v[96:97], s[12:13], v64, s7, v[130:131]
	v_cvt_pk_bf16_f32 v64, v81, s0
	global_store_short v[96:97], v64, off
	v_cvt_pk_bf16_f32 v64, v65, s0
	global_store_short v[96:97], v64, off offset:64
	v_or_b32_e32 v64, v98, v183
	v_mad_i64_i32 v[64:65], s[12:13], v64, s7, v[130:131]
	v_cvt_pk_bf16_f32 v80, v82, s0
	global_store_short v[64:65], v80, off
	global_store_short v[64:65], v66, off offset:64
	v_or_b32_e32 v64, v98, v184
	v_mad_i64_i32 v[64:65], s[12:13], v64, s7, v[130:131]
	v_cvt_pk_bf16_f32 v66, v83, s0
	global_store_short v[64:65], v66, off
	v_cvt_pk_bf16_f32 v66, v67, s0
	global_store_short v[64:65], v66, off offset:64
	v_or_b32_e32 v64, v98, v185
	v_mad_i64_i32 v[64:65], s[12:13], v64, s7, v[130:131]
	v_cvt_pk_bf16_f32 v66, v84, s0
	global_store_short v[64:65], v66, off
	v_cvt_pk_bf16_f32 v66, v68, s0
	global_store_short v[64:65], v66, off offset:64
	v_or_b32_e32 v64, v98, v186
	v_mad_i64_i32 v[64:65], s[12:13], v64, s7, v[130:131]
	v_cvt_pk_bf16_f32 v66, v85, s0
	global_store_short v[64:65], v66, off
	v_cvt_pk_bf16_f32 v66, v69, s0
	global_store_short v[64:65], v66, off offset:64
	v_or_b32_e32 v64, v98, v187
	v_mad_i64_i32 v[64:65], s[12:13], v64, s7, v[130:131]
	v_cvt_pk_bf16_f32 v66, v86, s0
	global_store_short v[64:65], v66, off
	v_cvt_pk_bf16_f32 v66, v70, s0
	global_store_short v[64:65], v66, off offset:64
	v_or_b32_e32 v64, v98, v188
	v_mad_i64_i32 v[64:65], s[12:13], v64, s7, v[130:131]
	v_cvt_pk_bf16_f32 v66, v87, s0
	global_store_short v[64:65], v66, off
	v_cvt_pk_bf16_f32 v66, v71, s0
	global_store_short v[64:65], v66, off offset:64
	v_or_b32_e32 v64, v98, v189
	v_mad_i64_i32 v[64:65], s[12:13], v64, s7, v[130:131]
	v_cvt_pk_bf16_f32 v66, v88, s0
	global_store_short v[64:65], v66, off
	v_cvt_pk_bf16_f32 v66, v72, s0
	global_store_short v[64:65], v66, off offset:64
	v_or_b32_e32 v64, v98, v190
	v_mad_i64_i32 v[64:65], s[12:13], v64, s7, v[130:131]
	v_cvt_pk_bf16_f32 v66, v89, s0
	global_store_short v[64:65], v66, off
	v_cvt_pk_bf16_f32 v66, v73, s0
	global_store_short v[64:65], v66, off offset:64
	v_or_b32_e32 v64, v98, v191
	v_mad_i64_i32 v[64:65], s[12:13], v64, s7, v[130:131]
	v_cvt_pk_bf16_f32 v66, v90, s0
	global_store_short v[64:65], v66, off
	v_cvt_pk_bf16_f32 v66, v74, s0
	global_store_short v[64:65], v66, off offset:64
	v_or_b32_e32 v64, v98, v192
	v_mad_i64_i32 v[64:65], s[12:13], v64, s7, v[130:131]
	v_cvt_pk_bf16_f32 v66, v91, s0
	global_store_short v[64:65], v66, off
	v_cvt_pk_bf16_f32 v66, v75, s0
	global_store_short v[64:65], v66, off offset:64
	v_or_b32_e32 v64, v98, v193
	v_mad_i64_i32 v[64:65], s[12:13], v64, s7, v[130:131]
	v_cvt_pk_bf16_f32 v66, v92, s0
	global_store_short v[64:65], v66, off
	v_cvt_pk_bf16_f32 v66, v76, s0
	global_store_short v[64:65], v66, off offset:64
	v_or_b32_e32 v64, v98, v194
	v_mad_i64_i32 v[64:65], s[12:13], v64, s7, v[130:131]
	v_cvt_pk_bf16_f32 v66, v93, s0
	global_store_short v[64:65], v66, off
	v_cvt_pk_bf16_f32 v66, v77, s0
	global_store_short v[64:65], v66, off offset:64
	v_or_b32_e32 v64, v98, v195
	v_mad_i64_i32 v[64:65], s[12:13], v64, s7, v[130:131]
	v_cvt_pk_bf16_f32 v66, v94, s0
	global_store_short v[64:65], v66, off
	v_cvt_pk_bf16_f32 v66, v78, s0
	global_store_short v[64:65], v66, off offset:64
	v_or_b32_e32 v64, v98, v196
	v_mad_i64_i32 v[64:65], s[12:13], v64, s7, v[130:131]
	v_cvt_pk_bf16_f32 v66, v95, s0
	global_store_short v[64:65], v66, off
	v_cvt_pk_bf16_f32 v66, v79, s0
	global_store_short v[64:65], v66, off offset:64
	v_or_b32_e32 v66, 64, v134
	v_or_b32_e32 v64, v66, v181
	v_mad_i64_i32 v[64:65], s[12:13], v64, s7, v[130:131]
	v_cvt_pk_bf16_f32 v32, v32, s0
	global_store_short v[64:65], v32, off offset:64
	v_or_b32_e32 v32, v66, v182
	global_store_short v[64:65], v48, off
	v_mad_i64_i32 v[64:65], s[12:13], v32, s7, v[130:131]
	v_cvt_pk_bf16_f32 v32, v49, s0
	global_store_short v[64:65], v32, off
	v_cvt_pk_bf16_f32 v32, v33, s0
	global_store_short v[64:65], v32, off offset:64
	v_or_b32_e32 v32, v66, v183
	v_mad_i64_i32 v[32:33], s[12:13], v32, s7, v[130:131]
	v_cvt_pk_bf16_f32 v48, v50, s0
	v_cvt_pk_bf16_f32 v34, v34, s0
	global_store_short v[32:33], v48, off
	global_store_short v[32:33], v34, off offset:64
	v_or_b32_e32 v32, v66, v184
	v_mad_i64_i32 v[32:33], s[12:13], v32, s7, v[130:131]
	v_cvt_pk_bf16_f32 v34, v51, s0
	global_store_short v[32:33], v34, off
	v_cvt_pk_bf16_f32 v34, v35, s0
	global_store_short v[32:33], v34, off offset:64
	v_or_b32_e32 v32, v66, v185
	v_mad_i64_i32 v[32:33], s[12:13], v32, s7, v[130:131]
	v_cvt_pk_bf16_f32 v34, v52, s0
	global_store_short v[32:33], v34, off
	v_cvt_pk_bf16_f32 v34, v36, s0
	global_store_short v[32:33], v34, off offset:64
	v_or_b32_e32 v32, v66, v186
	v_mad_i64_i32 v[32:33], s[12:13], v32, s7, v[130:131]
	v_cvt_pk_bf16_f32 v34, v53, s0
	global_store_short v[32:33], v34, off
	v_cvt_pk_bf16_f32 v34, v37, s0
	global_store_short v[32:33], v34, off offset:64
	v_or_b32_e32 v32, v66, v187
	v_mad_i64_i32 v[32:33], s[12:13], v32, s7, v[130:131]
	v_cvt_pk_bf16_f32 v34, v54, s0
	global_store_short v[32:33], v34, off
	v_cvt_pk_bf16_f32 v34, v38, s0
	global_store_short v[32:33], v34, off offset:64
	v_or_b32_e32 v32, v66, v188
	v_mad_i64_i32 v[32:33], s[12:13], v32, s7, v[130:131]
	v_cvt_pk_bf16_f32 v34, v55, s0
	global_store_short v[32:33], v34, off
	v_cvt_pk_bf16_f32 v34, v39, s0
	global_store_short v[32:33], v34, off offset:64
	v_or_b32_e32 v32, v66, v189
	v_mad_i64_i32 v[32:33], s[12:13], v32, s7, v[130:131]
	v_cvt_pk_bf16_f32 v34, v56, s0
	global_store_short v[32:33], v34, off
	v_cvt_pk_bf16_f32 v34, v40, s0
	global_store_short v[32:33], v34, off offset:64
	v_or_b32_e32 v32, v66, v190
	v_mad_i64_i32 v[32:33], s[12:13], v32, s7, v[130:131]
	v_cvt_pk_bf16_f32 v34, v57, s0
	global_store_short v[32:33], v34, off
	v_cvt_pk_bf16_f32 v34, v41, s0
	global_store_short v[32:33], v34, off offset:64
	v_or_b32_e32 v32, v66, v191
	v_mad_i64_i32 v[32:33], s[12:13], v32, s7, v[130:131]
	v_cvt_pk_bf16_f32 v34, v58, s0
	global_store_short v[32:33], v34, off
	v_cvt_pk_bf16_f32 v34, v42, s0
	global_store_short v[32:33], v34, off offset:64
	v_or_b32_e32 v32, v66, v192
	v_mad_i64_i32 v[32:33], s[12:13], v32, s7, v[130:131]
	v_cvt_pk_bf16_f32 v34, v59, s0
	global_store_short v[32:33], v34, off
	v_cvt_pk_bf16_f32 v34, v43, s0
	global_store_short v[32:33], v34, off offset:64
	v_or_b32_e32 v32, v66, v193
	v_mad_i64_i32 v[32:33], s[12:13], v32, s7, v[130:131]
	v_cvt_pk_bf16_f32 v34, v60, s0
	global_store_short v[32:33], v34, off
	v_cvt_pk_bf16_f32 v34, v44, s0
	global_store_short v[32:33], v34, off offset:64
	v_or_b32_e32 v32, v66, v194
	v_mad_i64_i32 v[32:33], s[12:13], v32, s7, v[130:131]
	v_cvt_pk_bf16_f32 v34, v61, s0
	global_store_short v[32:33], v34, off
	v_cvt_pk_bf16_f32 v34, v45, s0
	global_store_short v[32:33], v34, off offset:64
	v_or_b32_e32 v32, v66, v195
	v_mad_i64_i32 v[32:33], s[12:13], v32, s7, v[130:131]
	v_cvt_pk_bf16_f32 v34, v62, s0
	global_store_short v[32:33], v34, off
	v_cvt_pk_bf16_f32 v34, v46, s0
	global_store_short v[32:33], v34, off offset:64
	v_or_b32_e32 v32, v66, v196
	v_mad_i64_i32 v[32:33], s[12:13], v32, s7, v[130:131]
	v_cvt_pk_bf16_f32 v34, v63, s0
	global_store_short v[32:33], v34, off
	v_cvt_pk_bf16_f32 v34, v47, s0
	global_store_short v[32:33], v34, off offset:64
	v_or_b32_e32 v34, 0x60, v134
	v_or_b32_e32 v32, v34, v181
	v_mad_i64_i32 v[32:33], s[12:13], v32, s7, v[130:131]
	v_cvt_pk_bf16_f32 v0, v0, s0
	global_store_short v[32:33], v0, off offset:64
	v_or_b32_e32 v0, v34, v182
	global_store_short v[32:33], v16, off
	v_mad_i64_i32 v[32:33], s[12:13], v0, s7, v[130:131]
	v_cvt_pk_bf16_f32 v0, v17, s0
	global_store_short v[32:33], v0, off
	v_cvt_pk_bf16_f32 v0, v1, s0
	global_store_short v[32:33], v0, off offset:64
	v_or_b32_e32 v0, v34, v183
	v_mad_i64_i32 v[0:1], s[12:13], v0, s7, v[130:131]
	v_cvt_pk_bf16_f32 v16, v18, s0
	v_cvt_pk_bf16_f32 v2, v2, s0
	global_store_short v[0:1], v16, off
	global_store_short v[0:1], v2, off offset:64
	v_or_b32_e32 v0, v34, v184
	v_mad_i64_i32 v[0:1], s[12:13], v0, s7, v[130:131]
	v_cvt_pk_bf16_f32 v2, v19, s0
	global_store_short v[0:1], v2, off
	v_cvt_pk_bf16_f32 v2, v3, s0
	global_store_short v[0:1], v2, off offset:64
	v_or_b32_e32 v0, v34, v185
	v_mad_i64_i32 v[0:1], s[12:13], v0, s7, v[130:131]
	v_cvt_pk_bf16_f32 v2, v20, s0
	global_store_short v[0:1], v2, off
	v_cvt_pk_bf16_f32 v2, v4, s0
	global_store_short v[0:1], v2, off offset:64
	v_or_b32_e32 v0, v34, v186
	v_mad_i64_i32 v[0:1], s[12:13], v0, s7, v[130:131]
	v_cvt_pk_bf16_f32 v2, v21, s0
	global_store_short v[0:1], v2, off
	v_cvt_pk_bf16_f32 v2, v5, s0
	global_store_short v[0:1], v2, off offset:64
	v_or_b32_e32 v0, v34, v187
	v_mad_i64_i32 v[0:1], s[12:13], v0, s7, v[130:131]
	v_cvt_pk_bf16_f32 v2, v22, s0
	global_store_short v[0:1], v2, off
	v_cvt_pk_bf16_f32 v2, v6, s0
	global_store_short v[0:1], v2, off offset:64
	v_or_b32_e32 v0, v34, v188
	v_mad_i64_i32 v[0:1], s[12:13], v0, s7, v[130:131]
	v_cvt_pk_bf16_f32 v2, v23, s0
	global_store_short v[0:1], v2, off
	v_cvt_pk_bf16_f32 v2, v7, s0
	global_store_short v[0:1], v2, off offset:64
	v_or_b32_e32 v0, v34, v189
	v_mad_i64_i32 v[0:1], s[12:13], v0, s7, v[130:131]
	v_cvt_pk_bf16_f32 v2, v24, s0
	global_store_short v[0:1], v2, off
	v_cvt_pk_bf16_f32 v2, v8, s0
	global_store_short v[0:1], v2, off offset:64
	v_or_b32_e32 v0, v34, v190
	v_mad_i64_i32 v[0:1], s[12:13], v0, s7, v[130:131]
	v_cvt_pk_bf16_f32 v2, v25, s0
	global_store_short v[0:1], v2, off
	v_cvt_pk_bf16_f32 v2, v9, s0
	global_store_short v[0:1], v2, off offset:64
	v_or_b32_e32 v0, v34, v191
	v_mad_i64_i32 v[0:1], s[12:13], v0, s7, v[130:131]
	v_cvt_pk_bf16_f32 v2, v26, s0
	global_store_short v[0:1], v2, off
	v_cvt_pk_bf16_f32 v2, v10, s0
	global_store_short v[0:1], v2, off offset:64
	v_or_b32_e32 v0, v34, v192
	v_mad_i64_i32 v[0:1], s[12:13], v0, s7, v[130:131]
	v_cvt_pk_bf16_f32 v2, v27, s0
	global_store_short v[0:1], v2, off
	v_cvt_pk_bf16_f32 v2, v11, s0
	global_store_short v[0:1], v2, off offset:64
	v_or_b32_e32 v0, v34, v193
	v_mad_i64_i32 v[0:1], s[12:13], v0, s7, v[130:131]
	v_cvt_pk_bf16_f32 v2, v28, s0
	global_store_short v[0:1], v2, off
	v_cvt_pk_bf16_f32 v2, v12, s0
	global_store_short v[0:1], v2, off offset:64
	v_or_b32_e32 v0, v34, v194
	v_mad_i64_i32 v[0:1], s[12:13], v0, s7, v[130:131]
	v_cvt_pk_bf16_f32 v2, v29, s0
	global_store_short v[0:1], v2, off
	v_cvt_pk_bf16_f32 v2, v13, s0
	global_store_short v[0:1], v2, off offset:64
	v_or_b32_e32 v0, v34, v195
	v_mad_i64_i32 v[0:1], s[12:13], v0, s7, v[130:131]
	v_cvt_pk_bf16_f32 v2, v30, s0
	global_store_short v[0:1], v2, off
	v_cvt_pk_bf16_f32 v2, v14, s0
	global_store_short v[0:1], v2, off offset:64
	v_or_b32_e32 v0, v34, v196
	v_mad_i64_i32 v[0:1], s[12:13], v0, s7, v[130:131]
	v_readlane_b32 s7, v252, 7
	s_add_i32 s10, s10, s7
	s_add_i32 s4, s4, s7
	v_readlane_b32 s7, v252, 8
	v_cvt_pk_bf16_f32 v2, v31, s0
	s_add_i32 s6, s6, s7
	global_store_short v[0:1], v2, off
	v_cvt_pk_bf16_f32 v2, v15, s0
	s_cmpk_gt_i32 s10, 0x5f
	global_store_short v[0:1], v2, off offset:64
	s_cbranch_scc0 .LBB0_146

.LBB0_262:
	s_and_b32 s5, s2, 7
	v_lshl_add_u32 v0, s5, 8, v201
	v_ashrrev_i32_e32 v1, 31, v0
	v_lshlrev_b64 v[0:1], 11, v[0:1]
	s_and_b32 s5, s4, 0xffffff00
	v_lshl_add_u64 v[170:171], v[160:161], 0, v[0:1]
	v_add_u32_e32 v0, s5, v175
	s_and_b32 s5, s6, 7
	v_ashrrev_i32_e32 v1, 31, v0
	s_or_b32 s5, s5, s3
	v_lshlrev_b64 v[0:1], 11, v[0:1]
	s_lshl_b32 s5, s5, 8
	v_lshl_add_u64 v[172:173], v[168:169], 0, v[0:1]
	v_add_u32_e32 v0, s5, v175
	s_lshl_b32 s7, s6, 5
	v_ashrrev_i32_e32 v1, 31, v0
	s_and_b32 s7, s7, 0xffffff00
	v_add_u32_e32 v2, s7, v175
	v_lshlrev_b64 v[0:1], 11, v[0:1]
	s_waitcnt vmcnt(0) lgkmcnt(0)
	s_barrier
	v_ashrrev_i32_e32 v3, 31, v2
	v_lshl_add_u64 v[0:1], v[154:155], 0, v[0:1]
	v_readfirstlane_b32 s10, v180
	s_mov_b32 m0, s10
	s_nop 0
	global_load_lds_dwordx4 v[0:1], off
	v_lshlrev_b64 v[2:3], 11, v[2:3]
	v_lshl_add_u64 v[4:5], v[0:1], 0, s[34:35]
	s_add_i32 s11, s10, 0x2000
	s_mov_b32 m0, s11
	s_nop 0
	global_load_lds_dwordx4 v[4:5], off
	v_lshl_add_u64 v[2:3], v[156:157], 0, v[2:3]
	s_add_i32 s11, s10, 0x4000
	s_mov_b32 m0, s11
	s_nop 0
	global_load_lds_dwordx4 v[2:3], off
	v_lshl_add_u64 v[4:5], v[2:3], 0, s[34:35]
	s_add_i32 s11, s10, 0x6000
	s_mov_b32 m0, s11
	s_nop 0
	global_load_lds_dwordx4 v[4:5], off
	s_add_i32 s11, s10, 0x8000
	v_lshl_add_u64 v[4:5], v[0:1], 0, 64
	s_mov_b32 m0, s11
	s_nop 0
	global_load_lds_dwordx4 v[4:5], off
	s_mov_b64 s[12:13], 0x40040
	v_lshl_add_u64 v[4:5], v[0:1], 0, s[12:13]
	s_add_i32 s11, s10, 0xa000
	s_mov_b32 m0, s11
	s_nop 0
	global_load_lds_dwordx4 v[4:5], off
	v_lshl_add_u64 v[4:5], v[2:3], 0, 64
	s_add_i32 s11, s10, 0xc000
	s_mov_b32 m0, s11
	s_nop 0
	global_load_lds_dwordx4 v[4:5], off
	v_lshl_add_u64 v[4:5], v[2:3], 0, s[12:13]
	s_add_i32 s11, s10, 0xe000
	s_mov_b32 m0, s11
	s_nop 0
	global_load_lds_dwordx4 v[4:5], off
	s_mov_b64 s[12:13], 0x80
	s_add_i32 s11, s10, 0x10000
	v_lshl_add_u64 v[4:5], v[0:1], 0, s[12:13]
	s_mov_b32 m0, s11
	s_nop 0
	global_load_lds_dwordx4 v[4:5], off
	s_mov_b64 s[14:15], 0x40080
	v_lshl_add_u64 v[0:1], v[0:1], 0, s[14:15]
	s_add_i32 s11, s10, 0x12000
	s_mov_b32 m0, s11
	s_nop 0
	global_load_lds_dwordx4 v[0:1], off
	v_lshl_add_u64 v[0:1], v[2:3], 0, s[12:13]
	s_add_i32 s11, s10, 0x14000
	s_mov_b32 m0, s11
	s_nop 0
	global_load_lds_dwordx4 v[0:1], off
	v_lshl_add_u64 v[0:1], v[2:3], 0, s[14:15]
	s_add_i32 s10, s10, 0x16000
	s_mov_b32 m0, s10
	s_nop 0
	global_load_lds_dwordx4 v[0:1], off
	v_mov_b32_e32 v130, 0
	v_mov_b32_e32 v134, 0
	v_mov_b32_e32 v0, 0
	s_mov_b32 s10, 0x18000
	v_mov_b32_e32 v1, v0
	v_mov_b32_e32 v2, v0
	v_mov_b32_e32 v3, v0
	v_mov_b32_e32 v4, v0
	v_mov_b32_e32 v5, v0
	v_mov_b32_e32 v6, v0
	v_mov_b32_e32 v7, v0
	v_mov_b32_e32 v8, v0
	v_mov_b32_e32 v9, v0
	v_mov_b32_e32 v10, v0
	v_mov_b32_e32 v11, v0
	v_mov_b32_e32 v12, v0
	v_mov_b32_e32 v13, v0
	v_mov_b32_e32 v14, v0
	v_mov_b32_e32 v15, v0
	v_mov_b32_e32 v16, v0
	v_mov_b32_e32 v17, v0
	v_mov_b32_e32 v18, v0
	v_mov_b32_e32 v19, v0
	v_mov_b32_e32 v20, v0
	v_mov_b32_e32 v21, v0
	v_mov_b32_e32 v22, v0
	v_mov_b32_e32 v23, v0
	v_mov_b32_e32 v24, v0
	v_mov_b32_e32 v25, v0
	v_mov_b32_e32 v26, v0
	v_mov_b32_e32 v27, v0
	v_mov_b32_e32 v28, v0
	v_mov_b32_e32 v29, v0
	v_mov_b32_e32 v30, v0
	v_mov_b32_e32 v31, v0
	v_mov_b32_e32 v32, v0
	v_mov_b32_e32 v33, v0
	v_mov_b32_e32 v34, v0
	v_mov_b32_e32 v35, v0
	v_mov_b32_e32 v36, v0
	v_mov_b32_e32 v37, v0
	v_mov_b32_e32 v38, v0
	v_mov_b32_e32 v39, v0
	v_mov_b32_e32 v40, v0
	v_mov_b32_e32 v41, v0
	v_mov_b32_e32 v42, v0
	v_mov_b32_e32 v43, v0
	v_mov_b32_e32 v44, v0
	v_mov_b32_e32 v45, v0
	v_mov_b32_e32 v46, v0
	v_mov_b32_e32 v47, v0
	v_mov_b32_e32 v48, v0
	v_mov_b32_e32 v49, v0
	v_mov_b32_e32 v50, v0
	v_mov_b32_e32 v51, v0
	v_mov_b32_e32 v52, v0
	v_mov_b32_e32 v53, v0
	v_mov_b32_e32 v54, v0
	v_mov_b32_e32 v55, v0
	v_mov_b32_e32 v56, v0
	v_mov_b32_e32 v57, v0
	v_mov_b32_e32 v58, v0
	v_mov_b32_e32 v59, v0
	v_mov_b32_e32 v60, v0
	v_mov_b32_e32 v61, v0
	v_mov_b32_e32 v62, v0
	v_mov_b32_e32 v63, v0
	v_mov_b32_e32 v64, v0
	v_mov_b32_e32 v65, v0
	v_mov_b32_e32 v66, v0
	v_mov_b32_e32 v67, v0
	v_mov_b32_e32 v68, v0
	v_mov_b32_e32 v69, v0
	v_mov_b32_e32 v70, v0
	v_mov_b32_e32 v71, v0
	v_mov_b32_e32 v72, v0
	v_mov_b32_e32 v73, v0
	v_mov_b32_e32 v74, v0
	v_mov_b32_e32 v75, v0
	v_mov_b32_e32 v76, v0
	v_mov_b32_e32 v77, v0
	v_mov_b32_e32 v78, v0
	v_mov_b32_e32 v79, v0
	v_mov_b32_e32 v80, v0
	v_mov_b32_e32 v81, v0
	v_mov_b32_e32 v82, v0
	v_mov_b32_e32 v83, v0
	v_mov_b32_e32 v84, v0
	v_mov_b32_e32 v85, v0
	v_mov_b32_e32 v86, v0
	v_mov_b32_e32 v87, v0
	v_mov_b32_e32 v88, v0
	v_mov_b32_e32 v89, v0
	v_mov_b32_e32 v90, v0
	v_mov_b32_e32 v91, v0
	v_mov_b32_e32 v92, v0
	v_mov_b32_e32 v93, v0
	v_mov_b32_e32 v94, v0
	v_mov_b32_e32 v95, v0
	v_mov_b32_e32 v96, v0
	v_mov_b32_e32 v97, v0
	v_mov_b32_e32 v98, v0
	v_mov_b32_e32 v99, v0
	v_mov_b32_e32 v100, v0
	v_mov_b32_e32 v101, v0
	v_mov_b32_e32 v102, v0
	v_mov_b32_e32 v103, v0
	v_mov_b32_e32 v104, v0
	v_mov_b32_e32 v105, v0
	v_mov_b32_e32 v106, v0
	v_mov_b32_e32 v107, v0
	v_mov_b32_e32 v108, v0
	v_mov_b32_e32 v109, v0
	v_mov_b32_e32 v110, v0
	v_mov_b32_e32 v111, v0
	v_mov_b32_e32 v112, v0
	v_mov_b32_e32 v113, v0
	v_mov_b32_e32 v114, v0
	v_mov_b32_e32 v115, v0
	v_mov_b32_e32 v116, v0
	v_mov_b32_e32 v117, v0
	v_mov_b32_e32 v118, v0
	v_mov_b32_e32 v119, v0
	v_mov_b32_e32 v120, v0
	v_mov_b32_e32 v121, v0
	v_mov_b32_e32 v122, v0
	v_mov_b32_e32 v123, v0
	v_mov_b32_e32 v124, v0
	v_mov_b32_e32 v125, v0
	v_mov_b32_e32 v126, v0
	v_mov_b32_e32 v127, v0
	v_mov_b32_e32 v135, v134
	v_mov_b32_e32 v136, v134
	v_mov_b32_e32 v137, v134
	v_mov_b32_e32 v138, v134
	v_mov_b32_e32 v139, v134
	v_mov_b32_e32 v140, v134
	v_mov_b32_e32 v141, v134
	v_mov_b32_e32 v146, v134
	v_mov_b32_e32 v147, v134
	v_mov_b32_e32 v148, v134
	v_mov_b32_e32 v149, v134
	v_mov_b32_e32 v150, v134
	v_mov_b32_e32 v151, v134
	v_mov_b32_e32 v152, v134
	v_mov_b32_e32 v153, v134
	v_mov_b32_e32 v131, v130
	v_mov_b32_e32 v132, v130
	v_mov_b32_e32 v133, v130
	v_mov_b32_e32 v142, v130
	v_mov_b32_e32 v143, v130
	v_mov_b32_e32 v144, v130
	v_mov_b32_e32 v145, v130
	v_readfirstlane_b32 s100, v163
	s_cmp_ge_u32 s100, 0x100
	s_cbranch_scc1 .Lky_1
.LBB0_263:
	s_and_b32 s11, s10, 0x18000
	v_add_u32_e32 v222, s11, v180
	s_add_i32 s11, s10, 0xfffe8000
	s_and_b32 s11, s11, 0x18000
	v_or_b32_e32 v223, s11, v179
	v_add_u32_e32 v233, s11, v176
	s_waitcnt vmcnt(8) lgkmcnt(0)
	s_barrier
	v_mfma_f32_32x32x16_bf16 v[112:127], v[150:153], v[142:145], v[112:127]
	v_mfma_f32_32x32x16_bf16 v[96:111], v[150:153], v[130:133], v[96:111]
	v_add_u32_e32 v206, v223, v177
	v_add_u32_e32 v234, v233, v177
	ds_read_b128 v[202:205], v206 offset:16384
	ds_read_b128 v[206:209], v206 offset:18432
	ds_read_b128 v[210:213], v234
	ds_read_b128 v[214:217], v234 offset:2048
	ds_read_b128 v[224:227], v234 offset:4096
	ds_read_b128 v[234:237], v234 offset:6144
	v_mfma_f32_32x32x16_bf16 v[80:95], v[146:149], v[142:145], v[80:95]
	v_mfma_f32_32x32x16_bf16 v[64:79], v[146:149], v[130:133], v[64:79]
	v_readfirstlane_b32 s11, v222
	s_mov_b32 m0, s11
	s_nop 0
	global_load_lds_dwordx4 v[170:171], off
	v_mfma_f32_32x32x16_bf16 v[48:63], v[138:141], v[142:145], v[48:63]
	v_mfma_f32_32x32x16_bf16 v[32:47], v[138:141], v[130:133], v[32:47]
	s_add_i32 s12, s11, 0x2000
	v_lshl_add_u64 v[150:151], v[170:171], 0, s[34:35]
	s_mov_b32 m0, s12
	s_nop 0
	global_load_lds_dwordx4 v[150:151], off
	v_mfma_f32_32x32x16_bf16 v[16:31], v[134:137], v[142:145], v[16:31]
	v_mfma_f32_32x32x16_bf16 v[0:15], v[134:137], v[130:133], v[0:15]
	v_add_u32_e32 v130, v223, v178
	v_add_u32_e32 v134, v233, v178
	ds_read_b128 v[142:145], v130 offset:16384
	ds_read_b128 v[130:133], v130 offset:18432
	ds_read_b128 v[150:153], v134
	ds_read_b128 v[146:149], v134 offset:2048
	ds_read_b128 v[138:141], v134 offset:4096
	ds_read_b128 v[134:137], v134 offset:6144
	s_waitcnt lgkmcnt(9)
	v_mfma_f32_32x32x16_bf16 v[112:127], v[210:213], v[202:205], v[112:127]
	s_add_i32 s12, s11, 0x6000
	s_addk_i32 s11, 0x4000
	v_mfma_f32_32x32x16_bf16 v[96:111], v[210:213], v[206:209], v[96:111]
	s_mov_b32 m0, s11
	s_nop 0
	global_load_lds_dwordx4 v[172:173], off
	v_lshl_add_u64 v[222:223], v[172:173], 0, s[34:35]
	s_waitcnt lgkmcnt(8)
	v_mfma_f32_32x32x16_bf16 v[80:95], v[214:217], v[202:205], v[80:95]
	v_mfma_f32_32x32x16_bf16 v[64:79], v[214:217], v[206:209], v[64:79]
	s_waitcnt lgkmcnt(7)
	v_mfma_f32_32x32x16_bf16 v[48:63], v[224:227], v[202:205], v[48:63]
	v_mfma_f32_32x32x16_bf16 v[32:47], v[224:227], v[206:209], v[32:47]
	s_mov_b32 m0, s12
	s_nop 0
	global_load_lds_dwordx4 v[222:223], off
	s_waitcnt lgkmcnt(6)
	v_mfma_f32_32x32x16_bf16 v[16:31], v[234:237], v[202:205], v[16:31]
	s_add_i32 s10, s10, 0x8000
	v_lshl_add_u64 v[170:171], v[170:171], 0, 64
	v_lshl_add_u64 v[172:173], v[172:173], 0, 64
	s_cmp_eq_u32 s10, 0x100000
	v_mfma_f32_32x32x16_bf16 v[0:15], v[234:237], v[206:209], v[0:15]
	s_cbranch_scc0 .LBB0_263
	s_branch .Lktail_1
.Lky_1:
	s_and_b32 s11, s10, 0x18000
	v_add_u32_e32 v222, s11, v180
	s_add_i32 s11, s10, 0xfffe8000
	s_and_b32 s11, s11, 0x18000
	v_or_b32_e32 v223, s11, v179
	v_add_u32_e32 v233, s11, v176
	s_waitcnt vmcnt(8) lgkmcnt(0)
	s_barrier
	v_add_u32_e32 v206, v223, v177
	v_add_u32_e32 v234, v233, v177
	ds_read_b128 v[202:205], v206 offset:16384
	ds_read_b128 v[206:209], v206 offset:18432
	ds_read_b128 v[210:213], v234
	ds_read_b128 v[214:217], v234 offset:2048
	ds_read_b128 v[224:227], v234 offset:4096
	ds_read_b128 v[234:237], v234 offset:6144
	v_mfma_f32_32x32x16_bf16 v[112:127], v[150:153], v[142:145], v[112:127]
	v_mfma_f32_32x32x16_bf16 v[96:111], v[150:153], v[130:133], v[96:111]
	v_readfirstlane_b32 s11, v222
	s_mov_b32 m0, s11
	s_nop 0
	global_load_lds_dwordx4 v[170:171], off
	v_mfma_f32_32x32x16_bf16 v[80:95], v[146:149], v[142:145], v[80:95]
	v_mfma_f32_32x32x16_bf16 v[64:79], v[146:149], v[130:133], v[64:79]
	v_mfma_f32_32x32x16_bf16 v[48:63], v[138:141], v[142:145], v[48:63]
	v_mfma_f32_32x32x16_bf16 v[32:47], v[138:141], v[130:133], v[32:47]
	s_add_i32 s12, s11, 0x2000
	v_lshl_add_u64 v[150:151], v[170:171], 0, s[34:35]
	s_mov_b32 m0, s12
	s_nop 0
	global_load_lds_dwordx4 v[150:151], off
	v_mfma_f32_32x32x16_bf16 v[16:31], v[134:137], v[142:145], v[16:31]
	v_mfma_f32_32x32x16_bf16 v[0:15], v[134:137], v[130:133], v[0:15]
	v_add_u32_e32 v130, v223, v178
	v_add_u32_e32 v134, v233, v178
	ds_read_b128 v[142:145], v130 offset:16384
	ds_read_b128 v[130:133], v130 offset:18432
	ds_read_b128 v[150:153], v134
	ds_read_b128 v[146:149], v134 offset:2048
	ds_read_b128 v[138:141], v134 offset:4096
	ds_read_b128 v[134:137], v134 offset:6144
	s_waitcnt lgkmcnt(9)
	v_mfma_f32_32x32x16_bf16 v[112:127], v[210:213], v[202:205], v[112:127]
	s_add_i32 s12, s11, 0x6000
	s_addk_i32 s11, 0x4000
	v_mfma_f32_32x32x16_bf16 v[96:111], v[210:213], v[206:209], v[96:111]
	s_mov_b32 m0, s11
	s_nop 0
	global_load_lds_dwordx4 v[172:173], off
	v_lshl_add_u64 v[222:223], v[172:173], 0, s[34:35]
	s_waitcnt lgkmcnt(8)
	v_mfma_f32_32x32x16_bf16 v[80:95], v[214:217], v[202:205], v[80:95]
	v_mfma_f32_32x32x16_bf16 v[64:79], v[214:217], v[206:209], v[64:79]
	s_waitcnt lgkmcnt(7)
	v_mfma_f32_32x32x16_bf16 v[48:63], v[224:227], v[202:205], v[48:63]
	v_mfma_f32_32x32x16_bf16 v[32:47], v[224:227], v[206:209], v[32:47]
	s_mov_b32 m0, s12
	s_nop 0
	global_load_lds_dwordx4 v[222:223], off
	s_waitcnt lgkmcnt(6)
	v_mfma_f32_32x32x16_bf16 v[16:31], v[234:237], v[202:205], v[16:31]
	s_add_i32 s10, s10, 0x8000
	v_lshl_add_u64 v[170:171], v[170:171], 0, 64
	v_lshl_add_u64 v[172:173], v[172:173], 0, 64
	s_cmp_eq_u32 s10, 0x100000
	v_mfma_f32_32x32x16_bf16 v[0:15], v[234:237], v[206:209], v[0:15]
	s_cbranch_scc0 .Lky_1
.Lktail_1:
	s_waitcnt vmcnt(8) lgkmcnt(0)
	s_barrier
	v_add_u32_e32 v202, v179, v177
	v_add_u32_e32 v222, v176, v177
	ds_read_b128 v[170:173], v202 offset:49152
	ds_read_b128 v[202:205], v202 offset:51200
	ds_read_b128 v[206:209], v222 offset:32768
	ds_read_b128 v[210:213], v222 offset:34816
	ds_read_b128 v[214:217], v222 offset:36864
	ds_read_b128 v[224:227], v222 offset:38912
	s_waitcnt lgkmcnt(9)
	v_mfma_f32_32x32x16_bf16 v[112:127], v[150:153], v[142:145], v[112:127]
	v_mfma_f32_32x32x16_bf16 v[96:111], v[150:153], v[130:133], v[96:111]
	s_waitcnt lgkmcnt(8)
	v_mfma_f32_32x32x16_bf16 v[80:95], v[146:149], v[142:145], v[80:95]
	v_mfma_f32_32x32x16_bf16 v[64:79], v[146:149], v[130:133], v[64:79]
	s_waitcnt lgkmcnt(7)
	v_mfma_f32_32x32x16_bf16 v[48:63], v[138:141], v[142:145], v[48:63]
	v_mfma_f32_32x32x16_bf16 v[32:47], v[138:141], v[130:133], v[32:47]
	s_waitcnt lgkmcnt(6)
	v_mfma_f32_32x32x16_bf16 v[16:31], v[134:137], v[142:145], v[16:31]
	v_mfma_f32_32x32x16_bf16 v[0:15], v[134:137], v[130:133], v[0:15]
	v_add_u32_e32 v134, v179, v178
	v_add_u32_e32 v150, v176, v178
	ds_read_b128 v[130:133], v134 offset:49152
	ds_read_b128 v[134:137], v134 offset:51200
	ds_read_b128 v[138:141], v150 offset:32768
	ds_read_b128 v[142:145], v150 offset:34816
	ds_read_b128 v[146:149], v150 offset:36864
	ds_read_b128 v[150:153], v150 offset:38912
	s_waitcnt lgkmcnt(9)
	v_mfma_f32_32x32x16_bf16 v[112:127], v[206:209], v[170:173], v[112:127]
	v_mfma_f32_32x32x16_bf16 v[96:111], v[206:209], v[202:205], v[96:111]
	s_waitcnt lgkmcnt(8)
	v_mfma_f32_32x32x16_bf16 v[80:95], v[210:213], v[170:173], v[80:95]
	v_mfma_f32_32x32x16_bf16 v[64:79], v[210:213], v[202:205], v[64:79]
	s_waitcnt lgkmcnt(7)
	v_mfma_f32_32x32x16_bf16 v[48:63], v[214:217], v[170:173], v[48:63]
	v_mfma_f32_32x32x16_bf16 v[32:47], v[214:217], v[202:205], v[32:47]
	s_waitcnt lgkmcnt(6)
	v_mfma_f32_32x32x16_bf16 v[0:15], v[224:227], v[202:205], v[0:15]
	s_waitcnt vmcnt(4) lgkmcnt(0)
	s_barrier
	v_add_u32_e32 v202, v199, v177
	v_add_u32_e32 v222, v200, v177
	v_mfma_f32_32x32x16_bf16 v[16:31], v[224:227], v[170:173], v[16:31]
	ds_read_b128 v[170:173], v202 offset:16384
	ds_read_b128 v[202:205], v202 offset:18432
	ds_read_b128 v[206:209], v222
	ds_read_b128 v[210:213], v222 offset:2048
	ds_read_b128 v[214:217], v222 offset:4096
	ds_read_b128 v[224:227], v222 offset:6144
	s_waitcnt lgkmcnt(9)
	v_mfma_f32_32x32x16_bf16 v[112:127], v[138:141], v[130:133], v[112:127]
	v_mfma_f32_32x32x16_bf16 v[96:111], v[138:141], v[134:137], v[96:111]
	s_waitcnt lgkmcnt(8)
	v_mfma_f32_32x32x16_bf16 v[80:95], v[142:145], v[130:133], v[80:95]
	v_mfma_f32_32x32x16_bf16 v[64:79], v[142:145], v[134:137], v[64:79]
	s_waitcnt lgkmcnt(7)
	v_mfma_f32_32x32x16_bf16 v[48:63], v[146:149], v[130:133], v[48:63]
	v_mfma_f32_32x32x16_bf16 v[32:47], v[146:149], v[134:137], v[32:47]
	s_waitcnt lgkmcnt(6)
	v_mfma_f32_32x32x16_bf16 v[16:31], v[150:153], v[130:133], v[16:31]
	v_mfma_f32_32x32x16_bf16 v[0:15], v[150:153], v[134:137], v[0:15]
	v_add_u32_e32 v134, v199, v178
	v_add_u32_e32 v150, v200, v178
	ds_read_b128 v[130:133], v134 offset:16384
	ds_read_b128 v[134:137], v134 offset:18432
	ds_read_b128 v[138:141], v150
	ds_read_b128 v[142:145], v150 offset:2048
	ds_read_b128 v[146:149], v150 offset:4096
	ds_read_b128 v[150:153], v150 offset:6144
	s_waitcnt lgkmcnt(9)
	v_mfma_f32_32x32x16_bf16 v[112:127], v[206:209], v[170:173], v[112:127]
	v_mfma_f32_32x32x16_bf16 v[96:111], v[206:209], v[202:205], v[96:111]
	s_waitcnt lgkmcnt(8)
	v_mfma_f32_32x32x16_bf16 v[80:95], v[210:213], v[170:173], v[80:95]
	v_mfma_f32_32x32x16_bf16 v[64:79], v[210:213], v[202:205], v[64:79]
	s_waitcnt lgkmcnt(7)
	v_mfma_f32_32x32x16_bf16 v[48:63], v[214:217], v[170:173], v[48:63]
	v_mfma_f32_32x32x16_bf16 v[32:47], v[214:217], v[202:205], v[32:47]
	s_waitcnt lgkmcnt(6)
	v_mfma_f32_32x32x16_bf16 v[0:15], v[224:227], v[202:205], v[0:15]
	s_waitcnt vmcnt(0) lgkmcnt(0)
	s_barrier
	v_add_u32_e32 v202, v197, v177
	v_add_u32_e32 v222, v198, v177
	v_mfma_f32_32x32x16_bf16 v[16:31], v[224:227], v[170:173], v[16:31]
	ds_read_b128 v[170:173], v202 offset:16384
	ds_read_b128 v[202:205], v202 offset:18432
	ds_read_b128 v[206:209], v222
	ds_read_b128 v[210:213], v222 offset:2048
	ds_read_b128 v[214:217], v222 offset:4096
	ds_read_b128 v[224:227], v222 offset:6144
	s_waitcnt lgkmcnt(9)
	v_mfma_f32_32x32x16_bf16 v[112:127], v[138:141], v[130:133], v[112:127]
	v_mfma_f32_32x32x16_bf16 v[96:111], v[138:141], v[134:137], v[96:111]
	s_waitcnt lgkmcnt(8)
	v_mfma_f32_32x32x16_bf16 v[80:95], v[142:145], v[130:133], v[80:95]
	v_mfma_f32_32x32x16_bf16 v[64:79], v[142:145], v[134:137], v[64:79]
	s_waitcnt lgkmcnt(7)
	v_mfma_f32_32x32x16_bf16 v[48:63], v[146:149], v[130:133], v[48:63]
	v_mfma_f32_32x32x16_bf16 v[32:47], v[146:149], v[134:137], v[32:47]
	s_waitcnt lgkmcnt(6)
	v_mfma_f32_32x32x16_bf16 v[16:31], v[150:153], v[130:133], v[16:31]
	v_mfma_f32_32x32x16_bf16 v[0:15], v[150:153], v[134:137], v[0:15]
	v_add_u32_e32 v134, v197, v178
	v_add_u32_e32 v150, v198, v178
	ds_read_b128 v[130:133], v134 offset:16384
	ds_read_b128 v[134:137], v134 offset:18432
	ds_read_b128 v[138:141], v150
	ds_read_b128 v[142:145], v150 offset:2048
	ds_read_b128 v[146:149], v150 offset:4096
	ds_read_b128 v[150:153], v150 offset:6144
	s_waitcnt lgkmcnt(9)
	v_mfma_f32_32x32x16_bf16 v[112:127], v[206:209], v[170:173], v[112:127]
	v_mfma_f32_32x32x16_bf16 v[96:111], v[206:209], v[202:205], v[96:111]
	s_waitcnt lgkmcnt(8)
	v_mfma_f32_32x32x16_bf16 v[80:95], v[210:213], v[170:173], v[80:95]
	v_mfma_f32_32x32x16_bf16 v[64:79], v[210:213], v[202:205], v[64:79]
	s_waitcnt lgkmcnt(7)
	v_mfma_f32_32x32x16_bf16 v[48:63], v[214:217], v[170:173], v[48:63]
	v_mfma_f32_32x32x16_bf16 v[32:47], v[214:217], v[202:205], v[32:47]
	s_waitcnt lgkmcnt(6)
	v_mfma_f32_32x32x16_bf16 v[16:31], v[224:227], v[170:173], v[16:31]
	v_mfma_f32_32x32x16_bf16 v[0:15], v[224:227], v[202:205], v[0:15]
	s_waitcnt lgkmcnt(3)
	v_mfma_f32_32x32x16_bf16 v[112:127], v[138:141], v[130:133], v[112:127]
	v_mfma_f32_32x32x16_bf16 v[96:111], v[138:141], v[134:137], v[96:111]
	s_nop 10
	v_cvt_pk_bf16_f32 v112, v112, s0
	s_waitcnt lgkmcnt(2)
	v_mfma_f32_32x32x16_bf16 v[80:95], v[142:145], v[130:133], v[80:95]
	v_cvt_pk_bf16_f32 v96, v96, s0
	v_cvt_pk_bf16_f32 v98, v98, s0
	s_waitcnt lgkmcnt(1)
	v_mfma_f32_32x32x16_bf16 v[48:63], v[146:149], v[130:133], v[48:63]
	s_nop 7
	v_cvt_pk_bf16_f32 v80, v80, s0
	s_waitcnt lgkmcnt(0)
	v_mfma_f32_32x32x16_bf16 v[16:31], v[150:153], v[130:133], v[16:31]
	v_add_u32_e32 v132, s5, v128
	v_or_b32_e32 v130, s7, v174
	v_ashrrev_i32_e32 v131, 31, v130
	v_lshl_add_u64 v[130:131], v[130:131], 1, v[158:159]
	v_cvt_pk_bf16_f32 v48, v48, s0
	v_readlane_b32 s5, v252, 7
	s_add_i32 s6, s6, s5
	v_mfma_f32_32x32x16_bf16 v[64:79], v[142:145], v[134:137], v[64:79]
	s_nop 3
	v_cvt_pk_bf16_f32 v16, v16, s0
	s_add_i32 s2, s2, s5
	v_readlane_b32 s5, v252, 8
	s_add_i32 s4, s4, s5
	s_cmp_gt_i32 s6, 31
	s_nop 2
	v_cvt_pk_bf16_f32 v64, v64, s0
	v_mfma_f32_32x32x16_bf16 v[32:47], v[146:149], v[134:137], v[32:47]
	v_cvt_pk_bf16_f32 v66, v66, s0
	v_mfma_f32_32x32x16_bf16 v[0:15], v[150:153], v[134:137], v[0:15]
	v_or_b32_e32 v134, v132, v181
	v_ashrrev_i32_e32 v135, 31, v134
	v_lshlrev_b64 v[134:135], 11, v[134:135]
	v_lshl_add_u64 v[134:135], v[130:131], 0, v[134:135]
	global_store_short v[134:135], v112, off
	global_store_short v[134:135], v96, off offset:64
	v_or_b32_e32 v134, v132, v182
	v_ashrrev_i32_e32 v135, 31, v134
	v_lshlrev_b64 v[134:135], 11, v[134:135]
	v_lshl_add_u64 v[134:135], v[130:131], 0, v[134:135]
	v_cvt_pk_bf16_f32 v96, v113, s0
	global_store_short v[134:135], v96, off
	v_cvt_pk_bf16_f32 v96, v97, s0
	global_store_short v[134:135], v96, off offset:64
	v_or_b32_e32 v96, v132, v183
	v_ashrrev_i32_e32 v97, 31, v96
	v_lshlrev_b64 v[96:97], 11, v[96:97]
	v_lshl_add_u64 v[96:97], v[130:131], 0, v[96:97]
	v_cvt_pk_bf16_f32 v112, v114, s0
	global_store_short v[96:97], v112, off
	global_store_short v[96:97], v98, off offset:64
	v_or_b32_e32 v96, v132, v184
	v_ashrrev_i32_e32 v97, 31, v96
	v_lshlrev_b64 v[96:97], 11, v[96:97]
	v_lshl_add_u64 v[96:97], v[130:131], 0, v[96:97]
	v_cvt_pk_bf16_f32 v98, v115, s0
	global_store_short v[96:97], v98, off
	v_cvt_pk_bf16_f32 v98, v99, s0
	global_store_short v[96:97], v98, off offset:64
	v_or_b32_e32 v96, v132, v185
	v_ashrrev_i32_e32 v97, 31, v96
	v_lshlrev_b64 v[96:97], 11, v[96:97]
	v_lshl_add_u64 v[96:97], v[130:131], 0, v[96:97]
	v_cvt_pk_bf16_f32 v98, v116, s0
	global_store_short v[96:97], v98, off
	v_cvt_pk_bf16_f32 v98, v100, s0
	global_store_short v[96:97], v98, off offset:64
	v_or_b32_e32 v96, v132, v186
	v_ashrrev_i32_e32 v97, 31, v96
	v_lshlrev_b64 v[96:97], 11, v[96:97]
	v_lshl_add_u64 v[96:97], v[130:131], 0, v[96:97]
	v_cvt_pk_bf16_f32 v98, v117, s0
	global_store_short v[96:97], v98, off
	v_cvt_pk_bf16_f32 v98, v101, s0
	global_store_short v[96:97], v98, off offset:64
	v_or_b32_e32 v96, v132, v187
	v_ashrrev_i32_e32 v97, 31, v96
	v_lshlrev_b64 v[96:97], 11, v[96:97]
	v_lshl_add_u64 v[96:97], v[130:131], 0, v[96:97]
	v_cvt_pk_bf16_f32 v98, v118, s0
	global_store_short v[96:97], v98, off
	v_cvt_pk_bf16_f32 v98, v102, s0
	global_store_short v[96:97], v98, off offset:64
	v_or_b32_e32 v96, v132, v188
	v_ashrrev_i32_e32 v97, 31, v96
	v_lshlrev_b64 v[96:97], 11, v[96:97]
	v_lshl_add_u64 v[96:97], v[130:131], 0, v[96:97]
	v_cvt_pk_bf16_f32 v98, v119, s0
	global_store_short v[96:97], v98, off
	v_cvt_pk_bf16_f32 v98, v103, s0
	global_store_short v[96:97], v98, off offset:64
	v_or_b32_e32 v96, v132, v189
	v_ashrrev_i32_e32 v97, 31, v96
	v_lshlrev_b64 v[96:97], 11, v[96:97]
	v_lshl_add_u64 v[96:97], v[130:131], 0, v[96:97]
	v_cvt_pk_bf16_f32 v98, v120, s0
	global_store_short v[96:97], v98, off
	v_cvt_pk_bf16_f32 v98, v104, s0
	global_store_short v[96:97], v98, off offset:64
	v_or_b32_e32 v96, v132, v190
	v_ashrrev_i32_e32 v97, 31, v96
	v_lshlrev_b64 v[96:97], 11, v[96:97]
	v_lshl_add_u64 v[96:97], v[130:131], 0, v[96:97]
	v_cvt_pk_bf16_f32 v98, v121, s0
	global_store_short v[96:97], v98, off
	v_cvt_pk_bf16_f32 v98, v105, s0
	global_store_short v[96:97], v98, off offset:64
	v_or_b32_e32 v96, v132, v191
	v_ashrrev_i32_e32 v97, 31, v96
	v_lshlrev_b64 v[96:97], 11, v[96:97]
	v_lshl_add_u64 v[96:97], v[130:131], 0, v[96:97]
	v_cvt_pk_bf16_f32 v98, v122, s0
	global_store_short v[96:97], v98, off
	v_cvt_pk_bf16_f32 v98, v106, s0
	global_store_short v[96:97], v98, off offset:64
	v_or_b32_e32 v96, v132, v192
	v_ashrrev_i32_e32 v97, 31, v96
	v_lshlrev_b64 v[96:97], 11, v[96:97]
	v_lshl_add_u64 v[96:97], v[130:131], 0, v[96:97]
	v_cvt_pk_bf16_f32 v98, v123, s0
	global_store_short v[96:97], v98, off
	v_cvt_pk_bf16_f32 v98, v107, s0
	global_store_short v[96:97], v98, off offset:64
	v_or_b32_e32 v96, v132, v193
	v_ashrrev_i32_e32 v97, 31, v96
	v_lshlrev_b64 v[96:97], 11, v[96:97]
	v_lshl_add_u64 v[96:97], v[130:131], 0, v[96:97]
	v_cvt_pk_bf16_f32 v98, v124, s0
	global_store_short v[96:97], v98, off
	v_cvt_pk_bf16_f32 v98, v108, s0
	global_store_short v[96:97], v98, off offset:64
	v_or_b32_e32 v96, v132, v194
	v_ashrrev_i32_e32 v97, 31, v96
	v_lshlrev_b64 v[96:97], 11, v[96:97]
	v_lshl_add_u64 v[96:97], v[130:131], 0, v[96:97]
	v_cvt_pk_bf16_f32 v98, v125, s0
	global_store_short v[96:97], v98, off
	v_cvt_pk_bf16_f32 v98, v109, s0
	global_store_short v[96:97], v98, off offset:64
	v_or_b32_e32 v96, v132, v195
	v_ashrrev_i32_e32 v97, 31, v96
	v_lshlrev_b64 v[96:97], 11, v[96:97]
	v_lshl_add_u64 v[96:97], v[130:131], 0, v[96:97]
	v_cvt_pk_bf16_f32 v98, v126, s0
	global_store_short v[96:97], v98, off
	v_cvt_pk_bf16_f32 v98, v110, s0
	global_store_short v[96:97], v98, off offset:64
	v_or_b32_e32 v96, v132, v196
	v_ashrrev_i32_e32 v97, 31, v96
	v_lshlrev_b64 v[96:97], 11, v[96:97]
	v_lshl_add_u64 v[96:97], v[130:131], 0, v[96:97]
	v_cvt_pk_bf16_f32 v98, v127, s0
	global_store_short v[96:97], v98, off
	v_cvt_pk_bf16_f32 v98, v111, s0
	global_store_short v[96:97], v98, off offset:64
	v_or_b32_e32 v98, 32, v132
	v_or_b32_e32 v96, v98, v181
	v_ashrrev_i32_e32 v97, 31, v96
	v_lshlrev_b64 v[96:97], 11, v[96:97]
	v_lshl_add_u64 v[96:97], v[130:131], 0, v[96:97]
	global_store_short v[96:97], v80, off
	global_store_short v[96:97], v64, off offset:64
	v_or_b32_e32 v96, v98, v182
	v_ashrrev_i32_e32 v97, 31, v96
	v_lshlrev_b64 v[96:97], 11, v[96:97]
	v_lshl_add_u64 v[96:97], v[130:131], 0, v[96:97]
	v_cvt_pk_bf16_f32 v64, v81, s0
	global_store_short v[96:97], v64, off
	v_cvt_pk_bf16_f32 v64, v65, s0
	global_store_short v[96:97], v64, off offset:64
	v_or_b32_e32 v64, v98, v183
	v_ashrrev_i32_e32 v65, 31, v64
	v_lshlrev_b64 v[64:65], 11, v[64:65]
	v_lshl_add_u64 v[64:65], v[130:131], 0, v[64:65]
	v_cvt_pk_bf16_f32 v80, v82, s0
	global_store_short v[64:65], v80, off
	global_store_short v[64:65], v66, off offset:64
	v_or_b32_e32 v64, v98, v184
	v_ashrrev_i32_e32 v65, 31, v64
	v_lshlrev_b64 v[64:65], 11, v[64:65]
	v_lshl_add_u64 v[64:65], v[130:131], 0, v[64:65]
	v_cvt_pk_bf16_f32 v66, v83, s0
	global_store_short v[64:65], v66, off
	v_cvt_pk_bf16_f32 v66, v67, s0
	global_store_short v[64:65], v66, off offset:64
	v_or_b32_e32 v64, v98, v185
	v_ashrrev_i32_e32 v65, 31, v64
	v_lshlrev_b64 v[64:65], 11, v[64:65]
	v_lshl_add_u64 v[64:65], v[130:131], 0, v[64:65]
	v_cvt_pk_bf16_f32 v66, v84, s0
	global_store_short v[64:65], v66, off
	v_cvt_pk_bf16_f32 v66, v68, s0
	global_store_short v[64:65], v66, off offset:64
	v_or_b32_e32 v64, v98, v186
	v_ashrrev_i32_e32 v65, 31, v64
	v_lshlrev_b64 v[64:65], 11, v[64:65]
	v_lshl_add_u64 v[64:65], v[130:131], 0, v[64:65]
	v_cvt_pk_bf16_f32 v66, v85, s0
	global_store_short v[64:65], v66, off
	v_cvt_pk_bf16_f32 v66, v69, s0
	global_store_short v[64:65], v66, off offset:64
	v_or_b32_e32 v64, v98, v187
	v_ashrrev_i32_e32 v65, 31, v64
	v_lshlrev_b64 v[64:65], 11, v[64:65]
	v_lshl_add_u64 v[64:65], v[130:131], 0, v[64:65]
	v_cvt_pk_bf16_f32 v66, v86, s0
	global_store_short v[64:65], v66, off
	v_cvt_pk_bf16_f32 v66, v70, s0
	global_store_short v[64:65], v66, off offset:64
	v_or_b32_e32 v64, v98, v188
	v_ashrrev_i32_e32 v65, 31, v64
	v_lshlrev_b64 v[64:65], 11, v[64:65]
	v_lshl_add_u64 v[64:65], v[130:131], 0, v[64:65]
	v_cvt_pk_bf16_f32 v66, v87, s0
	global_store_short v[64:65], v66, off
	v_cvt_pk_bf16_f32 v66, v71, s0
	global_store_short v[64:65], v66, off offset:64
	v_or_b32_e32 v64, v98, v189
	v_ashrrev_i32_e32 v65, 31, v64
	v_lshlrev_b64 v[64:65], 11, v[64:65]
	v_lshl_add_u64 v[64:65], v[130:131], 0, v[64:65]
	v_cvt_pk_bf16_f32 v66, v88, s0
	global_store_short v[64:65], v66, off
	v_cvt_pk_bf16_f32 v66, v72, s0
	global_store_short v[64:65], v66, off offset:64
	v_or_b32_e32 v64, v98, v190
	v_ashrrev_i32_e32 v65, 31, v64
	v_lshlrev_b64 v[64:65], 11, v[64:65]
	v_lshl_add_u64 v[64:65], v[130:131], 0, v[64:65]
	v_cvt_pk_bf16_f32 v66, v89, s0
	global_store_short v[64:65], v66, off
	v_cvt_pk_bf16_f32 v66, v73, s0
	global_store_short v[64:65], v66, off offset:64
	v_or_b32_e32 v64, v98, v191
	v_ashrrev_i32_e32 v65, 31, v64
	v_lshlrev_b64 v[64:65], 11, v[64:65]
	v_lshl_add_u64 v[64:65], v[130:131], 0, v[64:65]
	v_cvt_pk_bf16_f32 v66, v90, s0
	global_store_short v[64:65], v66, off
	v_cvt_pk_bf16_f32 v66, v74, s0
	global_store_short v[64:65], v66, off offset:64
	v_or_b32_e32 v64, v98, v192
	v_ashrrev_i32_e32 v65, 31, v64
	v_lshlrev_b64 v[64:65], 11, v[64:65]
	v_lshl_add_u64 v[64:65], v[130:131], 0, v[64:65]
	v_cvt_pk_bf16_f32 v66, v91, s0
	global_store_short v[64:65], v66, off
	v_cvt_pk_bf16_f32 v66, v75, s0
	global_store_short v[64:65], v66, off offset:64
	v_or_b32_e32 v64, v98, v193
	v_ashrrev_i32_e32 v65, 31, v64
	v_lshlrev_b64 v[64:65], 11, v[64:65]
	v_lshl_add_u64 v[64:65], v[130:131], 0, v[64:65]
	v_cvt_pk_bf16_f32 v66, v92, s0
	global_store_short v[64:65], v66, off
	v_cvt_pk_bf16_f32 v66, v76, s0
	global_store_short v[64:65], v66, off offset:64
	v_or_b32_e32 v64, v98, v194
	v_ashrrev_i32_e32 v65, 31, v64
	v_lshlrev_b64 v[64:65], 11, v[64:65]
	v_lshl_add_u64 v[64:65], v[130:131], 0, v[64:65]
	v_cvt_pk_bf16_f32 v66, v93, s0
	global_store_short v[64:65], v66, off
	v_cvt_pk_bf16_f32 v66, v77, s0
	global_store_short v[64:65], v66, off offset:64
	v_or_b32_e32 v64, v98, v195
	v_ashrrev_i32_e32 v65, 31, v64
	v_lshlrev_b64 v[64:65], 11, v[64:65]
	v_lshl_add_u64 v[64:65], v[130:131], 0, v[64:65]
	v_cvt_pk_bf16_f32 v66, v94, s0
	global_store_short v[64:65], v66, off
	v_cvt_pk_bf16_f32 v66, v78, s0
	global_store_short v[64:65], v66, off offset:64
	v_or_b32_e32 v64, v98, v196
	v_ashrrev_i32_e32 v65, 31, v64
	v_lshlrev_b64 v[64:65], 11, v[64:65]
	v_lshl_add_u64 v[64:65], v[130:131], 0, v[64:65]
	v_cvt_pk_bf16_f32 v66, v95, s0
	global_store_short v[64:65], v66, off
	v_cvt_pk_bf16_f32 v66, v79, s0
	global_store_short v[64:65], v66, off offset:64
	v_or_b32_e32 v66, 64, v132
	v_or_b32_e32 v64, v66, v181
	v_ashrrev_i32_e32 v65, 31, v64
	v_lshlrev_b64 v[64:65], 11, v[64:65]
	v_lshl_add_u64 v[64:65], v[130:131], 0, v[64:65]
	v_cvt_pk_bf16_f32 v32, v32, s0
	global_store_short v[64:65], v48, off
	global_store_short v[64:65], v32, off offset:64
	v_or_b32_e32 v64, v66, v182
	v_ashrrev_i32_e32 v65, 31, v64
	v_lshlrev_b64 v[64:65], 11, v[64:65]
	v_lshl_add_u64 v[64:65], v[130:131], 0, v[64:65]
	v_cvt_pk_bf16_f32 v32, v49, s0
	global_store_short v[64:65], v32, off
	v_cvt_pk_bf16_f32 v32, v33, s0
	global_store_short v[64:65], v32, off offset:64
	v_or_b32_e32 v32, v66, v183
	v_ashrrev_i32_e32 v33, 31, v32
	v_lshlrev_b64 v[32:33], 11, v[32:33]
	v_lshl_add_u64 v[32:33], v[130:131], 0, v[32:33]
	v_cvt_pk_bf16_f32 v48, v50, s0
	v_cvt_pk_bf16_f32 v34, v34, s0
	global_store_short v[32:33], v48, off
	global_store_short v[32:33], v34, off offset:64
	v_or_b32_e32 v32, v66, v184
	v_ashrrev_i32_e32 v33, 31, v32
	v_lshlrev_b64 v[32:33], 11, v[32:33]
	v_lshl_add_u64 v[32:33], v[130:131], 0, v[32:33]
	v_cvt_pk_bf16_f32 v34, v51, s0
	global_store_short v[32:33], v34, off
	v_cvt_pk_bf16_f32 v34, v35, s0
	global_store_short v[32:33], v34, off offset:64
	v_or_b32_e32 v32, v66, v185
	v_ashrrev_i32_e32 v33, 31, v32
	v_lshlrev_b64 v[32:33], 11, v[32:33]
	v_lshl_add_u64 v[32:33], v[130:131], 0, v[32:33]
	v_cvt_pk_bf16_f32 v34, v52, s0
	global_store_short v[32:33], v34, off
	v_cvt_pk_bf16_f32 v34, v36, s0
	global_store_short v[32:33], v34, off offset:64
	v_or_b32_e32 v32, v66, v186
	v_ashrrev_i32_e32 v33, 31, v32
	v_lshlrev_b64 v[32:33], 11, v[32:33]
	v_lshl_add_u64 v[32:33], v[130:131], 0, v[32:33]
	v_cvt_pk_bf16_f32 v34, v53, s0
	global_store_short v[32:33], v34, off
	v_cvt_pk_bf16_f32 v34, v37, s0
	global_store_short v[32:33], v34, off offset:64
	v_or_b32_e32 v32, v66, v187
	v_ashrrev_i32_e32 v33, 31, v32
	v_lshlrev_b64 v[32:33], 11, v[32:33]
	v_lshl_add_u64 v[32:33], v[130:131], 0, v[32:33]
	v_cvt_pk_bf16_f32 v34, v54, s0
	global_store_short v[32:33], v34, off
	v_cvt_pk_bf16_f32 v34, v38, s0
	global_store_short v[32:33], v34, off offset:64
	v_or_b32_e32 v32, v66, v188
	v_ashrrev_i32_e32 v33, 31, v32
	v_lshlrev_b64 v[32:33], 11, v[32:33]
	v_lshl_add_u64 v[32:33], v[130:131], 0, v[32:33]
	v_cvt_pk_bf16_f32 v34, v55, s0
	global_store_short v[32:33], v34, off
	v_cvt_pk_bf16_f32 v34, v39, s0
	global_store_short v[32:33], v34, off offset:64
	v_or_b32_e32 v32, v66, v189
	v_ashrrev_i32_e32 v33, 31, v32
	v_lshlrev_b64 v[32:33], 11, v[32:33]
	v_lshl_add_u64 v[32:33], v[130:131], 0, v[32:33]
	v_cvt_pk_bf16_f32 v34, v56, s0
	global_store_short v[32:33], v34, off
	v_cvt_pk_bf16_f32 v34, v40, s0
	global_store_short v[32:33], v34, off offset:64
	v_or_b32_e32 v32, v66, v190
	v_ashrrev_i32_e32 v33, 31, v32
	v_lshlrev_b64 v[32:33], 11, v[32:33]
	v_lshl_add_u64 v[32:33], v[130:131], 0, v[32:33]
	v_cvt_pk_bf16_f32 v34, v57, s0
	global_store_short v[32:33], v34, off
	v_cvt_pk_bf16_f32 v34, v41, s0
	global_store_short v[32:33], v34, off offset:64
	v_or_b32_e32 v32, v66, v191
	v_ashrrev_i32_e32 v33, 31, v32
	v_lshlrev_b64 v[32:33], 11, v[32:33]
	v_lshl_add_u64 v[32:33], v[130:131], 0, v[32:33]
	v_cvt_pk_bf16_f32 v34, v58, s0
	global_store_short v[32:33], v34, off
	v_cvt_pk_bf16_f32 v34, v42, s0
	global_store_short v[32:33], v34, off offset:64
	v_or_b32_e32 v32, v66, v192
	v_ashrrev_i32_e32 v33, 31, v32
	v_lshlrev_b64 v[32:33], 11, v[32:33]
	v_lshl_add_u64 v[32:33], v[130:131], 0, v[32:33]
	v_cvt_pk_bf16_f32 v34, v59, s0
	global_store_short v[32:33], v34, off
	v_cvt_pk_bf16_f32 v34, v43, s0
	global_store_short v[32:33], v34, off offset:64
	v_or_b32_e32 v32, v66, v193
	v_ashrrev_i32_e32 v33, 31, v32
	v_lshlrev_b64 v[32:33], 11, v[32:33]
	v_lshl_add_u64 v[32:33], v[130:131], 0, v[32:33]
	v_cvt_pk_bf16_f32 v34, v60, s0
	global_store_short v[32:33], v34, off
	v_cvt_pk_bf16_f32 v34, v44, s0
	global_store_short v[32:33], v34, off offset:64
	v_or_b32_e32 v32, v66, v194
	v_ashrrev_i32_e32 v33, 31, v32
	v_lshlrev_b64 v[32:33], 11, v[32:33]
	v_lshl_add_u64 v[32:33], v[130:131], 0, v[32:33]
	v_cvt_pk_bf16_f32 v34, v61, s0
	global_store_short v[32:33], v34, off
	v_cvt_pk_bf16_f32 v34, v45, s0
	global_store_short v[32:33], v34, off offset:64
	v_or_b32_e32 v32, v66, v195
	v_ashrrev_i32_e32 v33, 31, v32
	v_lshlrev_b64 v[32:33], 11, v[32:33]
	v_lshl_add_u64 v[32:33], v[130:131], 0, v[32:33]
	v_cvt_pk_bf16_f32 v34, v62, s0
	global_store_short v[32:33], v34, off
	v_cvt_pk_bf16_f32 v34, v46, s0
	global_store_short v[32:33], v34, off offset:64
	v_or_b32_e32 v32, v66, v196
	v_ashrrev_i32_e32 v33, 31, v32
	v_lshlrev_b64 v[32:33], 11, v[32:33]
	v_lshl_add_u64 v[32:33], v[130:131], 0, v[32:33]
	v_cvt_pk_bf16_f32 v34, v63, s0
	global_store_short v[32:33], v34, off
	v_cvt_pk_bf16_f32 v34, v47, s0
	global_store_short v[32:33], v34, off offset:64
	v_or_b32_e32 v34, 0x60, v132
	v_or_b32_e32 v32, v34, v181
	v_ashrrev_i32_e32 v33, 31, v32
	v_lshlrev_b64 v[32:33], 11, v[32:33]
	v_lshl_add_u64 v[32:33], v[130:131], 0, v[32:33]
	v_cvt_pk_bf16_f32 v0, v0, s0
	global_store_short v[32:33], v16, off
	global_store_short v[32:33], v0, off offset:64
	v_or_b32_e32 v32, v34, v182
	v_ashrrev_i32_e32 v33, 31, v32
	v_lshlrev_b64 v[32:33], 11, v[32:33]
	v_lshl_add_u64 v[32:33], v[130:131], 0, v[32:33]
	v_cvt_pk_bf16_f32 v0, v17, s0
	global_store_short v[32:33], v0, off
	v_cvt_pk_bf16_f32 v0, v1, s0
	global_store_short v[32:33], v0, off offset:64
	v_or_b32_e32 v0, v34, v183
	v_ashrrev_i32_e32 v1, 31, v0
	v_lshlrev_b64 v[0:1], 11, v[0:1]
	v_lshl_add_u64 v[0:1], v[130:131], 0, v[0:1]
	v_cvt_pk_bf16_f32 v16, v18, s0
	v_cvt_pk_bf16_f32 v2, v2, s0
	global_store_short v[0:1], v16, off
	global_store_short v[0:1], v2, off offset:64
	v_or_b32_e32 v0, v34, v184
	v_ashrrev_i32_e32 v1, 31, v0
	v_lshlrev_b64 v[0:1], 11, v[0:1]
	v_lshl_add_u64 v[0:1], v[130:131], 0, v[0:1]
	v_cvt_pk_bf16_f32 v2, v19, s0
	global_store_short v[0:1], v2, off
	v_cvt_pk_bf16_f32 v2, v3, s0
	global_store_short v[0:1], v2, off offset:64
	v_or_b32_e32 v0, v34, v185
	v_ashrrev_i32_e32 v1, 31, v0
	v_lshlrev_b64 v[0:1], 11, v[0:1]
	v_lshl_add_u64 v[0:1], v[130:131], 0, v[0:1]
	v_cvt_pk_bf16_f32 v2, v20, s0
	global_store_short v[0:1], v2, off
	v_cvt_pk_bf16_f32 v2, v4, s0
	global_store_short v[0:1], v2, off offset:64
	v_or_b32_e32 v0, v34, v186
	v_ashrrev_i32_e32 v1, 31, v0
	v_lshlrev_b64 v[0:1], 11, v[0:1]
	v_lshl_add_u64 v[0:1], v[130:131], 0, v[0:1]
	v_cvt_pk_bf16_f32 v2, v21, s0
	global_store_short v[0:1], v2, off
	v_cvt_pk_bf16_f32 v2, v5, s0
	global_store_short v[0:1], v2, off offset:64
	v_or_b32_e32 v0, v34, v187
	v_ashrrev_i32_e32 v1, 31, v0
	v_lshlrev_b64 v[0:1], 11, v[0:1]
	v_lshl_add_u64 v[0:1], v[130:131], 0, v[0:1]
	v_cvt_pk_bf16_f32 v2, v22, s0
	global_store_short v[0:1], v2, off
	v_cvt_pk_bf16_f32 v2, v6, s0
	global_store_short v[0:1], v2, off offset:64
	v_or_b32_e32 v0, v34, v188
	v_ashrrev_i32_e32 v1, 31, v0
	v_lshlrev_b64 v[0:1], 11, v[0:1]
	v_lshl_add_u64 v[0:1], v[130:131], 0, v[0:1]
	v_cvt_pk_bf16_f32 v2, v23, s0
	global_store_short v[0:1], v2, off
	v_cvt_pk_bf16_f32 v2, v7, s0
	global_store_short v[0:1], v2, off offset:64
	v_or_b32_e32 v0, v34, v189
	v_ashrrev_i32_e32 v1, 31, v0
	v_lshlrev_b64 v[0:1], 11, v[0:1]
	v_lshl_add_u64 v[0:1], v[130:131], 0, v[0:1]
	v_cvt_pk_bf16_f32 v2, v24, s0
	global_store_short v[0:1], v2, off
	v_cvt_pk_bf16_f32 v2, v8, s0
	global_store_short v[0:1], v2, off offset:64
	v_or_b32_e32 v0, v34, v190
	v_ashrrev_i32_e32 v1, 31, v0
	v_lshlrev_b64 v[0:1], 11, v[0:1]
	v_lshl_add_u64 v[0:1], v[130:131], 0, v[0:1]
	v_cvt_pk_bf16_f32 v2, v25, s0
	global_store_short v[0:1], v2, off
	v_cvt_pk_bf16_f32 v2, v9, s0
	global_store_short v[0:1], v2, off offset:64
	v_or_b32_e32 v0, v34, v191
	v_ashrrev_i32_e32 v1, 31, v0
	v_lshlrev_b64 v[0:1], 11, v[0:1]
	v_lshl_add_u64 v[0:1], v[130:131], 0, v[0:1]
	v_cvt_pk_bf16_f32 v2, v26, s0
	global_store_short v[0:1], v2, off
	v_cvt_pk_bf16_f32 v2, v10, s0
	global_store_short v[0:1], v2, off offset:64
	v_or_b32_e32 v0, v34, v192
	v_ashrrev_i32_e32 v1, 31, v0
	v_lshlrev_b64 v[0:1], 11, v[0:1]
	v_lshl_add_u64 v[0:1], v[130:131], 0, v[0:1]
	v_cvt_pk_bf16_f32 v2, v27, s0
	global_store_short v[0:1], v2, off
	v_cvt_pk_bf16_f32 v2, v11, s0
	global_store_short v[0:1], v2, off offset:64
	v_or_b32_e32 v0, v34, v193
	v_ashrrev_i32_e32 v1, 31, v0
	v_lshlrev_b64 v[0:1], 11, v[0:1]
	v_lshl_add_u64 v[0:1], v[130:131], 0, v[0:1]
	v_cvt_pk_bf16_f32 v2, v28, s0
	global_store_short v[0:1], v2, off
	v_cvt_pk_bf16_f32 v2, v12, s0
	global_store_short v[0:1], v2, off offset:64
	v_or_b32_e32 v0, v34, v194
	v_ashrrev_i32_e32 v1, 31, v0
	v_lshlrev_b64 v[0:1], 11, v[0:1]
	v_lshl_add_u64 v[0:1], v[130:131], 0, v[0:1]
	v_cvt_pk_bf16_f32 v2, v29, s0
	global_store_short v[0:1], v2, off
	v_cvt_pk_bf16_f32 v2, v13, s0
	global_store_short v[0:1], v2, off offset:64
	v_or_b32_e32 v0, v34, v195
	v_ashrrev_i32_e32 v1, 31, v0
	v_lshlrev_b64 v[0:1], 11, v[0:1]
	v_lshl_add_u64 v[0:1], v[130:131], 0, v[0:1]
	v_cvt_pk_bf16_f32 v2, v30, s0
	global_store_short v[0:1], v2, off
	v_cvt_pk_bf16_f32 v2, v14, s0
	global_store_short v[0:1], v2, off offset:64
	v_or_b32_e32 v0, v34, v196
	v_ashrrev_i32_e32 v1, 31, v0
	v_lshlrev_b64 v[0:1], 11, v[0:1]
	v_lshl_add_u64 v[0:1], v[130:131], 0, v[0:1]
	v_cvt_pk_bf16_f32 v2, v31, s0
	global_store_short v[0:1], v2, off
	v_cvt_pk_bf16_f32 v2, v15, s0
	global_store_short v[0:1], v2, off offset:64
	s_cbranch_scc0 .LBB0_262

.LBB0_329:
	s_and_b32 s0, s31, 7
	v_lshl_add_u32 v0, s0, 8, v189
	v_ashrrev_i32_e32 v1, 31, v0
	v_lshlrev_b64 v[0:1], 11, v[0:1]
	s_and_b32 s0, s35, 0xffffff00
	v_lshl_add_u64 v[172:173], v[168:169], 0, v[0:1]
	v_add_u32_e32 v0, s0, v177
	s_and_b32 s0, s30, 7
	v_ashrrev_i32_e32 v1, 31, v0
	s_or_b32 s0, s0, s34
	v_lshlrev_b64 v[0:1], 11, v[0:1]
	s_lshl_b32 s0, s0, 8
	v_lshl_add_u64 v[174:175], v[170:171], 0, v[0:1]
	v_add_u32_e32 v0, s0, v177
	s_lshl_b32 s1, s30, 5
	v_ashrrev_i32_e32 v1, 31, v0
	s_and_b32 s1, s1, 0xffffff00
	v_lshlrev_b64 v[0:1], 11, v[0:1]
	v_add_u32_e32 v2, s1, v177
	s_waitcnt vmcnt(0) lgkmcnt(0)
	s_barrier
	v_ashrrev_i32_e32 v3, 31, v2
	v_lshl_add_u64 v[0:1], v[158:159], 0, v[0:1]
	v_readfirstlane_b32 s2, v182
	s_mov_b32 m0, s2
	s_nop 0
	global_load_lds_dwordx4 v[0:1], off
	s_mov_b64 s[26:27], 0x40000
	v_lshlrev_b64 v[2:3], 11, v[2:3]
	v_lshl_add_u64 v[4:5], v[0:1], 0, s[26:27]
	s_add_i32 s3, s2, 0x2000
	s_mov_b32 m0, s3
	s_nop 0
	global_load_lds_dwordx4 v[4:5], off
	v_lshl_add_u64 v[2:3], v[160:161], 0, v[2:3]
	s_add_i32 s3, s2, 0x4000
	s_mov_b32 m0, s3
	s_nop 0
	global_load_lds_dwordx4 v[2:3], off
	v_lshl_add_u64 v[4:5], v[2:3], 0, s[26:27]
	s_add_i32 s3, s2, 0x6000
	s_mov_b32 m0, s3
	s_nop 0
	global_load_lds_dwordx4 v[4:5], off
	s_add_i32 s3, s2, 0x8000
	v_lshl_add_u64 v[4:5], v[0:1], 0, 64
	s_mov_b32 m0, s3
	s_nop 0
	global_load_lds_dwordx4 v[4:5], off
	s_mov_b64 s[24:25], 0x40040
	v_lshl_add_u64 v[4:5], v[0:1], 0, s[24:25]
	s_add_i32 s3, s2, 0xa000
	s_mov_b32 m0, s3
	s_nop 0
	global_load_lds_dwordx4 v[4:5], off
	v_lshl_add_u64 v[4:5], v[2:3], 0, 64
	s_add_i32 s3, s2, 0xc000
	s_mov_b32 m0, s3
	s_nop 0
	global_load_lds_dwordx4 v[4:5], off
	v_lshl_add_u64 v[4:5], v[2:3], 0, s[24:25]
	s_add_i32 s3, s2, 0xe000
	s_mov_b32 m0, s3
	s_nop 0
	global_load_lds_dwordx4 v[4:5], off
	s_mov_b64 s[24:25], 0x80
	s_add_i32 s3, s2, 0x10000
	v_lshl_add_u64 v[4:5], v[0:1], 0, s[24:25]
	s_mov_b32 m0, s3
	s_nop 0
	global_load_lds_dwordx4 v[4:5], off
	s_mov_b64 s[28:29], 0x40080
	v_lshl_add_u64 v[0:1], v[0:1], 0, s[28:29]
	s_add_i32 s3, s2, 0x12000
	s_mov_b32 m0, s3
	s_nop 0
	global_load_lds_dwordx4 v[0:1], off
	v_lshl_add_u64 v[0:1], v[2:3], 0, s[24:25]
	s_add_i32 s3, s2, 0x14000
	s_mov_b32 m0, s3
	s_nop 0
	global_load_lds_dwordx4 v[0:1], off
	v_lshl_add_u64 v[0:1], v[2:3], 0, s[28:29]
	s_add_i32 s2, s2, 0x16000
	s_mov_b32 m0, s2
	s_nop 0
	global_load_lds_dwordx4 v[0:1], off
	v_mov_b32_e32 v130, 0
	v_mov_b32_e32 v134, 0
	v_mov_b32_e32 v0, 0
	s_mov_b32 s2, 0x18000
	v_mov_b32_e32 v1, v0
	v_mov_b32_e32 v2, v0
	v_mov_b32_e32 v3, v0
	v_mov_b32_e32 v4, v0
	v_mov_b32_e32 v5, v0
	v_mov_b32_e32 v6, v0
	v_mov_b32_e32 v7, v0
	v_mov_b32_e32 v8, v0
	v_mov_b32_e32 v9, v0
	v_mov_b32_e32 v10, v0
	v_mov_b32_e32 v11, v0
	v_mov_b32_e32 v12, v0
	v_mov_b32_e32 v13, v0
	v_mov_b32_e32 v14, v0
	v_mov_b32_e32 v15, v0
	v_mov_b32_e32 v16, v0
	v_mov_b32_e32 v17, v0
	v_mov_b32_e32 v18, v0
	v_mov_b32_e32 v19, v0
	v_mov_b32_e32 v20, v0
	v_mov_b32_e32 v21, v0
	v_mov_b32_e32 v22, v0
	v_mov_b32_e32 v23, v0
	v_mov_b32_e32 v24, v0
	v_mov_b32_e32 v25, v0
	v_mov_b32_e32 v26, v0
	v_mov_b32_e32 v27, v0
	v_mov_b32_e32 v28, v0
	v_mov_b32_e32 v29, v0
	v_mov_b32_e32 v30, v0
	v_mov_b32_e32 v31, v0
	v_mov_b32_e32 v32, v0
	v_mov_b32_e32 v33, v0
	v_mov_b32_e32 v34, v0
	v_mov_b32_e32 v35, v0
	v_mov_b32_e32 v36, v0
	v_mov_b32_e32 v37, v0
	v_mov_b32_e32 v38, v0
	v_mov_b32_e32 v39, v0
	v_mov_b32_e32 v40, v0
	v_mov_b32_e32 v41, v0
	v_mov_b32_e32 v42, v0
	v_mov_b32_e32 v43, v0
	v_mov_b32_e32 v44, v0
	v_mov_b32_e32 v45, v0
	v_mov_b32_e32 v46, v0
	v_mov_b32_e32 v47, v0
	v_mov_b32_e32 v48, v0
	v_mov_b32_e32 v49, v0
	v_mov_b32_e32 v50, v0
	v_mov_b32_e32 v51, v0
	v_mov_b32_e32 v52, v0
	v_mov_b32_e32 v53, v0
	v_mov_b32_e32 v54, v0
	v_mov_b32_e32 v55, v0
	v_mov_b32_e32 v56, v0
	v_mov_b32_e32 v57, v0
	v_mov_b32_e32 v58, v0
	v_mov_b32_e32 v59, v0
	v_mov_b32_e32 v60, v0
	v_mov_b32_e32 v61, v0
	v_mov_b32_e32 v62, v0
	v_mov_b32_e32 v63, v0
	v_mov_b32_e32 v64, v0
	v_mov_b32_e32 v65, v0
	v_mov_b32_e32 v66, v0
	v_mov_b32_e32 v67, v0
	v_mov_b32_e32 v68, v0
	v_mov_b32_e32 v69, v0
	v_mov_b32_e32 v70, v0
	v_mov_b32_e32 v71, v0
	v_mov_b32_e32 v72, v0
	v_mov_b32_e32 v73, v0
	v_mov_b32_e32 v74, v0
	v_mov_b32_e32 v75, v0
	v_mov_b32_e32 v76, v0
	v_mov_b32_e32 v77, v0
	v_mov_b32_e32 v78, v0
	v_mov_b32_e32 v79, v0
	v_mov_b32_e32 v80, v0
	v_mov_b32_e32 v81, v0
	v_mov_b32_e32 v82, v0
	v_mov_b32_e32 v83, v0
	v_mov_b32_e32 v84, v0
	v_mov_b32_e32 v85, v0
	v_mov_b32_e32 v86, v0
	v_mov_b32_e32 v87, v0
	v_mov_b32_e32 v88, v0
	v_mov_b32_e32 v89, v0
	v_mov_b32_e32 v90, v0
	v_mov_b32_e32 v91, v0
	v_mov_b32_e32 v92, v0
	v_mov_b32_e32 v93, v0
	v_mov_b32_e32 v94, v0
	v_mov_b32_e32 v95, v0
	v_mov_b32_e32 v96, v0
	v_mov_b32_e32 v97, v0
	v_mov_b32_e32 v98, v0
	v_mov_b32_e32 v99, v0
	v_mov_b32_e32 v100, v0
	v_mov_b32_e32 v101, v0
	v_mov_b32_e32 v102, v0
	v_mov_b32_e32 v103, v0
	v_mov_b32_e32 v104, v0
	v_mov_b32_e32 v105, v0
	v_mov_b32_e32 v106, v0
	v_mov_b32_e32 v107, v0
	v_mov_b32_e32 v108, v0
	v_mov_b32_e32 v109, v0
	v_mov_b32_e32 v110, v0
	v_mov_b32_e32 v111, v0
	v_mov_b32_e32 v112, v0
	v_mov_b32_e32 v113, v0
	v_mov_b32_e32 v114, v0
	v_mov_b32_e32 v115, v0
	v_mov_b32_e32 v116, v0
	v_mov_b32_e32 v117, v0
	v_mov_b32_e32 v118, v0
	v_mov_b32_e32 v119, v0
	v_mov_b32_e32 v120, v0
	v_mov_b32_e32 v121, v0
	v_mov_b32_e32 v122, v0
	v_mov_b32_e32 v123, v0
	v_mov_b32_e32 v124, v0
	v_mov_b32_e32 v125, v0
	v_mov_b32_e32 v126, v0
	v_mov_b32_e32 v127, v0
	v_mov_b32_e32 v135, v134
	v_mov_b32_e32 v136, v134
	v_mov_b32_e32 v137, v134
	v_mov_b32_e32 v138, v134
	v_mov_b32_e32 v139, v134
	v_mov_b32_e32 v140, v134
	v_mov_b32_e32 v141, v134
	v_mov_b32_e32 v146, v134
	v_mov_b32_e32 v147, v134
	v_mov_b32_e32 v148, v134
	v_mov_b32_e32 v149, v134
	v_mov_b32_e32 v150, v134
	v_mov_b32_e32 v151, v134
	v_mov_b32_e32 v152, v134
	v_mov_b32_e32 v153, v134
	v_mov_b32_e32 v131, v130
	v_mov_b32_e32 v132, v130
	v_mov_b32_e32 v133, v130
	v_mov_b32_e32 v142, v130
	v_mov_b32_e32 v143, v130
	v_mov_b32_e32 v144, v130
	v_mov_b32_e32 v145, v130
	v_readfirstlane_b32 s100, v163
	s_cmp_ge_u32 s100, 0x100
	s_cbranch_scc1 .Lky_2
.LBB0_330:
	s_and_b32 s3, s2, 0x18000
	v_add_u32_e32 v128, s3, v182
	s_add_i32 s3, s2, 0xfffe8000
	s_and_b32 s3, s3, 0x18000
	v_or_b32_e32 v214, s3, v181
	v_add_u32_e32 v215, s3, v178
	s_waitcnt vmcnt(8) lgkmcnt(0)
	s_barrier
	v_mfma_f32_32x32x16_bf16 v[112:127], v[150:153], v[142:145], v[112:127]
	v_mfma_f32_32x32x16_bf16 v[96:111], v[150:153], v[130:133], v[96:111]
	v_add_u32_e32 v194, v214, v179
	v_add_u32_e32 v210, v215, v179
	ds_read_b128 v[190:193], v194 offset:16384
	ds_read_b128 v[194:197], v194 offset:18432
	ds_read_b128 v[198:201], v210
	ds_read_b128 v[202:205], v210 offset:2048
	ds_read_b128 v[206:209], v210 offset:4096
	ds_read_b128 v[210:213], v210 offset:6144
	v_mfma_f32_32x32x16_bf16 v[80:95], v[146:149], v[142:145], v[80:95]
	v_mfma_f32_32x32x16_bf16 v[64:79], v[146:149], v[130:133], v[64:79]
	v_readfirstlane_b32 s3, v128
	s_mov_b32 m0, s3
	s_nop 0
	global_load_lds_dwordx4 v[172:173], off
	v_mfma_f32_32x32x16_bf16 v[48:63], v[138:141], v[142:145], v[48:63]
	v_mfma_f32_32x32x16_bf16 v[32:47], v[138:141], v[130:133], v[32:47]
	s_add_i32 s24, s3, 0x2000
	v_lshl_add_u64 v[150:151], v[172:173], 0, s[26:27]
	s_mov_b32 m0, s24
	s_nop 0
	global_load_lds_dwordx4 v[150:151], off
	v_mfma_f32_32x32x16_bf16 v[16:31], v[134:137], v[142:145], v[16:31]
	v_mfma_f32_32x32x16_bf16 v[0:15], v[134:137], v[130:133], v[0:15]
	v_add_u32_e32 v128, v214, v180
	ds_read_b128 v[142:145], v128 offset:16384
	ds_read_b128 v[130:133], v128 offset:18432
	v_add_u32_e32 v128, v215, v180
	ds_read_b128 v[150:153], v128
	ds_read_b128 v[146:149], v128 offset:2048
	ds_read_b128 v[138:141], v128 offset:4096
	ds_read_b128 v[134:137], v128 offset:6144
	s_waitcnt lgkmcnt(9)
	v_mfma_f32_32x32x16_bf16 v[112:127], v[198:201], v[190:193], v[112:127]
	s_add_i32 s24, s3, 0x6000
	s_addk_i32 s3, 0x4000
	v_mfma_f32_32x32x16_bf16 v[96:111], v[198:201], v[194:197], v[96:111]
	s_mov_b32 m0, s3
	s_nop 0
	global_load_lds_dwordx4 v[174:175], off
	v_lshl_add_u64 v[214:215], v[174:175], 0, s[26:27]
	s_waitcnt lgkmcnt(8)
	v_mfma_f32_32x32x16_bf16 v[80:95], v[202:205], v[190:193], v[80:95]
	v_mfma_f32_32x32x16_bf16 v[64:79], v[202:205], v[194:197], v[64:79]
	s_waitcnt lgkmcnt(7)
	v_mfma_f32_32x32x16_bf16 v[48:63], v[206:209], v[190:193], v[48:63]
	v_mfma_f32_32x32x16_bf16 v[32:47], v[206:209], v[194:197], v[32:47]
	s_mov_b32 m0, s24
	s_nop 0
	global_load_lds_dwordx4 v[214:215], off
	s_waitcnt lgkmcnt(6)
	v_mfma_f32_32x32x16_bf16 v[16:31], v[210:213], v[190:193], v[16:31]
	s_add_i32 s2, s2, 0x8000
	v_lshl_add_u64 v[172:173], v[172:173], 0, 64
	v_lshl_add_u64 v[174:175], v[174:175], 0, 64
	s_cmp_eq_u32 s2, 0x100000
	v_mfma_f32_32x32x16_bf16 v[0:15], v[210:213], v[194:197], v[0:15]
	s_cbranch_scc0 .LBB0_330
	s_branch .Lktail_2
.Lky_2:
	s_and_b32 s3, s2, 0x18000
	v_add_u32_e32 v128, s3, v182
	s_add_i32 s3, s2, 0xfffe8000
	s_and_b32 s3, s3, 0x18000
	v_or_b32_e32 v214, s3, v181
	v_add_u32_e32 v215, s3, v178
	s_waitcnt vmcnt(8) lgkmcnt(0)
	s_barrier
	v_add_u32_e32 v194, v214, v179
	v_add_u32_e32 v210, v215, v179
	ds_read_b128 v[190:193], v194 offset:16384
	ds_read_b128 v[194:197], v194 offset:18432
	ds_read_b128 v[198:201], v210
	ds_read_b128 v[202:205], v210 offset:2048
	ds_read_b128 v[206:209], v210 offset:4096
	ds_read_b128 v[210:213], v210 offset:6144
	v_mfma_f32_32x32x16_bf16 v[112:127], v[150:153], v[142:145], v[112:127]
	v_mfma_f32_32x32x16_bf16 v[96:111], v[150:153], v[130:133], v[96:111]
	v_readfirstlane_b32 s3, v128
	s_mov_b32 m0, s3
	s_nop 0
	global_load_lds_dwordx4 v[172:173], off
	v_mfma_f32_32x32x16_bf16 v[80:95], v[146:149], v[142:145], v[80:95]
	v_mfma_f32_32x32x16_bf16 v[64:79], v[146:149], v[130:133], v[64:79]
	v_mfma_f32_32x32x16_bf16 v[48:63], v[138:141], v[142:145], v[48:63]
	v_mfma_f32_32x32x16_bf16 v[32:47], v[138:141], v[130:133], v[32:47]
	s_add_i32 s24, s3, 0x2000
	v_lshl_add_u64 v[150:151], v[172:173], 0, s[26:27]
	s_mov_b32 m0, s24
	s_nop 0
	global_load_lds_dwordx4 v[150:151], off
	v_mfma_f32_32x32x16_bf16 v[16:31], v[134:137], v[142:145], v[16:31]
	v_mfma_f32_32x32x16_bf16 v[0:15], v[134:137], v[130:133], v[0:15]
	v_add_u32_e32 v128, v214, v180
	ds_read_b128 v[142:145], v128 offset:16384
	ds_read_b128 v[130:133], v128 offset:18432
	v_add_u32_e32 v128, v215, v180
	ds_read_b128 v[150:153], v128
	ds_read_b128 v[146:149], v128 offset:2048
	ds_read_b128 v[138:141], v128 offset:4096
	ds_read_b128 v[134:137], v128 offset:6144
	s_waitcnt lgkmcnt(9)
	v_mfma_f32_32x32x16_bf16 v[112:127], v[198:201], v[190:193], v[112:127]
	s_add_i32 s24, s3, 0x6000
	s_addk_i32 s3, 0x4000
	v_mfma_f32_32x32x16_bf16 v[96:111], v[198:201], v[194:197], v[96:111]
	s_mov_b32 m0, s3
	s_nop 0
	global_load_lds_dwordx4 v[174:175], off
	v_lshl_add_u64 v[214:215], v[174:175], 0, s[26:27]
	s_waitcnt lgkmcnt(8)
	v_mfma_f32_32x32x16_bf16 v[80:95], v[202:205], v[190:193], v[80:95]
	v_mfma_f32_32x32x16_bf16 v[64:79], v[202:205], v[194:197], v[64:79]
	s_waitcnt lgkmcnt(7)
	v_mfma_f32_32x32x16_bf16 v[48:63], v[206:209], v[190:193], v[48:63]
	v_mfma_f32_32x32x16_bf16 v[32:47], v[206:209], v[194:197], v[32:47]
	s_mov_b32 m0, s24
	s_nop 0
	global_load_lds_dwordx4 v[214:215], off
	s_waitcnt lgkmcnt(6)
	v_mfma_f32_32x32x16_bf16 v[16:31], v[210:213], v[190:193], v[16:31]
	s_add_i32 s2, s2, 0x8000
	v_lshl_add_u64 v[172:173], v[172:173], 0, 64
	v_lshl_add_u64 v[174:175], v[174:175], 0, 64
	s_cmp_eq_u32 s2, 0x100000
	v_mfma_f32_32x32x16_bf16 v[0:15], v[210:213], v[194:197], v[0:15]
	s_cbranch_scc0 .Lky_2
.Lktail_2:
	s_waitcnt vmcnt(8) lgkmcnt(0)
	s_barrier
	v_add_u32_e32 v128, v181, v179
	ds_read_b128 v[172:175], v128 offset:49152
	ds_read_b128 v[190:193], v128 offset:51200
	v_add_u32_e32 v128, v178, v179
	ds_read_b128 v[194:197], v128 offset:32768
	ds_read_b128 v[198:201], v128 offset:34816
	ds_read_b128 v[202:205], v128 offset:36864
	ds_read_b128 v[206:209], v128 offset:38912
	s_waitcnt lgkmcnt(9)
	v_mfma_f32_32x32x16_bf16 v[112:127], v[150:153], v[142:145], v[112:127]
	v_mfma_f32_32x32x16_bf16 v[96:111], v[150:153], v[130:133], v[96:111]
	s_waitcnt lgkmcnt(8)
	v_mfma_f32_32x32x16_bf16 v[80:95], v[146:149], v[142:145], v[80:95]
	v_mfma_f32_32x32x16_bf16 v[64:79], v[146:149], v[130:133], v[64:79]
	s_waitcnt lgkmcnt(7)
	v_mfma_f32_32x32x16_bf16 v[48:63], v[138:141], v[142:145], v[48:63]
	v_mfma_f32_32x32x16_bf16 v[32:47], v[138:141], v[130:133], v[32:47]
	s_waitcnt lgkmcnt(6)
	v_mfma_f32_32x32x16_bf16 v[16:31], v[134:137], v[142:145], v[16:31]
	v_mfma_f32_32x32x16_bf16 v[0:15], v[134:137], v[130:133], v[0:15]
	v_add_u32_e32 v128, v181, v180
	ds_read_b128 v[130:133], v128 offset:49152
	ds_read_b128 v[134:137], v128 offset:51200
	v_add_u32_e32 v128, v178, v180
	ds_read_b128 v[138:141], v128 offset:32768
	ds_read_b128 v[142:145], v128 offset:34816
	ds_read_b128 v[146:149], v128 offset:36864
	ds_read_b128 v[150:153], v128 offset:38912
	s_waitcnt lgkmcnt(9)
	v_mfma_f32_32x32x16_bf16 v[112:127], v[194:197], v[172:175], v[112:127]
	v_mfma_f32_32x32x16_bf16 v[96:111], v[194:197], v[190:193], v[96:111]
	s_waitcnt lgkmcnt(8)
	v_mfma_f32_32x32x16_bf16 v[80:95], v[198:201], v[172:175], v[80:95]
	v_mfma_f32_32x32x16_bf16 v[64:79], v[198:201], v[190:193], v[64:79]
	s_waitcnt lgkmcnt(7)
	v_mfma_f32_32x32x16_bf16 v[48:63], v[202:205], v[172:175], v[48:63]
	v_mfma_f32_32x32x16_bf16 v[32:47], v[202:205], v[190:193], v[32:47]
	s_waitcnt vmcnt(4) lgkmcnt(0)
	s_barrier
	v_add_u32_e32 v128, v187, v179
	s_waitcnt lgkmcnt(6)
	v_mfma_f32_32x32x16_bf16 v[16:31], v[206:209], v[172:175], v[16:31]
	v_mfma_f32_32x32x16_bf16 v[0:15], v[206:209], v[190:193], v[0:15]
	ds_read_b128 v[172:175], v128 offset:16384
	ds_read_b128 v[190:193], v128 offset:18432
	v_add_u32_e32 v128, v188, v179
	ds_read_b128 v[194:197], v128
	ds_read_b128 v[198:201], v128 offset:2048
	ds_read_b128 v[202:205], v128 offset:4096
	ds_read_b128 v[206:209], v128 offset:6144
	s_waitcnt lgkmcnt(9)
	v_mfma_f32_32x32x16_bf16 v[112:127], v[138:141], v[130:133], v[112:127]
	v_mfma_f32_32x32x16_bf16 v[96:111], v[138:141], v[134:137], v[96:111]
	s_waitcnt lgkmcnt(8)
	v_mfma_f32_32x32x16_bf16 v[80:95], v[142:145], v[130:133], v[80:95]
	v_mfma_f32_32x32x16_bf16 v[64:79], v[142:145], v[134:137], v[64:79]
	s_waitcnt lgkmcnt(7)
	v_mfma_f32_32x32x16_bf16 v[48:63], v[146:149], v[130:133], v[48:63]
	v_mfma_f32_32x32x16_bf16 v[32:47], v[146:149], v[134:137], v[32:47]
	s_waitcnt lgkmcnt(6)
	v_mfma_f32_32x32x16_bf16 v[16:31], v[150:153], v[130:133], v[16:31]
	v_mfma_f32_32x32x16_bf16 v[0:15], v[150:153], v[134:137], v[0:15]
	v_add_u32_e32 v128, v187, v180
	ds_read_b128 v[130:133], v128 offset:16384
	ds_read_b128 v[134:137], v128 offset:18432
	v_add_u32_e32 v128, v188, v180
	ds_read_b128 v[138:141], v128
	ds_read_b128 v[142:145], v128 offset:2048
	ds_read_b128 v[146:149], v128 offset:4096
	ds_read_b128 v[150:153], v128 offset:6144
	s_waitcnt lgkmcnt(9)
	v_mfma_f32_32x32x16_bf16 v[112:127], v[194:197], v[172:175], v[112:127]
	v_mfma_f32_32x32x16_bf16 v[96:111], v[194:197], v[190:193], v[96:111]
	s_waitcnt lgkmcnt(8)
	v_mfma_f32_32x32x16_bf16 v[80:95], v[198:201], v[172:175], v[80:95]
	v_mfma_f32_32x32x16_bf16 v[64:79], v[198:201], v[190:193], v[64:79]
	s_waitcnt lgkmcnt(7)
	v_mfma_f32_32x32x16_bf16 v[48:63], v[202:205], v[172:175], v[48:63]
	v_mfma_f32_32x32x16_bf16 v[32:47], v[202:205], v[190:193], v[32:47]
	s_waitcnt vmcnt(0) lgkmcnt(0)
	s_barrier
	v_add_u32_e32 v128, v185, v179
	s_waitcnt lgkmcnt(6)
	v_mfma_f32_32x32x16_bf16 v[16:31], v[206:209], v[172:175], v[16:31]
	v_mfma_f32_32x32x16_bf16 v[0:15], v[206:209], v[190:193], v[0:15]
	ds_read_b128 v[172:175], v128 offset:16384
	ds_read_b128 v[190:193], v128 offset:18432
	v_add_u32_e32 v128, v186, v179
	ds_read_b128 v[194:197], v128
	ds_read_b128 v[198:201], v128 offset:2048
	ds_read_b128 v[202:205], v128 offset:4096
	ds_read_b128 v[206:209], v128 offset:6144
	s_waitcnt lgkmcnt(9)
	v_mfma_f32_32x32x16_bf16 v[112:127], v[138:141], v[130:133], v[112:127]
	v_mfma_f32_32x32x16_bf16 v[96:111], v[138:141], v[134:137], v[96:111]
	s_waitcnt lgkmcnt(8)
	v_mfma_f32_32x32x16_bf16 v[80:95], v[142:145], v[130:133], v[80:95]
	v_mfma_f32_32x32x16_bf16 v[64:79], v[142:145], v[134:137], v[64:79]
	s_waitcnt lgkmcnt(7)
	v_mfma_f32_32x32x16_bf16 v[48:63], v[146:149], v[130:133], v[48:63]
	v_mfma_f32_32x32x16_bf16 v[32:47], v[146:149], v[134:137], v[32:47]
	s_waitcnt lgkmcnt(6)
	v_mfma_f32_32x32x16_bf16 v[16:31], v[150:153], v[130:133], v[16:31]
	v_mfma_f32_32x32x16_bf16 v[0:15], v[150:153], v[134:137], v[0:15]
	v_add_u32_e32 v128, v185, v180
	ds_read_b128 v[130:133], v128 offset:16384
	ds_read_b128 v[138:141], v128 offset:18432
	v_add_u32_e32 v128, v186, v180
	ds_read_b128 v[134:137], v128
	ds_read_b128 v[142:145], v128 offset:2048
	ds_read_b128 v[146:149], v128 offset:4096
	ds_read_b128 v[210:213], v128 offset:6144
	s_waitcnt lgkmcnt(9)
	v_mfma_f32_32x32x16_bf16 v[112:127], v[194:197], v[172:175], v[112:127]
	v_mfma_f32_32x32x16_bf16 v[96:111], v[194:197], v[190:193], v[96:111]
	s_waitcnt lgkmcnt(8)
	v_mfma_f32_32x32x16_bf16 v[80:95], v[198:201], v[172:175], v[80:95]
	v_mfma_f32_32x32x16_bf16 v[64:79], v[198:201], v[190:193], v[64:79]
	s_waitcnt lgkmcnt(7)
	v_mfma_f32_32x32x16_bf16 v[48:63], v[202:205], v[172:175], v[48:63]
	v_mfma_f32_32x32x16_bf16 v[32:47], v[202:205], v[190:193], v[32:47]
	s_waitcnt lgkmcnt(6)
	v_mfma_f32_32x32x16_bf16 v[16:31], v[206:209], v[172:175], v[16:31]
	v_add_u32_e32 v150, s0, v157
	s_movk_i32 s2, 0x2000
	s_movk_i32 s0, 0x1fff
	v_cmp_gt_i32_e32 vcc, s2, v150
	s_movk_i32 s2, 0x7ff
	v_mfma_f32_32x32x16_bf16 v[0:15], v[206:209], v[190:193], v[0:15]
	s_waitcnt lgkmcnt(3)
	v_mfma_f32_32x32x16_bf16 v[112:127], v[134:137], v[130:133], v[112:127]
	v_mfma_f32_32x32x16_bf16 v[96:111], v[134:137], v[138:141], v[96:111]
	v_or_b32_e32 v136, s1, v176
	v_cmp_lt_i32_e64 s[0:1], s0, v150
	v_cmp_lt_i32_e64 s[2:3], s2, v136
	s_waitcnt lgkmcnt(2)
	v_mfma_f32_32x32x16_bf16 v[80:95], v[142:145], v[130:133], v[80:95]
	v_mfma_f32_32x32x16_bf16 v[64:79], v[142:145], v[138:141], v[64:79]
	s_waitcnt lgkmcnt(1)
	v_mfma_f32_32x32x16_bf16 v[48:63], v[146:149], v[130:133], v[48:63]
	v_mfma_f32_32x32x16_bf16 v[32:47], v[146:149], v[138:141], v[32:47]
	s_waitcnt lgkmcnt(0)
	v_mfma_f32_32x32x16_bf16 v[16:31], v[210:213], v[130:133], v[16:31]
	v_or_b32_e32 v130, v150, v183
	v_mfma_f32_32x32x16_bf16 v[0:15], v[210:213], v[138:141], v[0:15]
	s_and_saveexec_b64 s[24:25], s[2:3]
	s_xor_b64 s[2:3], exec, s[24:25]
	s_cbranch_execz .LBB0_461
	v_ashrrev_i32_e32 v134, 8, v150
	v_ashrrev_i32_e32 v135, 31, v134
	s_and_saveexec_b64 s[24:25], vcc
	s_xor_b64 s[24:25], exec, s[24:25]
	v_lshlrev_b64 v[140:141], 18, v[134:135]
	v_and_b32_e32 v128, 0x84, v130
	s_or_saveexec_b64 s[24:25], s[24:25]
	v_mov_b64_e32 v[138:139], 0x100
	s_xor_b64 exec, exec, s[24:25]
	v_add_u32_e32 v128, 0xffffe000, v150
	v_lshrrev_b32_e32 v128, 11, v128
	s_mov_b32 s26, 0x240000
	v_mad_u64_u32 v[140:141], s[26:27], v128, s26, v[166:167]
	v_and_b32_e32 v128, 0x784, v130
	v_add_u32_e32 v128, 0x100, v128
	v_mov_b64_e32 v[138:139], 0x900
	s_or_b64 exec, exec, s[24:25]
	v_add_u32_e32 v132, v136, v184
	v_or_b32_e32 v142, 1, v130
	v_or_b32_e32 v144, 2, v130
	v_or_b32_e32 v146, 3, v130
	v_lshl_add_u64 v[140:141], v[140:141], 1, s[6:7]
	v_mad_u64_u32 v[152:153], s[24:25], v138, v132, 0
	v_ashrrev_i32_e32 v131, 31, v130
	v_ashrrev_i32_e32 v143, 31, v142
	v_ashrrev_i32_e32 v145, 31, v144
	v_ashrrev_i32_e32 v147, 31, v146
	v_lshl_add_u64 v[152:153], v[152:153], 1, v[140:141]
	v_lshlrev_b64 v[136:137], 12, v[130:131]
	v_lshlrev_b64 v[142:143], 12, v[142:143]
	v_lshlrev_b64 v[144:145], 12, v[144:145]
	v_lshlrev_b64 v[146:147], 12, v[146:147]
	v_cvt_pk_bf16_f32 v148, v112, v113
	v_cvt_pk_bf16_f32 v149, v114, v115
	v_mov_b32_e32 v133, v129
	v_lshl_add_u64 v[152:153], v[128:129], 1, v[152:153]
	global_store_dwordx2 v[152:153], v[148:149], off
	v_lshl_add_u64 v[148:149], s[18:19], 0, v[136:137]
	v_lshlrev_b64 v[136:137], 2, v[132:133]
	v_lshl_add_u64 v[152:153], s[18:19], 0, v[142:143]
	v_lshl_add_u64 v[172:173], s[18:19], 0, v[144:145]
	v_lshl_add_u64 v[174:175], s[18:19], 0, v[146:147]
	v_lshl_add_u64 v[142:143], v[148:149], 0, v[136:137]
	v_lshl_add_u64 v[144:145], v[152:153], 0, v[136:137]
	v_lshl_add_u64 v[146:147], v[172:173], 0, v[136:137]
	v_lshl_add_u64 v[148:149], v[174:175], 0, v[136:137]
	s_and_saveexec_b64 s[24:25], vcc
	s_cbranch_execz .LBB0_338
	global_store_dword v[142:143], v112, off nt
	global_store_dword v[144:145], v113, off nt
	global_store_dword v[146:147], v114, off nt
	global_store_dword v[148:149], v115, off nt

.LBB0_1101:
	s_and_b32 s3, s0, 7
	v_lshl_add_u32 v0, s3, 8, v201
	v_ashrrev_i32_e32 v1, 31, v0
	v_lshlrev_b64 v[0:1], 11, v[0:1]
	s_and_b32 s3, s2, 0xffffff00
	v_lshl_add_u64 v[170:171], v[160:161], 0, v[0:1]
	v_add_u32_e32 v0, s3, v175
	s_and_b32 s3, s4, 7
	v_ashrrev_i32_e32 v1, 31, v0
	s_or_b32 s3, s3, s1
	v_lshlrev_b64 v[0:1], 11, v[0:1]
	s_lshl_b32 s3, s3, 8
	v_lshl_add_u64 v[172:173], v[168:169], 0, v[0:1]
	v_add_u32_e32 v0, s3, v175
	s_lshl_b32 s5, s4, 5
	v_ashrrev_i32_e32 v1, 31, v0
	s_and_b32 s5, s5, 0xffffff00
	v_add_u32_e32 v2, s5, v175
	v_lshlrev_b64 v[0:1], 11, v[0:1]
	s_waitcnt vmcnt(0) lgkmcnt(0)
	s_barrier
	v_ashrrev_i32_e32 v3, 31, v2
	v_lshl_add_u64 v[0:1], v[154:155], 0, v[0:1]
	v_readfirstlane_b32 s6, v180
	s_mov_b32 m0, s6
	s_nop 0
	global_load_lds_dwordx4 v[0:1], off
	v_lshlrev_b64 v[2:3], 11, v[2:3]
	v_lshl_add_u64 v[4:5], v[0:1], 0, s[34:35]
	s_add_i32 s7, s6, 0x2000
	s_mov_b32 m0, s7
	s_nop 0
	global_load_lds_dwordx4 v[4:5], off
	v_lshl_add_u64 v[2:3], v[156:157], 0, v[2:3]
	s_add_i32 s7, s6, 0x4000
	s_mov_b32 m0, s7
	s_nop 0
	global_load_lds_dwordx4 v[2:3], off
	v_lshl_add_u64 v[4:5], v[2:3], 0, s[34:35]
	s_add_i32 s7, s6, 0x6000
	s_mov_b32 m0, s7
	s_nop 0
	global_load_lds_dwordx4 v[4:5], off
	s_add_i32 s7, s6, 0x8000
	v_lshl_add_u64 v[4:5], v[0:1], 0, 64
	s_mov_b32 m0, s7
	s_nop 0
	global_load_lds_dwordx4 v[4:5], off
	s_mov_b64 s[10:11], 0x40040
	v_lshl_add_u64 v[4:5], v[0:1], 0, s[10:11]
	s_add_i32 s7, s6, 0xa000
	s_mov_b32 m0, s7
	s_nop 0
	global_load_lds_dwordx4 v[4:5], off
	v_lshl_add_u64 v[4:5], v[2:3], 0, 64
	s_add_i32 s7, s6, 0xc000
	s_mov_b32 m0, s7
	s_nop 0
	global_load_lds_dwordx4 v[4:5], off
	v_lshl_add_u64 v[4:5], v[2:3], 0, s[10:11]
	s_add_i32 s7, s6, 0xe000
	s_mov_b32 m0, s7
	s_nop 0
	global_load_lds_dwordx4 v[4:5], off
	s_mov_b64 s[10:11], 0x80
	s_add_i32 s7, s6, 0x10000
	v_lshl_add_u64 v[4:5], v[0:1], 0, s[10:11]
	s_mov_b32 m0, s7
	s_nop 0
	global_load_lds_dwordx4 v[4:5], off
	s_mov_b64 s[12:13], 0x40080
	v_lshl_add_u64 v[0:1], v[0:1], 0, s[12:13]
	s_add_i32 s7, s6, 0x12000
	s_mov_b32 m0, s7
	s_nop 0
	global_load_lds_dwordx4 v[0:1], off
	v_lshl_add_u64 v[0:1], v[2:3], 0, s[10:11]
	s_add_i32 s7, s6, 0x14000
	s_mov_b32 m0, s7
	s_nop 0
	global_load_lds_dwordx4 v[0:1], off
	v_lshl_add_u64 v[0:1], v[2:3], 0, s[12:13]
	s_add_i32 s6, s6, 0x16000
	s_mov_b32 m0, s6
	s_nop 0
	global_load_lds_dwordx4 v[0:1], off
	v_mov_b32_e32 v130, 0
	v_mov_b32_e32 v134, 0
	v_mov_b32_e32 v0, 0
	s_mov_b32 s6, 0x18000
	v_mov_b32_e32 v1, v0
	v_mov_b32_e32 v2, v0
	v_mov_b32_e32 v3, v0
	v_mov_b32_e32 v4, v0
	v_mov_b32_e32 v5, v0
	v_mov_b32_e32 v6, v0
	v_mov_b32_e32 v7, v0
	v_mov_b32_e32 v8, v0
	v_mov_b32_e32 v9, v0
	v_mov_b32_e32 v10, v0
	v_mov_b32_e32 v11, v0
	v_mov_b32_e32 v12, v0
	v_mov_b32_e32 v13, v0
	v_mov_b32_e32 v14, v0
	v_mov_b32_e32 v15, v0
	v_mov_b32_e32 v16, v0
	v_mov_b32_e32 v17, v0
	v_mov_b32_e32 v18, v0
	v_mov_b32_e32 v19, v0
	v_mov_b32_e32 v20, v0
	v_mov_b32_e32 v21, v0
	v_mov_b32_e32 v22, v0
	v_mov_b32_e32 v23, v0
	v_mov_b32_e32 v24, v0
	v_mov_b32_e32 v25, v0
	v_mov_b32_e32 v26, v0
	v_mov_b32_e32 v27, v0
	v_mov_b32_e32 v28, v0
	v_mov_b32_e32 v29, v0
	v_mov_b32_e32 v30, v0
	v_mov_b32_e32 v31, v0
	v_mov_b32_e32 v32, v0
	v_mov_b32_e32 v33, v0
	v_mov_b32_e32 v34, v0
	v_mov_b32_e32 v35, v0
	v_mov_b32_e32 v36, v0
	v_mov_b32_e32 v37, v0
	v_mov_b32_e32 v38, v0
	v_mov_b32_e32 v39, v0
	v_mov_b32_e32 v40, v0
	v_mov_b32_e32 v41, v0
	v_mov_b32_e32 v42, v0
	v_mov_b32_e32 v43, v0
	v_mov_b32_e32 v44, v0
	v_mov_b32_e32 v45, v0
	v_mov_b32_e32 v46, v0
	v_mov_b32_e32 v47, v0
	v_mov_b32_e32 v48, v0
	v_mov_b32_e32 v49, v0
	v_mov_b32_e32 v50, v0
	v_mov_b32_e32 v51, v0
	v_mov_b32_e32 v52, v0
	v_mov_b32_e32 v53, v0
	v_mov_b32_e32 v54, v0
	v_mov_b32_e32 v55, v0
	v_mov_b32_e32 v56, v0
	v_mov_b32_e32 v57, v0
	v_mov_b32_e32 v58, v0
	v_mov_b32_e32 v59, v0
	v_mov_b32_e32 v60, v0
	v_mov_b32_e32 v61, v0
	v_mov_b32_e32 v62, v0
	v_mov_b32_e32 v63, v0
	v_mov_b32_e32 v64, v0
	v_mov_b32_e32 v65, v0
	v_mov_b32_e32 v66, v0
	v_mov_b32_e32 v67, v0
	v_mov_b32_e32 v68, v0
	v_mov_b32_e32 v69, v0
	v_mov_b32_e32 v70, v0
	v_mov_b32_e32 v71, v0
	v_mov_b32_e32 v72, v0
	v_mov_b32_e32 v73, v0
	v_mov_b32_e32 v74, v0
	v_mov_b32_e32 v75, v0
	v_mov_b32_e32 v76, v0
	v_mov_b32_e32 v77, v0
	v_mov_b32_e32 v78, v0
	v_mov_b32_e32 v79, v0
	v_mov_b32_e32 v80, v0
	v_mov_b32_e32 v81, v0
	v_mov_b32_e32 v82, v0
	v_mov_b32_e32 v83, v0
	v_mov_b32_e32 v84, v0
	v_mov_b32_e32 v85, v0
	v_mov_b32_e32 v86, v0
	v_mov_b32_e32 v87, v0
	v_mov_b32_e32 v88, v0
	v_mov_b32_e32 v89, v0
	v_mov_b32_e32 v90, v0
	v_mov_b32_e32 v91, v0
	v_mov_b32_e32 v92, v0
	v_mov_b32_e32 v93, v0
	v_mov_b32_e32 v94, v0
	v_mov_b32_e32 v95, v0
	v_mov_b32_e32 v96, v0
	v_mov_b32_e32 v97, v0
	v_mov_b32_e32 v98, v0
	v_mov_b32_e32 v99, v0
	v_mov_b32_e32 v100, v0
	v_mov_b32_e32 v101, v0
	v_mov_b32_e32 v102, v0
	v_mov_b32_e32 v103, v0
	v_mov_b32_e32 v104, v0
	v_mov_b32_e32 v105, v0
	v_mov_b32_e32 v106, v0
	v_mov_b32_e32 v107, v0
	v_mov_b32_e32 v108, v0
	v_mov_b32_e32 v109, v0
	v_mov_b32_e32 v110, v0
	v_mov_b32_e32 v111, v0
	v_mov_b32_e32 v112, v0
	v_mov_b32_e32 v113, v0
	v_mov_b32_e32 v114, v0
	v_mov_b32_e32 v115, v0
	v_mov_b32_e32 v116, v0
	v_mov_b32_e32 v117, v0
	v_mov_b32_e32 v118, v0
	v_mov_b32_e32 v119, v0
	v_mov_b32_e32 v120, v0
	v_mov_b32_e32 v121, v0
	v_mov_b32_e32 v122, v0
	v_mov_b32_e32 v123, v0
	v_mov_b32_e32 v124, v0
	v_mov_b32_e32 v125, v0
	v_mov_b32_e32 v126, v0
	v_mov_b32_e32 v127, v0
	v_mov_b32_e32 v135, v134
	v_mov_b32_e32 v136, v134
	v_mov_b32_e32 v137, v134
	v_mov_b32_e32 v138, v134
	v_mov_b32_e32 v139, v134
	v_mov_b32_e32 v140, v134
	v_mov_b32_e32 v141, v134
	v_mov_b32_e32 v146, v134
	v_mov_b32_e32 v147, v134
	v_mov_b32_e32 v148, v134
	v_mov_b32_e32 v149, v134
	v_mov_b32_e32 v150, v134
	v_mov_b32_e32 v151, v134
	v_mov_b32_e32 v152, v134
	v_mov_b32_e32 v153, v134
	v_mov_b32_e32 v131, v130
	v_mov_b32_e32 v132, v130
	v_mov_b32_e32 v133, v130
	v_mov_b32_e32 v142, v130
	v_mov_b32_e32 v143, v130
	v_mov_b32_e32 v144, v130
	v_mov_b32_e32 v145, v130
	v_readfirstlane_b32 s100, v163
	s_cmp_ge_u32 s100, 0x100
	s_cbranch_scc1 .Lky_3
.LBB0_1102:
	s_and_b32 s7, s6, 0x18000
	v_add_u32_e32 v222, s7, v180
	s_add_i32 s7, s6, 0xfffe8000
	s_and_b32 s7, s7, 0x18000
	v_or_b32_e32 v223, s7, v179
	v_add_u32_e32 v233, s7, v176
	s_waitcnt vmcnt(8) lgkmcnt(0)
	s_barrier
	v_mfma_f32_32x32x16_bf16 v[112:127], v[150:153], v[142:145], v[112:127]
	v_mfma_f32_32x32x16_bf16 v[96:111], v[150:153], v[130:133], v[96:111]
	v_add_u32_e32 v206, v223, v177
	v_add_u32_e32 v234, v233, v177
	ds_read_b128 v[202:205], v206 offset:16384
	ds_read_b128 v[206:209], v206 offset:18432
	ds_read_b128 v[210:213], v234
	ds_read_b128 v[214:217], v234 offset:2048
	ds_read_b128 v[224:227], v234 offset:4096
	ds_read_b128 v[234:237], v234 offset:6144
	v_mfma_f32_32x32x16_bf16 v[80:95], v[146:149], v[142:145], v[80:95]
	v_mfma_f32_32x32x16_bf16 v[64:79], v[146:149], v[130:133], v[64:79]
	v_readfirstlane_b32 s7, v222
	s_mov_b32 m0, s7
	s_nop 0
	global_load_lds_dwordx4 v[170:171], off
	v_mfma_f32_32x32x16_bf16 v[48:63], v[138:141], v[142:145], v[48:63]
	v_mfma_f32_32x32x16_bf16 v[32:47], v[138:141], v[130:133], v[32:47]
	s_add_i32 s10, s7, 0x2000
	v_lshl_add_u64 v[150:151], v[170:171], 0, s[34:35]
	s_mov_b32 m0, s10
	s_nop 0
	global_load_lds_dwordx4 v[150:151], off
	v_mfma_f32_32x32x16_bf16 v[16:31], v[134:137], v[142:145], v[16:31]
	v_mfma_f32_32x32x16_bf16 v[0:15], v[134:137], v[130:133], v[0:15]
	v_add_u32_e32 v130, v223, v178
	v_add_u32_e32 v134, v233, v178
	ds_read_b128 v[142:145], v130 offset:16384
	ds_read_b128 v[130:133], v130 offset:18432
	ds_read_b128 v[150:153], v134
	ds_read_b128 v[146:149], v134 offset:2048
	ds_read_b128 v[138:141], v134 offset:4096
	ds_read_b128 v[134:137], v134 offset:6144
	s_waitcnt lgkmcnt(9)
	v_mfma_f32_32x32x16_bf16 v[112:127], v[210:213], v[202:205], v[112:127]
	s_add_i32 s10, s7, 0x6000
	s_addk_i32 s7, 0x4000
	v_mfma_f32_32x32x16_bf16 v[96:111], v[210:213], v[206:209], v[96:111]
	s_mov_b32 m0, s7
	s_nop 0
	global_load_lds_dwordx4 v[172:173], off
	v_lshl_add_u64 v[222:223], v[172:173], 0, s[34:35]
	s_waitcnt lgkmcnt(8)
	v_mfma_f32_32x32x16_bf16 v[80:95], v[214:217], v[202:205], v[80:95]
	v_mfma_f32_32x32x16_bf16 v[64:79], v[214:217], v[206:209], v[64:79]
	s_waitcnt lgkmcnt(7)
	v_mfma_f32_32x32x16_bf16 v[48:63], v[224:227], v[202:205], v[48:63]
	v_mfma_f32_32x32x16_bf16 v[32:47], v[224:227], v[206:209], v[32:47]
	s_mov_b32 m0, s10
	s_nop 0
	global_load_lds_dwordx4 v[222:223], off
	s_waitcnt lgkmcnt(6)
	v_mfma_f32_32x32x16_bf16 v[16:31], v[234:237], v[202:205], v[16:31]
	s_add_i32 s6, s6, 0x8000
	v_lshl_add_u64 v[170:171], v[170:171], 0, 64
	v_lshl_add_u64 v[172:173], v[172:173], 0, 64
	s_cmp_eq_u32 s6, 0x100000
	v_mfma_f32_32x32x16_bf16 v[0:15], v[234:237], v[206:209], v[0:15]
	s_cbranch_scc0 .LBB0_1102
	s_branch .Lktail_3
.Lky_3:
	s_and_b32 s7, s6, 0x18000
	v_add_u32_e32 v222, s7, v180
	s_add_i32 s7, s6, 0xfffe8000
	s_and_b32 s7, s7, 0x18000
	v_or_b32_e32 v223, s7, v179
	v_add_u32_e32 v233, s7, v176
	s_waitcnt vmcnt(8) lgkmcnt(0)
	s_barrier
	v_add_u32_e32 v206, v223, v177
	v_add_u32_e32 v234, v233, v177
	ds_read_b128 v[202:205], v206 offset:16384
	ds_read_b128 v[206:209], v206 offset:18432
	ds_read_b128 v[210:213], v234
	ds_read_b128 v[214:217], v234 offset:2048
	ds_read_b128 v[224:227], v234 offset:4096
	ds_read_b128 v[234:237], v234 offset:6144
	v_mfma_f32_32x32x16_bf16 v[112:127], v[150:153], v[142:145], v[112:127]
	v_mfma_f32_32x32x16_bf16 v[96:111], v[150:153], v[130:133], v[96:111]
	v_readfirstlane_b32 s7, v222
	s_mov_b32 m0, s7
	s_nop 0
	global_load_lds_dwordx4 v[170:171], off
	v_mfma_f32_32x32x16_bf16 v[80:95], v[146:149], v[142:145], v[80:95]
	v_mfma_f32_32x32x16_bf16 v[64:79], v[146:149], v[130:133], v[64:79]
	v_mfma_f32_32x32x16_bf16 v[48:63], v[138:141], v[142:145], v[48:63]
	v_mfma_f32_32x32x16_bf16 v[32:47], v[138:141], v[130:133], v[32:47]
	s_add_i32 s10, s7, 0x2000
	v_lshl_add_u64 v[150:151], v[170:171], 0, s[34:35]
	s_mov_b32 m0, s10
	s_nop 0
	global_load_lds_dwordx4 v[150:151], off
	v_mfma_f32_32x32x16_bf16 v[16:31], v[134:137], v[142:145], v[16:31]
	v_mfma_f32_32x32x16_bf16 v[0:15], v[134:137], v[130:133], v[0:15]
	v_add_u32_e32 v130, v223, v178
	v_add_u32_e32 v134, v233, v178
	ds_read_b128 v[142:145], v130 offset:16384
	ds_read_b128 v[130:133], v130 offset:18432
	ds_read_b128 v[150:153], v134
	ds_read_b128 v[146:149], v134 offset:2048
	ds_read_b128 v[138:141], v134 offset:4096
	ds_read_b128 v[134:137], v134 offset:6144
	s_waitcnt lgkmcnt(9)
	v_mfma_f32_32x32x16_bf16 v[112:127], v[210:213], v[202:205], v[112:127]
	s_add_i32 s10, s7, 0x6000
	s_addk_i32 s7, 0x4000
	v_mfma_f32_32x32x16_bf16 v[96:111], v[210:213], v[206:209], v[96:111]
	s_mov_b32 m0, s7
	s_nop 0
	global_load_lds_dwordx4 v[172:173], off
	v_lshl_add_u64 v[222:223], v[172:173], 0, s[34:35]
	s_waitcnt lgkmcnt(8)
	v_mfma_f32_32x32x16_bf16 v[80:95], v[214:217], v[202:205], v[80:95]
	v_mfma_f32_32x32x16_bf16 v[64:79], v[214:217], v[206:209], v[64:79]
	s_waitcnt lgkmcnt(7)
	v_mfma_f32_32x32x16_bf16 v[48:63], v[224:227], v[202:205], v[48:63]
	v_mfma_f32_32x32x16_bf16 v[32:47], v[224:227], v[206:209], v[32:47]
	s_mov_b32 m0, s10
	s_nop 0
	global_load_lds_dwordx4 v[222:223], off
	s_waitcnt lgkmcnt(6)
	v_mfma_f32_32x32x16_bf16 v[16:31], v[234:237], v[202:205], v[16:31]
	s_add_i32 s6, s6, 0x8000
	v_lshl_add_u64 v[170:171], v[170:171], 0, 64
	v_lshl_add_u64 v[172:173], v[172:173], 0, 64
	s_cmp_eq_u32 s6, 0x100000
	v_mfma_f32_32x32x16_bf16 v[0:15], v[234:237], v[206:209], v[0:15]
	s_cbranch_scc0 .Lky_3
.Lktail_3:
	s_waitcnt vmcnt(8) lgkmcnt(0)
	s_barrier
	v_add_u32_e32 v202, v179, v177
	v_add_u32_e32 v222, v176, v177
	ds_read_b128 v[170:173], v202 offset:49152
	ds_read_b128 v[202:205], v202 offset:51200
	ds_read_b128 v[206:209], v222 offset:32768
	ds_read_b128 v[210:213], v222 offset:34816
	ds_read_b128 v[214:217], v222 offset:36864
	ds_read_b128 v[224:227], v222 offset:38912
	s_waitcnt lgkmcnt(9)
	v_mfma_f32_32x32x16_bf16 v[112:127], v[150:153], v[142:145], v[112:127]
	v_mfma_f32_32x32x16_bf16 v[96:111], v[150:153], v[130:133], v[96:111]
	s_waitcnt lgkmcnt(8)
	v_mfma_f32_32x32x16_bf16 v[80:95], v[146:149], v[142:145], v[80:95]
	v_mfma_f32_32x32x16_bf16 v[64:79], v[146:149], v[130:133], v[64:79]
	s_waitcnt lgkmcnt(7)
	v_mfma_f32_32x32x16_bf16 v[48:63], v[138:141], v[142:145], v[48:63]
	v_mfma_f32_32x32x16_bf16 v[32:47], v[138:141], v[130:133], v[32:47]
	s_waitcnt lgkmcnt(6)
	v_mfma_f32_32x32x16_bf16 v[16:31], v[134:137], v[142:145], v[16:31]
	v_mfma_f32_32x32x16_bf16 v[0:15], v[134:137], v[130:133], v[0:15]
	v_add_u32_e32 v134, v179, v178
	v_add_u32_e32 v150, v176, v178
	ds_read_b128 v[130:133], v134 offset:49152
	ds_read_b128 v[134:137], v134 offset:51200
	ds_read_b128 v[138:141], v150 offset:32768
	ds_read_b128 v[142:145], v150 offset:34816
	ds_read_b128 v[146:149], v150 offset:36864
	ds_read_b128 v[150:153], v150 offset:38912
	s_waitcnt lgkmcnt(9)
	v_mfma_f32_32x32x16_bf16 v[112:127], v[206:209], v[170:173], v[112:127]
	v_mfma_f32_32x32x16_bf16 v[96:111], v[206:209], v[202:205], v[96:111]
	s_waitcnt lgkmcnt(8)
	v_mfma_f32_32x32x16_bf16 v[80:95], v[210:213], v[170:173], v[80:95]
	v_mfma_f32_32x32x16_bf16 v[64:79], v[210:213], v[202:205], v[64:79]
	s_waitcnt lgkmcnt(7)
	v_mfma_f32_32x32x16_bf16 v[48:63], v[214:217], v[170:173], v[48:63]
	v_mfma_f32_32x32x16_bf16 v[32:47], v[214:217], v[202:205], v[32:47]
	s_waitcnt lgkmcnt(6)
	v_mfma_f32_32x32x16_bf16 v[0:15], v[224:227], v[202:205], v[0:15]
	s_waitcnt vmcnt(4) lgkmcnt(0)
	s_barrier
	v_add_u32_e32 v202, v199, v177
	v_add_u32_e32 v222, v200, v177
	v_mfma_f32_32x32x16_bf16 v[16:31], v[224:227], v[170:173], v[16:31]
	ds_read_b128 v[170:173], v202 offset:16384
	ds_read_b128 v[202:205], v202 offset:18432
	ds_read_b128 v[206:209], v222
	ds_read_b128 v[210:213], v222 offset:2048
	ds_read_b128 v[214:217], v222 offset:4096
	ds_read_b128 v[224:227], v222 offset:6144
	s_waitcnt lgkmcnt(9)
	v_mfma_f32_32x32x16_bf16 v[112:127], v[138:141], v[130:133], v[112:127]
	v_mfma_f32_32x32x16_bf16 v[96:111], v[138:141], v[134:137], v[96:111]
	s_waitcnt lgkmcnt(8)
	v_mfma_f32_32x32x16_bf16 v[80:95], v[142:145], v[130:133], v[80:95]
	v_mfma_f32_32x32x16_bf16 v[64:79], v[142:145], v[134:137], v[64:79]
	s_waitcnt lgkmcnt(7)
	v_mfma_f32_32x32x16_bf16 v[48:63], v[146:149], v[130:133], v[48:63]
	v_mfma_f32_32x32x16_bf16 v[32:47], v[146:149], v[134:137], v[32:47]
	s_waitcnt lgkmcnt(6)
	v_mfma_f32_32x32x16_bf16 v[16:31], v[150:153], v[130:133], v[16:31]
	v_mfma_f32_32x32x16_bf16 v[0:15], v[150:153], v[134:137], v[0:15]
	v_add_u32_e32 v134, v199, v178
	v_add_u32_e32 v150, v200, v178
	ds_read_b128 v[130:133], v134 offset:16384
	ds_read_b128 v[134:137], v134 offset:18432
	ds_read_b128 v[138:141], v150
	ds_read_b128 v[142:145], v150 offset:2048
	ds_read_b128 v[146:149], v150 offset:4096
	ds_read_b128 v[150:153], v150 offset:6144
	s_waitcnt lgkmcnt(9)
	v_mfma_f32_32x32x16_bf16 v[112:127], v[206:209], v[170:173], v[112:127]
	v_mfma_f32_32x32x16_bf16 v[96:111], v[206:209], v[202:205], v[96:111]
	s_waitcnt lgkmcnt(8)
	v_mfma_f32_32x32x16_bf16 v[80:95], v[210:213], v[170:173], v[80:95]
	v_mfma_f32_32x32x16_bf16 v[64:79], v[210:213], v[202:205], v[64:79]
	s_waitcnt lgkmcnt(7)
	v_mfma_f32_32x32x16_bf16 v[48:63], v[214:217], v[170:173], v[48:63]
	v_mfma_f32_32x32x16_bf16 v[32:47], v[214:217], v[202:205], v[32:47]
	s_waitcnt lgkmcnt(6)
	v_mfma_f32_32x32x16_bf16 v[0:15], v[224:227], v[202:205], v[0:15]
	s_waitcnt vmcnt(0) lgkmcnt(0)
	s_barrier
	v_add_u32_e32 v202, v197, v177
	v_add_u32_e32 v222, v198, v177
	v_mfma_f32_32x32x16_bf16 v[16:31], v[224:227], v[170:173], v[16:31]
	ds_read_b128 v[170:173], v202 offset:16384
	ds_read_b128 v[202:205], v202 offset:18432
	ds_read_b128 v[206:209], v222
	ds_read_b128 v[210:213], v222 offset:2048
	ds_read_b128 v[214:217], v222 offset:4096
	ds_read_b128 v[224:227], v222 offset:6144
	s_waitcnt lgkmcnt(9)
	v_mfma_f32_32x32x16_bf16 v[112:127], v[138:141], v[130:133], v[112:127]
	v_mfma_f32_32x32x16_bf16 v[96:111], v[138:141], v[134:137], v[96:111]
	s_waitcnt lgkmcnt(8)
	v_mfma_f32_32x32x16_bf16 v[80:95], v[142:145], v[130:133], v[80:95]
	v_mfma_f32_32x32x16_bf16 v[64:79], v[142:145], v[134:137], v[64:79]
	s_waitcnt lgkmcnt(7)
	v_mfma_f32_32x32x16_bf16 v[48:63], v[146:149], v[130:133], v[48:63]
	v_mfma_f32_32x32x16_bf16 v[32:47], v[146:149], v[134:137], v[32:47]
	s_waitcnt lgkmcnt(6)
	v_mfma_f32_32x32x16_bf16 v[16:31], v[150:153], v[130:133], v[16:31]
	v_mfma_f32_32x32x16_bf16 v[0:15], v[150:153], v[134:137], v[0:15]
	v_add_u32_e32 v134, v197, v178
	v_add_u32_e32 v150, v198, v178
	ds_read_b128 v[130:133], v134 offset:16384
	ds_read_b128 v[134:137], v134 offset:18432
	ds_read_b128 v[138:141], v150
	ds_read_b128 v[142:145], v150 offset:2048
	ds_read_b128 v[146:149], v150 offset:4096
	ds_read_b128 v[150:153], v150 offset:6144
	s_waitcnt lgkmcnt(9)
	v_mfma_f32_32x32x16_bf16 v[112:127], v[206:209], v[170:173], v[112:127]
	v_mfma_f32_32x32x16_bf16 v[96:111], v[206:209], v[202:205], v[96:111]
	s_waitcnt lgkmcnt(8)
	v_mfma_f32_32x32x16_bf16 v[80:95], v[210:213], v[170:173], v[80:95]
	v_mfma_f32_32x32x16_bf16 v[64:79], v[210:213], v[202:205], v[64:79]
	s_waitcnt lgkmcnt(7)
	v_mfma_f32_32x32x16_bf16 v[48:63], v[214:217], v[170:173], v[48:63]
	v_mfma_f32_32x32x16_bf16 v[32:47], v[214:217], v[202:205], v[32:47]
	s_waitcnt lgkmcnt(6)
	v_mfma_f32_32x32x16_bf16 v[16:31], v[224:227], v[170:173], v[16:31]
	v_mfma_f32_32x32x16_bf16 v[0:15], v[224:227], v[202:205], v[0:15]
	s_waitcnt lgkmcnt(3)
	v_mfma_f32_32x32x16_bf16 v[112:127], v[138:141], v[130:133], v[112:127]
	v_mfma_f32_32x32x16_bf16 v[96:111], v[138:141], v[134:137], v[96:111]
	s_nop 10
	v_cvt_pk_bf16_f32 v112, v112, s0
	s_waitcnt lgkmcnt(2)
	v_mfma_f32_32x32x16_bf16 v[80:95], v[142:145], v[130:133], v[80:95]
	v_cvt_pk_bf16_f32 v96, v96, s0
	v_cvt_pk_bf16_f32 v98, v98, s0
	s_waitcnt lgkmcnt(1)
	v_mfma_f32_32x32x16_bf16 v[48:63], v[146:149], v[130:133], v[48:63]
	s_nop 7
	v_cvt_pk_bf16_f32 v80, v80, s0
	s_waitcnt lgkmcnt(0)
	v_mfma_f32_32x32x16_bf16 v[16:31], v[150:153], v[130:133], v[16:31]
	v_add_u32_e32 v132, s3, v128
	v_or_b32_e32 v130, s5, v174
	v_ashrrev_i32_e32 v131, 31, v130
	v_lshl_add_u64 v[130:131], v[130:131], 1, v[158:159]
	v_cvt_pk_bf16_f32 v48, v48, s0
	v_readlane_b32 s3, v252, 7
	s_add_i32 s4, s4, s3
	v_mfma_f32_32x32x16_bf16 v[64:79], v[142:145], v[134:137], v[64:79]
	s_nop 3
	v_cvt_pk_bf16_f32 v16, v16, s0
	v_mfma_f32_32x32x16_bf16 v[32:47], v[146:149], v[134:137], v[32:47]
	s_nop 5
	v_cvt_pk_bf16_f32 v64, v64, s0
	v_cvt_pk_bf16_f32 v66, v66, s0
	v_mfma_f32_32x32x16_bf16 v[0:15], v[150:153], v[134:137], v[0:15]
	v_or_b32_e32 v134, v132, v181
	v_ashrrev_i32_e32 v135, 31, v134
	v_lshlrev_b64 v[134:135], 11, v[134:135]
	v_lshl_add_u64 v[134:135], v[130:131], 0, v[134:135]
	global_store_short v[134:135], v112, off
	global_store_short v[134:135], v96, off offset:64
	v_or_b32_e32 v134, v132, v182
	v_ashrrev_i32_e32 v135, 31, v134
	v_lshlrev_b64 v[134:135], 11, v[134:135]
	v_lshl_add_u64 v[134:135], v[130:131], 0, v[134:135]
	v_cvt_pk_bf16_f32 v96, v113, s0
	global_store_short v[134:135], v96, off
	v_cvt_pk_bf16_f32 v96, v97, s0
	global_store_short v[134:135], v96, off offset:64
	v_or_b32_e32 v96, v132, v183
	v_ashrrev_i32_e32 v97, 31, v96
	v_lshlrev_b64 v[96:97], 11, v[96:97]
	v_lshl_add_u64 v[96:97], v[130:131], 0, v[96:97]
	v_cvt_pk_bf16_f32 v112, v114, s0
	global_store_short v[96:97], v112, off
	global_store_short v[96:97], v98, off offset:64
	v_or_b32_e32 v96, v132, v184
	v_ashrrev_i32_e32 v97, 31, v96
	v_lshlrev_b64 v[96:97], 11, v[96:97]
	v_lshl_add_u64 v[96:97], v[130:131], 0, v[96:97]
	v_cvt_pk_bf16_f32 v98, v115, s0
	global_store_short v[96:97], v98, off
	v_cvt_pk_bf16_f32 v98, v99, s0
	global_store_short v[96:97], v98, off offset:64
	v_or_b32_e32 v96, v132, v185
	v_ashrrev_i32_e32 v97, 31, v96
	v_lshlrev_b64 v[96:97], 11, v[96:97]
	v_lshl_add_u64 v[96:97], v[130:131], 0, v[96:97]
	v_cvt_pk_bf16_f32 v98, v116, s0
	global_store_short v[96:97], v98, off
	v_cvt_pk_bf16_f32 v98, v100, s0
	global_store_short v[96:97], v98, off offset:64
	v_or_b32_e32 v96, v132, v186
	v_ashrrev_i32_e32 v97, 31, v96
	v_lshlrev_b64 v[96:97], 11, v[96:97]
	v_lshl_add_u64 v[96:97], v[130:131], 0, v[96:97]
	v_cvt_pk_bf16_f32 v98, v117, s0
	global_store_short v[96:97], v98, off
	v_cvt_pk_bf16_f32 v98, v101, s0
	global_store_short v[96:97], v98, off offset:64
	v_or_b32_e32 v96, v132, v187
	v_ashrrev_i32_e32 v97, 31, v96
	v_lshlrev_b64 v[96:97], 11, v[96:97]
	v_lshl_add_u64 v[96:97], v[130:131], 0, v[96:97]
	v_cvt_pk_bf16_f32 v98, v118, s0
	global_store_short v[96:97], v98, off
	v_cvt_pk_bf16_f32 v98, v102, s0
	global_store_short v[96:97], v98, off offset:64
	v_or_b32_e32 v96, v132, v188
	v_ashrrev_i32_e32 v97, 31, v96
	v_lshlrev_b64 v[96:97], 11, v[96:97]
	v_lshl_add_u64 v[96:97], v[130:131], 0, v[96:97]
	v_cvt_pk_bf16_f32 v98, v119, s0
	global_store_short v[96:97], v98, off
	v_cvt_pk_bf16_f32 v98, v103, s0
	global_store_short v[96:97], v98, off offset:64
	v_or_b32_e32 v96, v132, v189
	v_ashrrev_i32_e32 v97, 31, v96
	v_lshlrev_b64 v[96:97], 11, v[96:97]
	v_lshl_add_u64 v[96:97], v[130:131], 0, v[96:97]
	v_cvt_pk_bf16_f32 v98, v120, s0
	global_store_short v[96:97], v98, off
	v_cvt_pk_bf16_f32 v98, v104, s0
	global_store_short v[96:97], v98, off offset:64
	v_or_b32_e32 v96, v132, v190
	v_ashrrev_i32_e32 v97, 31, v96
	v_lshlrev_b64 v[96:97], 11, v[96:97]
	v_lshl_add_u64 v[96:97], v[130:131], 0, v[96:97]
	v_cvt_pk_bf16_f32 v98, v121, s0
	global_store_short v[96:97], v98, off
	v_cvt_pk_bf16_f32 v98, v105, s0
	global_store_short v[96:97], v98, off offset:64
	v_or_b32_e32 v96, v132, v191
	v_ashrrev_i32_e32 v97, 31, v96
	v_lshlrev_b64 v[96:97], 11, v[96:97]
	v_lshl_add_u64 v[96:97], v[130:131], 0, v[96:97]
	v_cvt_pk_bf16_f32 v98, v122, s0
	global_store_short v[96:97], v98, off
	v_cvt_pk_bf16_f32 v98, v106, s0
	global_store_short v[96:97], v98, off offset:64
	v_or_b32_e32 v96, v132, v192
	v_ashrrev_i32_e32 v97, 31, v96
	v_lshlrev_b64 v[96:97], 11, v[96:97]
	v_lshl_add_u64 v[96:97], v[130:131], 0, v[96:97]
	v_cvt_pk_bf16_f32 v98, v123, s0
	global_store_short v[96:97], v98, off
	v_cvt_pk_bf16_f32 v98, v107, s0
	global_store_short v[96:97], v98, off offset:64
	v_or_b32_e32 v96, v132, v193
	v_ashrrev_i32_e32 v97, 31, v96
	v_lshlrev_b64 v[96:97], 11, v[96:97]
	v_lshl_add_u64 v[96:97], v[130:131], 0, v[96:97]
	v_cvt_pk_bf16_f32 v98, v124, s0
	global_store_short v[96:97], v98, off
	v_cvt_pk_bf16_f32 v98, v108, s0
	global_store_short v[96:97], v98, off offset:64
	v_or_b32_e32 v96, v132, v194
	v_ashrrev_i32_e32 v97, 31, v96
	v_lshlrev_b64 v[96:97], 11, v[96:97]
	v_lshl_add_u64 v[96:97], v[130:131], 0, v[96:97]
	v_cvt_pk_bf16_f32 v98, v125, s0
	global_store_short v[96:97], v98, off
	v_cvt_pk_bf16_f32 v98, v109, s0
	global_store_short v[96:97], v98, off offset:64
	v_or_b32_e32 v96, v132, v195
	v_ashrrev_i32_e32 v97, 31, v96
	v_lshlrev_b64 v[96:97], 11, v[96:97]
	v_lshl_add_u64 v[96:97], v[130:131], 0, v[96:97]
	v_cvt_pk_bf16_f32 v98, v126, s0
	global_store_short v[96:97], v98, off
	v_cvt_pk_bf16_f32 v98, v110, s0
	global_store_short v[96:97], v98, off offset:64
	v_or_b32_e32 v96, v132, v196
	v_ashrrev_i32_e32 v97, 31, v96
	v_lshlrev_b64 v[96:97], 11, v[96:97]
	v_lshl_add_u64 v[96:97], v[130:131], 0, v[96:97]
	v_cvt_pk_bf16_f32 v98, v127, s0
	global_store_short v[96:97], v98, off
	v_cvt_pk_bf16_f32 v98, v111, s0
	global_store_short v[96:97], v98, off offset:64
	v_or_b32_e32 v98, 32, v132
	v_or_b32_e32 v96, v98, v181
	v_ashrrev_i32_e32 v97, 31, v96
	v_lshlrev_b64 v[96:97], 11, v[96:97]
	v_lshl_add_u64 v[96:97], v[130:131], 0, v[96:97]
	global_store_short v[96:97], v80, off
	global_store_short v[96:97], v64, off offset:64
	v_or_b32_e32 v96, v98, v182
	v_ashrrev_i32_e32 v97, 31, v96
	v_lshlrev_b64 v[96:97], 11, v[96:97]
	v_lshl_add_u64 v[96:97], v[130:131], 0, v[96:97]
	v_cvt_pk_bf16_f32 v64, v81, s0
	global_store_short v[96:97], v64, off
	v_cvt_pk_bf16_f32 v64, v65, s0
	global_store_short v[96:97], v64, off offset:64
	v_or_b32_e32 v64, v98, v183
	v_ashrrev_i32_e32 v65, 31, v64
	v_lshlrev_b64 v[64:65], 11, v[64:65]
	v_lshl_add_u64 v[64:65], v[130:131], 0, v[64:65]
	v_cvt_pk_bf16_f32 v80, v82, s0
	global_store_short v[64:65], v80, off
	global_store_short v[64:65], v66, off offset:64
	v_or_b32_e32 v64, v98, v184
	v_ashrrev_i32_e32 v65, 31, v64
	v_lshlrev_b64 v[64:65], 11, v[64:65]
	v_lshl_add_u64 v[64:65], v[130:131], 0, v[64:65]
	v_cvt_pk_bf16_f32 v66, v83, s0
	global_store_short v[64:65], v66, off
	v_cvt_pk_bf16_f32 v66, v67, s0
	global_store_short v[64:65], v66, off offset:64
	v_or_b32_e32 v64, v98, v185
	v_ashrrev_i32_e32 v65, 31, v64
	v_lshlrev_b64 v[64:65], 11, v[64:65]
	v_lshl_add_u64 v[64:65], v[130:131], 0, v[64:65]
	v_cvt_pk_bf16_f32 v66, v84, s0
	global_store_short v[64:65], v66, off
	v_cvt_pk_bf16_f32 v66, v68, s0
	global_store_short v[64:65], v66, off offset:64
	v_or_b32_e32 v64, v98, v186
	v_ashrrev_i32_e32 v65, 31, v64
	v_lshlrev_b64 v[64:65], 11, v[64:65]
	v_lshl_add_u64 v[64:65], v[130:131], 0, v[64:65]
	v_cvt_pk_bf16_f32 v66, v85, s0
	global_store_short v[64:65], v66, off
	v_cvt_pk_bf16_f32 v66, v69, s0
	global_store_short v[64:65], v66, off offset:64
	v_or_b32_e32 v64, v98, v187
	v_ashrrev_i32_e32 v65, 31, v64
	v_lshlrev_b64 v[64:65], 11, v[64:65]
	v_lshl_add_u64 v[64:65], v[130:131], 0, v[64:65]
	v_cvt_pk_bf16_f32 v66, v86, s0
	global_store_short v[64:65], v66, off
	v_cvt_pk_bf16_f32 v66, v70, s0
	global_store_short v[64:65], v66, off offset:64
	v_or_b32_e32 v64, v98, v188
	v_ashrrev_i32_e32 v65, 31, v64
	v_lshlrev_b64 v[64:65], 11, v[64:65]
	v_lshl_add_u64 v[64:65], v[130:131], 0, v[64:65]
	v_cvt_pk_bf16_f32 v66, v87, s0
	global_store_short v[64:65], v66, off
	v_cvt_pk_bf16_f32 v66, v71, s0
	global_store_short v[64:65], v66, off offset:64
	v_or_b32_e32 v64, v98, v189
	v_ashrrev_i32_e32 v65, 31, v64
	v_lshlrev_b64 v[64:65], 11, v[64:65]
	v_lshl_add_u64 v[64:65], v[130:131], 0, v[64:65]
	v_cvt_pk_bf16_f32 v66, v88, s0
	global_store_short v[64:65], v66, off
	v_cvt_pk_bf16_f32 v66, v72, s0
	global_store_short v[64:65], v66, off offset:64
	v_or_b32_e32 v64, v98, v190
	v_ashrrev_i32_e32 v65, 31, v64
	v_lshlrev_b64 v[64:65], 11, v[64:65]
	v_lshl_add_u64 v[64:65], v[130:131], 0, v[64:65]
	v_cvt_pk_bf16_f32 v66, v89, s0
	global_store_short v[64:65], v66, off
	v_cvt_pk_bf16_f32 v66, v73, s0
	global_store_short v[64:65], v66, off offset:64
	v_or_b32_e32 v64, v98, v191
	v_ashrrev_i32_e32 v65, 31, v64
	v_lshlrev_b64 v[64:65], 11, v[64:65]
	v_lshl_add_u64 v[64:65], v[130:131], 0, v[64:65]
	v_cvt_pk_bf16_f32 v66, v90, s0
	global_store_short v[64:65], v66, off
	v_cvt_pk_bf16_f32 v66, v74, s0
	global_store_short v[64:65], v66, off offset:64
	v_or_b32_e32 v64, v98, v192
	v_ashrrev_i32_e32 v65, 31, v64
	v_lshlrev_b64 v[64:65], 11, v[64:65]
	v_lshl_add_u64 v[64:65], v[130:131], 0, v[64:65]
	v_cvt_pk_bf16_f32 v66, v91, s0
	global_store_short v[64:65], v66, off
	v_cvt_pk_bf16_f32 v66, v75, s0
	global_store_short v[64:65], v66, off offset:64
	v_or_b32_e32 v64, v98, v193
	v_ashrrev_i32_e32 v65, 31, v64
	v_lshlrev_b64 v[64:65], 11, v[64:65]
	v_lshl_add_u64 v[64:65], v[130:131], 0, v[64:65]
	v_cvt_pk_bf16_f32 v66, v92, s0
	global_store_short v[64:65], v66, off
	v_cvt_pk_bf16_f32 v66, v76, s0
	global_store_short v[64:65], v66, off offset:64
	v_or_b32_e32 v64, v98, v194
	v_ashrrev_i32_e32 v65, 31, v64
	v_lshlrev_b64 v[64:65], 11, v[64:65]
	v_lshl_add_u64 v[64:65], v[130:131], 0, v[64:65]
	v_cvt_pk_bf16_f32 v66, v93, s0
	global_store_short v[64:65], v66, off
	v_cvt_pk_bf16_f32 v66, v77, s0
	global_store_short v[64:65], v66, off offset:64
	v_or_b32_e32 v64, v98, v195
	v_ashrrev_i32_e32 v65, 31, v64
	v_lshlrev_b64 v[64:65], 11, v[64:65]
	v_lshl_add_u64 v[64:65], v[130:131], 0, v[64:65]
	v_cvt_pk_bf16_f32 v66, v94, s0
	global_store_short v[64:65], v66, off
	v_cvt_pk_bf16_f32 v66, v78, s0
	global_store_short v[64:65], v66, off offset:64
	v_or_b32_e32 v64, v98, v196
	v_ashrrev_i32_e32 v65, 31, v64
	v_lshlrev_b64 v[64:65], 11, v[64:65]
	v_lshl_add_u64 v[64:65], v[130:131], 0, v[64:65]
	v_cvt_pk_bf16_f32 v66, v95, s0
	global_store_short v[64:65], v66, off
	v_cvt_pk_bf16_f32 v66, v79, s0
	global_store_short v[64:65], v66, off offset:64
	v_or_b32_e32 v66, 64, v132
	v_or_b32_e32 v64, v66, v181
	v_ashrrev_i32_e32 v65, 31, v64
	v_lshlrev_b64 v[64:65], 11, v[64:65]
	v_lshl_add_u64 v[64:65], v[130:131], 0, v[64:65]
	v_cvt_pk_bf16_f32 v32, v32, s0
	global_store_short v[64:65], v48, off
	global_store_short v[64:65], v32, off offset:64
	v_or_b32_e32 v64, v66, v182
	v_ashrrev_i32_e32 v65, 31, v64
	v_lshlrev_b64 v[64:65], 11, v[64:65]
	v_lshl_add_u64 v[64:65], v[130:131], 0, v[64:65]
	v_cvt_pk_bf16_f32 v32, v49, s0
	global_store_short v[64:65], v32, off
	v_cvt_pk_bf16_f32 v32, v33, s0
	global_store_short v[64:65], v32, off offset:64
	v_or_b32_e32 v32, v66, v183
	v_ashrrev_i32_e32 v33, 31, v32
	v_lshlrev_b64 v[32:33], 11, v[32:33]
	v_lshl_add_u64 v[32:33], v[130:131], 0, v[32:33]
	v_cvt_pk_bf16_f32 v48, v50, s0
	v_cvt_pk_bf16_f32 v34, v34, s0
	global_store_short v[32:33], v48, off
	global_store_short v[32:33], v34, off offset:64
	v_or_b32_e32 v32, v66, v184
	v_ashrrev_i32_e32 v33, 31, v32
	v_lshlrev_b64 v[32:33], 11, v[32:33]
	v_lshl_add_u64 v[32:33], v[130:131], 0, v[32:33]
	v_cvt_pk_bf16_f32 v34, v51, s0
	global_store_short v[32:33], v34, off
	v_cvt_pk_bf16_f32 v34, v35, s0
	global_store_short v[32:33], v34, off offset:64
	v_or_b32_e32 v32, v66, v185
	v_ashrrev_i32_e32 v33, 31, v32
	v_lshlrev_b64 v[32:33], 11, v[32:33]
	v_lshl_add_u64 v[32:33], v[130:131], 0, v[32:33]
	v_cvt_pk_bf16_f32 v34, v52, s0
	global_store_short v[32:33], v34, off
	v_cvt_pk_bf16_f32 v34, v36, s0
	global_store_short v[32:33], v34, off offset:64
	v_or_b32_e32 v32, v66, v186
	v_ashrrev_i32_e32 v33, 31, v32
	v_lshlrev_b64 v[32:33], 11, v[32:33]
	v_lshl_add_u64 v[32:33], v[130:131], 0, v[32:33]
	v_cvt_pk_bf16_f32 v34, v53, s0
	global_store_short v[32:33], v34, off
	v_cvt_pk_bf16_f32 v34, v37, s0
	global_store_short v[32:33], v34, off offset:64
	v_or_b32_e32 v32, v66, v187
	v_ashrrev_i32_e32 v33, 31, v32
	v_lshlrev_b64 v[32:33], 11, v[32:33]
	v_lshl_add_u64 v[32:33], v[130:131], 0, v[32:33]
	v_cvt_pk_bf16_f32 v34, v54, s0
	global_store_short v[32:33], v34, off
	v_cvt_pk_bf16_f32 v34, v38, s0
	global_store_short v[32:33], v34, off offset:64
	v_or_b32_e32 v32, v66, v188
	v_ashrrev_i32_e32 v33, 31, v32
	v_lshlrev_b64 v[32:33], 11, v[32:33]
	v_lshl_add_u64 v[32:33], v[130:131], 0, v[32:33]
	v_cvt_pk_bf16_f32 v34, v55, s0
	global_store_short v[32:33], v34, off
	v_cvt_pk_bf16_f32 v34, v39, s0
	global_store_short v[32:33], v34, off offset:64
	v_or_b32_e32 v32, v66, v189
	v_ashrrev_i32_e32 v33, 31, v32
	v_lshlrev_b64 v[32:33], 11, v[32:33]
	v_lshl_add_u64 v[32:33], v[130:131], 0, v[32:33]
	v_cvt_pk_bf16_f32 v34, v56, s0
	global_store_short v[32:33], v34, off
	v_cvt_pk_bf16_f32 v34, v40, s0
	global_store_short v[32:33], v34, off offset:64
	v_or_b32_e32 v32, v66, v190
	v_ashrrev_i32_e32 v33, 31, v32
	v_lshlrev_b64 v[32:33], 11, v[32:33]
	v_lshl_add_u64 v[32:33], v[130:131], 0, v[32:33]
	v_cvt_pk_bf16_f32 v34, v57, s0
	global_store_short v[32:33], v34, off
	v_cvt_pk_bf16_f32 v34, v41, s0
	global_store_short v[32:33], v34, off offset:64
	v_or_b32_e32 v32, v66, v191
	v_ashrrev_i32_e32 v33, 31, v32
	v_lshlrev_b64 v[32:33], 11, v[32:33]
	v_lshl_add_u64 v[32:33], v[130:131], 0, v[32:33]
	v_cvt_pk_bf16_f32 v34, v58, s0
	global_store_short v[32:33], v34, off
	v_cvt_pk_bf16_f32 v34, v42, s0
	global_store_short v[32:33], v34, off offset:64
	v_or_b32_e32 v32, v66, v192
	v_ashrrev_i32_e32 v33, 31, v32
	v_lshlrev_b64 v[32:33], 11, v[32:33]
	v_lshl_add_u64 v[32:33], v[130:131], 0, v[32:33]
	v_cvt_pk_bf16_f32 v34, v59, s0
	global_store_short v[32:33], v34, off
	v_cvt_pk_bf16_f32 v34, v43, s0
	global_store_short v[32:33], v34, off offset:64
	v_or_b32_e32 v32, v66, v193
	v_ashrrev_i32_e32 v33, 31, v32
	v_lshlrev_b64 v[32:33], 11, v[32:33]
	v_lshl_add_u64 v[32:33], v[130:131], 0, v[32:33]
	v_cvt_pk_bf16_f32 v34, v60, s0
	global_store_short v[32:33], v34, off
	v_cvt_pk_bf16_f32 v34, v44, s0
	global_store_short v[32:33], v34, off offset:64
	v_or_b32_e32 v32, v66, v194
	v_ashrrev_i32_e32 v33, 31, v32
	v_lshlrev_b64 v[32:33], 11, v[32:33]
	v_lshl_add_u64 v[32:33], v[130:131], 0, v[32:33]
	v_cvt_pk_bf16_f32 v34, v61, s0
	global_store_short v[32:33], v34, off
	v_cvt_pk_bf16_f32 v34, v45, s0
	global_store_short v[32:33], v34, off offset:64
	v_or_b32_e32 v32, v66, v195
	v_ashrrev_i32_e32 v33, 31, v32
	v_lshlrev_b64 v[32:33], 11, v[32:33]
	v_lshl_add_u64 v[32:33], v[130:131], 0, v[32:33]
	v_cvt_pk_bf16_f32 v34, v62, s0
	global_store_short v[32:33], v34, off
	v_cvt_pk_bf16_f32 v34, v46, s0
	global_store_short v[32:33], v34, off offset:64
	v_or_b32_e32 v32, v66, v196
	v_ashrrev_i32_e32 v33, 31, v32
	v_lshlrev_b64 v[32:33], 11, v[32:33]
	v_lshl_add_u64 v[32:33], v[130:131], 0, v[32:33]
	v_cvt_pk_bf16_f32 v34, v63, s0
	global_store_short v[32:33], v34, off
	v_cvt_pk_bf16_f32 v34, v47, s0
	global_store_short v[32:33], v34, off offset:64
	v_or_b32_e32 v34, 0x60, v132
	v_or_b32_e32 v32, v34, v181
	v_ashrrev_i32_e32 v33, 31, v32
	v_lshlrev_b64 v[32:33], 11, v[32:33]
	v_lshl_add_u64 v[32:33], v[130:131], 0, v[32:33]
	v_cvt_pk_bf16_f32 v0, v0, s0
	global_store_short v[32:33], v16, off
	global_store_short v[32:33], v0, off offset:64
	v_or_b32_e32 v32, v34, v182
	v_ashrrev_i32_e32 v33, 31, v32
	v_lshlrev_b64 v[32:33], 11, v[32:33]
	v_lshl_add_u64 v[32:33], v[130:131], 0, v[32:33]
	v_cvt_pk_bf16_f32 v0, v17, s0
	global_store_short v[32:33], v0, off
	v_cvt_pk_bf16_f32 v0, v1, s0
	global_store_short v[32:33], v0, off offset:64
	v_or_b32_e32 v0, v34, v183
	v_ashrrev_i32_e32 v1, 31, v0
	v_lshlrev_b64 v[0:1], 11, v[0:1]
	v_lshl_add_u64 v[0:1], v[130:131], 0, v[0:1]
	v_cvt_pk_bf16_f32 v16, v18, s0
	v_cvt_pk_bf16_f32 v2, v2, s0
	global_store_short v[0:1], v16, off
	global_store_short v[0:1], v2, off offset:64
	v_or_b32_e32 v0, v34, v184
	v_ashrrev_i32_e32 v1, 31, v0
	v_lshlrev_b64 v[0:1], 11, v[0:1]
	v_lshl_add_u64 v[0:1], v[130:131], 0, v[0:1]
	v_cvt_pk_bf16_f32 v2, v19, s0
	global_store_short v[0:1], v2, off
	v_cvt_pk_bf16_f32 v2, v3, s0
	global_store_short v[0:1], v2, off offset:64
	v_or_b32_e32 v0, v34, v185
	v_ashrrev_i32_e32 v1, 31, v0
	v_lshlrev_b64 v[0:1], 11, v[0:1]
	v_lshl_add_u64 v[0:1], v[130:131], 0, v[0:1]
	v_cvt_pk_bf16_f32 v2, v20, s0
	global_store_short v[0:1], v2, off
	v_cvt_pk_bf16_f32 v2, v4, s0
	global_store_short v[0:1], v2, off offset:64
	v_or_b32_e32 v0, v34, v186
	v_ashrrev_i32_e32 v1, 31, v0
	v_lshlrev_b64 v[0:1], 11, v[0:1]
	v_lshl_add_u64 v[0:1], v[130:131], 0, v[0:1]
	v_cvt_pk_bf16_f32 v2, v21, s0
	global_store_short v[0:1], v2, off
	v_cvt_pk_bf16_f32 v2, v5, s0
	global_store_short v[0:1], v2, off offset:64
	v_or_b32_e32 v0, v34, v187
	v_ashrrev_i32_e32 v1, 31, v0
	v_lshlrev_b64 v[0:1], 11, v[0:1]
	v_lshl_add_u64 v[0:1], v[130:131], 0, v[0:1]
	v_cvt_pk_bf16_f32 v2, v22, s0
	global_store_short v[0:1], v2, off
	v_cvt_pk_bf16_f32 v2, v6, s0
	global_store_short v[0:1], v2, off offset:64
	v_or_b32_e32 v0, v34, v188
	v_ashrrev_i32_e32 v1, 31, v0
	v_lshlrev_b64 v[0:1], 11, v[0:1]
	v_lshl_add_u64 v[0:1], v[130:131], 0, v[0:1]
	v_cvt_pk_bf16_f32 v2, v23, s0
	global_store_short v[0:1], v2, off
	v_cvt_pk_bf16_f32 v2, v7, s0
	global_store_short v[0:1], v2, off offset:64
	v_or_b32_e32 v0, v34, v189
	v_ashrrev_i32_e32 v1, 31, v0
	v_lshlrev_b64 v[0:1], 11, v[0:1]
	v_lshl_add_u64 v[0:1], v[130:131], 0, v[0:1]
	v_cvt_pk_bf16_f32 v2, v24, s0
	global_store_short v[0:1], v2, off
	v_cvt_pk_bf16_f32 v2, v8, s0
	global_store_short v[0:1], v2, off offset:64
	v_or_b32_e32 v0, v34, v190
	v_ashrrev_i32_e32 v1, 31, v0
	v_lshlrev_b64 v[0:1], 11, v[0:1]
	v_lshl_add_u64 v[0:1], v[130:131], 0, v[0:1]
	v_cvt_pk_bf16_f32 v2, v25, s0
	global_store_short v[0:1], v2, off
	v_cvt_pk_bf16_f32 v2, v9, s0
	global_store_short v[0:1], v2, off offset:64
	v_or_b32_e32 v0, v34, v191
	v_ashrrev_i32_e32 v1, 31, v0
	v_lshlrev_b64 v[0:1], 11, v[0:1]
	v_lshl_add_u64 v[0:1], v[130:131], 0, v[0:1]
	v_cvt_pk_bf16_f32 v2, v26, s0
	global_store_short v[0:1], v2, off
	v_cvt_pk_bf16_f32 v2, v10, s0
	global_store_short v[0:1], v2, off offset:64
	v_or_b32_e32 v0, v34, v192
	v_ashrrev_i32_e32 v1, 31, v0
	v_lshlrev_b64 v[0:1], 11, v[0:1]
	v_lshl_add_u64 v[0:1], v[130:131], 0, v[0:1]
	v_cvt_pk_bf16_f32 v2, v27, s0
	global_store_short v[0:1], v2, off
	v_cvt_pk_bf16_f32 v2, v11, s0
	global_store_short v[0:1], v2, off offset:64
	v_or_b32_e32 v0, v34, v193
	v_ashrrev_i32_e32 v1, 31, v0
	v_lshlrev_b64 v[0:1], 11, v[0:1]
	v_lshl_add_u64 v[0:1], v[130:131], 0, v[0:1]
	v_cvt_pk_bf16_f32 v2, v28, s0
	global_store_short v[0:1], v2, off
	v_cvt_pk_bf16_f32 v2, v12, s0
	global_store_short v[0:1], v2, off offset:64
	v_or_b32_e32 v0, v34, v194
	v_ashrrev_i32_e32 v1, 31, v0
	v_lshlrev_b64 v[0:1], 11, v[0:1]
	v_lshl_add_u64 v[0:1], v[130:131], 0, v[0:1]
	v_cvt_pk_bf16_f32 v2, v29, s0
	global_store_short v[0:1], v2, off
	v_cvt_pk_bf16_f32 v2, v13, s0
	global_store_short v[0:1], v2, off offset:64
	v_or_b32_e32 v0, v34, v195
	v_ashrrev_i32_e32 v1, 31, v0
	v_lshlrev_b64 v[0:1], 11, v[0:1]
	v_lshl_add_u64 v[0:1], v[130:131], 0, v[0:1]
	v_cvt_pk_bf16_f32 v2, v30, s0
	global_store_short v[0:1], v2, off
	v_cvt_pk_bf16_f32 v2, v14, s0
	global_store_short v[0:1], v2, off offset:64
	v_or_b32_e32 v0, v34, v196
	v_ashrrev_i32_e32 v1, 31, v0
	v_lshlrev_b64 v[0:1], 11, v[0:1]
	v_lshl_add_u64 v[0:1], v[130:131], 0, v[0:1]
	v_cvt_pk_bf16_f32 v2, v31, s0
	global_store_short v[0:1], v2, off
	v_cvt_pk_bf16_f32 v2, v15, s0
	s_add_i32 s0, s0, s3
	v_readlane_b32 s3, v252, 8
	s_add_i32 s2, s2, s3
	s_cmp_gt_i32 s4, 31
	global_store_short v[0:1], v2, off offset:64
	s_cbranch_scc0 .LBB0_1101

.LBB0_1160:
	s_and_b32 s0, s31, 7
	s_nop 0
	v_lshl_add_u32 v0, s0, 8, v238
	v_ashrrev_i32_e32 v1, 31, v0
	v_lshlrev_b64 v[0:1], 11, v[0:1]
	s_and_b32 s0, s35, 0xffffff00
	v_lshl_add_u64 v[172:173], v[168:169], 0, v[0:1]
	v_add_u32_e32 v0, s0, v198
	s_and_b32 s0, s30, 7
	v_ashrrev_i32_e32 v1, 31, v0
	s_or_b32 s0, s0, s34
	v_lshlrev_b64 v[0:1], 11, v[0:1]
	s_lshl_b32 s0, s0, 8
	v_lshl_add_u64 v[174:175], v[170:171], 0, v[0:1]
	v_add_u32_e32 v0, s0, v198
	s_lshl_b32 s24, s30, 5
	v_ashrrev_i32_e32 v1, 31, v0
	s_and_b32 s1, s24, 0xffffff00
	v_lshlrev_b64 v[0:1], 11, v[0:1]
	v_add_u32_e32 v2, s1, v198
	s_waitcnt vmcnt(0) lgkmcnt(0)
	s_barrier
	v_ashrrev_i32_e32 v3, 31, v2
	v_lshl_add_u64 v[0:1], v[154:155], 0, v[0:1]
	v_readfirstlane_b32 s20, v203
	s_mov_b32 m0, s20
	s_nop 0
	global_load_lds_dwordx4 v[0:1], off
	s_mov_b64 s[26:27], 0x40000
	v_lshlrev_b64 v[2:3], 11, v[2:3]
	v_lshl_add_u64 v[4:5], v[0:1], 0, s[26:27]
	s_add_i32 s21, s20, 0x2000
	s_mov_b32 m0, s21
	s_nop 0
	global_load_lds_dwordx4 v[4:5], off
	v_lshl_add_u64 v[2:3], v[156:157], 0, v[2:3]
	s_add_i32 s21, s20, 0x4000
	s_mov_b32 m0, s21
	s_nop 0
	global_load_lds_dwordx4 v[2:3], off
	v_lshl_add_u64 v[4:5], v[2:3], 0, s[26:27]
	s_add_i32 s21, s20, 0x6000
	s_mov_b32 m0, s21
	s_nop 0
	global_load_lds_dwordx4 v[4:5], off
	s_add_i32 s21, s20, 0x8000
	v_lshl_add_u64 v[4:5], v[0:1], 0, 64
	s_mov_b32 m0, s21
	s_nop 0
	global_load_lds_dwordx4 v[4:5], off
	s_mov_b64 s[22:23], 0x40040
	v_lshl_add_u64 v[4:5], v[0:1], 0, s[22:23]
	s_add_i32 s21, s20, 0xa000
	s_mov_b32 m0, s21
	s_nop 0
	global_load_lds_dwordx4 v[4:5], off
	v_lshl_add_u64 v[4:5], v[2:3], 0, 64
	s_add_i32 s21, s20, 0xc000
	s_mov_b32 m0, s21
	s_nop 0
	global_load_lds_dwordx4 v[4:5], off
	v_lshl_add_u64 v[4:5], v[2:3], 0, s[22:23]
	s_add_i32 s21, s20, 0xe000
	s_mov_b32 m0, s21
	s_nop 0
	global_load_lds_dwordx4 v[4:5], off
	s_mov_b64 s[22:23], 0x80
	s_add_i32 s21, s20, 0x10000
	v_lshl_add_u64 v[4:5], v[0:1], 0, s[22:23]
	s_mov_b32 m0, s21
	s_nop 0
	global_load_lds_dwordx4 v[4:5], off
	s_mov_b64 s[28:29], 0x40080
	v_lshl_add_u64 v[0:1], v[0:1], 0, s[28:29]
	s_add_i32 s21, s20, 0x12000
	s_mov_b32 m0, s21
	s_nop 0
	global_load_lds_dwordx4 v[0:1], off
	v_lshl_add_u64 v[0:1], v[2:3], 0, s[22:23]
	s_add_i32 s21, s20, 0x14000
	s_mov_b32 m0, s21
	s_nop 0
	global_load_lds_dwordx4 v[0:1], off
	v_lshl_add_u64 v[0:1], v[2:3], 0, s[28:29]
	s_add_i32 s20, s20, 0x16000
	s_mov_b32 m0, s20
	s_nop 0
	global_load_lds_dwordx4 v[0:1], off
	v_mov_b32_e32 v130, 0
	v_mov_b32_e32 v134, 0
	v_mov_b32_e32 v0, 0
	s_mov_b32 s20, 0x18000
	v_mov_b32_e32 v1, v0
	v_mov_b32_e32 v2, v0
	v_mov_b32_e32 v3, v0
	v_mov_b32_e32 v4, v0
	v_mov_b32_e32 v5, v0
	v_mov_b32_e32 v6, v0
	v_mov_b32_e32 v7, v0
	v_mov_b32_e32 v8, v0
	v_mov_b32_e32 v9, v0
	v_mov_b32_e32 v10, v0
	v_mov_b32_e32 v11, v0
	v_mov_b32_e32 v12, v0
	v_mov_b32_e32 v13, v0
	v_mov_b32_e32 v14, v0
	v_mov_b32_e32 v15, v0
	v_mov_b32_e32 v16, v0
	v_mov_b32_e32 v17, v0
	v_mov_b32_e32 v18, v0
	v_mov_b32_e32 v19, v0
	v_mov_b32_e32 v20, v0
	v_mov_b32_e32 v21, v0
	v_mov_b32_e32 v22, v0
	v_mov_b32_e32 v23, v0
	v_mov_b32_e32 v24, v0
	v_mov_b32_e32 v25, v0
	v_mov_b32_e32 v26, v0
	v_mov_b32_e32 v27, v0
	v_mov_b32_e32 v28, v0
	v_mov_b32_e32 v29, v0
	v_mov_b32_e32 v30, v0
	v_mov_b32_e32 v31, v0
	v_mov_b32_e32 v32, v0
	v_mov_b32_e32 v33, v0
	v_mov_b32_e32 v34, v0
	v_mov_b32_e32 v35, v0
	v_mov_b32_e32 v36, v0
	v_mov_b32_e32 v37, v0
	v_mov_b32_e32 v38, v0
	v_mov_b32_e32 v39, v0
	v_mov_b32_e32 v40, v0
	v_mov_b32_e32 v41, v0
	v_mov_b32_e32 v42, v0
	v_mov_b32_e32 v43, v0
	v_mov_b32_e32 v44, v0
	v_mov_b32_e32 v45, v0
	v_mov_b32_e32 v46, v0
	v_mov_b32_e32 v47, v0
	v_mov_b32_e32 v48, v0
	v_mov_b32_e32 v49, v0
	v_mov_b32_e32 v50, v0
	v_mov_b32_e32 v51, v0
	v_mov_b32_e32 v52, v0
	v_mov_b32_e32 v53, v0
	v_mov_b32_e32 v54, v0
	v_mov_b32_e32 v55, v0
	v_mov_b32_e32 v56, v0
	v_mov_b32_e32 v57, v0
	v_mov_b32_e32 v58, v0
	v_mov_b32_e32 v59, v0
	v_mov_b32_e32 v60, v0
	v_mov_b32_e32 v61, v0
	v_mov_b32_e32 v62, v0
	v_mov_b32_e32 v63, v0
	v_mov_b32_e32 v64, v0
	v_mov_b32_e32 v65, v0
	v_mov_b32_e32 v66, v0
	v_mov_b32_e32 v67, v0
	v_mov_b32_e32 v68, v0
	v_mov_b32_e32 v69, v0
	v_mov_b32_e32 v70, v0
	v_mov_b32_e32 v71, v0
	v_mov_b32_e32 v72, v0
	v_mov_b32_e32 v73, v0
	v_mov_b32_e32 v74, v0
	v_mov_b32_e32 v75, v0
	v_mov_b32_e32 v76, v0
	v_mov_b32_e32 v77, v0
	v_mov_b32_e32 v78, v0
	v_mov_b32_e32 v79, v0
	v_mov_b32_e32 v80, v0
	v_mov_b32_e32 v81, v0
	v_mov_b32_e32 v82, v0
	v_mov_b32_e32 v83, v0
	v_mov_b32_e32 v84, v0
	v_mov_b32_e32 v85, v0
	v_mov_b32_e32 v86, v0
	v_mov_b32_e32 v87, v0
	v_mov_b32_e32 v88, v0
	v_mov_b32_e32 v89, v0
	v_mov_b32_e32 v90, v0
	v_mov_b32_e32 v91, v0
	v_mov_b32_e32 v92, v0
	v_mov_b32_e32 v93, v0
	v_mov_b32_e32 v94, v0
	v_mov_b32_e32 v95, v0
	v_mov_b32_e32 v96, v0
	v_mov_b32_e32 v97, v0
	v_mov_b32_e32 v98, v0
	v_mov_b32_e32 v99, v0
	v_mov_b32_e32 v100, v0
	v_mov_b32_e32 v101, v0
	v_mov_b32_e32 v102, v0
	v_mov_b32_e32 v103, v0
	v_mov_b32_e32 v104, v0
	v_mov_b32_e32 v105, v0
	v_mov_b32_e32 v106, v0
	v_mov_b32_e32 v107, v0
	v_mov_b32_e32 v108, v0
	v_mov_b32_e32 v109, v0
	v_mov_b32_e32 v110, v0
	v_mov_b32_e32 v111, v0
	v_mov_b32_e32 v112, v0
	v_mov_b32_e32 v113, v0
	v_mov_b32_e32 v114, v0
	v_mov_b32_e32 v115, v0
	v_mov_b32_e32 v116, v0
	v_mov_b32_e32 v117, v0
	v_mov_b32_e32 v118, v0
	v_mov_b32_e32 v119, v0
	v_mov_b32_e32 v120, v0
	v_mov_b32_e32 v121, v0
	v_mov_b32_e32 v122, v0
	v_mov_b32_e32 v123, v0
	v_mov_b32_e32 v124, v0
	v_mov_b32_e32 v125, v0
	v_mov_b32_e32 v126, v0
	v_mov_b32_e32 v127, v0
	v_mov_b32_e32 v135, v134
	v_mov_b32_e32 v136, v134
	v_mov_b32_e32 v137, v134
	v_mov_b32_e32 v138, v134
	v_mov_b32_e32 v139, v134
	v_mov_b32_e32 v140, v134
	v_mov_b32_e32 v141, v134
	v_mov_b32_e32 v146, v134
	v_mov_b32_e32 v147, v134
	v_mov_b32_e32 v148, v134
	v_mov_b32_e32 v149, v134
	v_mov_b32_e32 v150, v134
	v_mov_b32_e32 v151, v134
	v_mov_b32_e32 v152, v134
	v_mov_b32_e32 v153, v134
	v_mov_b32_e32 v131, v130
	v_mov_b32_e32 v132, v130
	v_mov_b32_e32 v133, v130
	v_mov_b32_e32 v142, v130
	v_mov_b32_e32 v143, v130
	v_mov_b32_e32 v144, v130
	v_mov_b32_e32 v145, v130
	v_readfirstlane_b32 s100, v163
	s_cmp_ge_u32 s100, 0x100
	s_cbranch_scc1 .Lky_4
.LBB0_1161:
	s_and_b32 s21, s20, 0x18000
	v_add_u32_e32 v128, s21, v203
	s_add_i32 s21, s20, 0xfffe8000
	s_and_b32 s21, s21, 0x18000
	v_or_b32_e32 v222, s21, v202
	v_add_u32_e32 v223, s21, v199
	s_waitcnt vmcnt(8) lgkmcnt(0)
	s_barrier
	v_mfma_f32_32x32x16_bf16 v[112:127], v[150:153], v[142:145], v[112:127]
	v_mfma_f32_32x32x16_bf16 v[96:111], v[150:153], v[130:133], v[96:111]
	v_add_u32_e32 v180, v222, v200
	v_add_u32_e32 v224, v223, v200
	ds_read_b128 v[176:179], v180 offset:16384
	ds_read_b128 v[180:183], v180 offset:18432
	ds_read_b128 v[184:187], v224
	ds_read_b128 v[188:191], v224 offset:2048
	ds_read_b128 v[192:195], v224 offset:4096
	ds_read_b128 v[240:243], v224 offset:6144
	v_mfma_f32_32x32x16_bf16 v[80:95], v[146:149], v[142:145], v[80:95]
	v_mfma_f32_32x32x16_bf16 v[64:79], v[146:149], v[130:133], v[64:79]
	v_readfirstlane_b32 s21, v128
	s_mov_b32 m0, s21
	s_nop 0
	global_load_lds_dwordx4 v[172:173], off
	v_mfma_f32_32x32x16_bf16 v[48:63], v[138:141], v[142:145], v[48:63]
	v_mfma_f32_32x32x16_bf16 v[32:47], v[138:141], v[130:133], v[32:47]
	s_add_i32 s22, s21, 0x2000
	v_lshl_add_u64 v[150:151], v[172:173], 0, s[26:27]
	s_mov_b32 m0, s22
	s_nop 0
	global_load_lds_dwordx4 v[150:151], off
	v_mfma_f32_32x32x16_bf16 v[16:31], v[134:137], v[142:145], v[16:31]
	v_mfma_f32_32x32x16_bf16 v[0:15], v[134:137], v[130:133], v[0:15]
	v_add_u32_e32 v128, v222, v201
	ds_read_b128 v[142:145], v128 offset:16384
	ds_read_b128 v[130:133], v128 offset:18432
	v_add_u32_e32 v128, v223, v201
	ds_read_b128 v[150:153], v128
	ds_read_b128 v[146:149], v128 offset:2048
	ds_read_b128 v[138:141], v128 offset:4096
	ds_read_b128 v[134:137], v128 offset:6144
	s_waitcnt lgkmcnt(9)
	v_mfma_f32_32x32x16_bf16 v[112:127], v[184:187], v[176:179], v[112:127]
	s_add_i32 s22, s21, 0x6000
	s_addk_i32 s21, 0x4000
	v_mfma_f32_32x32x16_bf16 v[96:111], v[184:187], v[180:183], v[96:111]
	s_mov_b32 m0, s21
	s_nop 0
	global_load_lds_dwordx4 v[174:175], off
	v_lshl_add_u64 v[224:225], v[174:175], 0, s[26:27]
	s_waitcnt lgkmcnt(8)
	v_mfma_f32_32x32x16_bf16 v[80:95], v[188:191], v[176:179], v[80:95]
	v_mfma_f32_32x32x16_bf16 v[64:79], v[188:191], v[180:183], v[64:79]
	s_waitcnt lgkmcnt(7)
	v_mfma_f32_32x32x16_bf16 v[48:63], v[192:195], v[176:179], v[48:63]
	v_mfma_f32_32x32x16_bf16 v[32:47], v[192:195], v[180:183], v[32:47]
	s_mov_b32 m0, s22
	s_nop 0
	global_load_lds_dwordx4 v[224:225], off
	s_waitcnt lgkmcnt(6)
	v_mfma_f32_32x32x16_bf16 v[16:31], v[240:243], v[176:179], v[16:31]
	s_add_i32 s20, s20, 0x8000
	v_lshl_add_u64 v[172:173], v[172:173], 0, 64
	v_lshl_add_u64 v[174:175], v[174:175], 0, 64
	s_cmp_eq_u32 s20, 0x100000
	v_mfma_f32_32x32x16_bf16 v[0:15], v[240:243], v[180:183], v[0:15]
	s_cbranch_scc0 .LBB0_1161
	s_branch .Lktail_4
.Lky_4:
	s_and_b32 s21, s20, 0x18000
	v_add_u32_e32 v128, s21, v203
	s_add_i32 s21, s20, 0xfffe8000
	s_and_b32 s21, s21, 0x18000
	v_or_b32_e32 v222, s21, v202
	v_add_u32_e32 v223, s21, v199
	s_waitcnt vmcnt(8) lgkmcnt(0)
	s_barrier
	v_add_u32_e32 v180, v222, v200
	v_add_u32_e32 v224, v223, v200
	ds_read_b128 v[176:179], v180 offset:16384
	ds_read_b128 v[180:183], v180 offset:18432
	ds_read_b128 v[184:187], v224
	ds_read_b128 v[188:191], v224 offset:2048
	ds_read_b128 v[192:195], v224 offset:4096
	ds_read_b128 v[240:243], v224 offset:6144
	v_mfma_f32_32x32x16_bf16 v[112:127], v[150:153], v[142:145], v[112:127]
	v_mfma_f32_32x32x16_bf16 v[96:111], v[150:153], v[130:133], v[96:111]
	v_readfirstlane_b32 s21, v128
	s_mov_b32 m0, s21
	s_nop 0
	global_load_lds_dwordx4 v[172:173], off
	v_mfma_f32_32x32x16_bf16 v[80:95], v[146:149], v[142:145], v[80:95]
	v_mfma_f32_32x32x16_bf16 v[64:79], v[146:149], v[130:133], v[64:79]
	v_mfma_f32_32x32x16_bf16 v[48:63], v[138:141], v[142:145], v[48:63]
	v_mfma_f32_32x32x16_bf16 v[32:47], v[138:141], v[130:133], v[32:47]
	s_add_i32 s22, s21, 0x2000
	v_lshl_add_u64 v[150:151], v[172:173], 0, s[26:27]
	s_mov_b32 m0, s22
	s_nop 0
	global_load_lds_dwordx4 v[150:151], off
	v_mfma_f32_32x32x16_bf16 v[16:31], v[134:137], v[142:145], v[16:31]
	v_mfma_f32_32x32x16_bf16 v[0:15], v[134:137], v[130:133], v[0:15]
	v_add_u32_e32 v128, v222, v201
	ds_read_b128 v[142:145], v128 offset:16384
	ds_read_b128 v[130:133], v128 offset:18432
	v_add_u32_e32 v128, v223, v201
	ds_read_b128 v[150:153], v128
	ds_read_b128 v[146:149], v128 offset:2048
	ds_read_b128 v[138:141], v128 offset:4096
	ds_read_b128 v[134:137], v128 offset:6144
	s_waitcnt lgkmcnt(9)
	v_mfma_f32_32x32x16_bf16 v[112:127], v[184:187], v[176:179], v[112:127]
	s_add_i32 s22, s21, 0x6000
	s_addk_i32 s21, 0x4000
	v_mfma_f32_32x32x16_bf16 v[96:111], v[184:187], v[180:183], v[96:111]
	s_mov_b32 m0, s21
	s_nop 0
	global_load_lds_dwordx4 v[174:175], off
	v_lshl_add_u64 v[224:225], v[174:175], 0, s[26:27]
	s_waitcnt lgkmcnt(8)
	v_mfma_f32_32x32x16_bf16 v[80:95], v[188:191], v[176:179], v[80:95]
	v_mfma_f32_32x32x16_bf16 v[64:79], v[188:191], v[180:183], v[64:79]
	s_waitcnt lgkmcnt(7)
	v_mfma_f32_32x32x16_bf16 v[48:63], v[192:195], v[176:179], v[48:63]
	v_mfma_f32_32x32x16_bf16 v[32:47], v[192:195], v[180:183], v[32:47]
	s_mov_b32 m0, s22
	s_nop 0
	global_load_lds_dwordx4 v[224:225], off
	s_waitcnt lgkmcnt(6)
	v_mfma_f32_32x32x16_bf16 v[16:31], v[240:243], v[176:179], v[16:31]
	s_add_i32 s20, s20, 0x8000
	v_lshl_add_u64 v[172:173], v[172:173], 0, 64
	v_lshl_add_u64 v[174:175], v[174:175], 0, 64
	s_cmp_eq_u32 s20, 0x100000
	v_mfma_f32_32x32x16_bf16 v[0:15], v[240:243], v[180:183], v[0:15]
	s_cbranch_scc0 .Lky_4
.Lktail_4:
	s_waitcnt vmcnt(8) lgkmcnt(0)
	s_barrier
	v_add_u32_e32 v128, v202, v200
	ds_read_b128 v[172:175], v128 offset:49152
	ds_read_b128 v[176:179], v128 offset:51200
	v_add_u32_e32 v128, v199, v200
	ds_read_b128 v[180:183], v128 offset:32768
	ds_read_b128 v[184:187], v128 offset:34816
	ds_read_b128 v[188:191], v128 offset:36864
	ds_read_b128 v[192:195], v128 offset:38912
	s_waitcnt lgkmcnt(9)
	v_mfma_f32_32x32x16_bf16 v[112:127], v[150:153], v[142:145], v[112:127]
	v_mfma_f32_32x32x16_bf16 v[96:111], v[150:153], v[130:133], v[96:111]
	s_waitcnt lgkmcnt(8)
	v_mfma_f32_32x32x16_bf16 v[80:95], v[146:149], v[142:145], v[80:95]
	v_mfma_f32_32x32x16_bf16 v[64:79], v[146:149], v[130:133], v[64:79]
	s_waitcnt lgkmcnt(7)
	v_mfma_f32_32x32x16_bf16 v[48:63], v[138:141], v[142:145], v[48:63]
	v_mfma_f32_32x32x16_bf16 v[32:47], v[138:141], v[130:133], v[32:47]
	s_waitcnt lgkmcnt(6)
	v_mfma_f32_32x32x16_bf16 v[16:31], v[134:137], v[142:145], v[16:31]
	v_mfma_f32_32x32x16_bf16 v[0:15], v[134:137], v[130:133], v[0:15]
	v_add_u32_e32 v128, v202, v201
	ds_read_b128 v[130:133], v128 offset:49152
	ds_read_b128 v[134:137], v128 offset:51200
	v_add_u32_e32 v128, v199, v201
	ds_read_b128 v[138:141], v128 offset:32768
	ds_read_b128 v[142:145], v128 offset:34816
	ds_read_b128 v[146:149], v128 offset:36864
	ds_read_b128 v[150:153], v128 offset:38912
	s_waitcnt lgkmcnt(9)
	v_mfma_f32_32x32x16_bf16 v[112:127], v[180:183], v[172:175], v[112:127]
	v_mfma_f32_32x32x16_bf16 v[96:111], v[180:183], v[176:179], v[96:111]
	s_waitcnt lgkmcnt(8)
	v_mfma_f32_32x32x16_bf16 v[80:95], v[184:187], v[172:175], v[80:95]
	v_mfma_f32_32x32x16_bf16 v[64:79], v[184:187], v[176:179], v[64:79]
	s_waitcnt lgkmcnt(7)
	v_mfma_f32_32x32x16_bf16 v[48:63], v[188:191], v[172:175], v[48:63]
	v_mfma_f32_32x32x16_bf16 v[32:47], v[188:191], v[176:179], v[32:47]
	s_waitcnt vmcnt(4) lgkmcnt(0)
	s_barrier
	v_add_u32_e32 v128, v236, v200
	s_waitcnt lgkmcnt(6)
	v_mfma_f32_32x32x16_bf16 v[16:31], v[192:195], v[172:175], v[16:31]
	v_mfma_f32_32x32x16_bf16 v[0:15], v[192:195], v[176:179], v[0:15]
	ds_read_b128 v[172:175], v128 offset:16384
	ds_read_b128 v[176:179], v128 offset:18432
	v_add_u32_e32 v128, v237, v200
	ds_read_b128 v[180:183], v128
	ds_read_b128 v[184:187], v128 offset:2048
	ds_read_b128 v[188:191], v128 offset:4096
	ds_read_b128 v[192:195], v128 offset:6144
	s_waitcnt lgkmcnt(9)
	v_mfma_f32_32x32x16_bf16 v[112:127], v[138:141], v[130:133], v[112:127]
	v_mfma_f32_32x32x16_bf16 v[96:111], v[138:141], v[134:137], v[96:111]
	s_waitcnt lgkmcnt(8)
	v_mfma_f32_32x32x16_bf16 v[80:95], v[142:145], v[130:133], v[80:95]
	v_mfma_f32_32x32x16_bf16 v[64:79], v[142:145], v[134:137], v[64:79]
	s_waitcnt lgkmcnt(7)
	v_mfma_f32_32x32x16_bf16 v[48:63], v[146:149], v[130:133], v[48:63]
	v_mfma_f32_32x32x16_bf16 v[32:47], v[146:149], v[134:137], v[32:47]
	s_waitcnt lgkmcnt(6)
	v_mfma_f32_32x32x16_bf16 v[16:31], v[150:153], v[130:133], v[16:31]
	v_mfma_f32_32x32x16_bf16 v[0:15], v[150:153], v[134:137], v[0:15]
	v_add_u32_e32 v128, v236, v201
	ds_read_b128 v[130:133], v128 offset:16384
	ds_read_b128 v[134:137], v128 offset:18432
	v_add_u32_e32 v128, v237, v201
	ds_read_b128 v[138:141], v128
	ds_read_b128 v[142:145], v128 offset:2048
	ds_read_b128 v[146:149], v128 offset:4096
	ds_read_b128 v[150:153], v128 offset:6144
	s_waitcnt lgkmcnt(9)
	v_mfma_f32_32x32x16_bf16 v[112:127], v[180:183], v[172:175], v[112:127]
	v_mfma_f32_32x32x16_bf16 v[96:111], v[180:183], v[176:179], v[96:111]
	s_waitcnt lgkmcnt(8)
	v_mfma_f32_32x32x16_bf16 v[80:95], v[184:187], v[172:175], v[80:95]
	v_mfma_f32_32x32x16_bf16 v[64:79], v[184:187], v[176:179], v[64:79]
	s_waitcnt lgkmcnt(7)
	v_mfma_f32_32x32x16_bf16 v[48:63], v[188:191], v[172:175], v[48:63]
	v_mfma_f32_32x32x16_bf16 v[32:47], v[188:191], v[176:179], v[32:47]
	s_waitcnt vmcnt(0) lgkmcnt(0)
	s_barrier
	v_add_u32_e32 v128, v234, v200
	s_waitcnt lgkmcnt(6)
	v_mfma_f32_32x32x16_bf16 v[16:31], v[192:195], v[172:175], v[16:31]
	v_mfma_f32_32x32x16_bf16 v[0:15], v[192:195], v[176:179], v[0:15]
	ds_read_b128 v[172:175], v128 offset:16384
	ds_read_b128 v[176:179], v128 offset:18432
	v_add_u32_e32 v128, v235, v200
	ds_read_b128 v[180:183], v128
	ds_read_b128 v[184:187], v128 offset:2048
	ds_read_b128 v[188:191], v128 offset:4096
	ds_read_b128 v[192:195], v128 offset:6144
	s_waitcnt lgkmcnt(9)
	v_mfma_f32_32x32x16_bf16 v[112:127], v[138:141], v[130:133], v[112:127]
	v_mfma_f32_32x32x16_bf16 v[96:111], v[138:141], v[134:137], v[96:111]
	s_waitcnt lgkmcnt(8)
	v_mfma_f32_32x32x16_bf16 v[80:95], v[142:145], v[130:133], v[80:95]
	v_mfma_f32_32x32x16_bf16 v[64:79], v[142:145], v[134:137], v[64:79]
	s_waitcnt lgkmcnt(7)
	v_mfma_f32_32x32x16_bf16 v[48:63], v[146:149], v[130:133], v[48:63]
	v_mfma_f32_32x32x16_bf16 v[32:47], v[146:149], v[134:137], v[32:47]
	s_waitcnt lgkmcnt(6)
	v_mfma_f32_32x32x16_bf16 v[16:31], v[150:153], v[130:133], v[16:31]
	v_mfma_f32_32x32x16_bf16 v[0:15], v[150:153], v[134:137], v[0:15]
	v_add_u32_e32 v128, v234, v201
	ds_read_b128 v[130:133], v128 offset:16384
	ds_read_b128 v[136:139], v128 offset:18432
	v_add_u32_e32 v128, v235, v201
	ds_read_b128 v[140:143], v128
	ds_read_b128 v[144:147], v128 offset:2048
	ds_read_b128 v[148:151], v128 offset:4096
	ds_read_b128 v[240:243], v128 offset:6144
	s_waitcnt lgkmcnt(9)
	v_mfma_f32_32x32x16_bf16 v[112:127], v[180:183], v[172:175], v[112:127]
	v_mfma_f32_32x32x16_bf16 v[96:111], v[180:183], v[176:179], v[96:111]
	s_waitcnt lgkmcnt(8)
	v_mfma_f32_32x32x16_bf16 v[80:95], v[184:187], v[172:175], v[80:95]
	v_mfma_f32_32x32x16_bf16 v[64:79], v[184:187], v[176:179], v[64:79]
	s_waitcnt lgkmcnt(7)
	v_mfma_f32_32x32x16_bf16 v[48:63], v[188:191], v[172:175], v[48:63]
	v_mfma_f32_32x32x16_bf16 v[32:47], v[188:191], v[176:179], v[32:47]
	s_waitcnt lgkmcnt(6)
	v_mfma_f32_32x32x16_bf16 v[16:31], v[192:195], v[172:175], v[16:31]
	v_or_b32_e32 v134, s1, v196
	s_movk_i32 s1, 0x1840
	v_cmp_gt_i32_e32 vcc, s1, v134
	v_mfma_f32_32x32x16_bf16 v[0:15], v[192:195], v[176:179], v[0:15]
	s_waitcnt lgkmcnt(3)
	v_mfma_f32_32x32x16_bf16 v[112:127], v[140:143], v[130:133], v[112:127]
	v_mfma_f32_32x32x16_bf16 v[96:111], v[140:143], v[136:139], v[96:111]
	s_waitcnt lgkmcnt(2)
	v_mfma_f32_32x32x16_bf16 v[80:95], v[144:147], v[130:133], v[80:95]
	v_mfma_f32_32x32x16_bf16 v[64:79], v[144:147], v[136:139], v[64:79]
	s_waitcnt lgkmcnt(1)
	v_mfma_f32_32x32x16_bf16 v[48:63], v[148:151], v[130:133], v[48:63]
	v_mfma_f32_32x32x16_bf16 v[32:47], v[148:151], v[136:139], v[32:47]
	s_waitcnt lgkmcnt(0)
	v_mfma_f32_32x32x16_bf16 v[16:31], v[240:243], v[130:133], v[16:31]
	v_mfma_f32_32x32x16_bf16 v[0:15], v[240:243], v[136:139], v[0:15]
	s_and_saveexec_b64 s[20:21], vcc
	s_cbranch_execz .LBB0_1159
	v_add_u32_e32 v239, s0, v159
	s_movk_i32 s0, 0x7ff
	v_cmp_lt_i32_e32 vcc, s0, v134
	s_and_saveexec_b64 s[0:1], vcc
	s_xor_b64 s[22:23], exec, s[0:1]
	s_cbranch_execz .LBB0_1816
	s_cmpk_lt_u32 s24, 0x1800
	v_or_b32_e32 v130, v134, v197
	s_mov_b64 s[0:1], -1
	s_cbranch_scc0 .LBB0_1302
	v_add_u32_e32 v128, 0xfffff800, v130
	v_lshlrev_b64 v[132:133], 2, v[128:129]
	v_lshl_add_u64 v[134:135], s[16:17], 0, v[132:133]
	v_add_co_u32_e32 v136, vcc, 0x4000, v134
	v_lshl_add_u64 v[132:133], s[18:19], 0, v[132:133]
	s_nop 0
	v_addc_co_u32_e32 v137, vcc, 0, v135, vcc
	v_add_co_u32_e32 v138, vcc, 0x8000, v134
	v_mov_b32_e32 v131, v113
	s_nop 0
	v_addc_co_u32_e32 v139, vcc, 0, v135, vcc
	global_load_dword v188, v[134:135], off
	s_nop 0
	global_load_dword v134, v[136:137], off
	global_load_dword v186, v[138:139], off
	global_load_dword v190, v[132:133], off
	v_ashrrev_i32_e32 v132, 7, v239
	v_ashrrev_i32_e32 v133, 31, v132
	v_lshlrev_b64 v[136:137], 15, v[132:133]
	v_lshl_add_u64 v[178:179], s[2:3], 0, v[136:137]
	v_lshl_add_u64 v[136:137], v[128:129], 1, v[178:179]
	s_and_saveexec_b64 s[0:1], s[6:7]
	s_xor_b64 s[0:1], exec, s[0:1]
	s_cbranch_execz .LBB0_1167
	v_add_co_u32_e32 v138, vcc, 0x4000, v136
	v_cvt_pk_bf16_f32 v131, v30, s0
	s_nop 0
	v_addc_co_u32_e32 v139, vcc, 0, v137, vcc
	global_store_short v[138:139], v131, off
	v_mov_b32_e32 v131, v31

.LBB0_2225:
	s_and_b32 s6, s2, 7
	v_lshl_add_u32 v0, s6, 8, v201
	v_ashrrev_i32_e32 v1, 31, v0
	v_lshlrev_b64 v[0:1], 12, v[0:1]
	s_and_b32 s6, s5, 0xffffff00
	v_lshl_add_u64 v[170:171], v[160:161], 0, v[0:1]
	v_add_u32_e32 v0, s6, v175
	s_and_b32 s6, s4, 7
	v_ashrrev_i32_e32 v1, 31, v0
	s_or_b32 s6, s6, s3
	v_lshlrev_b64 v[0:1], 12, v[0:1]
	s_lshl_b32 s6, s6, 8
	v_lshl_add_u64 v[172:173], v[168:169], 0, v[0:1]
	v_add_u32_e32 v0, s6, v175
	s_lshl_b32 s7, s4, 5
	v_ashrrev_i32_e32 v1, 31, v0
	s_and_b32 s7, s7, 0xffffff00
	v_add_u32_e32 v2, s7, v175
	v_lshlrev_b64 v[0:1], 12, v[0:1]
	s_waitcnt vmcnt(0) lgkmcnt(0)
	s_barrier
	v_and_b32_e32 v238, 0xff, v163
	v_add_u32_e32 v239, s6, v238
	v_lshlrev_b32_e32 v239, 2, v239
	global_load_dword v239, v239, s[0:1]
	v_lshlrev_b32_e32 v238, 2, v238
	v_add_u32_e32 v238, 0x20020, v238
	v_mov_b32_e32 v250, 0x20020
	v_ashrrev_i32_e32 v3, 31, v2
	v_lshl_add_u64 v[0:1], v[154:155], 0, v[0:1]
	v_readfirstlane_b32 s8, v180
	s_mov_b32 m0, s8
	s_nop 0
	global_load_lds_dwordx4 v[0:1], off
	s_mov_b64 s[12:13], 0x80000
	v_lshlrev_b64 v[2:3], 12, v[2:3]
	v_lshl_add_u64 v[4:5], v[0:1], 0, s[12:13]
	s_add_i32 s9, s8, 0x2000
	s_mov_b32 m0, s9
	s_nop 0
	global_load_lds_dwordx4 v[4:5], off
	v_lshl_add_u64 v[2:3], v[156:157], 0, v[2:3]
	s_add_i32 s9, s8, 0x4000
	s_mov_b32 m0, s9
	s_nop 0
	global_load_lds_dwordx4 v[2:3], off
	v_lshl_add_u64 v[4:5], v[2:3], 0, s[12:13]
	s_add_i32 s9, s8, 0x6000
	s_mov_b32 m0, s9
	s_nop 0
	global_load_lds_dwordx4 v[4:5], off
	s_add_i32 s9, s8, 0x8000
	v_lshl_add_u64 v[4:5], v[0:1], 0, 64
	s_mov_b32 m0, s9
	s_nop 0
	global_load_lds_dwordx4 v[4:5], off
	s_mov_b64 s[10:11], 0x80040
	v_lshl_add_u64 v[4:5], v[0:1], 0, s[10:11]
	s_add_i32 s9, s8, 0xa000
	s_mov_b32 m0, s9
	s_nop 0
	global_load_lds_dwordx4 v[4:5], off
	v_lshl_add_u64 v[4:5], v[2:3], 0, 64
	s_add_i32 s9, s8, 0xc000
	s_mov_b32 m0, s9
	s_nop 0
	global_load_lds_dwordx4 v[4:5], off
	v_lshl_add_u64 v[4:5], v[2:3], 0, s[10:11]
	s_add_i32 s9, s8, 0xe000
	s_mov_b32 m0, s9
	s_nop 0
	global_load_lds_dwordx4 v[4:5], off
	s_mov_b64 s[10:11], 0x80
	s_add_i32 s9, s8, 0x10000
	v_lshl_add_u64 v[4:5], v[0:1], 0, s[10:11]
	s_mov_b32 m0, s9
	s_nop 0
	global_load_lds_dwordx4 v[4:5], off
	s_mov_b64 s[14:15], 0x80080
	v_lshl_add_u64 v[0:1], v[0:1], 0, s[14:15]
	s_add_i32 s9, s8, 0x12000
	s_mov_b32 m0, s9
	s_nop 0
	global_load_lds_dwordx4 v[0:1], off
	v_lshl_add_u64 v[0:1], v[2:3], 0, s[10:11]
	s_add_i32 s9, s8, 0x14000
	s_mov_b32 m0, s9
	s_nop 0
	global_load_lds_dwordx4 v[0:1], off
	v_lshl_add_u64 v[0:1], v[2:3], 0, s[14:15]
	s_add_i32 s8, s8, 0x16000
	s_mov_b32 m0, s8
	s_nop 0
	global_load_lds_dwordx4 v[0:1], off
	s_waitcnt vmcnt(12)
	ds_write_b32 v238, v239
	v_mov_b32_e32 v130, 0
	v_mov_b32_e32 v134, 0
	v_mov_b32_e32 v0, 0
	s_mov_b32 s8, 0x18000
	v_mov_b32_e32 v1, v0
	v_mov_b32_e32 v2, v0
	v_mov_b32_e32 v3, v0
	v_mov_b32_e32 v4, v0
	v_mov_b32_e32 v5, v0
	v_mov_b32_e32 v6, v0
	v_mov_b32_e32 v7, v0
	v_mov_b32_e32 v8, v0
	v_mov_b32_e32 v9, v0
	v_mov_b32_e32 v10, v0
	v_mov_b32_e32 v11, v0
	v_mov_b32_e32 v12, v0
	v_mov_b32_e32 v13, v0
	v_mov_b32_e32 v14, v0
	v_mov_b32_e32 v15, v0
	v_mov_b32_e32 v16, v0
	v_mov_b32_e32 v17, v0
	v_mov_b32_e32 v18, v0
	v_mov_b32_e32 v19, v0
	v_mov_b32_e32 v20, v0
	v_mov_b32_e32 v21, v0
	v_mov_b32_e32 v22, v0
	v_mov_b32_e32 v23, v0
	v_mov_b32_e32 v24, v0
	v_mov_b32_e32 v25, v0
	v_mov_b32_e32 v26, v0
	v_mov_b32_e32 v27, v0
	v_mov_b32_e32 v28, v0
	v_mov_b32_e32 v29, v0
	v_mov_b32_e32 v30, v0
	v_mov_b32_e32 v31, v0
	v_mov_b32_e32 v32, v0
	v_mov_b32_e32 v33, v0
	v_mov_b32_e32 v34, v0
	v_mov_b32_e32 v35, v0
	v_mov_b32_e32 v36, v0
	v_mov_b32_e32 v37, v0
	v_mov_b32_e32 v38, v0
	v_mov_b32_e32 v39, v0
	v_mov_b32_e32 v40, v0
	v_mov_b32_e32 v41, v0
	v_mov_b32_e32 v42, v0
	v_mov_b32_e32 v43, v0
	v_mov_b32_e32 v44, v0
	v_mov_b32_e32 v45, v0
	v_mov_b32_e32 v46, v0
	v_mov_b32_e32 v47, v0
	v_mov_b32_e32 v48, v0
	v_mov_b32_e32 v49, v0
	v_mov_b32_e32 v50, v0
	v_mov_b32_e32 v51, v0
	v_mov_b32_e32 v52, v0
	v_mov_b32_e32 v53, v0
	v_mov_b32_e32 v54, v0
	v_mov_b32_e32 v55, v0
	v_mov_b32_e32 v56, v0
	v_mov_b32_e32 v57, v0
	v_mov_b32_e32 v58, v0
	v_mov_b32_e32 v59, v0
	v_mov_b32_e32 v60, v0
	v_mov_b32_e32 v61, v0
	v_mov_b32_e32 v62, v0
	v_mov_b32_e32 v63, v0
	v_mov_b32_e32 v64, v0
	v_mov_b32_e32 v65, v0
	v_mov_b32_e32 v66, v0
	v_mov_b32_e32 v67, v0
	v_mov_b32_e32 v68, v0
	v_mov_b32_e32 v69, v0
	v_mov_b32_e32 v70, v0
	v_mov_b32_e32 v71, v0
	v_mov_b32_e32 v72, v0
	v_mov_b32_e32 v73, v0
	v_mov_b32_e32 v74, v0
	v_mov_b32_e32 v75, v0
	v_mov_b32_e32 v76, v0
	v_mov_b32_e32 v77, v0
	v_mov_b32_e32 v78, v0
	v_mov_b32_e32 v79, v0
	v_mov_b32_e32 v80, v0
	v_mov_b32_e32 v81, v0
	v_mov_b32_e32 v82, v0
	v_mov_b32_e32 v83, v0
	v_mov_b32_e32 v84, v0
	v_mov_b32_e32 v85, v0
	v_mov_b32_e32 v86, v0
	v_mov_b32_e32 v87, v0
	v_mov_b32_e32 v88, v0
	v_mov_b32_e32 v89, v0
	v_mov_b32_e32 v90, v0
	v_mov_b32_e32 v91, v0
	v_mov_b32_e32 v92, v0
	v_mov_b32_e32 v93, v0
	v_mov_b32_e32 v94, v0
	v_mov_b32_e32 v95, v0
	v_mov_b32_e32 v96, v0
	v_mov_b32_e32 v97, v0
	v_mov_b32_e32 v98, v0
	v_mov_b32_e32 v99, v0
	v_mov_b32_e32 v100, v0
	v_mov_b32_e32 v101, v0
	v_mov_b32_e32 v102, v0
	v_mov_b32_e32 v103, v0
	v_mov_b32_e32 v104, v0
	v_mov_b32_e32 v105, v0
	v_mov_b32_e32 v106, v0
	v_mov_b32_e32 v107, v0
	v_mov_b32_e32 v108, v0
	v_mov_b32_e32 v109, v0
	v_mov_b32_e32 v110, v0
	v_mov_b32_e32 v111, v0
	v_mov_b32_e32 v112, v0
	v_mov_b32_e32 v113, v0
	v_mov_b32_e32 v114, v0
	v_mov_b32_e32 v115, v0
	v_mov_b32_e32 v116, v0
	v_mov_b32_e32 v117, v0
	v_mov_b32_e32 v118, v0
	v_mov_b32_e32 v119, v0
	v_mov_b32_e32 v120, v0
	v_mov_b32_e32 v121, v0
	v_mov_b32_e32 v122, v0
	v_mov_b32_e32 v123, v0
	v_mov_b32_e32 v124, v0
	v_mov_b32_e32 v125, v0
	v_mov_b32_e32 v126, v0
	v_mov_b32_e32 v127, v0
	v_mov_b32_e32 v135, v134
	v_mov_b32_e32 v136, v134
	v_mov_b32_e32 v137, v134
	v_mov_b32_e32 v138, v134
	v_mov_b32_e32 v139, v134
	v_mov_b32_e32 v140, v134
	v_mov_b32_e32 v141, v134
	v_mov_b32_e32 v146, v134
	v_mov_b32_e32 v147, v134
	v_mov_b32_e32 v148, v134
	v_mov_b32_e32 v149, v134
	v_mov_b32_e32 v150, v134
	v_mov_b32_e32 v151, v134
	v_mov_b32_e32 v152, v134
	v_mov_b32_e32 v153, v134
	v_mov_b32_e32 v131, v130
	v_mov_b32_e32 v132, v130
	v_mov_b32_e32 v133, v130
	v_mov_b32_e32 v142, v130
	v_mov_b32_e32 v143, v130
	v_mov_b32_e32 v144, v130
	v_mov_b32_e32 v145, v130
	v_readfirstlane_b32 s100, v163
	s_cmp_ge_u32 s100, 0x100
	s_cbranch_scc1 .Lky_5
.LBB0_2226:
	s_and_b32 s9, s8, 0x18000
	v_add_u32_e32 v222, s9, v180
	s_add_i32 s9, s8, 0xfffe8000
	s_and_b32 s9, s9, 0x18000
	v_or_b32_e32 v223, s9, v179
	v_add_u32_e32 v233, s9, v176
	s_waitcnt vmcnt(8) lgkmcnt(0)
	s_barrier
	v_mfma_f32_32x32x16_bf16 v[112:127], v[150:153], v[142:145], v[112:127]
	v_mfma_f32_32x32x16_bf16 v[96:111], v[150:153], v[130:133], v[96:111]
	v_add_u32_e32 v206, v223, v177
	v_add_u32_e32 v234, v233, v177
	ds_read_b128 v[202:205], v206 offset:16384
	ds_read_b128 v[206:209], v206 offset:18432
	ds_read_b128 v[210:213], v234
	ds_read_b128 v[214:217], v234 offset:2048
	ds_read_b128 v[224:227], v234 offset:4096
	ds_read_b128 v[234:237], v234 offset:6144
	v_mfma_f32_32x32x16_bf16 v[80:95], v[146:149], v[142:145], v[80:95]
	v_mfma_f32_32x32x16_bf16 v[64:79], v[146:149], v[130:133], v[64:79]
	v_readfirstlane_b32 s9, v222
	s_mov_b32 m0, s9
	s_nop 0
	global_load_lds_dwordx4 v[170:171], off
	v_mfma_f32_32x32x16_bf16 v[48:63], v[138:141], v[142:145], v[48:63]
	v_mfma_f32_32x32x16_bf16 v[32:47], v[138:141], v[130:133], v[32:47]
	s_add_i32 s10, s9, 0x2000
	v_lshl_add_u64 v[150:151], v[170:171], 0, s[12:13]
	s_mov_b32 m0, s10
	s_nop 0
	global_load_lds_dwordx4 v[150:151], off
	v_mfma_f32_32x32x16_bf16 v[16:31], v[134:137], v[142:145], v[16:31]
	v_mfma_f32_32x32x16_bf16 v[0:15], v[134:137], v[130:133], v[0:15]
	v_add_u32_e32 v130, v223, v178
	v_add_u32_e32 v134, v233, v178
	ds_read_b128 v[142:145], v130 offset:16384
	ds_read_b128 v[130:133], v130 offset:18432
	ds_read_b128 v[150:153], v134
	ds_read_b128 v[146:149], v134 offset:2048
	ds_read_b128 v[138:141], v134 offset:4096
	ds_read_b128 v[134:137], v134 offset:6144
	s_waitcnt lgkmcnt(9)
	v_mfma_f32_32x32x16_bf16 v[112:127], v[210:213], v[202:205], v[112:127]
	s_add_i32 s10, s9, 0x6000
	s_addk_i32 s9, 0x4000
	v_mfma_f32_32x32x16_bf16 v[96:111], v[210:213], v[206:209], v[96:111]
	s_mov_b32 m0, s9
	s_nop 0
	global_load_lds_dwordx4 v[172:173], off
	v_lshl_add_u64 v[222:223], v[172:173], 0, s[12:13]
	s_waitcnt lgkmcnt(8)
	v_mfma_f32_32x32x16_bf16 v[80:95], v[214:217], v[202:205], v[80:95]
	v_mfma_f32_32x32x16_bf16 v[64:79], v[214:217], v[206:209], v[64:79]
	s_waitcnt lgkmcnt(7)
	v_mfma_f32_32x32x16_bf16 v[48:63], v[224:227], v[202:205], v[48:63]
	v_mfma_f32_32x32x16_bf16 v[32:47], v[224:227], v[206:209], v[32:47]
	s_mov_b32 m0, s10
	s_nop 0
	global_load_lds_dwordx4 v[222:223], off
	s_waitcnt lgkmcnt(6)
	v_mfma_f32_32x32x16_bf16 v[16:31], v[234:237], v[202:205], v[16:31]
	s_add_i32 s8, s8, 0x8000
	v_lshl_add_u64 v[170:171], v[170:171], 0, 64
	v_lshl_add_u64 v[172:173], v[172:173], 0, 64
	s_cmp_eq_u32 s8, 0x200000
	v_mfma_f32_32x32x16_bf16 v[0:15], v[234:237], v[206:209], v[0:15]
	s_cbranch_scc0 .LBB0_2226
	s_branch .Lktail_5
.Lky_5:
	s_and_b32 s9, s8, 0x18000
	v_add_u32_e32 v222, s9, v180
	s_add_i32 s9, s8, 0xfffe8000
	s_and_b32 s9, s9, 0x18000
	v_or_b32_e32 v223, s9, v179
	v_add_u32_e32 v233, s9, v176
	s_waitcnt vmcnt(8) lgkmcnt(0)
	s_barrier
	v_add_u32_e32 v206, v223, v177
	v_add_u32_e32 v234, v233, v177
	ds_read_b128 v[202:205], v206 offset:16384
	ds_read_b128 v[206:209], v206 offset:18432
	ds_read_b128 v[210:213], v234
	ds_read_b128 v[214:217], v234 offset:2048
	ds_read_b128 v[224:227], v234 offset:4096
	ds_read_b128 v[234:237], v234 offset:6144
	v_mfma_f32_32x32x16_bf16 v[112:127], v[150:153], v[142:145], v[112:127]
	v_mfma_f32_32x32x16_bf16 v[96:111], v[150:153], v[130:133], v[96:111]
	v_readfirstlane_b32 s9, v222
	s_mov_b32 m0, s9
	s_nop 0
	global_load_lds_dwordx4 v[170:171], off
	v_mfma_f32_32x32x16_bf16 v[80:95], v[146:149], v[142:145], v[80:95]
	v_mfma_f32_32x32x16_bf16 v[64:79], v[146:149], v[130:133], v[64:79]
	v_mfma_f32_32x32x16_bf16 v[48:63], v[138:141], v[142:145], v[48:63]
	v_mfma_f32_32x32x16_bf16 v[32:47], v[138:141], v[130:133], v[32:47]
	s_add_i32 s10, s9, 0x2000
	v_lshl_add_u64 v[150:151], v[170:171], 0, s[12:13]
	s_mov_b32 m0, s10
	s_nop 0
	global_load_lds_dwordx4 v[150:151], off
	v_mfma_f32_32x32x16_bf16 v[16:31], v[134:137], v[142:145], v[16:31]
	v_mfma_f32_32x32x16_bf16 v[0:15], v[134:137], v[130:133], v[0:15]
	v_add_u32_e32 v130, v223, v178
	v_add_u32_e32 v134, v233, v178
	ds_read_b128 v[142:145], v130 offset:16384
	ds_read_b128 v[130:133], v130 offset:18432
	ds_read_b128 v[150:153], v134
	ds_read_b128 v[146:149], v134 offset:2048
	ds_read_b128 v[138:141], v134 offset:4096
	ds_read_b128 v[134:137], v134 offset:6144
	s_waitcnt lgkmcnt(9)
	v_mfma_f32_32x32x16_bf16 v[112:127], v[210:213], v[202:205], v[112:127]
	s_add_i32 s10, s9, 0x6000
	s_addk_i32 s9, 0x4000
	v_mfma_f32_32x32x16_bf16 v[96:111], v[210:213], v[206:209], v[96:111]
	s_mov_b32 m0, s9
	s_nop 0
	global_load_lds_dwordx4 v[172:173], off
	v_lshl_add_u64 v[222:223], v[172:173], 0, s[12:13]
	s_waitcnt lgkmcnt(8)
	v_mfma_f32_32x32x16_bf16 v[80:95], v[214:217], v[202:205], v[80:95]
	v_mfma_f32_32x32x16_bf16 v[64:79], v[214:217], v[206:209], v[64:79]
	s_waitcnt lgkmcnt(7)
	v_mfma_f32_32x32x16_bf16 v[48:63], v[224:227], v[202:205], v[48:63]
	v_mfma_f32_32x32x16_bf16 v[32:47], v[224:227], v[206:209], v[32:47]
	s_mov_b32 m0, s10
	s_nop 0
	global_load_lds_dwordx4 v[222:223], off
	s_waitcnt lgkmcnt(6)
	v_mfma_f32_32x32x16_bf16 v[16:31], v[234:237], v[202:205], v[16:31]
	s_add_i32 s8, s8, 0x8000
	v_lshl_add_u64 v[170:171], v[170:171], 0, 64
	v_lshl_add_u64 v[172:173], v[172:173], 0, 64
	s_cmp_eq_u32 s8, 0x200000
	v_mfma_f32_32x32x16_bf16 v[0:15], v[234:237], v[206:209], v[0:15]
	s_cbranch_scc0 .Lky_5
.Lktail_5:
	s_waitcnt vmcnt(8) lgkmcnt(0)
	s_barrier
	v_add_u32_e32 v202, v179, v177
	v_add_u32_e32 v222, v176, v177
	ds_read_b128 v[170:173], v202 offset:49152
	ds_read_b128 v[202:205], v202 offset:51200
	ds_read_b128 v[206:209], v222 offset:32768
	ds_read_b128 v[210:213], v222 offset:34816
	ds_read_b128 v[214:217], v222 offset:36864
	ds_read_b128 v[224:227], v222 offset:38912
	s_waitcnt lgkmcnt(9)
	v_mfma_f32_32x32x16_bf16 v[112:127], v[150:153], v[142:145], v[112:127]
	v_mfma_f32_32x32x16_bf16 v[96:111], v[150:153], v[130:133], v[96:111]
	s_waitcnt lgkmcnt(8)
	v_mfma_f32_32x32x16_bf16 v[80:95], v[146:149], v[142:145], v[80:95]
	v_mfma_f32_32x32x16_bf16 v[64:79], v[146:149], v[130:133], v[64:79]
	s_waitcnt lgkmcnt(7)
	v_mfma_f32_32x32x16_bf16 v[48:63], v[138:141], v[142:145], v[48:63]
	v_mfma_f32_32x32x16_bf16 v[32:47], v[138:141], v[130:133], v[32:47]
	s_waitcnt lgkmcnt(6)
	v_mfma_f32_32x32x16_bf16 v[16:31], v[134:137], v[142:145], v[16:31]
	v_mfma_f32_32x32x16_bf16 v[0:15], v[134:137], v[130:133], v[0:15]
	v_add_u32_e32 v134, v179, v178
	v_add_u32_e32 v150, v176, v178
	ds_read_b128 v[130:133], v134 offset:49152
	ds_read_b128 v[134:137], v134 offset:51200
	ds_read_b128 v[138:141], v150 offset:32768
	ds_read_b128 v[142:145], v150 offset:34816
	ds_read_b128 v[146:149], v150 offset:36864
	ds_read_b128 v[150:153], v150 offset:38912
	s_waitcnt lgkmcnt(9)
	v_mfma_f32_32x32x16_bf16 v[112:127], v[206:209], v[170:173], v[112:127]
	v_mfma_f32_32x32x16_bf16 v[96:111], v[206:209], v[202:205], v[96:111]
	s_waitcnt lgkmcnt(8)
	v_mfma_f32_32x32x16_bf16 v[80:95], v[210:213], v[170:173], v[80:95]
	v_mfma_f32_32x32x16_bf16 v[64:79], v[210:213], v[202:205], v[64:79]
	s_waitcnt lgkmcnt(7)
	v_mfma_f32_32x32x16_bf16 v[48:63], v[214:217], v[170:173], v[48:63]
	v_mfma_f32_32x32x16_bf16 v[32:47], v[214:217], v[202:205], v[32:47]
	s_waitcnt lgkmcnt(6)
	v_mfma_f32_32x32x16_bf16 v[0:15], v[224:227], v[202:205], v[0:15]
	s_waitcnt vmcnt(4) lgkmcnt(0)
	s_barrier
	v_add_u32_e32 v202, v199, v177
	v_add_u32_e32 v222, v200, v177
	v_mfma_f32_32x32x16_bf16 v[16:31], v[224:227], v[170:173], v[16:31]
	ds_read_b128 v[170:173], v202 offset:16384
	ds_read_b128 v[202:205], v202 offset:18432
	ds_read_b128 v[206:209], v222
	ds_read_b128 v[210:213], v222 offset:2048
	ds_read_b128 v[214:217], v222 offset:4096
	ds_read_b128 v[224:227], v222 offset:6144
	s_waitcnt lgkmcnt(9)
	v_mfma_f32_32x32x16_bf16 v[112:127], v[138:141], v[130:133], v[112:127]
	v_mfma_f32_32x32x16_bf16 v[96:111], v[138:141], v[134:137], v[96:111]
	s_waitcnt lgkmcnt(8)
	v_mfma_f32_32x32x16_bf16 v[80:95], v[142:145], v[130:133], v[80:95]
	v_mfma_f32_32x32x16_bf16 v[64:79], v[142:145], v[134:137], v[64:79]
	s_waitcnt lgkmcnt(7)
	v_mfma_f32_32x32x16_bf16 v[48:63], v[146:149], v[130:133], v[48:63]
	v_mfma_f32_32x32x16_bf16 v[32:47], v[146:149], v[134:137], v[32:47]
	s_waitcnt lgkmcnt(6)
	v_mfma_f32_32x32x16_bf16 v[16:31], v[150:153], v[130:133], v[16:31]
	v_mfma_f32_32x32x16_bf16 v[0:15], v[150:153], v[134:137], v[0:15]
	v_add_u32_e32 v134, v199, v178
	v_add_u32_e32 v150, v200, v178
	ds_read_b128 v[130:133], v134 offset:16384
	ds_read_b128 v[134:137], v134 offset:18432
	ds_read_b128 v[138:141], v150
	ds_read_b128 v[142:145], v150 offset:2048
	ds_read_b128 v[146:149], v150 offset:4096
	ds_read_b128 v[150:153], v150 offset:6144
	s_waitcnt lgkmcnt(9)
	v_mfma_f32_32x32x16_bf16 v[112:127], v[206:209], v[170:173], v[112:127]
	v_mfma_f32_32x32x16_bf16 v[96:111], v[206:209], v[202:205], v[96:111]
	s_waitcnt lgkmcnt(8)
	v_mfma_f32_32x32x16_bf16 v[80:95], v[210:213], v[170:173], v[80:95]
	v_mfma_f32_32x32x16_bf16 v[64:79], v[210:213], v[202:205], v[64:79]
	s_waitcnt lgkmcnt(7)
	v_mfma_f32_32x32x16_bf16 v[48:63], v[214:217], v[170:173], v[48:63]
	v_mfma_f32_32x32x16_bf16 v[32:47], v[214:217], v[202:205], v[32:47]
	s_waitcnt lgkmcnt(6)
	v_mfma_f32_32x32x16_bf16 v[0:15], v[224:227], v[202:205], v[0:15]
	s_waitcnt vmcnt(0) lgkmcnt(0)
	s_barrier
	v_add_u32_e32 v202, v197, v177
	v_add_u32_e32 v222, v198, v177
	v_mfma_f32_32x32x16_bf16 v[16:31], v[224:227], v[170:173], v[16:31]
	ds_read_b128 v[170:173], v202 offset:16384
	ds_read_b128 v[202:205], v202 offset:18432
	ds_read_b128 v[206:209], v222
	ds_read_b128 v[210:213], v222 offset:2048
	ds_read_b128 v[214:217], v222 offset:4096
	ds_read_b128 v[224:227], v222 offset:6144
	s_waitcnt lgkmcnt(9)
	v_mfma_f32_32x32x16_bf16 v[112:127], v[138:141], v[130:133], v[112:127]
	v_mfma_f32_32x32x16_bf16 v[96:111], v[138:141], v[134:137], v[96:111]
	s_waitcnt lgkmcnt(8)
	v_mfma_f32_32x32x16_bf16 v[80:95], v[142:145], v[130:133], v[80:95]
	v_mfma_f32_32x32x16_bf16 v[64:79], v[142:145], v[134:137], v[64:79]
	s_waitcnt lgkmcnt(7)
	v_mfma_f32_32x32x16_bf16 v[48:63], v[146:149], v[130:133], v[48:63]
	v_mfma_f32_32x32x16_bf16 v[32:47], v[146:149], v[134:137], v[32:47]
	s_waitcnt lgkmcnt(6)
	v_mfma_f32_32x32x16_bf16 v[16:31], v[150:153], v[130:133], v[16:31]
	v_mfma_f32_32x32x16_bf16 v[0:15], v[150:153], v[134:137], v[0:15]
	v_add_u32_e32 v134, v197, v178
	v_add_u32_e32 v150, v198, v178
	ds_read_b128 v[130:133], v134 offset:16384
	ds_read_b128 v[134:137], v134 offset:18432
	ds_read_b128 v[138:141], v150
	ds_read_b128 v[142:145], v150 offset:2048
	ds_read_b128 v[146:149], v150 offset:4096
	ds_read_b128 v[150:153], v150 offset:6144
	s_waitcnt lgkmcnt(9)
	v_mfma_f32_32x32x16_bf16 v[112:127], v[206:209], v[170:173], v[112:127]
	v_mfma_f32_32x32x16_bf16 v[96:111], v[206:209], v[202:205], v[96:111]
	s_waitcnt lgkmcnt(8)
	v_mfma_f32_32x32x16_bf16 v[80:95], v[210:213], v[170:173], v[80:95]
	v_mfma_f32_32x32x16_bf16 v[64:79], v[210:213], v[202:205], v[64:79]
	s_waitcnt lgkmcnt(7)
	v_mfma_f32_32x32x16_bf16 v[48:63], v[214:217], v[170:173], v[48:63]
	v_mfma_f32_32x32x16_bf16 v[32:47], v[214:217], v[202:205], v[32:47]
	s_waitcnt lgkmcnt(6)
	v_mfma_f32_32x32x16_bf16 v[16:31], v[224:227], v[170:173], v[16:31]
	v_mfma_f32_32x32x16_bf16 v[0:15], v[224:227], v[202:205], v[0:15]
	s_waitcnt lgkmcnt(3)
	v_mfma_f32_32x32x16_bf16 v[112:127], v[138:141], v[130:133], v[112:127]
	s_waitcnt lgkmcnt(2)
	v_mfma_f32_32x32x16_bf16 v[80:95], v[142:145], v[130:133], v[80:95]
	s_waitcnt lgkmcnt(1)
	v_mfma_f32_32x32x16_bf16 v[48:63], v[146:149], v[130:133], v[48:63]
	s_waitcnt lgkmcnt(0)
	v_mfma_f32_32x32x16_bf16 v[16:31], v[150:153], v[130:133], v[16:31]
	v_add_u32_e32 v132, s6, v174
	v_or_b32_e32 v130, s7, v128
	v_ashrrev_i32_e32 v131, 31, v130
	v_lshl_add_u64 v[130:131], v[130:131], 1, v[158:159]
	v_readlane_b32 s6, v252, 7
	s_add_i32 s4, s4, s6
	s_add_i32 s2, s2, s6
	v_mfma_f32_32x32x16_bf16 v[96:111], v[138:141], v[134:137], v[96:111]
	v_or_b32_e32 v138, v132, v181
	v_ashrrev_i32_e32 v139, 31, v138
	v_readlane_b32 s6, v252, 8
	s_add_i32 s5, s5, s6
	s_cmp_gt_i32 s4, 31
	v_mfma_f32_32x32x16_bf16 v[64:79], v[142:145], v[134:137], v[64:79]
	v_mfma_f32_32x32x16_bf16 v[32:47], v[146:149], v[134:137], v[32:47]
	v_mfma_f32_32x32x16_bf16 v[0:15], v[150:153], v[134:137], v[0:15]
	v_and_b32_e32 v134, 0xff, v138
	v_lshl_add_u32 v134, v134, 2, v250
	ds_read_b96 v[134:136], v134
	v_lshlrev_b64 v[138:139], 11, v[138:139]
	v_lshl_add_u64 v[138:139], v[130:131], 0, v[138:139]
	s_waitcnt lgkmcnt(0)
	v_mul_f32_e32 v112, v112, v134
	v_mul_f32_e32 v96, v96, v134
	v_cvt_pk_bf16_f32 v112, v112, s0
	v_cvt_pk_bf16_f32 v96, v96, s0
	global_store_short v[138:139], v112, off
	global_store_short v[138:139], v96, off offset:64
	v_or_b32_e32 v138, v132, v182
	v_ashrrev_i32_e32 v139, 31, v138
	v_lshlrev_b64 v[138:139], 11, v[138:139]
	v_mul_f32_e32 v96, v113, v135
	v_lshl_add_u64 v[138:139], v[130:131], 0, v[138:139]
	v_cvt_pk_bf16_f32 v96, v96, s0
	global_store_short v[138:139], v96, off
	v_mul_f32_e32 v96, v97, v135
	v_cvt_pk_bf16_f32 v96, v96, s0
	global_store_short v[138:139], v96, off offset:64
	v_or_b32_e32 v96, v132, v183
	v_ashrrev_i32_e32 v97, 31, v96
	v_lshlrev_b64 v[96:97], 11, v[96:97]
	v_mul_f32_e32 v112, v114, v136
	v_mul_f32_e32 v98, v98, v136
	v_lshl_add_u64 v[96:97], v[130:131], 0, v[96:97]
	v_cvt_pk_bf16_f32 v112, v112, s0
	v_cvt_pk_bf16_f32 v98, v98, s0
	global_store_short v[96:97], v112, off
	global_store_short v[96:97], v98, off offset:64
	v_or_b32_e32 v96, v132, v184
	v_ashrrev_i32_e32 v97, 31, v96
	v_and_b32_e32 v112, 0xff, v96
	v_lshl_add_u32 v112, v112, 2, v250
	ds_read_b32 v98, v112
	v_lshlrev_b64 v[96:97], 11, v[96:97]
	v_lshl_add_u64 v[96:97], v[130:131], 0, v[96:97]
	s_waitcnt lgkmcnt(0)
	v_mul_f32_e32 v112, v115, v98
	v_cvt_pk_bf16_f32 v112, v112, s0
	global_store_short v[96:97], v112, off
	v_mul_f32_e32 v98, v99, v98
	v_or_b32_e32 v112, v132, v185
	v_cvt_pk_bf16_f32 v98, v98, s0
	v_ashrrev_i32_e32 v113, 31, v112
	global_store_short v[96:97], v98, off offset:64
	v_and_b32_e32 v96, 0xff, v112
	v_lshl_add_u32 v96, v96, 2, v250
	ds_read_b96 v[96:98], v96
	v_lshlrev_b64 v[112:113], 11, v[112:113]
	v_lshl_add_u64 v[112:113], v[130:131], 0, v[112:113]
	s_waitcnt lgkmcnt(0)
	v_mul_f32_e32 v99, v116, v96
	v_mul_f32_e32 v96, v100, v96
	v_cvt_pk_bf16_f32 v99, v99, s0
	v_cvt_pk_bf16_f32 v96, v96, s0
	global_store_short v[112:113], v99, off
	global_store_short v[112:113], v96, off offset:64
	v_or_b32_e32 v112, v132, v186
	v_ashrrev_i32_e32 v113, 31, v112
	v_lshlrev_b64 v[112:113], 11, v[112:113]
	v_mul_f32_e32 v96, v117, v97
	v_lshl_add_u64 v[112:113], v[130:131], 0, v[112:113]
	v_cvt_pk_bf16_f32 v96, v96, s0
	global_store_short v[112:113], v96, off
	v_mul_f32_e32 v96, v101, v97
	v_cvt_pk_bf16_f32 v96, v96, s0
	global_store_short v[112:113], v96, off offset:64
	v_or_b32_e32 v96, v132, v187
	v_ashrrev_i32_e32 v97, 31, v96
	v_lshlrev_b64 v[96:97], 11, v[96:97]
	v_mul_f32_e32 v99, v118, v98
	v_mul_f32_e32 v98, v102, v98
	v_lshl_add_u64 v[96:97], v[130:131], 0, v[96:97]
	v_cvt_pk_bf16_f32 v99, v99, s0
	v_cvt_pk_bf16_f32 v98, v98, s0
	global_store_short v[96:97], v99, off
	global_store_short v[96:97], v98, off offset:64
	v_or_b32_e32 v96, v132, v188
	v_ashrrev_i32_e32 v97, 31, v96
	v_and_b32_e32 v98, 0xff, v96
	v_lshl_add_u32 v98, v98, 2, v250
	ds_read_b32 v98, v98
	v_lshlrev_b64 v[96:97], 11, v[96:97]
	v_or_b32_e32 v100, v132, v189
	v_lshl_add_u64 v[96:97], v[130:131], 0, v[96:97]
	v_ashrrev_i32_e32 v101, 31, v100
	s_waitcnt lgkmcnt(0)
	v_mul_f32_e32 v99, v119, v98
	v_mul_f32_e32 v98, v103, v98
	v_cvt_pk_bf16_f32 v99, v99, s0
	v_cvt_pk_bf16_f32 v98, v98, s0
	global_store_short v[96:97], v99, off
	global_store_short v[96:97], v98, off offset:64
	v_and_b32_e32 v96, 0xff, v100
	v_lshl_add_u32 v96, v96, 2, v250
	ds_read_b96 v[96:98], v96
	v_lshlrev_b64 v[100:101], 11, v[100:101]
	v_lshl_add_u64 v[100:101], v[130:131], 0, v[100:101]
	s_waitcnt lgkmcnt(0)
	v_mul_f32_e32 v99, v120, v96
	v_mul_f32_e32 v96, v104, v96
	v_cvt_pk_bf16_f32 v99, v99, s0
	v_cvt_pk_bf16_f32 v96, v96, s0
	global_store_short v[100:101], v99, off
	global_store_short v[100:101], v96, off offset:64
	v_or_b32_e32 v100, v132, v190
	v_ashrrev_i32_e32 v101, 31, v100
	v_lshlrev_b64 v[100:101], 11, v[100:101]
	v_mul_f32_e32 v96, v121, v97
	v_lshl_add_u64 v[100:101], v[130:131], 0, v[100:101]
	v_cvt_pk_bf16_f32 v96, v96, s0
	global_store_short v[100:101], v96, off
	v_mul_f32_e32 v96, v105, v97
	v_cvt_pk_bf16_f32 v96, v96, s0
	global_store_short v[100:101], v96, off offset:64
	v_or_b32_e32 v96, v132, v191
	v_ashrrev_i32_e32 v97, 31, v96
	v_lshlrev_b64 v[96:97], 11, v[96:97]
	v_mul_f32_e32 v99, v122, v98
	v_mul_f32_e32 v98, v106, v98
	v_lshl_add_u64 v[96:97], v[130:131], 0, v[96:97]
	v_cvt_pk_bf16_f32 v99, v99, s0
	v_cvt_pk_bf16_f32 v98, v98, s0
	global_store_short v[96:97], v99, off
	global_store_short v[96:97], v98, off offset:64
	v_or_b32_e32 v96, v132, v192
	v_ashrrev_i32_e32 v97, 31, v96
	v_and_b32_e32 v98, 0xff, v96
	v_lshl_add_u32 v98, v98, 2, v250
	ds_read_b32 v98, v98
	v_lshlrev_b64 v[96:97], 11, v[96:97]
	v_or_b32_e32 v100, v132, v193
	v_lshl_add_u64 v[96:97], v[130:131], 0, v[96:97]
	v_ashrrev_i32_e32 v101, 31, v100
	s_waitcnt lgkmcnt(0)
	v_mul_f32_e32 v99, v123, v98
	v_mul_f32_e32 v98, v107, v98
	v_cvt_pk_bf16_f32 v99, v99, s0
	v_cvt_pk_bf16_f32 v98, v98, s0
	global_store_short v[96:97], v99, off
	global_store_short v[96:97], v98, off offset:64
	v_and_b32_e32 v96, 0xff, v100
	v_lshl_add_u32 v96, v96, 2, v250
	ds_read_b96 v[96:98], v96
	v_lshlrev_b64 v[100:101], 11, v[100:101]
	v_lshl_add_u64 v[100:101], v[130:131], 0, v[100:101]
	s_waitcnt lgkmcnt(0)
	v_mul_f32_e32 v99, v124, v96
	v_mul_f32_e32 v96, v108, v96
	v_cvt_pk_bf16_f32 v99, v99, s0
	v_cvt_pk_bf16_f32 v96, v96, s0
	global_store_short v[100:101], v99, off
	global_store_short v[100:101], v96, off offset:64
	v_or_b32_e32 v100, v132, v194
	v_ashrrev_i32_e32 v101, 31, v100
	v_lshlrev_b64 v[100:101], 11, v[100:101]
	v_mul_f32_e32 v96, v125, v97
	v_lshl_add_u64 v[100:101], v[130:131], 0, v[100:101]
	v_cvt_pk_bf16_f32 v96, v96, s0
	global_store_short v[100:101], v96, off
	v_mul_f32_e32 v96, v109, v97
	v_cvt_pk_bf16_f32 v96, v96, s0
	global_store_short v[100:101], v96, off offset:64
	v_or_b32_e32 v96, v132, v195
	v_ashrrev_i32_e32 v97, 31, v96
	v_lshlrev_b64 v[96:97], 11, v[96:97]
	v_mul_f32_e32 v99, v126, v98
	v_mul_f32_e32 v98, v110, v98
	v_lshl_add_u64 v[96:97], v[130:131], 0, v[96:97]
	v_cvt_pk_bf16_f32 v99, v99, s0
	v_cvt_pk_bf16_f32 v98, v98, s0
	global_store_short v[96:97], v99, off
	global_store_short v[96:97], v98, off offset:64
	v_or_b32_e32 v96, v132, v196
	v_ashrrev_i32_e32 v97, 31, v96
	v_and_b32_e32 v98, 0xff, v96
	v_lshl_add_u32 v98, v98, 2, v250
	ds_read_b32 v98, v98
	v_lshlrev_b64 v[96:97], 11, v[96:97]
	v_lshl_add_u64 v[96:97], v[130:131], 0, v[96:97]
	s_waitcnt lgkmcnt(0)
	v_mul_f32_e32 v99, v127, v98
	v_mul_f32_e32 v98, v111, v98
	v_cvt_pk_bf16_f32 v99, v99, s0
	v_cvt_pk_bf16_f32 v98, v98, s0
	global_store_short v[96:97], v99, off
	global_store_short v[96:97], v98, off offset:64
	v_or_b32_e32 v96, 32, v132
	v_or_b32_e32 v102, v96, v181
	v_ashrrev_i32_e32 v103, 31, v102
	v_and_b32_e32 v98, 0xff, v102
	v_lshl_add_u32 v98, v98, 2, v250
	ds_read_b96 v[98:100], v98
	v_lshlrev_b64 v[102:103], 11, v[102:103]
	v_lshl_add_u64 v[102:103], v[130:131], 0, v[102:103]
	s_waitcnt lgkmcnt(0)
	v_mul_f32_e32 v80, v80, v98
	v_mul_f32_e32 v64, v64, v98
	v_cvt_pk_bf16_f32 v80, v80, s0
	v_cvt_pk_bf16_f32 v64, v64, s0
	global_store_short v[102:103], v80, off
	global_store_short v[102:103], v64, off offset:64
	v_or_b32_e32 v102, v96, v182
	v_ashrrev_i32_e32 v103, 31, v102
	v_lshlrev_b64 v[102:103], 11, v[102:103]
	v_mul_f32_e32 v64, v81, v99
	v_lshl_add_u64 v[102:103], v[130:131], 0, v[102:103]
	v_cvt_pk_bf16_f32 v64, v64, s0
	global_store_short v[102:103], v64, off
	v_mul_f32_e32 v64, v65, v99
	v_cvt_pk_bf16_f32 v64, v64, s0
	global_store_short v[102:103], v64, off offset:64
	v_or_b32_e32 v64, v96, v183
	v_ashrrev_i32_e32 v65, 31, v64
	v_lshlrev_b64 v[64:65], 11, v[64:65]
	v_mul_f32_e32 v80, v82, v100
	v_mul_f32_e32 v66, v66, v100
	v_lshl_add_u64 v[64:65], v[130:131], 0, v[64:65]
	v_cvt_pk_bf16_f32 v80, v80, s0
	v_cvt_pk_bf16_f32 v66, v66, s0
	global_store_short v[64:65], v80, off
	global_store_short v[64:65], v66, off offset:64
	v_or_b32_e32 v64, v96, v184
	v_ashrrev_i32_e32 v65, 31, v64
	v_and_b32_e32 v80, 0xff, v64
	v_lshl_add_u32 v80, v80, 2, v250
	ds_read_b32 v66, v80
	v_lshlrev_b64 v[64:65], 11, v[64:65]
	v_lshl_add_u64 v[64:65], v[130:131], 0, v[64:65]
	s_waitcnt lgkmcnt(0)
	v_mul_f32_e32 v80, v83, v66
	v_cvt_pk_bf16_f32 v80, v80, s0
	global_store_short v[64:65], v80, off
	v_mul_f32_e32 v66, v67, v66
	v_or_b32_e32 v80, v96, v185
	v_cvt_pk_bf16_f32 v66, v66, s0
	v_ashrrev_i32_e32 v81, 31, v80
	global_store_short v[64:65], v66, off offset:64
	v_and_b32_e32 v64, 0xff, v80
	v_lshl_add_u32 v64, v64, 2, v250
	ds_read_b96 v[64:66], v64
	v_lshlrev_b64 v[80:81], 11, v[80:81]
	v_lshl_add_u64 v[80:81], v[130:131], 0, v[80:81]
	s_waitcnt lgkmcnt(0)
	v_mul_f32_e32 v67, v84, v64
	v_mul_f32_e32 v64, v68, v64
	v_cvt_pk_bf16_f32 v67, v67, s0
	v_cvt_pk_bf16_f32 v64, v64, s0
	global_store_short v[80:81], v67, off
	global_store_short v[80:81], v64, off offset:64
	v_or_b32_e32 v80, v96, v186
	v_ashrrev_i32_e32 v81, 31, v80
	v_lshlrev_b64 v[80:81], 11, v[80:81]
	v_mul_f32_e32 v64, v85, v65
	v_lshl_add_u64 v[80:81], v[130:131], 0, v[80:81]
	v_cvt_pk_bf16_f32 v64, v64, s0
	global_store_short v[80:81], v64, off
	v_mul_f32_e32 v64, v69, v65
	v_cvt_pk_bf16_f32 v64, v64, s0
	global_store_short v[80:81], v64, off offset:64
	v_or_b32_e32 v64, v96, v187
	v_ashrrev_i32_e32 v65, 31, v64
	v_lshlrev_b64 v[64:65], 11, v[64:65]
	v_mul_f32_e32 v67, v86, v66
	v_mul_f32_e32 v66, v70, v66
	v_lshl_add_u64 v[64:65], v[130:131], 0, v[64:65]
	v_cvt_pk_bf16_f32 v67, v67, s0
	v_cvt_pk_bf16_f32 v66, v66, s0
	global_store_short v[64:65], v67, off
	global_store_short v[64:65], v66, off offset:64
	v_or_b32_e32 v64, v96, v188
	v_ashrrev_i32_e32 v65, 31, v64
	v_and_b32_e32 v66, 0xff, v64
	v_lshl_add_u32 v66, v66, 2, v250
	ds_read_b32 v66, v66
	v_lshlrev_b64 v[64:65], 11, v[64:65]
	v_or_b32_e32 v68, v96, v189
	v_lshl_add_u64 v[64:65], v[130:131], 0, v[64:65]
	v_ashrrev_i32_e32 v69, 31, v68
	s_waitcnt lgkmcnt(0)
	v_mul_f32_e32 v67, v87, v66
	v_mul_f32_e32 v66, v71, v66
	v_cvt_pk_bf16_f32 v67, v67, s0
	v_cvt_pk_bf16_f32 v66, v66, s0
	global_store_short v[64:65], v67, off
	global_store_short v[64:65], v66, off offset:64
	v_and_b32_e32 v64, 0xff, v68
	v_lshl_add_u32 v64, v64, 2, v250
	ds_read_b96 v[64:66], v64
	v_lshlrev_b64 v[68:69], 11, v[68:69]
	v_lshl_add_u64 v[68:69], v[130:131], 0, v[68:69]
	s_waitcnt lgkmcnt(0)
	v_mul_f32_e32 v67, v88, v64
	v_mul_f32_e32 v64, v72, v64
	v_cvt_pk_bf16_f32 v67, v67, s0
	v_cvt_pk_bf16_f32 v64, v64, s0
	global_store_short v[68:69], v67, off
	global_store_short v[68:69], v64, off offset:64
	v_or_b32_e32 v68, v96, v190
	v_ashrrev_i32_e32 v69, 31, v68
	v_lshlrev_b64 v[68:69], 11, v[68:69]
	v_mul_f32_e32 v64, v89, v65
	v_lshl_add_u64 v[68:69], v[130:131], 0, v[68:69]
	v_cvt_pk_bf16_f32 v64, v64, s0
	global_store_short v[68:69], v64, off
	v_mul_f32_e32 v64, v73, v65
	v_cvt_pk_bf16_f32 v64, v64, s0
	global_store_short v[68:69], v64, off offset:64
	v_or_b32_e32 v64, v96, v191
	v_ashrrev_i32_e32 v65, 31, v64
	v_lshlrev_b64 v[64:65], 11, v[64:65]
	v_mul_f32_e32 v67, v90, v66
	v_mul_f32_e32 v66, v74, v66
	v_lshl_add_u64 v[64:65], v[130:131], 0, v[64:65]
	v_cvt_pk_bf16_f32 v67, v67, s0
	v_cvt_pk_bf16_f32 v66, v66, s0
	global_store_short v[64:65], v67, off
	global_store_short v[64:65], v66, off offset:64
	v_or_b32_e32 v64, v96, v192
	v_ashrrev_i32_e32 v65, 31, v64
	v_and_b32_e32 v66, 0xff, v64
	v_lshl_add_u32 v66, v66, 2, v250
	ds_read_b32 v66, v66
	v_lshlrev_b64 v[64:65], 11, v[64:65]
	v_or_b32_e32 v68, v96, v193
	v_lshl_add_u64 v[64:65], v[130:131], 0, v[64:65]
	v_ashrrev_i32_e32 v69, 31, v68
	s_waitcnt lgkmcnt(0)
	v_mul_f32_e32 v67, v91, v66
	v_mul_f32_e32 v66, v75, v66
	v_cvt_pk_bf16_f32 v67, v67, s0
	v_cvt_pk_bf16_f32 v66, v66, s0
	global_store_short v[64:65], v67, off
	global_store_short v[64:65], v66, off offset:64
	v_and_b32_e32 v64, 0xff, v68
	v_lshl_add_u32 v64, v64, 2, v250
	ds_read_b96 v[64:66], v64
	v_lshlrev_b64 v[68:69], 11, v[68:69]
	v_lshl_add_u64 v[68:69], v[130:131], 0, v[68:69]
	s_waitcnt lgkmcnt(0)
	v_mul_f32_e32 v67, v92, v64
	v_mul_f32_e32 v64, v76, v64
	v_cvt_pk_bf16_f32 v67, v67, s0
	v_cvt_pk_bf16_f32 v64, v64, s0
	global_store_short v[68:69], v67, off
	global_store_short v[68:69], v64, off offset:64
	v_or_b32_e32 v68, v96, v194
	v_ashrrev_i32_e32 v69, 31, v68
	v_lshlrev_b64 v[68:69], 11, v[68:69]
	v_mul_f32_e32 v64, v93, v65
	v_lshl_add_u64 v[68:69], v[130:131], 0, v[68:69]
	v_cvt_pk_bf16_f32 v64, v64, s0
	global_store_short v[68:69], v64, off
	v_mul_f32_e32 v64, v77, v65
	v_cvt_pk_bf16_f32 v64, v64, s0
	global_store_short v[68:69], v64, off offset:64
	v_or_b32_e32 v64, v96, v195
	v_ashrrev_i32_e32 v65, 31, v64
	v_lshlrev_b64 v[64:65], 11, v[64:65]
	v_mul_f32_e32 v67, v94, v66
	v_mul_f32_e32 v66, v78, v66
	v_lshl_add_u64 v[64:65], v[130:131], 0, v[64:65]
	v_cvt_pk_bf16_f32 v67, v67, s0
	v_cvt_pk_bf16_f32 v66, v66, s0
	global_store_short v[64:65], v67, off
	global_store_short v[64:65], v66, off offset:64
	v_or_b32_e32 v64, v96, v196
	v_ashrrev_i32_e32 v65, 31, v64
	v_and_b32_e32 v66, 0xff, v64
	v_lshl_add_u32 v66, v66, 2, v250
	ds_read_b32 v66, v66
	v_lshlrev_b64 v[64:65], 11, v[64:65]
	v_lshl_add_u64 v[64:65], v[130:131], 0, v[64:65]
	s_waitcnt lgkmcnt(0)
	v_mul_f32_e32 v67, v95, v66
	v_mul_f32_e32 v66, v79, v66
	v_cvt_pk_bf16_f32 v67, v67, s0
	v_cvt_pk_bf16_f32 v66, v66, s0
	global_store_short v[64:65], v67, off
	global_store_short v[64:65], v66, off offset:64
	v_or_b32_e32 v64, 64, v132
	v_or_b32_e32 v70, v64, v181
	v_ashrrev_i32_e32 v71, 31, v70
	v_and_b32_e32 v66, 0xff, v70
	v_lshl_add_u32 v66, v66, 2, v250
	ds_read_b96 v[66:68], v66
	v_lshlrev_b64 v[70:71], 11, v[70:71]
	v_lshl_add_u64 v[70:71], v[130:131], 0, v[70:71]
	s_waitcnt lgkmcnt(0)
	v_mul_f32_e32 v48, v48, v66
	v_mul_f32_e32 v32, v32, v66
	v_cvt_pk_bf16_f32 v48, v48, s0
	v_cvt_pk_bf16_f32 v32, v32, s0
	global_store_short v[70:71], v48, off
	global_store_short v[70:71], v32, off offset:64
	v_or_b32_e32 v70, v64, v182
	v_ashrrev_i32_e32 v71, 31, v70
	v_lshlrev_b64 v[70:71], 11, v[70:71]
	v_mul_f32_e32 v32, v49, v67
	v_lshl_add_u64 v[70:71], v[130:131], 0, v[70:71]
	v_cvt_pk_bf16_f32 v32, v32, s0
	global_store_short v[70:71], v32, off
	v_mul_f32_e32 v32, v33, v67
	v_cvt_pk_bf16_f32 v32, v32, s0
	global_store_short v[70:71], v32, off offset:64
	v_or_b32_e32 v32, v64, v183
	v_ashrrev_i32_e32 v33, 31, v32
	v_lshlrev_b64 v[32:33], 11, v[32:33]
	v_mul_f32_e32 v48, v50, v68
	v_mul_f32_e32 v34, v34, v68
	v_lshl_add_u64 v[32:33], v[130:131], 0, v[32:33]
	v_cvt_pk_bf16_f32 v48, v48, s0
	v_cvt_pk_bf16_f32 v34, v34, s0
	global_store_short v[32:33], v48, off
	global_store_short v[32:33], v34, off offset:64
	v_or_b32_e32 v32, v64, v184
	v_ashrrev_i32_e32 v33, 31, v32
	v_and_b32_e32 v48, 0xff, v32
	v_lshl_add_u32 v48, v48, 2, v250
	ds_read_b32 v34, v48
	v_lshlrev_b64 v[32:33], 11, v[32:33]
	v_lshl_add_u64 v[32:33], v[130:131], 0, v[32:33]
	s_waitcnt lgkmcnt(0)
	v_mul_f32_e32 v48, v51, v34
	v_cvt_pk_bf16_f32 v48, v48, s0
	global_store_short v[32:33], v48, off
	v_mul_f32_e32 v34, v35, v34
	v_or_b32_e32 v48, v64, v185
	v_cvt_pk_bf16_f32 v34, v34, s0
	v_ashrrev_i32_e32 v49, 31, v48
	global_store_short v[32:33], v34, off offset:64
	v_and_b32_e32 v32, 0xff, v48
	v_lshl_add_u32 v32, v32, 2, v250
	ds_read_b96 v[32:34], v32
	v_lshlrev_b64 v[48:49], 11, v[48:49]
	v_lshl_add_u64 v[48:49], v[130:131], 0, v[48:49]
	s_waitcnt lgkmcnt(0)
	v_mul_f32_e32 v35, v52, v32
	v_mul_f32_e32 v32, v36, v32
	v_cvt_pk_bf16_f32 v35, v35, s0
	v_cvt_pk_bf16_f32 v32, v32, s0
	global_store_short v[48:49], v35, off
	global_store_short v[48:49], v32, off offset:64
	v_or_b32_e32 v48, v64, v186
	v_ashrrev_i32_e32 v49, 31, v48
	v_lshlrev_b64 v[48:49], 11, v[48:49]
	v_mul_f32_e32 v32, v53, v33
	v_lshl_add_u64 v[48:49], v[130:131], 0, v[48:49]
	v_cvt_pk_bf16_f32 v32, v32, s0
	global_store_short v[48:49], v32, off
	v_mul_f32_e32 v32, v37, v33
	v_cvt_pk_bf16_f32 v32, v32, s0
	global_store_short v[48:49], v32, off offset:64
	v_or_b32_e32 v32, v64, v187
	v_ashrrev_i32_e32 v33, 31, v32
	v_lshlrev_b64 v[32:33], 11, v[32:33]
	v_mul_f32_e32 v35, v54, v34
	v_mul_f32_e32 v34, v38, v34
	v_lshl_add_u64 v[32:33], v[130:131], 0, v[32:33]
	v_cvt_pk_bf16_f32 v35, v35, s0
	v_cvt_pk_bf16_f32 v34, v34, s0
	global_store_short v[32:33], v35, off
	global_store_short v[32:33], v34, off offset:64
	v_or_b32_e32 v32, v64, v188
	v_ashrrev_i32_e32 v33, 31, v32
	v_and_b32_e32 v34, 0xff, v32
	v_lshl_add_u32 v34, v34, 2, v250
	ds_read_b32 v34, v34
	v_lshlrev_b64 v[32:33], 11, v[32:33]
	v_or_b32_e32 v36, v64, v189
	v_lshl_add_u64 v[32:33], v[130:131], 0, v[32:33]
	v_ashrrev_i32_e32 v37, 31, v36
	s_waitcnt lgkmcnt(0)
	v_mul_f32_e32 v35, v55, v34
	v_mul_f32_e32 v34, v39, v34
	v_cvt_pk_bf16_f32 v35, v35, s0
	v_cvt_pk_bf16_f32 v34, v34, s0
	global_store_short v[32:33], v35, off
	global_store_short v[32:33], v34, off offset:64
	v_and_b32_e32 v32, 0xff, v36
	v_lshl_add_u32 v32, v32, 2, v250
	ds_read_b96 v[32:34], v32
	v_lshlrev_b64 v[36:37], 11, v[36:37]
	v_lshl_add_u64 v[36:37], v[130:131], 0, v[36:37]
	s_waitcnt lgkmcnt(0)
	v_mul_f32_e32 v35, v56, v32
	v_mul_f32_e32 v32, v40, v32
	v_cvt_pk_bf16_f32 v35, v35, s0
	v_cvt_pk_bf16_f32 v32, v32, s0
	global_store_short v[36:37], v35, off
	global_store_short v[36:37], v32, off offset:64
	v_or_b32_e32 v36, v64, v190
	v_ashrrev_i32_e32 v37, 31, v36
	v_lshlrev_b64 v[36:37], 11, v[36:37]
	v_mul_f32_e32 v32, v57, v33
	v_lshl_add_u64 v[36:37], v[130:131], 0, v[36:37]
	v_cvt_pk_bf16_f32 v32, v32, s0
	global_store_short v[36:37], v32, off
	v_mul_f32_e32 v32, v41, v33
	v_cvt_pk_bf16_f32 v32, v32, s0
	global_store_short v[36:37], v32, off offset:64
	v_or_b32_e32 v32, v64, v191
	v_ashrrev_i32_e32 v33, 31, v32
	v_lshlrev_b64 v[32:33], 11, v[32:33]
	v_mul_f32_e32 v35, v58, v34
	v_mul_f32_e32 v34, v42, v34
	v_lshl_add_u64 v[32:33], v[130:131], 0, v[32:33]
	v_cvt_pk_bf16_f32 v35, v35, s0
	v_cvt_pk_bf16_f32 v34, v34, s0
	global_store_short v[32:33], v35, off
	global_store_short v[32:33], v34, off offset:64
	v_or_b32_e32 v32, v64, v192
	v_ashrrev_i32_e32 v33, 31, v32
	v_and_b32_e32 v34, 0xff, v32
	v_lshl_add_u32 v34, v34, 2, v250
	ds_read_b32 v34, v34
	v_lshlrev_b64 v[32:33], 11, v[32:33]
	v_or_b32_e32 v36, v64, v193
	v_lshl_add_u64 v[32:33], v[130:131], 0, v[32:33]
	v_ashrrev_i32_e32 v37, 31, v36
	s_waitcnt lgkmcnt(0)
	v_mul_f32_e32 v35, v59, v34
	v_mul_f32_e32 v34, v43, v34
	v_cvt_pk_bf16_f32 v35, v35, s0
	v_cvt_pk_bf16_f32 v34, v34, s0
	global_store_short v[32:33], v35, off
	global_store_short v[32:33], v34, off offset:64
	v_and_b32_e32 v32, 0xff, v36
	v_lshl_add_u32 v32, v32, 2, v250
	ds_read_b96 v[32:34], v32
	v_lshlrev_b64 v[36:37], 11, v[36:37]
	v_lshl_add_u64 v[36:37], v[130:131], 0, v[36:37]
	s_waitcnt lgkmcnt(0)
	v_mul_f32_e32 v35, v60, v32
	v_mul_f32_e32 v32, v44, v32
	v_cvt_pk_bf16_f32 v35, v35, s0
	v_cvt_pk_bf16_f32 v32, v32, s0
	global_store_short v[36:37], v35, off
	global_store_short v[36:37], v32, off offset:64
	v_or_b32_e32 v36, v64, v194
	v_ashrrev_i32_e32 v37, 31, v36
	v_lshlrev_b64 v[36:37], 11, v[36:37]
	v_mul_f32_e32 v32, v61, v33
	v_lshl_add_u64 v[36:37], v[130:131], 0, v[36:37]
	v_cvt_pk_bf16_f32 v32, v32, s0
	global_store_short v[36:37], v32, off
	v_mul_f32_e32 v32, v45, v33
	v_cvt_pk_bf16_f32 v32, v32, s0
	global_store_short v[36:37], v32, off offset:64
	v_or_b32_e32 v32, v64, v195
	v_ashrrev_i32_e32 v33, 31, v32
	v_lshlrev_b64 v[32:33], 11, v[32:33]
	v_mul_f32_e32 v35, v62, v34
	v_mul_f32_e32 v34, v46, v34
	v_lshl_add_u64 v[32:33], v[130:131], 0, v[32:33]
	v_cvt_pk_bf16_f32 v35, v35, s0
	v_cvt_pk_bf16_f32 v34, v34, s0
	global_store_short v[32:33], v35, off
	global_store_short v[32:33], v34, off offset:64
	v_or_b32_e32 v32, v64, v196
	v_ashrrev_i32_e32 v33, 31, v32
	v_and_b32_e32 v34, 0xff, v32
	v_lshl_add_u32 v34, v34, 2, v250
	ds_read_b32 v34, v34
	v_lshlrev_b64 v[32:33], 11, v[32:33]
	v_lshl_add_u64 v[32:33], v[130:131], 0, v[32:33]
	s_waitcnt lgkmcnt(0)
	v_mul_f32_e32 v35, v63, v34
	v_mul_f32_e32 v34, v47, v34
	v_cvt_pk_bf16_f32 v35, v35, s0
	v_cvt_pk_bf16_f32 v34, v34, s0
	global_store_short v[32:33], v35, off
	global_store_short v[32:33], v34, off offset:64
	v_or_b32_e32 v32, 0x60, v132
	v_or_b32_e32 v38, v32, v181
	v_ashrrev_i32_e32 v39, 31, v38
	v_and_b32_e32 v34, 0xff, v38
	v_lshl_add_u32 v34, v34, 2, v250
	ds_read_b96 v[34:36], v34
	v_lshlrev_b64 v[38:39], 11, v[38:39]
	v_lshl_add_u64 v[38:39], v[130:131], 0, v[38:39]
	s_waitcnt lgkmcnt(0)
	v_mul_f32_e32 v16, v16, v34
	v_mul_f32_e32 v0, v0, v34
	v_cvt_pk_bf16_f32 v16, v16, s0
	v_cvt_pk_bf16_f32 v0, v0, s0
	global_store_short v[38:39], v16, off
	global_store_short v[38:39], v0, off offset:64
	v_or_b32_e32 v38, v32, v182
	v_ashrrev_i32_e32 v39, 31, v38
	v_lshlrev_b64 v[38:39], 11, v[38:39]
	v_mul_f32_e32 v0, v17, v35
	v_lshl_add_u64 v[38:39], v[130:131], 0, v[38:39]
	v_cvt_pk_bf16_f32 v0, v0, s0
	global_store_short v[38:39], v0, off
	v_mul_f32_e32 v0, v1, v35
	v_cvt_pk_bf16_f32 v0, v0, s0
	global_store_short v[38:39], v0, off offset:64
	v_or_b32_e32 v0, v32, v183
	v_ashrrev_i32_e32 v1, 31, v0
	v_lshlrev_b64 v[0:1], 11, v[0:1]
	v_mul_f32_e32 v16, v18, v36
	v_mul_f32_e32 v2, v2, v36
	v_lshl_add_u64 v[0:1], v[130:131], 0, v[0:1]
	v_cvt_pk_bf16_f32 v16, v16, s0
	v_cvt_pk_bf16_f32 v2, v2, s0
	global_store_short v[0:1], v16, off
	global_store_short v[0:1], v2, off offset:64
	v_or_b32_e32 v0, v32, v184
	v_ashrrev_i32_e32 v1, 31, v0
	v_and_b32_e32 v16, 0xff, v0
	v_lshl_add_u32 v16, v16, 2, v250
	ds_read_b32 v2, v16
	v_lshlrev_b64 v[0:1], 11, v[0:1]
	v_lshl_add_u64 v[0:1], v[130:131], 0, v[0:1]
	s_waitcnt lgkmcnt(0)
	v_mul_f32_e32 v16, v19, v2
	v_cvt_pk_bf16_f32 v16, v16, s0
	global_store_short v[0:1], v16, off
	v_mul_f32_e32 v2, v3, v2
	v_or_b32_e32 v16, v32, v185
	v_cvt_pk_bf16_f32 v2, v2, s0
	v_ashrrev_i32_e32 v17, 31, v16
	global_store_short v[0:1], v2, off offset:64
	v_and_b32_e32 v0, 0xff, v16
	v_lshl_add_u32 v0, v0, 2, v250
	ds_read_b96 v[0:2], v0
	v_lshlrev_b64 v[16:17], 11, v[16:17]
	v_lshl_add_u64 v[16:17], v[130:131], 0, v[16:17]
	s_waitcnt lgkmcnt(0)
	v_mul_f32_e32 v3, v20, v0
	v_mul_f32_e32 v0, v4, v0
	v_cvt_pk_bf16_f32 v3, v3, s0
	v_cvt_pk_bf16_f32 v0, v0, s0
	global_store_short v[16:17], v3, off
	global_store_short v[16:17], v0, off offset:64
	v_or_b32_e32 v16, v32, v186
	v_ashrrev_i32_e32 v17, 31, v16
	v_lshlrev_b64 v[16:17], 11, v[16:17]
	v_mul_f32_e32 v0, v21, v1
	v_lshl_add_u64 v[16:17], v[130:131], 0, v[16:17]
	v_cvt_pk_bf16_f32 v0, v0, s0
	global_store_short v[16:17], v0, off
	v_mul_f32_e32 v0, v5, v1
	v_cvt_pk_bf16_f32 v0, v0, s0
	global_store_short v[16:17], v0, off offset:64
	v_or_b32_e32 v0, v32, v187
	v_ashrrev_i32_e32 v1, 31, v0
	v_lshlrev_b64 v[0:1], 11, v[0:1]
	v_mul_f32_e32 v3, v22, v2
	v_mul_f32_e32 v2, v6, v2
	v_lshl_add_u64 v[0:1], v[130:131], 0, v[0:1]
	v_cvt_pk_bf16_f32 v3, v3, s0
	v_cvt_pk_bf16_f32 v2, v2, s0
	global_store_short v[0:1], v3, off
	global_store_short v[0:1], v2, off offset:64
	v_or_b32_e32 v0, v32, v188
	v_ashrrev_i32_e32 v1, 31, v0
	v_and_b32_e32 v2, 0xff, v0
	v_lshl_add_u32 v2, v2, 2, v250
	ds_read_b32 v2, v2
	v_lshlrev_b64 v[0:1], 11, v[0:1]
	v_or_b32_e32 v4, v32, v189
	v_lshl_add_u64 v[0:1], v[130:131], 0, v[0:1]
	v_ashrrev_i32_e32 v5, 31, v4
	s_waitcnt lgkmcnt(0)
	v_mul_f32_e32 v3, v23, v2
	v_mul_f32_e32 v2, v7, v2
	v_cvt_pk_bf16_f32 v3, v3, s0
	v_cvt_pk_bf16_f32 v2, v2, s0
	global_store_short v[0:1], v3, off
	global_store_short v[0:1], v2, off offset:64
	v_and_b32_e32 v0, 0xff, v4
	v_lshl_add_u32 v0, v0, 2, v250
	ds_read_b96 v[0:2], v0
	v_lshlrev_b64 v[4:5], 11, v[4:5]
	v_lshl_add_u64 v[4:5], v[130:131], 0, v[4:5]
	s_waitcnt lgkmcnt(0)
	v_mul_f32_e32 v3, v24, v0
	v_mul_f32_e32 v0, v8, v0
	v_cvt_pk_bf16_f32 v3, v3, s0
	v_cvt_pk_bf16_f32 v0, v0, s0
	global_store_short v[4:5], v3, off
	global_store_short v[4:5], v0, off offset:64
	v_or_b32_e32 v4, v32, v190
	v_ashrrev_i32_e32 v5, 31, v4
	v_lshlrev_b64 v[4:5], 11, v[4:5]
	v_mul_f32_e32 v0, v25, v1
	v_lshl_add_u64 v[4:5], v[130:131], 0, v[4:5]
	v_cvt_pk_bf16_f32 v0, v0, s0
	global_store_short v[4:5], v0, off
	v_mul_f32_e32 v0, v9, v1
	v_cvt_pk_bf16_f32 v0, v0, s0
	global_store_short v[4:5], v0, off offset:64
	v_or_b32_e32 v0, v32, v191
	v_ashrrev_i32_e32 v1, 31, v0
	v_lshlrev_b64 v[0:1], 11, v[0:1]
	v_mul_f32_e32 v3, v26, v2
	v_mul_f32_e32 v2, v10, v2
	v_lshl_add_u64 v[0:1], v[130:131], 0, v[0:1]
	v_cvt_pk_bf16_f32 v3, v3, s0
	v_cvt_pk_bf16_f32 v2, v2, s0
	global_store_short v[0:1], v3, off
	global_store_short v[0:1], v2, off offset:64
	v_or_b32_e32 v0, v32, v192
	v_ashrrev_i32_e32 v1, 31, v0
	v_and_b32_e32 v2, 0xff, v0
	v_lshl_add_u32 v2, v2, 2, v250
	ds_read_b32 v2, v2
	v_lshlrev_b64 v[0:1], 11, v[0:1]
	v_or_b32_e32 v4, v32, v193
	v_lshl_add_u64 v[0:1], v[130:131], 0, v[0:1]
	v_ashrrev_i32_e32 v5, 31, v4
	s_waitcnt lgkmcnt(0)
	v_mul_f32_e32 v3, v27, v2
	v_mul_f32_e32 v2, v11, v2
	v_cvt_pk_bf16_f32 v3, v3, s0
	v_cvt_pk_bf16_f32 v2, v2, s0
	global_store_short v[0:1], v3, off
	global_store_short v[0:1], v2, off offset:64
	v_and_b32_e32 v0, 0xff, v4
	v_lshl_add_u32 v0, v0, 2, v250
	ds_read_b96 v[0:2], v0
	v_lshlrev_b64 v[4:5], 11, v[4:5]
	v_lshl_add_u64 v[4:5], v[130:131], 0, v[4:5]
	s_waitcnt lgkmcnt(0)
	v_mul_f32_e32 v3, v28, v0
	v_mul_f32_e32 v0, v12, v0
	v_cvt_pk_bf16_f32 v3, v3, s0
	v_cvt_pk_bf16_f32 v0, v0, s0
	global_store_short v[4:5], v3, off
	global_store_short v[4:5], v0, off offset:64
	v_or_b32_e32 v4, v32, v194
	v_ashrrev_i32_e32 v5, 31, v4
	v_lshlrev_b64 v[4:5], 11, v[4:5]
	v_mul_f32_e32 v0, v29, v1
	v_lshl_add_u64 v[4:5], v[130:131], 0, v[4:5]
	v_cvt_pk_bf16_f32 v0, v0, s0
	global_store_short v[4:5], v0, off
	v_mul_f32_e32 v0, v13, v1
	v_cvt_pk_bf16_f32 v0, v0, s0
	global_store_short v[4:5], v0, off offset:64
	v_or_b32_e32 v0, v32, v195
	v_ashrrev_i32_e32 v1, 31, v0
	v_lshlrev_b64 v[0:1], 11, v[0:1]
	v_mul_f32_e32 v3, v30, v2
	v_mul_f32_e32 v2, v14, v2
	v_lshl_add_u64 v[0:1], v[130:131], 0, v[0:1]
	v_cvt_pk_bf16_f32 v3, v3, s0
	v_cvt_pk_bf16_f32 v2, v2, s0
	global_store_short v[0:1], v3, off
	global_store_short v[0:1], v2, off offset:64
	v_or_b32_e32 v0, v32, v196
	v_ashrrev_i32_e32 v1, 31, v0
	v_and_b32_e32 v2, 0xff, v0
	v_lshl_add_u32 v2, v2, 2, v250
	ds_read_b32 v2, v2
	v_lshlrev_b64 v[0:1], 11, v[0:1]
	v_lshl_add_u64 v[0:1], v[130:131], 0, v[0:1]
	s_waitcnt lgkmcnt(0)
	v_mul_f32_e32 v3, v31, v2
	v_mul_f32_e32 v2, v15, v2
	v_cvt_pk_bf16_f32 v3, v3, s0
	v_cvt_pk_bf16_f32 v2, v2, s0
	global_store_short v[0:1], v3, off
	global_store_short v[0:1], v2, off offset:64
	s_cbranch_scc0 .LBB0_2225

.LBB0_2339:
	s_and_b32 s12, s15, 7
	v_lshl_add_u32 v0, s12, 8, v186
	v_ashrrev_i32_e32 v1, 31, v0
	v_lshlrev_b64 v[0:1], 11, v[0:1]
	s_and_b32 s12, s17, 0xffffff00
	v_lshl_add_u64 v[170:171], v[160:161], 0, v[0:1]
	v_add_u32_e32 v0, s12, v175
	s_and_b32 s12, s14, 7
	v_ashrrev_i32_e32 v1, 31, v0
	s_or_b32 s12, s12, s16
	v_lshlrev_b64 v[0:1], 11, v[0:1]
	s_lshl_b32 s13, s12, 8
	v_lshl_add_u64 v[172:173], v[168:169], 0, v[0:1]
	v_add_u32_e32 v0, s13, v175
	s_lshl_b32 s12, s14, 5
	v_ashrrev_i32_e32 v1, 31, v0
	s_and_b32 s12, s12, 0xffffff00
	v_lshlrev_b64 v[0:1], 11, v[0:1]
	v_add_u32_e32 v2, s12, v175
	s_waitcnt vmcnt(0) lgkmcnt(0)
	s_barrier
	v_ashrrev_i32_e32 v3, 31, v2
	v_lshl_add_u64 v[0:1], v[156:157], 0, v[0:1]
	v_readfirstlane_b32 s18, v180
	s_mov_b32 m0, s18
	s_nop 0
	global_load_lds_dwordx4 v[0:1], off
	v_lshlrev_b64 v[2:3], 11, v[2:3]
	v_lshl_add_u64 v[4:5], v[0:1], 0, s[34:35]
	s_add_i32 s19, s18, 0x2000
	s_mov_b32 m0, s19
	s_nop 0
	global_load_lds_dwordx4 v[4:5], off
	v_lshl_add_u64 v[2:3], v[158:159], 0, v[2:3]
	s_add_i32 s19, s18, 0x4000
	s_mov_b32 m0, s19
	s_nop 0
	global_load_lds_dwordx4 v[2:3], off
	v_lshl_add_u64 v[4:5], v[2:3], 0, s[34:35]
	s_add_i32 s19, s18, 0x6000
	s_mov_b32 m0, s19
	s_nop 0
	global_load_lds_dwordx4 v[4:5], off
	s_add_i32 s19, s18, 0x8000
	v_lshl_add_u64 v[4:5], v[0:1], 0, 64
	s_mov_b32 m0, s19
	s_nop 0
	global_load_lds_dwordx4 v[4:5], off
	s_mov_b64 s[20:21], 0x40040
	v_lshl_add_u64 v[4:5], v[0:1], 0, s[20:21]
	s_add_i32 s19, s18, 0xa000
	s_mov_b32 m0, s19
	s_nop 0
	global_load_lds_dwordx4 v[4:5], off
	v_lshl_add_u64 v[4:5], v[2:3], 0, 64
	s_add_i32 s19, s18, 0xc000
	s_mov_b32 m0, s19
	s_nop 0
	global_load_lds_dwordx4 v[4:5], off
	v_lshl_add_u64 v[4:5], v[2:3], 0, s[20:21]
	s_add_i32 s19, s18, 0xe000
	s_mov_b32 m0, s19
	s_nop 0
	global_load_lds_dwordx4 v[4:5], off
	s_mov_b64 s[20:21], 0x80
	s_add_i32 s19, s18, 0x10000
	v_lshl_add_u64 v[4:5], v[0:1], 0, s[20:21]
	s_mov_b32 m0, s19
	s_nop 0
	global_load_lds_dwordx4 v[4:5], off
	s_mov_b64 s[22:23], 0x40080
	v_lshl_add_u64 v[0:1], v[0:1], 0, s[22:23]
	s_add_i32 s19, s18, 0x12000
	s_mov_b32 m0, s19
	s_nop 0
	global_load_lds_dwordx4 v[0:1], off
	v_lshl_add_u64 v[0:1], v[2:3], 0, s[20:21]
	s_add_i32 s19, s18, 0x14000
	s_mov_b32 m0, s19
	s_nop 0
	global_load_lds_dwordx4 v[0:1], off
	v_lshl_add_u64 v[0:1], v[2:3], 0, s[22:23]
	s_add_i32 s18, s18, 0x16000
	s_mov_b32 m0, s18
	s_nop 0
	global_load_lds_dwordx4 v[0:1], off
	v_mov_b32_e32 v130, 0
	v_mov_b32_e32 v134, 0
	v_mov_b32_e32 v0, 0
	s_mov_b32 s18, 0x18000
	v_mov_b32_e32 v1, v0
	v_mov_b32_e32 v2, v0
	v_mov_b32_e32 v3, v0
	v_mov_b32_e32 v4, v0
	v_mov_b32_e32 v5, v0
	v_mov_b32_e32 v6, v0
	v_mov_b32_e32 v7, v0
	v_mov_b32_e32 v8, v0
	v_mov_b32_e32 v9, v0
	v_mov_b32_e32 v10, v0
	v_mov_b32_e32 v11, v0
	v_mov_b32_e32 v12, v0
	v_mov_b32_e32 v13, v0
	v_mov_b32_e32 v14, v0
	v_mov_b32_e32 v15, v0
	v_mov_b32_e32 v16, v0
	v_mov_b32_e32 v17, v0
	v_mov_b32_e32 v18, v0
	v_mov_b32_e32 v19, v0
	v_mov_b32_e32 v20, v0
	v_mov_b32_e32 v21, v0
	v_mov_b32_e32 v22, v0
	v_mov_b32_e32 v23, v0
	v_mov_b32_e32 v24, v0
	v_mov_b32_e32 v25, v0
	v_mov_b32_e32 v26, v0
	v_mov_b32_e32 v27, v0
	v_mov_b32_e32 v28, v0
	v_mov_b32_e32 v29, v0
	v_mov_b32_e32 v30, v0
	v_mov_b32_e32 v31, v0
	v_mov_b32_e32 v32, v0
	v_mov_b32_e32 v33, v0
	v_mov_b32_e32 v34, v0
	v_mov_b32_e32 v35, v0
	v_mov_b32_e32 v36, v0
	v_mov_b32_e32 v37, v0
	v_mov_b32_e32 v38, v0
	v_mov_b32_e32 v39, v0
	v_mov_b32_e32 v40, v0
	v_mov_b32_e32 v41, v0
	v_mov_b32_e32 v42, v0
	v_mov_b32_e32 v43, v0
	v_mov_b32_e32 v44, v0
	v_mov_b32_e32 v45, v0
	v_mov_b32_e32 v46, v0
	v_mov_b32_e32 v47, v0
	v_mov_b32_e32 v48, v0
	v_mov_b32_e32 v49, v0
	v_mov_b32_e32 v50, v0
	v_mov_b32_e32 v51, v0
	v_mov_b32_e32 v52, v0
	v_mov_b32_e32 v53, v0
	v_mov_b32_e32 v54, v0
	v_mov_b32_e32 v55, v0
	v_mov_b32_e32 v56, v0
	v_mov_b32_e32 v57, v0
	v_mov_b32_e32 v58, v0
	v_mov_b32_e32 v59, v0
	v_mov_b32_e32 v60, v0
	v_mov_b32_e32 v61, v0
	v_mov_b32_e32 v62, v0
	v_mov_b32_e32 v63, v0
	v_mov_b32_e32 v64, v0
	v_mov_b32_e32 v65, v0
	v_mov_b32_e32 v66, v0
	v_mov_b32_e32 v67, v0
	v_mov_b32_e32 v68, v0
	v_mov_b32_e32 v69, v0
	v_mov_b32_e32 v70, v0
	v_mov_b32_e32 v71, v0
	v_mov_b32_e32 v72, v0
	v_mov_b32_e32 v73, v0
	v_mov_b32_e32 v74, v0
	v_mov_b32_e32 v75, v0
	v_mov_b32_e32 v76, v0
	v_mov_b32_e32 v77, v0
	v_mov_b32_e32 v78, v0
	v_mov_b32_e32 v79, v0
	v_mov_b32_e32 v80, v0
	v_mov_b32_e32 v81, v0
	v_mov_b32_e32 v82, v0
	v_mov_b32_e32 v83, v0
	v_mov_b32_e32 v84, v0
	v_mov_b32_e32 v85, v0
	v_mov_b32_e32 v86, v0
	v_mov_b32_e32 v87, v0
	v_mov_b32_e32 v88, v0
	v_mov_b32_e32 v89, v0
	v_mov_b32_e32 v90, v0
	v_mov_b32_e32 v91, v0
	v_mov_b32_e32 v92, v0
	v_mov_b32_e32 v93, v0
	v_mov_b32_e32 v94, v0
	v_mov_b32_e32 v95, v0
	v_mov_b32_e32 v96, v0
	v_mov_b32_e32 v97, v0
	v_mov_b32_e32 v98, v0
	v_mov_b32_e32 v99, v0
	v_mov_b32_e32 v100, v0
	v_mov_b32_e32 v101, v0
	v_mov_b32_e32 v102, v0
	v_mov_b32_e32 v103, v0
	v_mov_b32_e32 v104, v0
	v_mov_b32_e32 v105, v0
	v_mov_b32_e32 v106, v0
	v_mov_b32_e32 v107, v0
	v_mov_b32_e32 v108, v0
	v_mov_b32_e32 v109, v0
	v_mov_b32_e32 v110, v0
	v_mov_b32_e32 v111, v0
	v_mov_b32_e32 v112, v0
	v_mov_b32_e32 v113, v0
	v_mov_b32_e32 v114, v0
	v_mov_b32_e32 v115, v0
	v_mov_b32_e32 v116, v0
	v_mov_b32_e32 v117, v0
	v_mov_b32_e32 v118, v0
	v_mov_b32_e32 v119, v0
	v_mov_b32_e32 v120, v0
	v_mov_b32_e32 v121, v0
	v_mov_b32_e32 v122, v0
	v_mov_b32_e32 v123, v0
	v_mov_b32_e32 v124, v0
	v_mov_b32_e32 v125, v0
	v_mov_b32_e32 v126, v0
	v_mov_b32_e32 v127, v0
	v_mov_b32_e32 v135, v134
	v_mov_b32_e32 v136, v134
	v_mov_b32_e32 v137, v134
	v_mov_b32_e32 v138, v134
	v_mov_b32_e32 v139, v134
	v_mov_b32_e32 v140, v134
	v_mov_b32_e32 v141, v134
	v_mov_b32_e32 v146, v134
	v_mov_b32_e32 v147, v134
	v_mov_b32_e32 v148, v134
	v_mov_b32_e32 v149, v134
	v_mov_b32_e32 v150, v134
	v_mov_b32_e32 v151, v134
	v_mov_b32_e32 v152, v134
	v_mov_b32_e32 v153, v134
	v_mov_b32_e32 v131, v130
	v_mov_b32_e32 v132, v130
	v_mov_b32_e32 v133, v130
	v_mov_b32_e32 v142, v130
	v_mov_b32_e32 v143, v130
	v_mov_b32_e32 v144, v130
	v_mov_b32_e32 v145, v130
	v_readfirstlane_b32 s100, v163
	s_cmp_ge_u32 s100, 0x100
	s_cbranch_scc1 .Lky_6
.LBB0_2340:
	s_and_b32 s19, s18, 0x18000
	v_add_u32_e32 v187, s19, v180
	s_add_i32 s19, s18, 0xfffe8000
	s_and_b32 s19, s19, 0x18000
	v_or_b32_e32 v212, s19, v179
	v_add_u32_e32 v213, s19, v176
	s_waitcnt vmcnt(8) lgkmcnt(0)
	s_barrier
	v_mfma_f32_32x32x16_bf16 v[112:127], v[150:153], v[142:145], v[112:127]
	v_mfma_f32_32x32x16_bf16 v[96:111], v[150:153], v[130:133], v[96:111]
	v_add_u32_e32 v192, v212, v177
	v_add_u32_e32 v208, v213, v177
	ds_read_b128 v[188:191], v192 offset:16384
	ds_read_b128 v[192:195], v192 offset:18432
	ds_read_b128 v[196:199], v208
	ds_read_b128 v[200:203], v208 offset:2048
	ds_read_b128 v[204:207], v208 offset:4096
	ds_read_b128 v[208:211], v208 offset:6144
	v_mfma_f32_32x32x16_bf16 v[80:95], v[146:149], v[142:145], v[80:95]
	v_mfma_f32_32x32x16_bf16 v[64:79], v[146:149], v[130:133], v[64:79]
	v_readfirstlane_b32 s19, v187
	s_mov_b32 m0, s19
	s_nop 0
	global_load_lds_dwordx4 v[170:171], off
	v_mfma_f32_32x32x16_bf16 v[48:63], v[138:141], v[142:145], v[48:63]
	v_mfma_f32_32x32x16_bf16 v[32:47], v[138:141], v[130:133], v[32:47]
	s_add_i32 s20, s19, 0x2000
	v_lshl_add_u64 v[150:151], v[170:171], 0, s[34:35]
	s_mov_b32 m0, s20
	s_nop 0
	global_load_lds_dwordx4 v[150:151], off
	v_mfma_f32_32x32x16_bf16 v[16:31], v[134:137], v[142:145], v[16:31]
	v_mfma_f32_32x32x16_bf16 v[0:15], v[134:137], v[130:133], v[0:15]
	v_add_u32_e32 v130, v212, v178
	v_add_u32_e32 v134, v213, v178
	ds_read_b128 v[142:145], v130 offset:16384
	ds_read_b128 v[130:133], v130 offset:18432
	ds_read_b128 v[150:153], v134
	ds_read_b128 v[146:149], v134 offset:2048
	ds_read_b128 v[138:141], v134 offset:4096
	ds_read_b128 v[134:137], v134 offset:6144
	s_waitcnt lgkmcnt(9)
	v_mfma_f32_32x32x16_bf16 v[112:127], v[196:199], v[188:191], v[112:127]
	s_add_i32 s20, s19, 0x6000
	s_addk_i32 s19, 0x4000
	v_mfma_f32_32x32x16_bf16 v[96:111], v[196:199], v[192:195], v[96:111]
	s_mov_b32 m0, s19
	s_nop 0
	global_load_lds_dwordx4 v[172:173], off
	v_lshl_add_u64 v[212:213], v[172:173], 0, s[34:35]
	s_waitcnt lgkmcnt(8)
	v_mfma_f32_32x32x16_bf16 v[80:95], v[200:203], v[188:191], v[80:95]
	v_mfma_f32_32x32x16_bf16 v[64:79], v[200:203], v[192:195], v[64:79]
	s_waitcnt lgkmcnt(7)
	v_mfma_f32_32x32x16_bf16 v[48:63], v[204:207], v[188:191], v[48:63]
	v_mfma_f32_32x32x16_bf16 v[32:47], v[204:207], v[192:195], v[32:47]
	s_mov_b32 m0, s20
	s_nop 0
	global_load_lds_dwordx4 v[212:213], off
	s_waitcnt lgkmcnt(6)
	v_mfma_f32_32x32x16_bf16 v[16:31], v[208:211], v[188:191], v[16:31]
	s_add_i32 s18, s18, 0x8000
	v_lshl_add_u64 v[170:171], v[170:171], 0, 64
	v_lshl_add_u64 v[172:173], v[172:173], 0, 64
	s_cmp_eq_u32 s18, 0x100000
	v_mfma_f32_32x32x16_bf16 v[0:15], v[208:211], v[192:195], v[0:15]
	s_cbranch_scc0 .LBB0_2340
	s_branch .Lktail_6
.Lky_6:
	s_and_b32 s19, s18, 0x18000
	v_add_u32_e32 v187, s19, v180
	s_add_i32 s19, s18, 0xfffe8000
	s_and_b32 s19, s19, 0x18000
	v_or_b32_e32 v212, s19, v179
	v_add_u32_e32 v213, s19, v176
	s_waitcnt vmcnt(8) lgkmcnt(0)
	s_barrier
	v_add_u32_e32 v192, v212, v177
	v_add_u32_e32 v208, v213, v177
	ds_read_b128 v[188:191], v192 offset:16384
	ds_read_b128 v[192:195], v192 offset:18432
	ds_read_b128 v[196:199], v208
	ds_read_b128 v[200:203], v208 offset:2048
	ds_read_b128 v[204:207], v208 offset:4096
	ds_read_b128 v[208:211], v208 offset:6144
	v_mfma_f32_32x32x16_bf16 v[112:127], v[150:153], v[142:145], v[112:127]
	v_mfma_f32_32x32x16_bf16 v[96:111], v[150:153], v[130:133], v[96:111]
	v_readfirstlane_b32 s19, v187
	s_mov_b32 m0, s19
	s_nop 0
	global_load_lds_dwordx4 v[170:171], off
	v_mfma_f32_32x32x16_bf16 v[80:95], v[146:149], v[142:145], v[80:95]
	v_mfma_f32_32x32x16_bf16 v[64:79], v[146:149], v[130:133], v[64:79]
	v_mfma_f32_32x32x16_bf16 v[48:63], v[138:141], v[142:145], v[48:63]
	v_mfma_f32_32x32x16_bf16 v[32:47], v[138:141], v[130:133], v[32:47]
	s_add_i32 s20, s19, 0x2000
	v_lshl_add_u64 v[150:151], v[170:171], 0, s[34:35]
	s_mov_b32 m0, s20
	s_nop 0
	global_load_lds_dwordx4 v[150:151], off
	v_mfma_f32_32x32x16_bf16 v[16:31], v[134:137], v[142:145], v[16:31]
	v_mfma_f32_32x32x16_bf16 v[0:15], v[134:137], v[130:133], v[0:15]
	v_add_u32_e32 v130, v212, v178
	v_add_u32_e32 v134, v213, v178
	ds_read_b128 v[142:145], v130 offset:16384
	ds_read_b128 v[130:133], v130 offset:18432
	ds_read_b128 v[150:153], v134
	ds_read_b128 v[146:149], v134 offset:2048
	ds_read_b128 v[138:141], v134 offset:4096
	ds_read_b128 v[134:137], v134 offset:6144
	s_waitcnt lgkmcnt(9)
	v_mfma_f32_32x32x16_bf16 v[112:127], v[196:199], v[188:191], v[112:127]
	s_add_i32 s20, s19, 0x6000
	s_addk_i32 s19, 0x4000
	v_mfma_f32_32x32x16_bf16 v[96:111], v[196:199], v[192:195], v[96:111]
	s_mov_b32 m0, s19
	s_nop 0
	global_load_lds_dwordx4 v[172:173], off
	v_lshl_add_u64 v[212:213], v[172:173], 0, s[34:35]
	s_waitcnt lgkmcnt(8)
	v_mfma_f32_32x32x16_bf16 v[80:95], v[200:203], v[188:191], v[80:95]
	v_mfma_f32_32x32x16_bf16 v[64:79], v[200:203], v[192:195], v[64:79]
	s_waitcnt lgkmcnt(7)
	v_mfma_f32_32x32x16_bf16 v[48:63], v[204:207], v[188:191], v[48:63]
	v_mfma_f32_32x32x16_bf16 v[32:47], v[204:207], v[192:195], v[32:47]
	s_mov_b32 m0, s20
	s_nop 0
	global_load_lds_dwordx4 v[212:213], off
	s_waitcnt lgkmcnt(6)
	v_mfma_f32_32x32x16_bf16 v[16:31], v[208:211], v[188:191], v[16:31]
	s_add_i32 s18, s18, 0x8000
	v_lshl_add_u64 v[170:171], v[170:171], 0, 64
	v_lshl_add_u64 v[172:173], v[172:173], 0, 64
	s_cmp_eq_u32 s18, 0x100000
	v_mfma_f32_32x32x16_bf16 v[0:15], v[208:211], v[192:195], v[0:15]
	s_cbranch_scc0 .Lky_6
.Lktail_6:
	s_waitcnt vmcnt(8) lgkmcnt(0)
	s_barrier
	v_add_u32_e32 v187, v179, v177
	ds_read_b128 v[170:173], v187 offset:49152
	ds_read_b128 v[188:191], v187 offset:51200
	v_add_u32_e32 v187, v176, v177
	ds_read_b128 v[192:195], v187 offset:32768
	ds_read_b128 v[196:199], v187 offset:34816
	ds_read_b128 v[200:203], v187 offset:36864
	ds_read_b128 v[204:207], v187 offset:38912
	s_waitcnt lgkmcnt(9)
	v_mfma_f32_32x32x16_bf16 v[112:127], v[150:153], v[142:145], v[112:127]
	v_mfma_f32_32x32x16_bf16 v[96:111], v[150:153], v[130:133], v[96:111]
	s_waitcnt lgkmcnt(8)
	v_mfma_f32_32x32x16_bf16 v[80:95], v[146:149], v[142:145], v[80:95]
	v_mfma_f32_32x32x16_bf16 v[64:79], v[146:149], v[130:133], v[64:79]
	s_waitcnt lgkmcnt(7)
	v_mfma_f32_32x32x16_bf16 v[48:63], v[138:141], v[142:145], v[48:63]
	v_mfma_f32_32x32x16_bf16 v[32:47], v[138:141], v[130:133], v[32:47]
	s_waitcnt lgkmcnt(6)
	v_mfma_f32_32x32x16_bf16 v[16:31], v[134:137], v[142:145], v[16:31]
	v_mfma_f32_32x32x16_bf16 v[0:15], v[134:137], v[130:133], v[0:15]
	v_add_u32_e32 v134, v179, v178
	v_add_u32_e32 v150, v176, v178
	ds_read_b128 v[130:133], v134 offset:49152
	ds_read_b128 v[134:137], v134 offset:51200
	ds_read_b128 v[138:141], v150 offset:32768
	ds_read_b128 v[142:145], v150 offset:34816
	ds_read_b128 v[146:149], v150 offset:36864
	ds_read_b128 v[150:153], v150 offset:38912
	s_waitcnt lgkmcnt(9)
	v_mfma_f32_32x32x16_bf16 v[112:127], v[192:195], v[170:173], v[112:127]
	v_mfma_f32_32x32x16_bf16 v[96:111], v[192:195], v[188:191], v[96:111]
	s_waitcnt lgkmcnt(8)
	v_mfma_f32_32x32x16_bf16 v[80:95], v[196:199], v[170:173], v[80:95]
	v_mfma_f32_32x32x16_bf16 v[64:79], v[196:199], v[188:191], v[64:79]
	s_waitcnt lgkmcnt(7)
	v_mfma_f32_32x32x16_bf16 v[48:63], v[200:203], v[170:173], v[48:63]
	v_mfma_f32_32x32x16_bf16 v[32:47], v[200:203], v[188:191], v[32:47]
	s_waitcnt vmcnt(4) lgkmcnt(0)
	s_barrier
	v_add_u32_e32 v187, v184, v177
	s_waitcnt lgkmcnt(6)
	v_mfma_f32_32x32x16_bf16 v[16:31], v[204:207], v[170:173], v[16:31]
	v_mfma_f32_32x32x16_bf16 v[0:15], v[204:207], v[188:191], v[0:15]
	ds_read_b128 v[170:173], v187 offset:16384
	ds_read_b128 v[188:191], v187 offset:18432
	v_add_u32_e32 v187, v185, v177
	ds_read_b128 v[192:195], v187
	ds_read_b128 v[196:199], v187 offset:2048
	ds_read_b128 v[200:203], v187 offset:4096
	ds_read_b128 v[204:207], v187 offset:6144
	s_waitcnt lgkmcnt(9)
	v_mfma_f32_32x32x16_bf16 v[112:127], v[138:141], v[130:133], v[112:127]
	v_mfma_f32_32x32x16_bf16 v[96:111], v[138:141], v[134:137], v[96:111]
	s_waitcnt lgkmcnt(8)
	v_mfma_f32_32x32x16_bf16 v[80:95], v[142:145], v[130:133], v[80:95]
	v_mfma_f32_32x32x16_bf16 v[64:79], v[142:145], v[134:137], v[64:79]
	s_waitcnt lgkmcnt(7)
	v_mfma_f32_32x32x16_bf16 v[48:63], v[146:149], v[130:133], v[48:63]
	v_mfma_f32_32x32x16_bf16 v[32:47], v[146:149], v[134:137], v[32:47]
	s_waitcnt lgkmcnt(6)
	v_mfma_f32_32x32x16_bf16 v[16:31], v[150:153], v[130:133], v[16:31]
	v_mfma_f32_32x32x16_bf16 v[0:15], v[150:153], v[134:137], v[0:15]
	v_add_u32_e32 v134, v184, v178
	v_add_u32_e32 v150, v185, v178
	ds_read_b128 v[130:133], v134 offset:16384
	ds_read_b128 v[134:137], v134 offset:18432
	ds_read_b128 v[138:141], v150
	ds_read_b128 v[142:145], v150 offset:2048
	ds_read_b128 v[146:149], v150 offset:4096
	ds_read_b128 v[150:153], v150 offset:6144
	s_waitcnt lgkmcnt(9)
	v_mfma_f32_32x32x16_bf16 v[112:127], v[192:195], v[170:173], v[112:127]
	v_mfma_f32_32x32x16_bf16 v[96:111], v[192:195], v[188:191], v[96:111]
	s_waitcnt lgkmcnt(8)
	v_mfma_f32_32x32x16_bf16 v[80:95], v[196:199], v[170:173], v[80:95]
	v_mfma_f32_32x32x16_bf16 v[64:79], v[196:199], v[188:191], v[64:79]
	s_waitcnt lgkmcnt(7)
	v_mfma_f32_32x32x16_bf16 v[48:63], v[200:203], v[170:173], v[48:63]
	v_mfma_f32_32x32x16_bf16 v[32:47], v[200:203], v[188:191], v[32:47]
	s_waitcnt vmcnt(0) lgkmcnt(0)
	s_barrier
	v_add_u32_e32 v187, v182, v177
	s_waitcnt lgkmcnt(6)
	v_mfma_f32_32x32x16_bf16 v[16:31], v[204:207], v[170:173], v[16:31]
	v_mfma_f32_32x32x16_bf16 v[0:15], v[204:207], v[188:191], v[0:15]
	ds_read_b128 v[170:173], v187 offset:16384
	ds_read_b128 v[188:191], v187 offset:18432
	v_add_u32_e32 v187, v183, v177
	ds_read_b128 v[192:195], v187
	ds_read_b128 v[196:199], v187 offset:2048
	ds_read_b128 v[200:203], v187 offset:4096
	ds_read_b128 v[204:207], v187 offset:6144
	s_waitcnt lgkmcnt(9)
	v_mfma_f32_32x32x16_bf16 v[112:127], v[138:141], v[130:133], v[112:127]
	v_mfma_f32_32x32x16_bf16 v[96:111], v[138:141], v[134:137], v[96:111]
	s_waitcnt lgkmcnt(8)
	v_mfma_f32_32x32x16_bf16 v[80:95], v[142:145], v[130:133], v[80:95]
	v_mfma_f32_32x32x16_bf16 v[64:79], v[142:145], v[134:137], v[64:79]
	s_waitcnt lgkmcnt(7)
	v_mfma_f32_32x32x16_bf16 v[48:63], v[146:149], v[130:133], v[48:63]
	v_mfma_f32_32x32x16_bf16 v[32:47], v[146:149], v[134:137], v[32:47]
	s_waitcnt lgkmcnt(6)
	v_mfma_f32_32x32x16_bf16 v[16:31], v[150:153], v[130:133], v[16:31]
	v_mfma_f32_32x32x16_bf16 v[0:15], v[150:153], v[134:137], v[0:15]
	v_add_u32_e32 v134, v182, v178
	v_add_u32_e32 v150, v183, v178
	ds_read_b128 v[130:133], v134 offset:16384
	ds_read_b128 v[134:137], v134 offset:18432
	ds_read_b128 v[138:141], v150
	ds_read_b128 v[142:145], v150 offset:2048
	ds_read_b128 v[146:149], v150 offset:4096
	ds_read_b128 v[150:153], v150 offset:6144
	s_waitcnt lgkmcnt(9)
	v_mfma_f32_32x32x16_bf16 v[112:127], v[192:195], v[170:173], v[112:127]
	v_mfma_f32_32x32x16_bf16 v[96:111], v[192:195], v[188:191], v[96:111]
	s_waitcnt lgkmcnt(8)
	v_mfma_f32_32x32x16_bf16 v[80:95], v[196:199], v[170:173], v[80:95]
	v_mfma_f32_32x32x16_bf16 v[64:79], v[196:199], v[188:191], v[64:79]
	s_waitcnt lgkmcnt(7)
	v_mfma_f32_32x32x16_bf16 v[48:63], v[200:203], v[170:173], v[48:63]
	v_mfma_f32_32x32x16_bf16 v[32:47], v[200:203], v[188:191], v[32:47]
	s_waitcnt lgkmcnt(6)
	v_mfma_f32_32x32x16_bf16 v[16:31], v[204:207], v[170:173], v[16:31]
	v_mfma_f32_32x32x16_bf16 v[0:15], v[204:207], v[188:191], v[0:15]
	s_waitcnt lgkmcnt(3)
	v_mfma_f32_32x32x16_bf16 v[112:127], v[138:141], v[130:133], v[112:127]
	s_waitcnt lgkmcnt(2)
	v_mfma_f32_32x32x16_bf16 v[80:95], v[142:145], v[130:133], v[80:95]
	s_waitcnt lgkmcnt(1)
	v_mfma_f32_32x32x16_bf16 v[48:63], v[146:149], v[130:133], v[48:63]
	s_waitcnt lgkmcnt(0)
	v_mfma_f32_32x32x16_bf16 v[16:31], v[150:153], v[130:133], v[16:31]
	v_or_b32_e32 v132, s12, v174
	v_ashrrev_i32_e32 v130, 1, v132
	v_or_b32_e32 v130, v130, v154
	v_ashrrev_i32_e32 v131, 31, v130
	s_movk_i32 s12, 0x5000
	v_mfma_f32_32x32x16_bf16 v[96:111], v[138:141], v[134:137], v[96:111]
	v_mfma_f32_32x32x16_bf16 v[64:79], v[142:145], v[134:137], v[64:79]
	v_add_u32_e32 v142, s13, v155
	s_mov_b32 s13, 0xb000
	v_ashrrev_i32_e32 v133, 7, v142
	v_mfma_f32_32x32x16_bf16 v[32:47], v[146:149], v[134:137], v[32:47]
	v_mfma_f32_32x32x16_bf16 v[0:15], v[150:153], v[134:137], v[0:15]
	v_lshl_add_u64 v[134:135], v[130:131], 2, s[10:11]
	v_add_co_u32_e32 v138, vcc, s12, v134
	s_mov_b32 s12, 0x8000
	s_nop 0
	v_addc_co_u32_e32 v139, vcc, 0, v135, vcc
	global_load_dword v137, v[138:139], off offset:2048
	v_add_co_u32_e32 v138, vcc, s13, v134
	global_load_dword v136, v[134:135], off
	s_nop 0
	v_addc_co_u32_e32 v139, vcc, 0, v135, vcc
	v_add_co_u32_e32 v140, vcc, s47, v134
	global_load_dword v139, v[138:139], off
	s_nop 0
	v_addc_co_u32_e32 v141, vcc, 0, v135, vcc
	global_load_dword v138, v[140:141], off offset:3072
	v_add_co_u32_e32 v140, vcc, s12, v134
	s_mov_b32 s12, 0xd000
	s_nop 0
	v_addc_co_u32_e32 v141, vcc, 0, v135, vcc
	v_add_co_u32_e32 v134, vcc, s12, v134
	global_load_dword v140, v[140:141], off offset:1024
	s_nop 0
	v_addc_co_u32_e32 v135, vcc, 0, v135, vcc
	global_load_dword v141, v[134:135], off offset:3072
	v_mov_b64_e32 v[134:135], s[8:9]
	v_mad_i64_i32 v[134:135], s[12:13], v133, s13, v[134:135]
	v_ashrrev_i32_e32 v133, 31, v132
	v_lshl_add_u64 v[132:133], v[132:133], 1, v[134:135]
	v_lshl_add_u64 v[132:133], v[132:133], 0, v[128:129]
	s_and_saveexec_b64 s[12:13], s[2:3]
	s_xor_b64 s[12:13], exec, s[12:13]
	s_cbranch_execz .LBB0_2343
	v_add_co_u32_e32 v134, vcc, 0x5000, v132
	v_cvt_pk_bf16_f32 v143, v30, s0
	s_nop 0
	v_addc_co_u32_e32 v135, vcc, 0, v133, vcc
	global_store_short v[134:135], v143, off offset:2048
	v_cvt_pk_bf16_f32 v143, v14, s0
	global_store_short v[134:135], v143, off offset:2112
	v_add_co_u32_e32 v134, vcc, 0x8000, v132
	v_cvt_pk_bf16_f32 v143, v31, s0
	s_nop 0
	v_addc_co_u32_e32 v135, vcc, 0, v133, vcc
	global_store_short v[134:135], v143, off offset:1024

.LBB0_2550:
	s_and_b32 s3, s0, 7
	v_lshl_add_u32 v0, s3, 8, v201
	s_and_b32 s3, s2, 0xffffff00
	v_mad_i64_i32 v[170:171], s[4:5], v0, s7, v[160:161]
	v_add_u32_e32 v0, s3, v175
	s_and_b32 s3, s6, 7
	v_mad_i64_i32 v[172:173], s[4:5], v0, s7, v[168:169]
	s_or_b32 s3, s3, s1
	s_lshl_b32 s3, s3, 8
	s_lshl_b32 s4, s6, 5
	v_add_u32_e32 v0, s3, v175
	s_and_b32 s4, s4, 0xffffff00
	s_waitcnt vmcnt(0) lgkmcnt(0)
	s_barrier
	v_add_u32_e32 v2, s4, v175
	v_mad_i64_i32 v[0:1], s[8:9], v0, s7, v[154:155]
	v_readfirstlane_b32 s5, v180
	s_mov_b32 m0, s5
	s_nop 0
	global_load_lds_dwordx4 v[0:1], off
	v_mad_i64_i32 v[2:3], s[8:9], v2, s7, v[156:157]
	v_lshl_add_u64 v[4:5], v[0:1], 0, s[10:11]
	s_add_i32 s7, s5, 0x2000
	s_mov_b32 m0, s7
	s_nop 0
	global_load_lds_dwordx4 v[4:5], off
	s_add_i32 s7, s5, 0x4000
	s_mov_b32 m0, s7
	s_nop 0
	global_load_lds_dwordx4 v[2:3], off
	v_lshl_add_u64 v[4:5], v[2:3], 0, s[10:11]
	s_add_i32 s7, s5, 0x6000
	s_mov_b32 m0, s7
	s_nop 0
	global_load_lds_dwordx4 v[4:5], off
	s_add_i32 s7, s5, 0x8000
	v_lshl_add_u64 v[4:5], v[0:1], 0, 64
	s_mov_b32 m0, s7
	s_nop 0
	global_load_lds_dwordx4 v[4:5], off
	s_mov_b64 s[8:9], 0xb0040
	v_lshl_add_u64 v[4:5], v[0:1], 0, s[8:9]
	s_add_i32 s7, s5, 0xa000
	s_mov_b32 m0, s7
	s_nop 0
	global_load_lds_dwordx4 v[4:5], off
	v_lshl_add_u64 v[4:5], v[2:3], 0, 64
	s_add_i32 s7, s5, 0xc000
	s_mov_b32 m0, s7
	s_nop 0
	global_load_lds_dwordx4 v[4:5], off
	v_lshl_add_u64 v[4:5], v[2:3], 0, s[8:9]
	s_add_i32 s7, s5, 0xe000
	s_mov_b32 m0, s7
	s_nop 0
	global_load_lds_dwordx4 v[4:5], off
	s_mov_b64 s[8:9], 0x80
	s_add_i32 s7, s5, 0x10000
	v_lshl_add_u64 v[4:5], v[0:1], 0, s[8:9]
	s_mov_b32 m0, s7
	s_nop 0
	global_load_lds_dwordx4 v[4:5], off
	s_mov_b64 s[12:13], 0xb0080
	v_lshl_add_u64 v[0:1], v[0:1], 0, s[12:13]
	s_add_i32 s7, s5, 0x12000
	s_mov_b32 m0, s7
	s_nop 0
	global_load_lds_dwordx4 v[0:1], off
	v_lshl_add_u64 v[0:1], v[2:3], 0, s[8:9]
	s_add_i32 s7, s5, 0x14000
	s_mov_b32 m0, s7
	s_nop 0
	global_load_lds_dwordx4 v[0:1], off
	v_lshl_add_u64 v[0:1], v[2:3], 0, s[12:13]
	s_add_i32 s5, s5, 0x16000
	s_mov_b32 m0, s5
	s_nop 0
	global_load_lds_dwordx4 v[0:1], off
	v_mov_b32_e32 v130, 0
	v_mov_b32_e32 v134, 0
	v_mov_b32_e32 v0, 0
	s_mov_b32 s5, 0x18000
	v_mov_b32_e32 v1, v0
	v_mov_b32_e32 v2, v0
	v_mov_b32_e32 v3, v0
	v_mov_b32_e32 v4, v0
	v_mov_b32_e32 v5, v0
	v_mov_b32_e32 v6, v0
	v_mov_b32_e32 v7, v0
	v_mov_b32_e32 v8, v0
	v_mov_b32_e32 v9, v0
	v_mov_b32_e32 v10, v0
	v_mov_b32_e32 v11, v0
	v_mov_b32_e32 v12, v0
	v_mov_b32_e32 v13, v0
	v_mov_b32_e32 v14, v0
	v_mov_b32_e32 v15, v0
	v_mov_b32_e32 v16, v0
	v_mov_b32_e32 v17, v0
	v_mov_b32_e32 v18, v0
	v_mov_b32_e32 v19, v0
	v_mov_b32_e32 v20, v0
	v_mov_b32_e32 v21, v0
	v_mov_b32_e32 v22, v0
	v_mov_b32_e32 v23, v0
	v_mov_b32_e32 v24, v0
	v_mov_b32_e32 v25, v0
	v_mov_b32_e32 v26, v0
	v_mov_b32_e32 v27, v0
	v_mov_b32_e32 v28, v0
	v_mov_b32_e32 v29, v0
	v_mov_b32_e32 v30, v0
	v_mov_b32_e32 v31, v0
	v_mov_b32_e32 v32, v0
	v_mov_b32_e32 v33, v0
	v_mov_b32_e32 v34, v0
	v_mov_b32_e32 v35, v0
	v_mov_b32_e32 v36, v0
	v_mov_b32_e32 v37, v0
	v_mov_b32_e32 v38, v0
	v_mov_b32_e32 v39, v0
	v_mov_b32_e32 v40, v0
	v_mov_b32_e32 v41, v0
	v_mov_b32_e32 v42, v0
	v_mov_b32_e32 v43, v0
	v_mov_b32_e32 v44, v0
	v_mov_b32_e32 v45, v0
	v_mov_b32_e32 v46, v0
	v_mov_b32_e32 v47, v0
	v_mov_b32_e32 v48, v0
	v_mov_b32_e32 v49, v0
	v_mov_b32_e32 v50, v0
	v_mov_b32_e32 v51, v0
	v_mov_b32_e32 v52, v0
	v_mov_b32_e32 v53, v0
	v_mov_b32_e32 v54, v0
	v_mov_b32_e32 v55, v0
	v_mov_b32_e32 v56, v0
	v_mov_b32_e32 v57, v0
	v_mov_b32_e32 v58, v0
	v_mov_b32_e32 v59, v0
	v_mov_b32_e32 v60, v0
	v_mov_b32_e32 v61, v0
	v_mov_b32_e32 v62, v0
	v_mov_b32_e32 v63, v0
	v_mov_b32_e32 v64, v0
	v_mov_b32_e32 v65, v0
	v_mov_b32_e32 v66, v0
	v_mov_b32_e32 v67, v0
	v_mov_b32_e32 v68, v0
	v_mov_b32_e32 v69, v0
	v_mov_b32_e32 v70, v0
	v_mov_b32_e32 v71, v0
	v_mov_b32_e32 v72, v0
	v_mov_b32_e32 v73, v0
	v_mov_b32_e32 v74, v0
	v_mov_b32_e32 v75, v0
	v_mov_b32_e32 v76, v0
	v_mov_b32_e32 v77, v0
	v_mov_b32_e32 v78, v0
	v_mov_b32_e32 v79, v0
	v_mov_b32_e32 v80, v0
	v_mov_b32_e32 v81, v0
	v_mov_b32_e32 v82, v0
	v_mov_b32_e32 v83, v0
	v_mov_b32_e32 v84, v0
	v_mov_b32_e32 v85, v0
	v_mov_b32_e32 v86, v0
	v_mov_b32_e32 v87, v0
	v_mov_b32_e32 v88, v0
	v_mov_b32_e32 v89, v0
	v_mov_b32_e32 v90, v0
	v_mov_b32_e32 v91, v0
	v_mov_b32_e32 v92, v0
	v_mov_b32_e32 v93, v0
	v_mov_b32_e32 v94, v0
	v_mov_b32_e32 v95, v0
	v_mov_b32_e32 v96, v0
	v_mov_b32_e32 v97, v0
	v_mov_b32_e32 v98, v0
	v_mov_b32_e32 v99, v0
	v_mov_b32_e32 v100, v0
	v_mov_b32_e32 v101, v0
	v_mov_b32_e32 v102, v0
	v_mov_b32_e32 v103, v0
	v_mov_b32_e32 v104, v0
	v_mov_b32_e32 v105, v0
	v_mov_b32_e32 v106, v0
	v_mov_b32_e32 v107, v0
	v_mov_b32_e32 v108, v0
	v_mov_b32_e32 v109, v0
	v_mov_b32_e32 v110, v0
	v_mov_b32_e32 v111, v0
	v_mov_b32_e32 v112, v0
	v_mov_b32_e32 v113, v0
	v_mov_b32_e32 v114, v0
	v_mov_b32_e32 v115, v0
	v_mov_b32_e32 v116, v0
	v_mov_b32_e32 v117, v0
	v_mov_b32_e32 v118, v0
	v_mov_b32_e32 v119, v0
	v_mov_b32_e32 v120, v0
	v_mov_b32_e32 v121, v0
	v_mov_b32_e32 v122, v0
	v_mov_b32_e32 v123, v0
	v_mov_b32_e32 v124, v0
	v_mov_b32_e32 v125, v0
	v_mov_b32_e32 v126, v0
	v_mov_b32_e32 v127, v0
	v_mov_b32_e32 v135, v134
	v_mov_b32_e32 v136, v134
	v_mov_b32_e32 v137, v134
	v_mov_b32_e32 v138, v134
	v_mov_b32_e32 v139, v134
	v_mov_b32_e32 v140, v134
	v_mov_b32_e32 v141, v134
	v_mov_b32_e32 v146, v134
	v_mov_b32_e32 v147, v134
	v_mov_b32_e32 v148, v134
	v_mov_b32_e32 v149, v134
	v_mov_b32_e32 v150, v134
	v_mov_b32_e32 v151, v134
	v_mov_b32_e32 v152, v134
	v_mov_b32_e32 v153, v134
	v_mov_b32_e32 v131, v130
	v_mov_b32_e32 v132, v130
	v_mov_b32_e32 v133, v130
	v_mov_b32_e32 v142, v130
	v_mov_b32_e32 v143, v130
	v_mov_b32_e32 v144, v130
	v_mov_b32_e32 v145, v130
	v_readfirstlane_b32 s100, v163
	s_cmp_ge_u32 s100, 0x100
	s_cbranch_scc1 .Lky_7
.LBB0_2551:
	s_and_b32 s7, s5, 0x18000
	v_add_u32_e32 v222, s7, v180
	s_add_i32 s7, s5, 0xfffe8000
	s_and_b32 s7, s7, 0x18000
	v_or_b32_e32 v223, s7, v179
	v_add_u32_e32 v233, s7, v176
	s_waitcnt vmcnt(8) lgkmcnt(0)
	s_barrier
	v_mfma_f32_32x32x16_bf16 v[112:127], v[150:153], v[142:145], v[112:127]
	v_mfma_f32_32x32x16_bf16 v[96:111], v[150:153], v[130:133], v[96:111]
	v_add_u32_e32 v206, v223, v177
	v_add_u32_e32 v234, v233, v177
	ds_read_b128 v[202:205], v206 offset:16384
	ds_read_b128 v[206:209], v206 offset:18432
	ds_read_b128 v[210:213], v234
	ds_read_b128 v[214:217], v234 offset:2048
	ds_read_b128 v[224:227], v234 offset:4096
	ds_read_b128 v[234:237], v234 offset:6144
	v_mfma_f32_32x32x16_bf16 v[80:95], v[146:149], v[142:145], v[80:95]
	v_mfma_f32_32x32x16_bf16 v[64:79], v[146:149], v[130:133], v[64:79]
	v_readfirstlane_b32 s7, v222
	s_mov_b32 m0, s7
	s_nop 0
	global_load_lds_dwordx4 v[170:171], off
	v_mfma_f32_32x32x16_bf16 v[48:63], v[138:141], v[142:145], v[48:63]
	v_mfma_f32_32x32x16_bf16 v[32:47], v[138:141], v[130:133], v[32:47]
	s_add_i32 s8, s7, 0x2000
	v_lshl_add_u64 v[150:151], v[170:171], 0, s[10:11]
	s_mov_b32 m0, s8
	s_nop 0
	global_load_lds_dwordx4 v[150:151], off
	v_mfma_f32_32x32x16_bf16 v[16:31], v[134:137], v[142:145], v[16:31]
	v_mfma_f32_32x32x16_bf16 v[0:15], v[134:137], v[130:133], v[0:15]
	v_add_u32_e32 v130, v223, v178
	v_add_u32_e32 v134, v233, v178
	ds_read_b128 v[142:145], v130 offset:16384
	ds_read_b128 v[130:133], v130 offset:18432
	ds_read_b128 v[150:153], v134
	ds_read_b128 v[146:149], v134 offset:2048
	ds_read_b128 v[138:141], v134 offset:4096
	ds_read_b128 v[134:137], v134 offset:6144
	s_waitcnt lgkmcnt(9)
	v_mfma_f32_32x32x16_bf16 v[112:127], v[210:213], v[202:205], v[112:127]
	s_add_i32 s8, s7, 0x6000
	s_addk_i32 s7, 0x4000
	v_mfma_f32_32x32x16_bf16 v[96:111], v[210:213], v[206:209], v[96:111]
	s_mov_b32 m0, s7
	s_nop 0
	global_load_lds_dwordx4 v[172:173], off
	v_lshl_add_u64 v[222:223], v[172:173], 0, s[10:11]
	s_waitcnt lgkmcnt(8)
	v_mfma_f32_32x32x16_bf16 v[80:95], v[214:217], v[202:205], v[80:95]
	v_mfma_f32_32x32x16_bf16 v[64:79], v[214:217], v[206:209], v[64:79]
	s_waitcnt lgkmcnt(7)
	v_mfma_f32_32x32x16_bf16 v[48:63], v[224:227], v[202:205], v[48:63]
	v_mfma_f32_32x32x16_bf16 v[32:47], v[224:227], v[206:209], v[32:47]
	s_mov_b32 m0, s8
	s_nop 0
	global_load_lds_dwordx4 v[222:223], off
	s_waitcnt lgkmcnt(6)
	v_mfma_f32_32x32x16_bf16 v[16:31], v[234:237], v[202:205], v[16:31]
	s_add_i32 s5, s5, 0x8000
	v_lshl_add_u64 v[170:171], v[170:171], 0, 64
	v_lshl_add_u64 v[172:173], v[172:173], 0, 64
	s_cmp_eq_u32 s5, 0x2c0000
	v_mfma_f32_32x32x16_bf16 v[0:15], v[234:237], v[206:209], v[0:15]
	s_cbranch_scc0 .LBB0_2551
	s_branch .Lktail_7
.Lky_7:
	s_and_b32 s7, s5, 0x18000
	v_add_u32_e32 v222, s7, v180
	s_add_i32 s7, s5, 0xfffe8000
	s_and_b32 s7, s7, 0x18000
	v_or_b32_e32 v223, s7, v179
	v_add_u32_e32 v233, s7, v176
	s_waitcnt vmcnt(8) lgkmcnt(0)
	s_barrier
	v_add_u32_e32 v206, v223, v177
	v_add_u32_e32 v234, v233, v177
	ds_read_b128 v[202:205], v206 offset:16384
	ds_read_b128 v[206:209], v206 offset:18432
	ds_read_b128 v[210:213], v234
	ds_read_b128 v[214:217], v234 offset:2048
	ds_read_b128 v[224:227], v234 offset:4096
	ds_read_b128 v[234:237], v234 offset:6144
	v_mfma_f32_32x32x16_bf16 v[112:127], v[150:153], v[142:145], v[112:127]
	v_mfma_f32_32x32x16_bf16 v[96:111], v[150:153], v[130:133], v[96:111]
	v_readfirstlane_b32 s7, v222
	s_mov_b32 m0, s7
	s_nop 0
	global_load_lds_dwordx4 v[170:171], off
	v_mfma_f32_32x32x16_bf16 v[80:95], v[146:149], v[142:145], v[80:95]
	v_mfma_f32_32x32x16_bf16 v[64:79], v[146:149], v[130:133], v[64:79]
	v_mfma_f32_32x32x16_bf16 v[48:63], v[138:141], v[142:145], v[48:63]
	v_mfma_f32_32x32x16_bf16 v[32:47], v[138:141], v[130:133], v[32:47]
	s_add_i32 s8, s7, 0x2000
	v_lshl_add_u64 v[150:151], v[170:171], 0, s[10:11]
	s_mov_b32 m0, s8
	s_nop 0
	global_load_lds_dwordx4 v[150:151], off
	v_mfma_f32_32x32x16_bf16 v[16:31], v[134:137], v[142:145], v[16:31]
	v_mfma_f32_32x32x16_bf16 v[0:15], v[134:137], v[130:133], v[0:15]
	v_add_u32_e32 v130, v223, v178
	v_add_u32_e32 v134, v233, v178
	ds_read_b128 v[142:145], v130 offset:16384
	ds_read_b128 v[130:133], v130 offset:18432
	ds_read_b128 v[150:153], v134
	ds_read_b128 v[146:149], v134 offset:2048
	ds_read_b128 v[138:141], v134 offset:4096
	ds_read_b128 v[134:137], v134 offset:6144
	s_waitcnt lgkmcnt(9)
	v_mfma_f32_32x32x16_bf16 v[112:127], v[210:213], v[202:205], v[112:127]
	s_add_i32 s8, s7, 0x6000
	s_addk_i32 s7, 0x4000
	v_mfma_f32_32x32x16_bf16 v[96:111], v[210:213], v[206:209], v[96:111]
	s_mov_b32 m0, s7
	s_nop 0
	global_load_lds_dwordx4 v[172:173], off
	v_lshl_add_u64 v[222:223], v[172:173], 0, s[10:11]
	s_waitcnt lgkmcnt(8)
	v_mfma_f32_32x32x16_bf16 v[80:95], v[214:217], v[202:205], v[80:95]
	v_mfma_f32_32x32x16_bf16 v[64:79], v[214:217], v[206:209], v[64:79]
	s_waitcnt lgkmcnt(7)
	v_mfma_f32_32x32x16_bf16 v[48:63], v[224:227], v[202:205], v[48:63]
	v_mfma_f32_32x32x16_bf16 v[32:47], v[224:227], v[206:209], v[32:47]
	s_mov_b32 m0, s8
	s_nop 0
	global_load_lds_dwordx4 v[222:223], off
	s_waitcnt lgkmcnt(6)
	v_mfma_f32_32x32x16_bf16 v[16:31], v[234:237], v[202:205], v[16:31]
	s_add_i32 s5, s5, 0x8000
	v_lshl_add_u64 v[170:171], v[170:171], 0, 64
	v_lshl_add_u64 v[172:173], v[172:173], 0, 64
	s_cmp_eq_u32 s5, 0x2c0000
	v_mfma_f32_32x32x16_bf16 v[0:15], v[234:237], v[206:209], v[0:15]
	s_cbranch_scc0 .Lky_7
.Lktail_7:
	s_waitcnt vmcnt(8) lgkmcnt(0)
	s_barrier
	v_add_u32_e32 v202, v179, v177
	v_add_u32_e32 v222, v176, v177
	ds_read_b128 v[170:173], v202 offset:49152
	ds_read_b128 v[202:205], v202 offset:51200
	ds_read_b128 v[206:209], v222 offset:32768
	ds_read_b128 v[210:213], v222 offset:34816
	ds_read_b128 v[214:217], v222 offset:36864
	ds_read_b128 v[224:227], v222 offset:38912
	s_waitcnt lgkmcnt(9)
	v_mfma_f32_32x32x16_bf16 v[112:127], v[150:153], v[142:145], v[112:127]
	v_mfma_f32_32x32x16_bf16 v[96:111], v[150:153], v[130:133], v[96:111]
	s_waitcnt lgkmcnt(8)
	v_mfma_f32_32x32x16_bf16 v[80:95], v[146:149], v[142:145], v[80:95]
	v_mfma_f32_32x32x16_bf16 v[64:79], v[146:149], v[130:133], v[64:79]
	s_waitcnt lgkmcnt(7)
	v_mfma_f32_32x32x16_bf16 v[48:63], v[138:141], v[142:145], v[48:63]
	v_mfma_f32_32x32x16_bf16 v[32:47], v[138:141], v[130:133], v[32:47]
	s_waitcnt lgkmcnt(6)
	v_mfma_f32_32x32x16_bf16 v[16:31], v[134:137], v[142:145], v[16:31]
	v_mfma_f32_32x32x16_bf16 v[0:15], v[134:137], v[130:133], v[0:15]
	v_add_u32_e32 v134, v179, v178
	v_add_u32_e32 v150, v176, v178
	ds_read_b128 v[130:133], v134 offset:49152
	ds_read_b128 v[134:137], v134 offset:51200
	ds_read_b128 v[138:141], v150 offset:32768
	ds_read_b128 v[142:145], v150 offset:34816
	ds_read_b128 v[146:149], v150 offset:36864
	ds_read_b128 v[150:153], v150 offset:38912
	s_waitcnt lgkmcnt(9)
	v_mfma_f32_32x32x16_bf16 v[112:127], v[206:209], v[170:173], v[112:127]
	v_mfma_f32_32x32x16_bf16 v[96:111], v[206:209], v[202:205], v[96:111]
	s_waitcnt lgkmcnt(8)
	v_mfma_f32_32x32x16_bf16 v[80:95], v[210:213], v[170:173], v[80:95]
	v_mfma_f32_32x32x16_bf16 v[64:79], v[210:213], v[202:205], v[64:79]
	s_waitcnt lgkmcnt(7)
	v_mfma_f32_32x32x16_bf16 v[48:63], v[214:217], v[170:173], v[48:63]
	v_mfma_f32_32x32x16_bf16 v[32:47], v[214:217], v[202:205], v[32:47]
	s_waitcnt lgkmcnt(6)
	v_mfma_f32_32x32x16_bf16 v[0:15], v[224:227], v[202:205], v[0:15]
	s_waitcnt vmcnt(4) lgkmcnt(0)
	s_barrier
	v_add_u32_e32 v202, v199, v177
	v_add_u32_e32 v222, v200, v177
	v_mfma_f32_32x32x16_bf16 v[16:31], v[224:227], v[170:173], v[16:31]
	ds_read_b128 v[170:173], v202 offset:16384
	ds_read_b128 v[202:205], v202 offset:18432
	ds_read_b128 v[206:209], v222
	ds_read_b128 v[210:213], v222 offset:2048
	ds_read_b128 v[214:217], v222 offset:4096
	ds_read_b128 v[224:227], v222 offset:6144
	s_waitcnt lgkmcnt(9)
	v_mfma_f32_32x32x16_bf16 v[112:127], v[138:141], v[130:133], v[112:127]
	v_mfma_f32_32x32x16_bf16 v[96:111], v[138:141], v[134:137], v[96:111]
	s_waitcnt lgkmcnt(8)
	v_mfma_f32_32x32x16_bf16 v[80:95], v[142:145], v[130:133], v[80:95]
	v_mfma_f32_32x32x16_bf16 v[64:79], v[142:145], v[134:137], v[64:79]
	s_waitcnt lgkmcnt(7)
	v_mfma_f32_32x32x16_bf16 v[48:63], v[146:149], v[130:133], v[48:63]
	v_mfma_f32_32x32x16_bf16 v[32:47], v[146:149], v[134:137], v[32:47]
	s_waitcnt lgkmcnt(6)
	v_mfma_f32_32x32x16_bf16 v[16:31], v[150:153], v[130:133], v[16:31]
	v_mfma_f32_32x32x16_bf16 v[0:15], v[150:153], v[134:137], v[0:15]
	v_add_u32_e32 v134, v199, v178
	v_add_u32_e32 v150, v200, v178
	ds_read_b128 v[130:133], v134 offset:16384
	ds_read_b128 v[134:137], v134 offset:18432
	ds_read_b128 v[138:141], v150
	ds_read_b128 v[142:145], v150 offset:2048
	ds_read_b128 v[146:149], v150 offset:4096
	ds_read_b128 v[150:153], v150 offset:6144
	s_waitcnt lgkmcnt(9)
	v_mfma_f32_32x32x16_bf16 v[112:127], v[206:209], v[170:173], v[112:127]
	v_mfma_f32_32x32x16_bf16 v[96:111], v[206:209], v[202:205], v[96:111]
	s_waitcnt lgkmcnt(8)
	v_mfma_f32_32x32x16_bf16 v[80:95], v[210:213], v[170:173], v[80:95]
	v_mfma_f32_32x32x16_bf16 v[64:79], v[210:213], v[202:205], v[64:79]
	s_waitcnt lgkmcnt(7)
	v_mfma_f32_32x32x16_bf16 v[48:63], v[214:217], v[170:173], v[48:63]
	v_mfma_f32_32x32x16_bf16 v[32:47], v[214:217], v[202:205], v[32:47]
	s_waitcnt lgkmcnt(6)
	v_mfma_f32_32x32x16_bf16 v[0:15], v[224:227], v[202:205], v[0:15]
	s_waitcnt vmcnt(0) lgkmcnt(0)
	s_barrier
	v_add_u32_e32 v202, v197, v177
	v_add_u32_e32 v222, v198, v177
	v_mfma_f32_32x32x16_bf16 v[16:31], v[224:227], v[170:173], v[16:31]
	ds_read_b128 v[170:173], v202 offset:16384
	ds_read_b128 v[202:205], v202 offset:18432
	ds_read_b128 v[206:209], v222
	ds_read_b128 v[210:213], v222 offset:2048
	ds_read_b128 v[214:217], v222 offset:4096
	ds_read_b128 v[224:227], v222 offset:6144
	s_waitcnt lgkmcnt(9)
	v_mfma_f32_32x32x16_bf16 v[112:127], v[138:141], v[130:133], v[112:127]
	v_mfma_f32_32x32x16_bf16 v[96:111], v[138:141], v[134:137], v[96:111]
	s_waitcnt lgkmcnt(8)
	v_mfma_f32_32x32x16_bf16 v[80:95], v[142:145], v[130:133], v[80:95]
	v_mfma_f32_32x32x16_bf16 v[64:79], v[142:145], v[134:137], v[64:79]
	s_waitcnt lgkmcnt(7)
	v_mfma_f32_32x32x16_bf16 v[48:63], v[146:149], v[130:133], v[48:63]
	v_mfma_f32_32x32x16_bf16 v[32:47], v[146:149], v[134:137], v[32:47]
	s_waitcnt lgkmcnt(6)
	v_mfma_f32_32x32x16_bf16 v[16:31], v[150:153], v[130:133], v[16:31]
	v_mfma_f32_32x32x16_bf16 v[0:15], v[150:153], v[134:137], v[0:15]
	v_add_u32_e32 v134, v197, v178
	v_add_u32_e32 v150, v198, v178
	ds_read_b128 v[130:133], v134 offset:16384
	ds_read_b128 v[134:137], v134 offset:18432
	ds_read_b128 v[138:141], v150
	ds_read_b128 v[142:145], v150 offset:2048
	ds_read_b128 v[146:149], v150 offset:4096
	ds_read_b128 v[150:153], v150 offset:6144
	s_waitcnt lgkmcnt(9)
	v_mfma_f32_32x32x16_bf16 v[112:127], v[206:209], v[170:173], v[112:127]
	v_mfma_f32_32x32x16_bf16 v[96:111], v[206:209], v[202:205], v[96:111]
	s_waitcnt lgkmcnt(8)
	v_mfma_f32_32x32x16_bf16 v[80:95], v[210:213], v[170:173], v[80:95]
	v_mfma_f32_32x32x16_bf16 v[64:79], v[210:213], v[202:205], v[64:79]
	s_waitcnt lgkmcnt(7)
	v_mfma_f32_32x32x16_bf16 v[48:63], v[214:217], v[170:173], v[48:63]
	v_mfma_f32_32x32x16_bf16 v[32:47], v[214:217], v[202:205], v[32:47]
	s_waitcnt lgkmcnt(6)
	v_mfma_f32_32x32x16_bf16 v[16:31], v[224:227], v[170:173], v[16:31]
	s_movk_i32 s7, 0x1600
	v_mfma_f32_32x32x16_bf16 v[0:15], v[224:227], v[202:205], v[0:15]
	s_waitcnt lgkmcnt(3)
	v_mfma_f32_32x32x16_bf16 v[112:127], v[138:141], v[130:133], v[112:127]
	v_mfma_f32_32x32x16_bf16 v[96:111], v[138:141], v[134:137], v[96:111]
	s_nop 10
	v_cvt_pk_bf16_f32 v112, v112, s0
	s_waitcnt lgkmcnt(2)
	v_mfma_f32_32x32x16_bf16 v[80:95], v[142:145], v[130:133], v[80:95]
	v_cvt_pk_bf16_f32 v96, v96, s0
	v_cvt_pk_bf16_f32 v98, v98, s0
	s_waitcnt lgkmcnt(1)
	v_mfma_f32_32x32x16_bf16 v[48:63], v[146:149], v[130:133], v[48:63]
	s_nop 7
	v_cvt_pk_bf16_f32 v80, v80, s0
	s_waitcnt lgkmcnt(0)
	v_mfma_f32_32x32x16_bf16 v[16:31], v[150:153], v[130:133], v[16:31]
	v_add_u32_e32 v132, s3, v128
	v_or_b32_e32 v130, s4, v174
	v_ashrrev_i32_e32 v131, 31, v130
	v_lshl_add_u64 v[130:131], v[130:131], 1, v[158:159]
	v_cvt_pk_bf16_f32 v48, v48, s0
	v_readlane_b32 s3, v252, 7
	s_add_i32 s6, s6, s3
	v_mfma_f32_32x32x16_bf16 v[64:79], v[142:145], v[134:137], v[64:79]
	s_nop 3
	v_cvt_pk_bf16_f32 v16, v16, s0
	v_mfma_f32_32x32x16_bf16 v[32:47], v[146:149], v[134:137], v[32:47]
	s_nop 5
	v_cvt_pk_bf16_f32 v64, v64, s0
	v_cvt_pk_bf16_f32 v66, v66, s0
	v_mfma_f32_32x32x16_bf16 v[0:15], v[150:153], v[134:137], v[0:15]
	v_or_b32_e32 v134, v132, v181
	v_ashrrev_i32_e32 v135, 31, v134
	v_lshlrev_b64 v[134:135], 11, v[134:135]
	v_lshl_add_u64 v[134:135], v[130:131], 0, v[134:135]
	global_store_short v[134:135], v112, off
	global_store_short v[134:135], v96, off offset:64
	v_or_b32_e32 v134, v132, v182
	v_ashrrev_i32_e32 v135, 31, v134
	v_lshlrev_b64 v[134:135], 11, v[134:135]
	v_lshl_add_u64 v[134:135], v[130:131], 0, v[134:135]
	v_cvt_pk_bf16_f32 v96, v113, s0
	global_store_short v[134:135], v96, off
	v_cvt_pk_bf16_f32 v96, v97, s0
	global_store_short v[134:135], v96, off offset:64
	v_or_b32_e32 v96, v132, v183
	v_ashrrev_i32_e32 v97, 31, v96
	v_lshlrev_b64 v[96:97], 11, v[96:97]
	v_lshl_add_u64 v[96:97], v[130:131], 0, v[96:97]
	v_cvt_pk_bf16_f32 v112, v114, s0
	global_store_short v[96:97], v112, off
	global_store_short v[96:97], v98, off offset:64
	v_or_b32_e32 v96, v132, v184
	v_ashrrev_i32_e32 v97, 31, v96
	v_lshlrev_b64 v[96:97], 11, v[96:97]
	v_lshl_add_u64 v[96:97], v[130:131], 0, v[96:97]
	v_cvt_pk_bf16_f32 v98, v115, s0
	global_store_short v[96:97], v98, off
	v_cvt_pk_bf16_f32 v98, v99, s0
	global_store_short v[96:97], v98, off offset:64
	v_or_b32_e32 v96, v132, v185
	v_ashrrev_i32_e32 v97, 31, v96
	v_lshlrev_b64 v[96:97], 11, v[96:97]
	v_lshl_add_u64 v[96:97], v[130:131], 0, v[96:97]
	v_cvt_pk_bf16_f32 v98, v116, s0
	global_store_short v[96:97], v98, off
	v_cvt_pk_bf16_f32 v98, v100, s0
	global_store_short v[96:97], v98, off offset:64
	v_or_b32_e32 v96, v132, v186
	v_ashrrev_i32_e32 v97, 31, v96
	v_lshlrev_b64 v[96:97], 11, v[96:97]
	v_lshl_add_u64 v[96:97], v[130:131], 0, v[96:97]
	v_cvt_pk_bf16_f32 v98, v117, s0
	global_store_short v[96:97], v98, off
	v_cvt_pk_bf16_f32 v98, v101, s0
	global_store_short v[96:97], v98, off offset:64
	v_or_b32_e32 v96, v132, v187
	v_ashrrev_i32_e32 v97, 31, v96
	v_lshlrev_b64 v[96:97], 11, v[96:97]
	v_lshl_add_u64 v[96:97], v[130:131], 0, v[96:97]
	v_cvt_pk_bf16_f32 v98, v118, s0
	global_store_short v[96:97], v98, off
	v_cvt_pk_bf16_f32 v98, v102, s0
	global_store_short v[96:97], v98, off offset:64
	v_or_b32_e32 v96, v132, v188
	v_ashrrev_i32_e32 v97, 31, v96
	v_lshlrev_b64 v[96:97], 11, v[96:97]
	v_lshl_add_u64 v[96:97], v[130:131], 0, v[96:97]
	v_cvt_pk_bf16_f32 v98, v119, s0
	global_store_short v[96:97], v98, off
	v_cvt_pk_bf16_f32 v98, v103, s0
	global_store_short v[96:97], v98, off offset:64
	v_or_b32_e32 v96, v132, v189
	v_ashrrev_i32_e32 v97, 31, v96
	v_lshlrev_b64 v[96:97], 11, v[96:97]
	v_lshl_add_u64 v[96:97], v[130:131], 0, v[96:97]
	v_cvt_pk_bf16_f32 v98, v120, s0
	global_store_short v[96:97], v98, off
	v_cvt_pk_bf16_f32 v98, v104, s0
	global_store_short v[96:97], v98, off offset:64
	v_or_b32_e32 v96, v132, v190
	v_ashrrev_i32_e32 v97, 31, v96
	v_lshlrev_b64 v[96:97], 11, v[96:97]
	v_lshl_add_u64 v[96:97], v[130:131], 0, v[96:97]
	v_cvt_pk_bf16_f32 v98, v121, s0
	global_store_short v[96:97], v98, off
	v_cvt_pk_bf16_f32 v98, v105, s0
	global_store_short v[96:97], v98, off offset:64
	v_or_b32_e32 v96, v132, v191
	v_ashrrev_i32_e32 v97, 31, v96
	v_lshlrev_b64 v[96:97], 11, v[96:97]
	v_lshl_add_u64 v[96:97], v[130:131], 0, v[96:97]
	v_cvt_pk_bf16_f32 v98, v122, s0
	global_store_short v[96:97], v98, off
	v_cvt_pk_bf16_f32 v98, v106, s0
	global_store_short v[96:97], v98, off offset:64
	v_or_b32_e32 v96, v132, v192
	v_ashrrev_i32_e32 v97, 31, v96
	v_lshlrev_b64 v[96:97], 11, v[96:97]
	v_lshl_add_u64 v[96:97], v[130:131], 0, v[96:97]
	v_cvt_pk_bf16_f32 v98, v123, s0
	global_store_short v[96:97], v98, off
	v_cvt_pk_bf16_f32 v98, v107, s0
	global_store_short v[96:97], v98, off offset:64
	v_or_b32_e32 v96, v132, v193
	v_ashrrev_i32_e32 v97, 31, v96
	v_lshlrev_b64 v[96:97], 11, v[96:97]
	v_lshl_add_u64 v[96:97], v[130:131], 0, v[96:97]
	v_cvt_pk_bf16_f32 v98, v124, s0
	global_store_short v[96:97], v98, off
	v_cvt_pk_bf16_f32 v98, v108, s0
	global_store_short v[96:97], v98, off offset:64
	v_or_b32_e32 v96, v132, v194
	v_ashrrev_i32_e32 v97, 31, v96
	v_lshlrev_b64 v[96:97], 11, v[96:97]
	v_lshl_add_u64 v[96:97], v[130:131], 0, v[96:97]
	v_cvt_pk_bf16_f32 v98, v125, s0
	global_store_short v[96:97], v98, off
	v_cvt_pk_bf16_f32 v98, v109, s0
	global_store_short v[96:97], v98, off offset:64
	v_or_b32_e32 v96, v132, v195
	v_ashrrev_i32_e32 v97, 31, v96
	v_lshlrev_b64 v[96:97], 11, v[96:97]
	v_lshl_add_u64 v[96:97], v[130:131], 0, v[96:97]
	v_cvt_pk_bf16_f32 v98, v126, s0
	global_store_short v[96:97], v98, off
	v_cvt_pk_bf16_f32 v98, v110, s0
	global_store_short v[96:97], v98, off offset:64
	v_or_b32_e32 v96, v132, v196
	v_ashrrev_i32_e32 v97, 31, v96
	v_lshlrev_b64 v[96:97], 11, v[96:97]
	v_lshl_add_u64 v[96:97], v[130:131], 0, v[96:97]
	v_cvt_pk_bf16_f32 v98, v127, s0
	global_store_short v[96:97], v98, off
	v_cvt_pk_bf16_f32 v98, v111, s0
	global_store_short v[96:97], v98, off offset:64
	v_or_b32_e32 v98, 32, v132
	v_or_b32_e32 v96, v98, v181
	v_ashrrev_i32_e32 v97, 31, v96
	v_lshlrev_b64 v[96:97], 11, v[96:97]
	v_lshl_add_u64 v[96:97], v[130:131], 0, v[96:97]
	global_store_short v[96:97], v80, off
	global_store_short v[96:97], v64, off offset:64
	v_or_b32_e32 v96, v98, v182
	v_ashrrev_i32_e32 v97, 31, v96
	v_lshlrev_b64 v[96:97], 11, v[96:97]
	v_lshl_add_u64 v[96:97], v[130:131], 0, v[96:97]
	v_cvt_pk_bf16_f32 v64, v81, s0
	global_store_short v[96:97], v64, off
	v_cvt_pk_bf16_f32 v64, v65, s0
	global_store_short v[96:97], v64, off offset:64
	v_or_b32_e32 v64, v98, v183
	v_ashrrev_i32_e32 v65, 31, v64
	v_lshlrev_b64 v[64:65], 11, v[64:65]
	v_lshl_add_u64 v[64:65], v[130:131], 0, v[64:65]
	v_cvt_pk_bf16_f32 v80, v82, s0
	global_store_short v[64:65], v80, off
	global_store_short v[64:65], v66, off offset:64
	v_or_b32_e32 v64, v98, v184
	v_ashrrev_i32_e32 v65, 31, v64
	v_lshlrev_b64 v[64:65], 11, v[64:65]
	v_lshl_add_u64 v[64:65], v[130:131], 0, v[64:65]
	v_cvt_pk_bf16_f32 v66, v83, s0
	global_store_short v[64:65], v66, off
	v_cvt_pk_bf16_f32 v66, v67, s0
	global_store_short v[64:65], v66, off offset:64
	v_or_b32_e32 v64, v98, v185
	v_ashrrev_i32_e32 v65, 31, v64
	v_lshlrev_b64 v[64:65], 11, v[64:65]
	v_lshl_add_u64 v[64:65], v[130:131], 0, v[64:65]
	v_cvt_pk_bf16_f32 v66, v84, s0
	global_store_short v[64:65], v66, off
	v_cvt_pk_bf16_f32 v66, v68, s0
	global_store_short v[64:65], v66, off offset:64
	v_or_b32_e32 v64, v98, v186
	v_ashrrev_i32_e32 v65, 31, v64
	v_lshlrev_b64 v[64:65], 11, v[64:65]
	v_lshl_add_u64 v[64:65], v[130:131], 0, v[64:65]
	v_cvt_pk_bf16_f32 v66, v85, s0
	global_store_short v[64:65], v66, off
	v_cvt_pk_bf16_f32 v66, v69, s0
	global_store_short v[64:65], v66, off offset:64
	v_or_b32_e32 v64, v98, v187
	v_ashrrev_i32_e32 v65, 31, v64
	v_lshlrev_b64 v[64:65], 11, v[64:65]
	v_lshl_add_u64 v[64:65], v[130:131], 0, v[64:65]
	v_cvt_pk_bf16_f32 v66, v86, s0
	global_store_short v[64:65], v66, off
	v_cvt_pk_bf16_f32 v66, v70, s0
	global_store_short v[64:65], v66, off offset:64
	v_or_b32_e32 v64, v98, v188
	v_ashrrev_i32_e32 v65, 31, v64
	v_lshlrev_b64 v[64:65], 11, v[64:65]
	v_lshl_add_u64 v[64:65], v[130:131], 0, v[64:65]
	v_cvt_pk_bf16_f32 v66, v87, s0
	global_store_short v[64:65], v66, off
	v_cvt_pk_bf16_f32 v66, v71, s0
	global_store_short v[64:65], v66, off offset:64
	v_or_b32_e32 v64, v98, v189
	v_ashrrev_i32_e32 v65, 31, v64
	v_lshlrev_b64 v[64:65], 11, v[64:65]
	v_lshl_add_u64 v[64:65], v[130:131], 0, v[64:65]
	v_cvt_pk_bf16_f32 v66, v88, s0
	global_store_short v[64:65], v66, off
	v_cvt_pk_bf16_f32 v66, v72, s0
	global_store_short v[64:65], v66, off offset:64
	v_or_b32_e32 v64, v98, v190
	v_ashrrev_i32_e32 v65, 31, v64
	v_lshlrev_b64 v[64:65], 11, v[64:65]
	v_lshl_add_u64 v[64:65], v[130:131], 0, v[64:65]
	v_cvt_pk_bf16_f32 v66, v89, s0
	global_store_short v[64:65], v66, off
	v_cvt_pk_bf16_f32 v66, v73, s0
	global_store_short v[64:65], v66, off offset:64
	v_or_b32_e32 v64, v98, v191
	v_ashrrev_i32_e32 v65, 31, v64
	v_lshlrev_b64 v[64:65], 11, v[64:65]
	v_lshl_add_u64 v[64:65], v[130:131], 0, v[64:65]
	v_cvt_pk_bf16_f32 v66, v90, s0
	global_store_short v[64:65], v66, off
	v_cvt_pk_bf16_f32 v66, v74, s0
	global_store_short v[64:65], v66, off offset:64
	v_or_b32_e32 v64, v98, v192
	v_ashrrev_i32_e32 v65, 31, v64
	v_lshlrev_b64 v[64:65], 11, v[64:65]
	v_lshl_add_u64 v[64:65], v[130:131], 0, v[64:65]
	v_cvt_pk_bf16_f32 v66, v91, s0
	global_store_short v[64:65], v66, off
	v_cvt_pk_bf16_f32 v66, v75, s0
	global_store_short v[64:65], v66, off offset:64
	v_or_b32_e32 v64, v98, v193
	v_ashrrev_i32_e32 v65, 31, v64
	v_lshlrev_b64 v[64:65], 11, v[64:65]
	v_lshl_add_u64 v[64:65], v[130:131], 0, v[64:65]
	v_cvt_pk_bf16_f32 v66, v92, s0
	global_store_short v[64:65], v66, off
	v_cvt_pk_bf16_f32 v66, v76, s0
	global_store_short v[64:65], v66, off offset:64
	v_or_b32_e32 v64, v98, v194
	v_ashrrev_i32_e32 v65, 31, v64
	v_lshlrev_b64 v[64:65], 11, v[64:65]
	v_lshl_add_u64 v[64:65], v[130:131], 0, v[64:65]
	v_cvt_pk_bf16_f32 v66, v93, s0
	global_store_short v[64:65], v66, off
	v_cvt_pk_bf16_f32 v66, v77, s0
	global_store_short v[64:65], v66, off offset:64
	v_or_b32_e32 v64, v98, v195
	v_ashrrev_i32_e32 v65, 31, v64
	v_lshlrev_b64 v[64:65], 11, v[64:65]
	v_lshl_add_u64 v[64:65], v[130:131], 0, v[64:65]
	v_cvt_pk_bf16_f32 v66, v94, s0
	global_store_short v[64:65], v66, off
	v_cvt_pk_bf16_f32 v66, v78, s0
	global_store_short v[64:65], v66, off offset:64
	v_or_b32_e32 v64, v98, v196
	v_ashrrev_i32_e32 v65, 31, v64
	v_lshlrev_b64 v[64:65], 11, v[64:65]
	v_lshl_add_u64 v[64:65], v[130:131], 0, v[64:65]
	v_cvt_pk_bf16_f32 v66, v95, s0
	global_store_short v[64:65], v66, off
	v_cvt_pk_bf16_f32 v66, v79, s0
	global_store_short v[64:65], v66, off offset:64
	v_or_b32_e32 v66, 64, v132
	v_or_b32_e32 v64, v66, v181
	v_ashrrev_i32_e32 v65, 31, v64
	v_lshlrev_b64 v[64:65], 11, v[64:65]
	v_lshl_add_u64 v[64:65], v[130:131], 0, v[64:65]
	v_cvt_pk_bf16_f32 v32, v32, s0
	global_store_short v[64:65], v48, off
	global_store_short v[64:65], v32, off offset:64
	v_or_b32_e32 v64, v66, v182
	v_ashrrev_i32_e32 v65, 31, v64
	v_lshlrev_b64 v[64:65], 11, v[64:65]
	v_lshl_add_u64 v[64:65], v[130:131], 0, v[64:65]
	v_cvt_pk_bf16_f32 v32, v49, s0
	global_store_short v[64:65], v32, off
	v_cvt_pk_bf16_f32 v32, v33, s0
	global_store_short v[64:65], v32, off offset:64
	v_or_b32_e32 v32, v66, v183
	v_ashrrev_i32_e32 v33, 31, v32
	v_lshlrev_b64 v[32:33], 11, v[32:33]
	v_lshl_add_u64 v[32:33], v[130:131], 0, v[32:33]
	v_cvt_pk_bf16_f32 v48, v50, s0
	v_cvt_pk_bf16_f32 v34, v34, s0
	global_store_short v[32:33], v48, off
	global_store_short v[32:33], v34, off offset:64
	v_or_b32_e32 v32, v66, v184
	v_ashrrev_i32_e32 v33, 31, v32
	v_lshlrev_b64 v[32:33], 11, v[32:33]
	v_lshl_add_u64 v[32:33], v[130:131], 0, v[32:33]
	v_cvt_pk_bf16_f32 v34, v51, s0
	global_store_short v[32:33], v34, off
	v_cvt_pk_bf16_f32 v34, v35, s0
	global_store_short v[32:33], v34, off offset:64
	v_or_b32_e32 v32, v66, v185
	v_ashrrev_i32_e32 v33, 31, v32
	v_lshlrev_b64 v[32:33], 11, v[32:33]
	v_lshl_add_u64 v[32:33], v[130:131], 0, v[32:33]
	v_cvt_pk_bf16_f32 v34, v52, s0
	global_store_short v[32:33], v34, off
	v_cvt_pk_bf16_f32 v34, v36, s0
	global_store_short v[32:33], v34, off offset:64
	v_or_b32_e32 v32, v66, v186
	v_ashrrev_i32_e32 v33, 31, v32
	v_lshlrev_b64 v[32:33], 11, v[32:33]
	v_lshl_add_u64 v[32:33], v[130:131], 0, v[32:33]
	v_cvt_pk_bf16_f32 v34, v53, s0
	global_store_short v[32:33], v34, off
	v_cvt_pk_bf16_f32 v34, v37, s0
	global_store_short v[32:33], v34, off offset:64
	v_or_b32_e32 v32, v66, v187
	v_ashrrev_i32_e32 v33, 31, v32
	v_lshlrev_b64 v[32:33], 11, v[32:33]
	v_lshl_add_u64 v[32:33], v[130:131], 0, v[32:33]
	v_cvt_pk_bf16_f32 v34, v54, s0
	global_store_short v[32:33], v34, off
	v_cvt_pk_bf16_f32 v34, v38, s0
	global_store_short v[32:33], v34, off offset:64
	v_or_b32_e32 v32, v66, v188
	v_ashrrev_i32_e32 v33, 31, v32
	v_lshlrev_b64 v[32:33], 11, v[32:33]
	v_lshl_add_u64 v[32:33], v[130:131], 0, v[32:33]
	v_cvt_pk_bf16_f32 v34, v55, s0
	global_store_short v[32:33], v34, off
	v_cvt_pk_bf16_f32 v34, v39, s0
	global_store_short v[32:33], v34, off offset:64
	v_or_b32_e32 v32, v66, v189
	v_ashrrev_i32_e32 v33, 31, v32
	v_lshlrev_b64 v[32:33], 11, v[32:33]
	v_lshl_add_u64 v[32:33], v[130:131], 0, v[32:33]
	v_cvt_pk_bf16_f32 v34, v56, s0
	global_store_short v[32:33], v34, off
	v_cvt_pk_bf16_f32 v34, v40, s0
	global_store_short v[32:33], v34, off offset:64
	v_or_b32_e32 v32, v66, v190
	v_ashrrev_i32_e32 v33, 31, v32
	v_lshlrev_b64 v[32:33], 11, v[32:33]
	v_lshl_add_u64 v[32:33], v[130:131], 0, v[32:33]
	v_cvt_pk_bf16_f32 v34, v57, s0
	global_store_short v[32:33], v34, off
	v_cvt_pk_bf16_f32 v34, v41, s0
	global_store_short v[32:33], v34, off offset:64
	v_or_b32_e32 v32, v66, v191
	v_ashrrev_i32_e32 v33, 31, v32
	v_lshlrev_b64 v[32:33], 11, v[32:33]
	v_lshl_add_u64 v[32:33], v[130:131], 0, v[32:33]
	v_cvt_pk_bf16_f32 v34, v58, s0
	global_store_short v[32:33], v34, off
	v_cvt_pk_bf16_f32 v34, v42, s0
	global_store_short v[32:33], v34, off offset:64
	v_or_b32_e32 v32, v66, v192
	v_ashrrev_i32_e32 v33, 31, v32
	v_lshlrev_b64 v[32:33], 11, v[32:33]
	v_lshl_add_u64 v[32:33], v[130:131], 0, v[32:33]
	v_cvt_pk_bf16_f32 v34, v59, s0
	global_store_short v[32:33], v34, off
	v_cvt_pk_bf16_f32 v34, v43, s0
	global_store_short v[32:33], v34, off offset:64
	v_or_b32_e32 v32, v66, v193
	v_ashrrev_i32_e32 v33, 31, v32
	v_lshlrev_b64 v[32:33], 11, v[32:33]
	v_lshl_add_u64 v[32:33], v[130:131], 0, v[32:33]
	v_cvt_pk_bf16_f32 v34, v60, s0
	global_store_short v[32:33], v34, off
	v_cvt_pk_bf16_f32 v34, v44, s0
	global_store_short v[32:33], v34, off offset:64
	v_or_b32_e32 v32, v66, v194
	v_ashrrev_i32_e32 v33, 31, v32
	v_lshlrev_b64 v[32:33], 11, v[32:33]
	v_lshl_add_u64 v[32:33], v[130:131], 0, v[32:33]
	v_cvt_pk_bf16_f32 v34, v61, s0
	global_store_short v[32:33], v34, off
	v_cvt_pk_bf16_f32 v34, v45, s0
	global_store_short v[32:33], v34, off offset:64
	v_or_b32_e32 v32, v66, v195
	v_ashrrev_i32_e32 v33, 31, v32
	v_lshlrev_b64 v[32:33], 11, v[32:33]
	v_lshl_add_u64 v[32:33], v[130:131], 0, v[32:33]
	v_cvt_pk_bf16_f32 v34, v62, s0
	global_store_short v[32:33], v34, off
	v_cvt_pk_bf16_f32 v34, v46, s0
	global_store_short v[32:33], v34, off offset:64
	v_or_b32_e32 v32, v66, v196
	v_ashrrev_i32_e32 v33, 31, v32
	v_lshlrev_b64 v[32:33], 11, v[32:33]
	v_lshl_add_u64 v[32:33], v[130:131], 0, v[32:33]
	v_cvt_pk_bf16_f32 v34, v63, s0
	global_store_short v[32:33], v34, off
	v_cvt_pk_bf16_f32 v34, v47, s0
	global_store_short v[32:33], v34, off offset:64
	v_or_b32_e32 v34, 0x60, v132
	v_or_b32_e32 v32, v34, v181
	v_ashrrev_i32_e32 v33, 31, v32
	v_lshlrev_b64 v[32:33], 11, v[32:33]
	v_lshl_add_u64 v[32:33], v[130:131], 0, v[32:33]
	v_cvt_pk_bf16_f32 v0, v0, s0
	global_store_short v[32:33], v16, off
	global_store_short v[32:33], v0, off offset:64
	v_or_b32_e32 v32, v34, v182
	v_ashrrev_i32_e32 v33, 31, v32
	v_lshlrev_b64 v[32:33], 11, v[32:33]
	v_lshl_add_u64 v[32:33], v[130:131], 0, v[32:33]
	v_cvt_pk_bf16_f32 v0, v17, s0
	global_store_short v[32:33], v0, off
	v_cvt_pk_bf16_f32 v0, v1, s0
	global_store_short v[32:33], v0, off offset:64
	v_or_b32_e32 v0, v34, v183
	v_ashrrev_i32_e32 v1, 31, v0
	v_lshlrev_b64 v[0:1], 11, v[0:1]
	v_lshl_add_u64 v[0:1], v[130:131], 0, v[0:1]
	v_cvt_pk_bf16_f32 v16, v18, s0
	v_cvt_pk_bf16_f32 v2, v2, s0
	global_store_short v[0:1], v16, off
	global_store_short v[0:1], v2, off offset:64
	v_or_b32_e32 v0, v34, v184
	v_ashrrev_i32_e32 v1, 31, v0
	v_lshlrev_b64 v[0:1], 11, v[0:1]
	v_lshl_add_u64 v[0:1], v[130:131], 0, v[0:1]
	v_cvt_pk_bf16_f32 v2, v19, s0
	global_store_short v[0:1], v2, off
	v_cvt_pk_bf16_f32 v2, v3, s0
	global_store_short v[0:1], v2, off offset:64
	v_or_b32_e32 v0, v34, v185
	v_ashrrev_i32_e32 v1, 31, v0
	v_lshlrev_b64 v[0:1], 11, v[0:1]
	v_lshl_add_u64 v[0:1], v[130:131], 0, v[0:1]
	v_cvt_pk_bf16_f32 v2, v20, s0
	global_store_short v[0:1], v2, off
	v_cvt_pk_bf16_f32 v2, v4, s0
	global_store_short v[0:1], v2, off offset:64
	v_or_b32_e32 v0, v34, v186
	v_ashrrev_i32_e32 v1, 31, v0
	v_lshlrev_b64 v[0:1], 11, v[0:1]
	v_lshl_add_u64 v[0:1], v[130:131], 0, v[0:1]
	v_cvt_pk_bf16_f32 v2, v21, s0
	global_store_short v[0:1], v2, off
	v_cvt_pk_bf16_f32 v2, v5, s0
	global_store_short v[0:1], v2, off offset:64
	v_or_b32_e32 v0, v34, v187
	v_ashrrev_i32_e32 v1, 31, v0
	v_lshlrev_b64 v[0:1], 11, v[0:1]
	v_lshl_add_u64 v[0:1], v[130:131], 0, v[0:1]
	v_cvt_pk_bf16_f32 v2, v22, s0
	global_store_short v[0:1], v2, off
	v_cvt_pk_bf16_f32 v2, v6, s0
	global_store_short v[0:1], v2, off offset:64
	v_or_b32_e32 v0, v34, v188
	v_ashrrev_i32_e32 v1, 31, v0
	v_lshlrev_b64 v[0:1], 11, v[0:1]
	v_lshl_add_u64 v[0:1], v[130:131], 0, v[0:1]
	v_cvt_pk_bf16_f32 v2, v23, s0
	global_store_short v[0:1], v2, off
	v_cvt_pk_bf16_f32 v2, v7, s0
	global_store_short v[0:1], v2, off offset:64
	v_or_b32_e32 v0, v34, v189
	v_ashrrev_i32_e32 v1, 31, v0
	v_lshlrev_b64 v[0:1], 11, v[0:1]
	v_lshl_add_u64 v[0:1], v[130:131], 0, v[0:1]
	v_cvt_pk_bf16_f32 v2, v24, s0
	global_store_short v[0:1], v2, off
	v_cvt_pk_bf16_f32 v2, v8, s0
	global_store_short v[0:1], v2, off offset:64
	v_or_b32_e32 v0, v34, v190
	v_ashrrev_i32_e32 v1, 31, v0
	v_lshlrev_b64 v[0:1], 11, v[0:1]
	v_lshl_add_u64 v[0:1], v[130:131], 0, v[0:1]
	v_cvt_pk_bf16_f32 v2, v25, s0
	global_store_short v[0:1], v2, off
	v_cvt_pk_bf16_f32 v2, v9, s0
	global_store_short v[0:1], v2, off offset:64
	v_or_b32_e32 v0, v34, v191
	v_ashrrev_i32_e32 v1, 31, v0
	v_lshlrev_b64 v[0:1], 11, v[0:1]
	v_lshl_add_u64 v[0:1], v[130:131], 0, v[0:1]
	v_cvt_pk_bf16_f32 v2, v26, s0
	global_store_short v[0:1], v2, off
	v_cvt_pk_bf16_f32 v2, v10, s0
	global_store_short v[0:1], v2, off offset:64
	v_or_b32_e32 v0, v34, v192
	v_ashrrev_i32_e32 v1, 31, v0
	v_lshlrev_b64 v[0:1], 11, v[0:1]
	v_lshl_add_u64 v[0:1], v[130:131], 0, v[0:1]
	v_cvt_pk_bf16_f32 v2, v27, s0
	global_store_short v[0:1], v2, off
	v_cvt_pk_bf16_f32 v2, v11, s0
	global_store_short v[0:1], v2, off offset:64
	v_or_b32_e32 v0, v34, v193
	v_ashrrev_i32_e32 v1, 31, v0
	v_lshlrev_b64 v[0:1], 11, v[0:1]
	v_lshl_add_u64 v[0:1], v[130:131], 0, v[0:1]
	v_cvt_pk_bf16_f32 v2, v28, s0
	global_store_short v[0:1], v2, off
	v_cvt_pk_bf16_f32 v2, v12, s0
	global_store_short v[0:1], v2, off offset:64
	v_or_b32_e32 v0, v34, v194
	v_ashrrev_i32_e32 v1, 31, v0
	v_lshlrev_b64 v[0:1], 11, v[0:1]
	v_lshl_add_u64 v[0:1], v[130:131], 0, v[0:1]
	v_cvt_pk_bf16_f32 v2, v29, s0
	global_store_short v[0:1], v2, off
	v_cvt_pk_bf16_f32 v2, v13, s0
	global_store_short v[0:1], v2, off offset:64
	v_or_b32_e32 v0, v34, v195
	v_ashrrev_i32_e32 v1, 31, v0
	v_lshlrev_b64 v[0:1], 11, v[0:1]
	v_lshl_add_u64 v[0:1], v[130:131], 0, v[0:1]
	v_cvt_pk_bf16_f32 v2, v30, s0
	global_store_short v[0:1], v2, off
	v_cvt_pk_bf16_f32 v2, v14, s0
	global_store_short v[0:1], v2, off offset:64
	v_or_b32_e32 v0, v34, v196
	v_ashrrev_i32_e32 v1, 31, v0
	v_lshlrev_b64 v[0:1], 11, v[0:1]
	v_lshl_add_u64 v[0:1], v[130:131], 0, v[0:1]
	v_cvt_pk_bf16_f32 v2, v31, s0
	global_store_short v[0:1], v2, off
	v_cvt_pk_bf16_f32 v2, v15, s0
	s_add_i32 s0, s0, s3
	v_readlane_b32 s3, v252, 8
	s_add_i32 s2, s2, s3
	s_cmp_gt_i32 s6, 31
	global_store_short v[0:1], v2, off offset:64
	s_cbranch_scc0 .LBB0_2550
